# v23: + cacheable kernarg pointer loads, GLA chunk-local item front part reorganised (loads first, straight-line a_pre/log-sigmoid with same arithmetic), GLA output-pass queue/og touch tweaks
# speedup vs baseline: 1.0299x; 1.0299x over previous
.LBB0_11:
	s_or_b64 exec, exec, s[6:7]
	s_memrealtime s[4:5]
	s_cmp_lt_i32 s90, 1
	s_waitcnt lgkmcnt(0)
	s_cselect_b64 s[4:5], -1, 0
	s_cmp_gt_i32 s91, 0
	s_cselect_b64 s[6:7], -1, 0
	s_and_b64 s[16:17], s[4:5], s[6:7]
	s_andn2_b64 vcc, exec, s[16:17]
	s_cbranch_vccnz .LBB0_673
	s_lshr_b32 s3, s2, 6
	s_lshl_b32 s2, s60, 3
	s_add_i32 s2, s3, s2
	s_min_i32 s13, s2, 0x53ff
	s_cmpk_lt_i32 s2, 0x5200
	s_cbranch_scc0 .LBB0_19
	s_mul_hi_i32 s4, s13, 0x63e7063f
	s_lshr_b32 s5, s4, 31
	s_ashr_i32 s4, s4, 12
	s_add_i32 s18, s4, s5
	s_mul_i32 s4, s18, 0x2900
	s_sub_i32 s22, s13, s4
	s_ashr_i32 s19, s18, 31
	s_mul_i32 s5, s18, 0x2a00000
	s_mul_hi_i32 s4, s18, 0x2a00000
	s_add_u32 s5, s94, s5
	s_addc_u32 s4, s95, s4
	s_add_u32 s6, s5, 0x200000
	s_addc_u32 s7, s4, 0
	s_cmpk_gt_i32 s22, 0xaff
	s_cbranch_scc0 .LBB0_20
	s_cmpk_gt_u32 s22, 0x107f
	s_cbranch_scc0 .LBB0_21
	s_cmpk_gt_u32 s22, 0x167f
	s_cbranch_scc0 .LBB0_22
	s_cmpk_gt_u32 s22, 0x187f
	s_cbranch_scc0 .LBB0_23
	s_cmpk_gt_u32 s22, 0x237f
	s_cbranch_scc0 .LBB0_24
	v_mov_b64_e32 v[2:3], s[0:1]
	global_load_dwordx2 v[2:3], v[2:3], off offset:192
	s_waitcnt vmcnt(0)
	s_add_u32 s8, s6, 0x2380000
	s_addc_u32 s9, s7, 0
	s_lshl_b32 s4, s22, 5
	s_lshl_b32 s5, s22, 1
	v_mov_b32_e32 v1, 0xb00000
	s_and_b32 s23, s4, 0x3e0
	s_and_b32 s4, s5, 0x7fffffc0
	s_add_i32 s12, s4, 0xffffb900
	s_mov_b64 s[10:11], 0
	s_waitcnt lgkmcnt(0)
	v_mad_i64_i32 v[2:3], s[4:5], s18, v1, v[2:3]
	s_branch .LBB0_25

.LBB0_25:
	s_andn2_b64 vcc, exec, s[10:11]
	s_cbranch_vccnz .LBB0_28
	v_mov_b64_e32 v[2:3], s[0:1]
	global_load_dwordx2 v[2:3], v[2:3], off offset:184
	s_waitcnt vmcnt(0)
	s_add_i32 s4, s22, 0xe780
	s_and_b32 s5, s4, 0xffff
	s_mul_i32 s5, s5, 0xba2f
	s_lshr_b32 s5, s5, 23
	s_mul_i32 s8, s5, 0xb0
	s_sub_i32 s4, s4, s8
	s_lshl_b32 s8, s4, 5
	s_and_b32 s23, s8, 0xffe0
	s_and_b32 s4, s4, 0xffff
	s_cmpk_gt_u32 s4, 0x57
	s_cbranch_scc0 .LBB0_29
	s_lshl_b32 s4, s23, 1
	s_add_i32 s4, s4, 0x7fffea00
	s_and_b32 s4, s4, 0x7fffff00
	s_and_b32 s8, s23, 0x60
	s_or_b32 s4, s8, s4
	s_bitset1_b32 s4, 7
	s_mov_b64 s[8:9], 0
	s_branch .LBB0_30

.LBB0_34:
	s_andn2_b64 vcc, exec, s[20:21]
	s_cbranch_vccnz .LBB0_36
	v_mov_b64_e32 v[2:3], s[0:1]
	global_load_dwordx2 v[2:3], v[2:3], off offset:176
	s_waitcnt vmcnt(0)
	s_lshl_b64 s[20:21], s[18:19], 22
	s_add_u32 s8, s6, 0x1680000
	s_addc_u32 s9, s7, 0
	s_lshl_b32 s4, s22, 5
	s_lshl_b32 s12, s22, 1
	s_and_b32 s23, s4, 0x3e0
	s_and_b32 s4, s12, 0x3fc0
	s_mov_b64 s[10:11], 0x400
	s_movk_i32 s5, 0x400
	s_add_i32 s12, s4, 0xffffd300
	s_mov_b32 s4, s23
	s_waitcnt lgkmcnt(0)
	v_lshl_add_u64 v[2:3], v[2:3], 0, s[20:21]

.LBB0_37:
	s_andn2_b64 vcc, exec, s[20:21]
	s_cbranch_vccnz .LBB0_39
	v_mov_b64_e32 v[2:3], s[0:1]
	global_load_dwordx2 v[2:3], v[2:3], off offset:112
	s_waitcnt vmcnt(0)
	s_add_i32 s4, s22, 0xef80
	s_and_b32 s8, s4, 0xffff
	s_mul_i32 s8, s8, 0xaaab
	s_lshr_b32 s12, s8, 16
	s_lshr_b32 s8, s8, 22
	s_mulk_i32 s8, 0x60
	s_sub_i32 s4, s4, s8
	s_add_u32 s8, s6, 0x1080000
	s_addc_u32 s9, s7, 0
	s_lshl_b32 s4, s4, 5
	v_mov_b32_e32 v1, 0xb28000
	s_and_b32 s23, s4, 0xffe0
	s_mov_b64 s[10:11], 0x400
	s_movk_i32 s5, 0xb28
	s_and_b32 s12, s12, 0xffc0
	s_mov_b32 s4, s23
	s_waitcnt lgkmcnt(0)
	v_mad_i64_i32 v[2:3], s[20:21], s18, v1, v[2:3]

.LBB0_40:
	v_mov_b64_e32 v[2:3], s[0:1]
	global_load_dwordx2 v[2:3], v[2:3], off offset:104
	s_waitcnt vmcnt(0)
	s_add_u32 s8, s6, 0xb00000
	s_addc_u32 s9, s7, 0
	s_lshl_b32 s4, s22, 5
	s_lshl_b32 s12, s22, 1
	v_mov_b32_e32 v1, 0xb00000
	s_and_b32 s23, s4, 0x3e0
	s_and_b32 s4, s12, 0x3fc0
	s_mov_b64 s[10:11], 0xb00
	s_movk_i32 s5, 0x400
	s_add_i32 s12, s4, 0xffffea00
	s_mov_b32 s4, s23
	s_waitcnt lgkmcnt(0)
	v_mad_i64_i32 v[2:3], s[20:21], s18, v1, v[2:3]

.LBB0_42:
	v_mov_b64_e32 v[2:3], s[0:1]
	global_load_dwordx2 v[2:3], v[2:3], off offset:96
	s_waitcnt vmcnt(0)
	s_mul_i32 s4, s22, 0xba3
	s_lshr_b32 s5, s4, 31
	s_ashr_i32 s4, s4, 19
	s_add_i32 s5, s4, s5
	s_mul_i32 s4, s5, 0xb0
	s_sub_i32 s4, s22, s4
	s_sext_i32_i16 s4, s4
	s_lshl_b32 s23, s4, 5
	s_cmpk_gt_i32 s4, 0x57
	s_cbranch_scc0 .LBB0_44
	s_lshl_b32 s4, s4, 6
	s_add_i32 s4, s4, 0x7fffea00
	s_and_b32 s4, s4, 0x7fffff00
	s_and_b32 s8, s23, 0x60
	s_or_b32 s4, s8, s4
	s_bitset1_b32 s4, 7
	s_cbranch_execz .LBB0_45
	s_branch .LBB0_46

.LBB0_48:
	v_mov_b64_e32 v[2:3], s[0:1]
	global_load_dwordx2 v[2:3], v[2:3], off offset:128
	s_waitcnt vmcnt(0)
	s_add_i32 s4, s13, 0xffffae00
	s_bfe_u32 s12, s13, 0x10006
	s_mov_b32 s7, 0
	s_lshr_b32 s6, s4, 7
	s_lshl_b32 s10, s12, 19
	s_mov_b32 s11, s7
	s_lshl_b64 s[18:19], s[6:7], 20
	s_lshl_b64 s[6:7], s[6:7], 19
	s_add_u32 s4, s94, s6
	s_addc_u32 s6, s95, s7
	s_add_u32 s8, s4, 0x28a00000
	s_addc_u32 s9, s6, 0
	s_lshl_b32 s6, s13, 5
	s_lshl_b32 s4, s12, 7
	s_lshl_b32 s7, s13, 4
	s_and_b32 s23, s6, 0x60
	s_movk_i32 s5, 0x80
	s_and_b32 s12, s7, 0x3c0
	s_or_b32 s4, s4, s23
	s_waitcnt lgkmcnt(0)
	v_lshl_add_u64 v[2:3], v[2:3], 0, s[18:19]
	v_lshl_add_u64 v[2:3], v[2:3], 0, s[10:11]
	s_mov_b64 s[10:11], 0x400

.LBB0_114:
	s_add_i32 s34, s13, s6
	s_cmpk_lt_i32 s34, 0x5400
	s_cselect_b64 s[20:21], -1, 0
	s_and_b64 s[22:23], s[20:21], exec
	s_cselect_b32 s36, s34, 0x53ff
	s_cmpk_lt_i32 s36, 0x5200
	s_mov_b64 s[38:39], -1
	s_cbranch_scc0 .LBB0_143
	s_mul_hi_i32 s18, s36, 0x63e7063f
	s_lshr_b32 s22, s18, 31
	s_ashr_i32 s18, s18, 12
	s_add_i32 s40, s18, s22
	s_mul_i32 s18, s40, 0x2900
	s_sub_i32 s18, s36, s18
	s_ashr_i32 s41, s40, 31
	s_mul_i32 s23, s40, 0x2a00000
	s_mul_hi_i32 s22, s40, 0x2a00000
	s_add_u32 s38, s5, s23
	s_addc_u32 s39, s7, s22
	s_cmpk_gt_i32 s18, 0xaff
	s_mov_b64 s[42:43], -1
	s_cbranch_scc0 .LBB0_136
	s_cmpk_gt_u32 s18, 0x107f
	s_cbranch_scc0 .LBB0_133
	s_cmpk_gt_u32 s18, 0x167f
	s_cbranch_scc0 .LBB0_130
	s_cmpk_gt_u32 s18, 0x187f
	s_cbranch_scc0 .LBB0_127
	s_cmpk_gt_u32 s18, 0x237f
	s_mov_b64 s[24:25], -1
	s_cbranch_scc0 .LBB0_121
	v_mov_b64_e32 v[34:35], s[0:1]
	global_load_dwordx2 v[34:35], v[34:35], off offset:192
	s_waitcnt vmcnt(0)
	s_add_u32 s22, s38, 0x2380000
	s_addc_u32 s23, s39, 0
	s_lshl_b32 s24, s18, 5
	s_lshl_b32 s25, s18, 1
	s_and_b32 s37, s24, 0x3e0
	s_and_b32 s24, s25, 0x7fffffc0
	s_add_i32 s26, s24, 0xffffb900
	s_waitcnt lgkmcnt(0)
	v_mad_i64_i32 v[34:35], s[24:25], s40, v110, v[34:35]
	s_mov_b64 s[24:25], 0
.LBB0_121:
	s_andn2_b64 vcc, exec, s[24:25]
	s_cbranch_vccnz .LBB0_274
	v_mov_b64_e32 v[34:35], s[0:1]
	global_load_dwordx2 v[34:35], v[34:35], off offset:184
	s_waitcnt vmcnt(0)
	s_add_i32 s22, s18, 0xe780
	s_and_b32 s23, s22, 0xffff
	s_mul_i32 s23, s23, 0xba2f
	s_lshr_b32 s24, s23, 23
	s_mul_i32 s23, s24, 0xb0
	s_sub_i32 s22, s22, s23
	s_lshl_b32 s23, s22, 5
	s_and_b32 s37, s23, 0xffe0
	s_and_b32 s22, s22, 0xffff
	s_cmpk_gt_u32 s22, 0x57
	s_mov_b64 s[22:23], -1
	s_cbranch_scc0 .LBB0_124
	s_lshl_b32 s22, s37, 1
	s_add_i32 s22, s22, 0x7fffea00
	s_and_b32 s22, s22, 0x7fffff00
	s_and_b32 s23, s37, 0x60
	s_or_b32 s22, s23, s22
	s_or_b32 s35, s22, 0x80
	s_mov_b64 s[22:23], 0

.LBB0_128:
	v_mov_b64_e32 v[34:35], s[0:1]
	global_load_dwordx2 v[34:35], v[34:35], off offset:176
	s_waitcnt vmcnt(0)
	s_lshl_b64 s[42:43], s[40:41], 22
	s_add_u32 s22, s38, 0x1680000
	s_addc_u32 s23, s39, 0
	s_lshl_b32 s26, s18, 5
	s_lshl_b32 s35, s18, 1
	s_and_b32 s37, s26, 0x3e0
	s_and_b32 s26, s35, 0x3fc0
	s_mov_b64 s[24:25], 0x400
	s_movk_i32 s27, 0x400
	s_addk_i32 s26, 0xd300
	s_mov_b32 s35, s37
	s_waitcnt lgkmcnt(0)
	v_lshl_add_u64 v[34:35], v[34:35], 0, s[42:43]

.LBB0_130:
	s_andn2_b64 vcc, exec, s[42:43]
	s_cbranch_vccnz .LBB0_132
	v_mov_b64_e32 v[34:35], s[0:1]
	global_load_dwordx2 v[34:35], v[34:35], off offset:112
	s_waitcnt vmcnt(0)
	s_add_i32 s22, s18, 0xef80
	s_and_b32 s23, s22, 0xffff
	s_mul_i32 s23, s23, 0xaaab
	s_lshr_b32 s26, s23, 16
	s_lshr_b32 s23, s23, 22
	s_mulk_i32 s23, 0x60
	s_sub_i32 s35, s22, s23
	s_add_u32 s22, s38, 0x1080000
	s_addc_u32 s23, s39, 0
	s_lshl_b32 s35, s35, 5
	s_and_b32 s37, s35, 0xffe0
	s_mov_b64 s[24:25], 0x400
	s_movk_i32 s27, 0xb28
	s_and_b32 s26, s26, 0xffc0
	s_mov_b32 s35, s37
	s_waitcnt lgkmcnt(0)
	v_mad_i64_i32 v[34:35], s[42:43], s40, v112, v[34:35]

.LBB0_133:
	s_andn2_b64 vcc, exec, s[42:43]
	s_cbranch_vccnz .LBB0_135
	v_mov_b64_e32 v[34:35], s[0:1]
	global_load_dwordx2 v[34:35], v[34:35], off offset:104
	s_waitcnt vmcnt(0)
	s_add_u32 s22, s38, 0xb00000
	s_addc_u32 s23, s39, 0
	s_lshl_b32 s26, s18, 5
	s_lshl_b32 s35, s18, 1
	s_and_b32 s37, s26, 0x3e0
	s_and_b32 s26, s35, 0x3fc0
	s_mov_b64 s[24:25], 0xb00
	s_movk_i32 s27, 0x400
	s_addk_i32 s26, 0xea00
	s_mov_b32 s35, s37
	s_waitcnt lgkmcnt(0)
	v_mad_i64_i32 v[34:35], s[42:43], s40, v110, v[34:35]

.LBB0_136:
	s_andn2_b64 vcc, exec, s[42:43]
	s_cbranch_vccnz .LBB0_142
	v_mov_b64_e32 v[34:35], s[0:1]
	global_load_dwordx2 v[34:35], v[34:35], off offset:96
	s_waitcnt vmcnt(0)
	s_mul_i32 s22, s18, 0xba3
	s_lshr_b32 s23, s22, 31
	s_ashr_i32 s24, s22, 19
	s_add_i32 s24, s24, s23
	s_mul_i32 s22, s24, 0xb0
	s_sub_i32 s18, s18, s22
	s_sext_i32_i16 s18, s18
	s_lshl_b32 s37, s18, 5
	s_cmpk_gt_i32 s18, 0x57
	s_mov_b64 s[22:23], -1
	s_cbranch_scc0 .LBB0_139
	s_lshl_b32 s18, s18, 6
	s_add_i32 s18, s18, 0x7fffea00
	s_and_b32 s18, s18, 0x7fffff00
	s_and_b32 s22, s37, 0x60
	s_or_b32 s18, s22, s18
	s_or_b32 s35, s18, 0x80
	s_mov_b64 s[22:23], 0

.LBB0_143:
	s_andn2_b64 vcc, exec, s[38:39]
	s_cbranch_vccnz .LBB0_145
	v_mov_b64_e32 v[34:35], s[0:1]
	global_load_dwordx2 v[34:35], v[34:35], off offset:128
	s_waitcnt vmcnt(0)
	s_add_i32 s18, s36, 0xffffae00
	s_bfe_u32 s26, s36, 0x10006
	s_lshr_b32 s18, s18, 7
	s_lshl_b32 s24, s26, 19
	s_lshl_b64 s[38:39], s[18:19], 20
	s_lshl_b64 s[22:23], s[18:19], 19
	s_add_u32 s22, s28, s22
	s_addc_u32 s23, s29, s23
	s_lshl_b32 s18, s26, 7
	s_lshl_b32 s26, s36, 5
	s_mov_b32 s25, s19
	s_lshl_b32 s35, s36, 4
	s_and_b32 s37, s26, 0x60
	s_movk_i32 s27, 0x80
	s_and_b32 s26, s35, 0x3c0
	s_or_b32 s35, s18, s37
	s_waitcnt lgkmcnt(0)
	v_lshl_add_u64 v[34:35], v[34:35], 0, s[38:39]
	v_lshl_add_u64 v[34:35], v[34:35], 0, s[24:25]
	s_mov_b64 s[24:25], 0x400

.LBB0_177:
	s_or_b64 exec, exec, s[38:39]
	v_add_u32_e32 v146, 0x400, v113
	v_add_u32_e32 v147, 0x800, v113
	v_add_u32_e32 v148, 0xc00, v113
	v_add_u32_e32 v149, 0x1000, v113
	v_add_u32_e32 v150, 0x1400, v113
	v_add_u32_e32 v151, 0x1800, v113
	v_add_u32_e32 v152, 0x1c00, v113
	s_waitcnt vmcnt(0)
	ds_write2_b32 v113, v2, v3 offset1:66
	ds_write2_b32 v113, v4, v5 offset0:132 offset1:198
	ds_write2_b32 v146, v6, v7 offset0:8 offset1:74
	ds_write2_b32 v146, v8, v9 offset0:140 offset1:206
	ds_write2_b32 v147, v10, v11 offset0:16 offset1:82
	ds_write2_b32 v147, v12, v13 offset0:148 offset1:214
	ds_write2_b32 v148, v14, v15 offset0:24 offset1:90
	ds_write2_b32 v148, v16, v17 offset0:156 offset1:222
	ds_write2_b32 v149, v18, v19 offset0:32 offset1:98
	ds_write2_b32 v149, v20, v21 offset0:164 offset1:230
	ds_write2_b32 v150, v22, v23 offset0:40 offset1:106
	ds_write2_b32 v150, v24, v25 offset0:172 offset1:238
	ds_write2_b32 v151, v26, v27 offset0:48 offset1:114
	ds_write2_b32 v151, v28, v29 offset0:180 offset1:246
	ds_write2_b32 v152, v30, v31 offset0:56 offset1:122
	ds_write2_b32 v152, v32, v33 offset0:188 offset1:254
	s_waitcnt lgkmcnt(0)
	ds_read2_b32 v[6:7], v106 offset1:8
	ds_read2_b32 v[8:9], v106 offset0:33 offset1:41
	ds_read2_b32 v[10:11], v106 offset0:66 offset1:74
	ds_read2_b32 v[12:13], v106 offset0:99 offset1:107
	ds_read2_b32 v[14:15], v106 offset0:132 offset1:140
	s_waitcnt lgkmcnt(4)
	s_waitcnt lgkmcnt(3)
	ds_read2_b32 v[16:17], v106 offset0:165 offset1:173
	v_cvt_pk_bf16_f32 v2, v6, v8
	s_waitcnt lgkmcnt(3)
	s_waitcnt lgkmcnt(2)
	ds_read2_b32 v[18:19], v106 offset0:198 offset1:206
	ds_read2_b32 v[20:21], v106 offset0:231 offset1:239
	v_cvt_pk_bf16_f32 v3, v10, v12
	s_waitcnt lgkmcnt(3)
	s_waitcnt lgkmcnt(2)
	v_cvt_pk_bf16_f32 v4, v14, v16
	s_waitcnt lgkmcnt(1)
	s_waitcnt lgkmcnt(0)
	v_cvt_pk_bf16_f32 v5, v18, v20
	v_add_u32_e32 v6, s4, v105
	v_ashrrev_i32_e32 v8, 31, v6
	v_mul_lo_u32 v8, s10, v8
	v_mul_lo_u32 v10, s11, v6
	v_mad_u64_u32 v[22:23], s[36:37], s10, v6, 0
	s_add_i32 s18, s30, s13
	v_add3_u32 v23, v23, v8, v10
	s_ashr_i32 s13, s12, 31
	v_lshl_add_u64 v[22:23], v[22:23], 1, s[8:9]
	s_lshl_b64 s[12:13], s[12:13], 1
	v_lshl_add_u64 v[22:23], v[22:23], 0, s[12:13]
	v_lshl_add_u64 v[22:23], v[22:23], 0, v[100:101]
	global_store_dwordx4 v[22:23], v[2:5], off
	s_nop 1
	v_cvt_pk_bf16_f32 v2, v7, v9
	v_cvt_pk_bf16_f32 v3, v11, v13
	v_cvt_pk_bf16_f32 v4, v15, v17
	v_cvt_pk_bf16_f32 v5, v19, v21
	v_add_u32_e32 v6, s4, v107
	v_ashrrev_i32_e32 v7, 31, v6
	v_mul_lo_u32 v8, s10, v7
	v_mul_lo_u32 v9, s11, v6
	v_mad_u64_u32 v[6:7], s[36:37], s10, v6, 0
	v_add3_u32 v7, v7, v8, v9
	v_lshl_add_u64 v[6:7], v[6:7], 1, s[8:9]
	v_lshl_add_u64 v[6:7], v[6:7], 0, s[12:13]
	ds_read2_b32 v[8:9], v106 offset0:16 offset1:24
	v_lshl_add_u64 v[6:7], v[6:7], 0, v[100:101]
	global_store_dwordx4 v[6:7], v[2:5], off
	ds_read2_b32 v[6:7], v106 offset0:49 offset1:57
	ds_read2_b32 v[10:11], v106 offset0:82 offset1:90
	ds_read2_b32 v[12:13], v106 offset0:115 offset1:123
	s_waitcnt lgkmcnt(3)
	s_waitcnt lgkmcnt(2)
	ds_read2_b32 v[14:15], v106 offset0:148 offset1:156
	ds_read2_b32 v[16:17], v106 offset0:181 offset1:189
	v_cvt_pk_bf16_f32 v2, v8, v6
	s_waitcnt lgkmcnt(3)
	s_waitcnt lgkmcnt(2)
	ds_read2_b32 v[18:19], v106 offset0:214 offset1:222
	ds_read2_b32 v[20:21], v106 offset0:247 offset1:255
	v_cvt_pk_bf16_f32 v3, v10, v12
	s_waitcnt lgkmcnt(3)
	s_waitcnt lgkmcnt(2)
	v_cvt_pk_bf16_f32 v4, v14, v16
	s_waitcnt lgkmcnt(1)
	s_waitcnt lgkmcnt(0)
	v_cvt_pk_bf16_f32 v5, v18, v20
	v_add_u32_e32 v6, s4, v108
	v_ashrrev_i32_e32 v8, 31, v6
	v_mul_lo_u32 v8, s10, v8
	v_mul_lo_u32 v10, s11, v6
	v_mad_u64_u32 v[22:23], s[36:37], s10, v6, 0
	v_add3_u32 v23, v23, v8, v10
	v_lshl_add_u64 v[22:23], v[22:23], 1, s[8:9]
	v_lshl_add_u64 v[22:23], v[22:23], 0, s[12:13]
	v_lshl_add_u64 v[22:23], v[22:23], 0, v[100:101]
	global_store_dwordx4 v[22:23], v[2:5], off
	s_nop 1
	v_cvt_pk_bf16_f32 v2, v9, v7
	v_cvt_pk_bf16_f32 v3, v11, v13
	v_cvt_pk_bf16_f32 v4, v15, v17
	v_cvt_pk_bf16_f32 v5, v19, v21
	v_add_u32_e32 v6, s4, v109
	v_ashrrev_i32_e32 v7, 31, v6
	v_mul_lo_u32 v8, s10, v7
	v_mul_lo_u32 v9, s11, v6
	v_mad_u64_u32 v[6:7], s[10:11], s10, v6, 0
	v_add3_u32 v7, v7, v8, v9
	v_lshl_add_u64 v[6:7], v[6:7], 1, s[8:9]
	v_lshl_add_u64 v[6:7], v[6:7], 0, s[12:13]
	v_lshl_add_u64 v[6:7], v[6:7], 0, v[100:101]
	global_store_dwordx4 v[6:7], v[2:5], off
	s_waitcnt lgkmcnt(0)
	s_min_i32 s27, s18, 0x53ff
	s_cmpk_lt_i32 s18, 0x5200
	s_mov_b64 s[38:39], -1
	s_cbranch_scc0 .LBB0_206
	s_mul_hi_i32 s4, s27, 0x63e7063f
	s_lshr_b32 s8, s4, 31
	s_ashr_i32 s4, s4, 12
	s_add_i32 s40, s4, s8
	s_mul_i32 s4, s40, 0x2900
	s_sub_i32 s18, s27, s4
	s_ashr_i32 s41, s40, 31
	s_mul_i32 s8, s40, 0x2a00000
	s_mul_hi_i32 s4, s40, 0x2a00000
	s_add_u32 s38, s5, s8
	s_addc_u32 s39, s7, s4
	s_cmpk_gt_i32 s18, 0xaff
	s_mov_b64 s[42:43], -1
	s_cbranch_scc0 .LBB0_199
	s_cmpk_gt_u32 s18, 0x107f
	s_cbranch_scc0 .LBB0_196
	s_cmpk_gt_u32 s18, 0x167f
	s_cbranch_scc0 .LBB0_193
	s_cmpk_gt_u32 s18, 0x187f
	s_cbranch_scc0 .LBB0_190
	s_cmpk_gt_u32 s18, 0x237f
	s_mov_b64 s[10:11], -1
	s_cbranch_scc0 .LBB0_184
	v_mov_b64_e32 v[2:3], s[0:1]
	global_load_dwordx2 v[2:3], v[2:3], off offset:192
	s_waitcnt vmcnt(0)
	s_add_u32 s8, s38, 0x2380000
	s_addc_u32 s9, s39, 0
	s_lshl_b32 s4, s18, 5
	s_lshl_b32 s10, s18, 1
	s_and_b32 s36, s4, 0x3e0
	s_and_b32 s4, s10, 0x7fffffc0
	s_add_i32 s12, s4, 0xffffb900
	s_waitcnt lgkmcnt(0)
	v_mad_i64_i32 v[34:35], s[10:11], s40, v110, v[2:3]
	s_mov_b64 s[10:11], 0
.LBB0_184:
	s_andn2_b64 vcc, exec, s[10:11]
	s_cbranch_vccnz .LBB0_275
	v_mov_b64_e32 v[2:3], s[0:1]
	global_load_dwordx2 v[2:3], v[2:3], off offset:184
	s_waitcnt vmcnt(0)
	s_add_i32 s4, s18, 0xe780
	s_and_b32 s8, s4, 0xffff
	s_mul_i32 s8, s8, 0xba2f
	s_lshr_b32 s10, s8, 23
	s_mul_i32 s8, s10, 0xb0
	s_sub_i32 s4, s4, s8
	s_lshl_b32 s8, s4, 5
	s_and_b32 s36, s8, 0xffe0
	s_and_b32 s4, s4, 0xffff
	s_cmpk_gt_u32 s4, 0x57
	s_mov_b64 s[8:9], -1
	s_cbranch_scc0 .LBB0_187
	s_lshl_b32 s4, s36, 1
	s_add_i32 s4, s4, 0x7fffea00
	s_and_b32 s4, s4, 0x7fffff00
	s_and_b32 s8, s36, 0x60
	s_or_b32 s4, s8, s4
	s_bitset1_b32 s4, 7
	s_mov_b64 s[8:9], 0

.LBB0_191:
	v_mov_b64_e32 v[2:3], s[0:1]
	global_load_dwordx2 v[2:3], v[2:3], off offset:176
	s_waitcnt vmcnt(0)
	s_lshl_b64 s[42:43], s[40:41], 22
	s_add_u32 s8, s38, 0x1680000
	s_addc_u32 s9, s39, 0
	s_lshl_b32 s4, s18, 5
	s_lshl_b32 s12, s18, 1
	s_and_b32 s36, s4, 0x3e0
	s_and_b32 s4, s12, 0x3fc0
	s_mov_b64 s[10:11], 0x400
	s_movk_i32 s13, 0x400
	s_add_i32 s12, s4, 0xffffd300
	s_mov_b32 s4, s36
	s_waitcnt lgkmcnt(0)
	v_lshl_add_u64 v[34:35], v[2:3], 0, s[42:43]

.LBB0_193:
	s_andn2_b64 vcc, exec, s[42:43]
	s_cbranch_vccnz .LBB0_195
	v_mov_b64_e32 v[2:3], s[0:1]
	global_load_dwordx2 v[2:3], v[2:3], off offset:112
	s_waitcnt vmcnt(0)
	s_add_i32 s4, s18, 0xef80
	s_and_b32 s8, s4, 0xffff
	s_mul_i32 s8, s8, 0xaaab
	s_lshr_b32 s12, s8, 16
	s_lshr_b32 s8, s8, 22
	s_mulk_i32 s8, 0x60
	s_sub_i32 s4, s4, s8
	s_add_u32 s8, s38, 0x1080000
	s_addc_u32 s9, s39, 0
	s_lshl_b32 s4, s4, 5
	s_and_b32 s36, s4, 0xffe0
	s_mov_b64 s[10:11], 0x400
	s_movk_i32 s13, 0xb28
	s_and_b32 s12, s12, 0xffc0
	s_mov_b32 s4, s36
	s_waitcnt lgkmcnt(0)
	v_mad_i64_i32 v[34:35], s[42:43], s40, v112, v[2:3]

.LBB0_196:
	s_andn2_b64 vcc, exec, s[42:43]
	s_cbranch_vccnz .LBB0_198
	v_mov_b64_e32 v[2:3], s[0:1]
	global_load_dwordx2 v[2:3], v[2:3], off offset:104
	s_waitcnt vmcnt(0)
	s_add_u32 s8, s38, 0xb00000
	s_addc_u32 s9, s39, 0
	s_lshl_b32 s4, s18, 5
	s_lshl_b32 s12, s18, 1
	s_and_b32 s36, s4, 0x3e0
	s_and_b32 s4, s12, 0x3fc0
	s_mov_b64 s[10:11], 0xb00
	s_movk_i32 s13, 0x400
	s_add_i32 s12, s4, 0xffffea00
	s_mov_b32 s4, s36
	s_waitcnt lgkmcnt(0)
	v_mad_i64_i32 v[34:35], s[42:43], s40, v110, v[2:3]

.LBB0_199:
	s_andn2_b64 vcc, exec, s[42:43]
	s_cbranch_vccnz .LBB0_205
	v_mov_b64_e32 v[2:3], s[0:1]
	global_load_dwordx2 v[2:3], v[2:3], off offset:96
	s_waitcnt vmcnt(0)
	s_mul_i32 s4, s18, 0xba3
	s_lshr_b32 s8, s4, 31
	s_ashr_i32 s10, s4, 19
	s_add_i32 s10, s10, s8
	s_mul_i32 s4, s10, 0xb0
	s_sub_i32 s4, s18, s4
	s_sext_i32_i16 s11, s4
	s_lshl_b32 s36, s11, 5
	s_cmpk_gt_i32 s11, 0x57
	s_mov_b64 s[8:9], -1
	s_cbranch_scc0 .LBB0_202
	s_lshl_b32 s4, s11, 6
	s_add_i32 s4, s4, 0x7fffea00
	s_and_b32 s4, s4, 0x7fffff00
	s_and_b32 s8, s36, 0x60
	s_or_b32 s4, s8, s4
	s_bitset1_b32 s4, 7
	s_mov_b64 s[8:9], 0

.LBB0_206:
	s_andn2_b64 vcc, exec, s[38:39]
	s_cbranch_vccnz .LBB0_208
	v_mov_b64_e32 v[2:3], s[0:1]
	global_load_dwordx2 v[2:3], v[2:3], off offset:128
	s_waitcnt vmcnt(0)
	s_add_i32 s4, s27, 0xffffae00
	s_bfe_u32 s12, s27, 0x10006
	s_lshr_b32 s18, s4, 7
	s_lshl_b32 s10, s12, 19
	s_lshl_b64 s[38:39], s[18:19], 20
	s_lshl_b64 s[8:9], s[18:19], 19
	s_add_u32 s8, s28, s8
	s_addc_u32 s9, s29, s9
	s_lshl_b32 s4, s12, 7
	s_lshl_b32 s12, s27, 5
	s_mov_b32 s11, s19
	s_lshl_b32 s18, s27, 4
	s_and_b32 s36, s12, 0x60
	s_movk_i32 s13, 0x80
	s_and_b32 s12, s18, 0x3c0
	s_or_b32 s4, s4, s36
	s_waitcnt lgkmcnt(0)
	v_lshl_add_u64 v[2:3], v[2:3], 0, s[38:39]
	v_lshl_add_u64 v[34:35], v[2:3], 0, s[10:11]
	s_mov_b64 s[10:11], 0x400

.LBB0_279:
	s_add_i32 s4, s6, 0xffffff80
	s_cmp_ge_i32 s2, s4
	s_cbranch_scc0 .LBB0_283
	s_waitcnt vmcnt(0)
	v_mov_b64_e32 v[2:3], s[0:1]
	global_load_dwordx2 v[4:5], v[2:3], off offset:120
	s_waitcnt vmcnt(0)
	global_load_dwordx2 v[6:7], v[2:3], off offset:128
	s_waitcnt vmcnt(0)
	s_sub_i32 s4, s2, s4
	s_mov_b32 s7, 0
	s_lshr_b32 s6, s4, 5
	s_and_b32 s4, s4, 31
	s_lshl_b64 s[22:23], s[6:7], 20
	s_mov_b32 s19, s7
	s_lshl_b64 s[20:21], s[6:7], 13
	s_lshl_b32 s18, s4, 15
	v_mov_b32_e32 v3, 0
	v_lshlrev_b32_e32 v2, 2, v98
	s_mov_b32 s13, s7
	s_lshl_b32 s12, s4, 8
	s_mov_b64 s[8:9], 0
	s_movk_i32 s2, 0x1000
	s_mov_b64 s[10:11], 0x2000
	s_waitcnt lgkmcnt(0)
	v_lshl_add_u64 v[4:5], v[4:5], 0, s[20:21]
	v_lshl_add_u64 v[6:7], v[6:7], 0, s[22:23]
	v_lshl_add_u64 v[6:7], v[6:7], 0, s[18:19]
	v_lshl_add_u64 v[4:5], v[4:5], 0, s[12:13]
	v_lshl_add_u64 v[6:7], v[6:7], 0, v[2:3]
	v_mov_b32_e32 v2, v3

.LBB0_283:
	s_waitcnt vmcnt(0)
	v_mov_b64_e32 v[2:3], s[0:1]
	global_load_dwordx2 v[4:5], v[2:3], off offset:16
	s_waitcnt vmcnt(0)
	global_load_dwordx2 v[6:7], v[2:3], off offset:24
	s_waitcnt vmcnt(0)
	global_load_dwordx2 v[8:9], v[2:3], off offset:72
	s_waitcnt vmcnt(0)
	s_and_b32 s4, s60, 0x7f
	s_mul_i32 s4, s4, 9
	s_lshr_b32 s8, s4, 1
	s_add_i32 s4, s4, 9
	s_ashr_i32 s2, s60, 7
	v_min_i32_e32 v16, 0xff, v0
	s_lshr_b32 s4, s4, 1
	s_add_i32 s3, s3, s8
	v_lshrrev_b32_e32 v22, 4, v16
	s_cmp_lt_u32 s3, s4
	s_movk_i32 s5, 0x200
	v_or_b32_e32 v22, 0x80, v22
	s_cselect_b64 s[12:13], -1, 0
	v_mov_b32_e32 v19, 0
	v_lshrrev_b32_e32 v27, 4, v0
	v_or_b32_e32 v13, 0x200, v0
	v_or_b32_e32 v14, 0x600, v0
	v_lshlrev_b32_e32 v16, 2, v16
	v_cmp_gt_u32_e32 vcc, s5, v0
	v_min_u32_e32 v22, 0x81, v22
	s_and_b64 s[4:5], s[12:13], exec
	v_mov_b32_e32 v24, 0x2400000
	v_lshlrev_b32_e32 v12, 4, v0
	v_lshlrev_b32_e32 v10, 12, v27
	v_lshrrev_b32_e32 v28, 4, v13
	v_lshrrev_b32_e32 v73, 4, v14
	v_mov_b32_e32 v23, v19
	v_and_b32_e32 v26, 60, v16
	v_lshlrev_b32_e32 v22, 12, v22
	s_cselect_b32 s3, s3, s8
	v_and_b32_e32 v72, 15, v0
	s_mov_b32 s19, 0
	v_mov_b32_e32 v11, v19
	v_and_b32_e32 v20, 0xf0, v12
	v_mov_b32_e32 v13, v19
	v_mov_b32_e32 v15, v19
	v_mov_b32_e32 v59, v19
	v_lshlrev_b32_e32 v12, 12, v28
	v_or_b32_e32 v14, 0x40000, v10
	v_or_b32_e32 v25, 0xffffff80, v73
	v_lshlrev_b32_e32 v58, 2, v26
	s_lshl_b32 s18, s3, 4
	v_lshrrev_b32_e32 v1, 4, v98
	s_mov_b32 s6, 0xfff80000
	v_lshlrev_b32_e32 v2, 2, v72
	v_mov_b32_e32 v3, v19
	v_cndmask_b32_e32 v16, v25, v73, vcc
	v_mul_u32_u24_e32 v18, 0x48000, v1
	s_mov_b32 s7, 0x9000
	s_mov_b32 s3, 0x12000
	v_mov_b32_e32 v21, v19
	v_mov_b32_e32 v17, v19
	v_lshlrev_b64 v[16:17], 12, v[16:17]
	s_waitcnt lgkmcnt(0)
	s_barrier
	v_and_b32_e32 v74, 0x78, v99
	v_lshl_add_u64 v[60:61], v[4:5], 0, v[22:23]
	v_lshl_add_u64 v[10:11], v[6:7], 0, v[10:11]
	v_mad_i64_i32 v[8:9], s[4:5], s2, v24, v[8:9]
	v_lshl_add_u64 v[12:13], v[6:7], 0, v[12:13]
	v_lshl_add_u64 v[14:15], v[6:7], 0, v[14:15]
	v_cndmask_b32_e32 v7, v5, v7, vcc
	v_cndmask_b32_e32 v6, v4, v6, vcc
	v_lshl_add_u64 v[4:5], s[18:19], 2, v[8:9]
	v_lshl_add_u64 v[24:25], v[60:61], 0, v[58:59]
	v_lshl_add_u64 v[30:31], v[4:5], 0, v[2:3]
	v_add_co_u32_e32 v2, vcc, s6, v24
	v_lshl_add_u64 v[70:71], v[30:31], 0, v[18:19]
	s_nop 0
	v_addc_co_u32_e32 v3, vcc, -1, v25, vcc
	v_add_co_u32_e32 v30, vcc, s7, v70
	v_lshl_add_u64 v[66:67], v[10:11], 0, v[20:21]
	s_nop 0
	v_addc_co_u32_e32 v31, vcc, 0, v71, vcc
	v_add_co_u32_e32 v32, vcc, s3, v70
	s_mov_b32 s3, 0x1b000
	s_nop 0
	v_addc_co_u32_e32 v33, vcc, 0, v71, vcc
	v_add_co_u32_e32 v34, vcc, s3, v70
	s_mov_b32 s3, 0x24000
	s_nop 0
	v_addc_co_u32_e32 v35, vcc, 0, v71, vcc
	v_lshl_add_u64 v[62:63], v[12:13], 0, v[20:21]
	v_lshl_add_u64 v[64:65], v[14:15], 0, v[20:21]
	v_lshl_add_u64 v[22:23], v[6:7], 0, v[16:17]
	global_load_dwordx4 v[14:17], v[66:67], off
	global_load_dwordx4 v[10:13], v[62:63], off
	global_load_dwordx4 v[6:9], v[64:65], off
	v_add_co_u32_e32 v36, vcc, s3, v70
	s_mov_b32 s3, 0x2d000
	s_nop 0
	v_addc_co_u32_e32 v37, vcc, 0, v71, vcc
	v_add_co_u32_e32 v38, vcc, s3, v70
	s_mov_b32 s3, 0x36000
	s_nop 0
	v_addc_co_u32_e32 v39, vcc, 0, v71, vcc
	v_add_co_u32_e32 v40, vcc, s3, v70
	s_mov_b32 s3, 0x3f000
	s_nop 0
	v_addc_co_u32_e32 v41, vcc, 0, v71, vcc
	v_add_co_u32_e32 v42, vcc, s3, v70
	s_mov_b32 s3, 0x120000
	s_nop 0
	v_addc_co_u32_e32 v43, vcc, 0, v71, vcc
	v_add_co_u32_e32 v44, vcc, s3, v70
	s_mov_b32 s3, 0x129000
	s_nop 0
	v_addc_co_u32_e32 v45, vcc, 0, v71, vcc
	v_lshl_add_u64 v[68:69], v[22:23], 0, v[20:21]
	global_load_dwordx4 v[2:5], v[2:3], off
	s_waitcnt vmcnt(3)
	v_mul_f32_e32 v29, 0xbfb8aa3b, v14
	global_load_dword v20, v[70:71], off nt
	global_load_dword v26, v[30:31], off nt
	global_load_dword v25, v[32:33], off nt
	global_load_dword v24, v[34:35], off nt
	global_load_dword v23, v[36:37], off nt
	global_load_dword v22, v[38:39], off nt
	global_load_dword v21, v[40:41], off nt
	global_load_dword v18, v[42:43], off nt
	global_load_dword v117, v[44:45], off nt
	v_add_co_u32_e32 v30, vcc, s3, v70
	s_mov_b32 s3, 0x132000
	s_nop 0
	v_addc_co_u32_e32 v31, vcc, 0, v71, vcc
	v_add_co_u32_e32 v32, vcc, s3, v70
	s_mov_b32 s3, 0x13b000
	s_nop 0
	v_addc_co_u32_e32 v33, vcc, 0, v71, vcc
	v_add_co_u32_e32 v34, vcc, s3, v70
	s_mov_b32 s3, 0x144000
	s_nop 0
	v_addc_co_u32_e32 v35, vcc, 0, v71, vcc
	v_add_co_u32_e32 v36, vcc, s3, v70
	s_mov_b32 s3, 0x14d000
	s_nop 0
	v_addc_co_u32_e32 v37, vcc, 0, v71, vcc
	v_add_co_u32_e32 v38, vcc, s3, v70
	s_mov_b32 s3, 0x156000
	s_nop 0
	v_addc_co_u32_e32 v39, vcc, 0, v71, vcc
	v_add_co_u32_e32 v40, vcc, s3, v70
	s_mov_b32 s3, 0x15f000
	s_nop 0
	v_addc_co_u32_e32 v41, vcc, 0, v71, vcc
	v_add_co_u32_e32 v42, vcc, s3, v70
	s_mov_b32 s3, 0x240000
	s_nop 0
	v_addc_co_u32_e32 v43, vcc, 0, v71, vcc
	v_add_co_u32_e32 v44, vcc, s3, v70
	s_mov_b32 s3, 0x249000
	s_nop 0
	v_addc_co_u32_e32 v45, vcc, 0, v71, vcc
	global_load_dword v135, v[30:31], off nt
	global_load_dword v132, v[32:33], off nt
	global_load_dword v129, v[34:35], off nt
	global_load_dword v126, v[36:37], off nt
	global_load_dword v123, v[38:39], off nt
	global_load_dword v120, v[40:41], off nt
	global_load_dword v113, v[42:43], off nt
	global_load_dword v85, v[44:45], off nt
	v_add_co_u32_e32 v30, vcc, s3, v70
	s_mov_b32 s3, 0x252000
	s_nop 0
	v_addc_co_u32_e32 v31, vcc, 0, v71, vcc
	v_add_co_u32_e32 v32, vcc, s3, v70
	s_mov_b32 s3, 0x25b000
	s_nop 0
	v_addc_co_u32_e32 v33, vcc, 0, v71, vcc
	v_add_co_u32_e32 v34, vcc, s3, v70
	s_mov_b32 s3, 0x264000
	s_nop 0
	v_addc_co_u32_e32 v35, vcc, 0, v71, vcc
	v_add_co_u32_e32 v36, vcc, s3, v70
	s_mov_b32 s3, 0x26d000
	s_nop 0
	v_addc_co_u32_e32 v37, vcc, 0, v71, vcc
	v_add_co_u32_e32 v38, vcc, s3, v70
	s_mov_b32 s3, 0x276000
	s_nop 0
	v_addc_co_u32_e32 v39, vcc, 0, v71, vcc
	v_add_co_u32_e32 v40, vcc, s3, v70
	s_mov_b32 s3, 0x27f000
	s_nop 0
	v_addc_co_u32_e32 v41, vcc, 0, v71, vcc
	v_add_co_u32_e32 v42, vcc, s3, v70
	s_mov_b32 s3, 0x360000
	s_nop 0
	v_addc_co_u32_e32 v43, vcc, 0, v71, vcc
	v_add_co_u32_e32 v44, vcc, s3, v70
	s_mov_b32 s3, 0x369000
	s_nop 0
	v_addc_co_u32_e32 v45, vcc, 0, v71, vcc
	global_load_dword v110, v[30:31], off nt
	global_load_dword v106, v[32:33], off nt
	global_load_dword v102, v[34:35], off nt
	global_load_dword v97, v[36:37], off nt
	global_load_dword v92, v[38:39], off nt
	global_load_dword v89, v[40:41], off nt
	global_load_dword v80, v[42:43], off nt
	global_load_dword v121, v[44:45], off nt
	v_add_co_u32_e32 v30, vcc, s3, v70
	s_mov_b32 s3, 0x372000
	s_nop 0
	v_addc_co_u32_e32 v31, vcc, 0, v71, vcc
	v_add_co_u32_e32 v32, vcc, s3, v70
	s_mov_b32 s3, 0x37b000
	s_nop 0
	v_addc_co_u32_e32 v33, vcc, 0, v71, vcc
	v_add_co_u32_e32 v34, vcc, s3, v70
	s_mov_b32 s3, 0x384000
	s_nop 0
	v_addc_co_u32_e32 v35, vcc, 0, v71, vcc
	v_add_co_u32_e32 v36, vcc, s3, v70
	s_mov_b32 s3, 0x38d000
	s_nop 0
	v_addc_co_u32_e32 v37, vcc, 0, v71, vcc
	v_add_co_u32_e32 v38, vcc, s3, v70
	s_mov_b32 s3, 0x396000
	s_nop 0
	v_addc_co_u32_e32 v39, vcc, 0, v71, vcc
	v_add_co_u32_e32 v40, vcc, s3, v70
	s_mov_b32 s3, 0x39f000
	s_nop 0
	v_addc_co_u32_e32 v41, vcc, 0, v71, vcc
	v_add_co_u32_e32 v42, vcc, s3, v70
	s_mov_b32 s3, 0x480000
	s_nop 0
	v_addc_co_u32_e32 v43, vcc, 0, v71, vcc
	v_add_co_u32_e32 v44, vcc, s3, v70
	s_mov_b32 s3, 0x489000
	s_nop 0
	v_addc_co_u32_e32 v45, vcc, 0, v71, vcc
	global_load_dword v137, v[30:31], off nt
	global_load_dword v136, v[32:33], off nt
	global_load_dword v133, v[34:35], off nt
	global_load_dword v130, v[36:37], off nt
	global_load_dword v127, v[38:39], off nt
	global_load_dword v125, v[40:41], off nt
	global_load_dword v118, v[42:43], off nt
	global_load_dword v86, v[44:45], off nt
	v_add_co_u32_e32 v30, vcc, s3, v70
	s_mov_b32 s3, 0x492000
	s_nop 0
	v_addc_co_u32_e32 v31, vcc, 0, v71, vcc
	v_add_co_u32_e32 v32, vcc, s3, v70
	s_mov_b32 s3, 0x49b000
	s_nop 0
	v_addc_co_u32_e32 v33, vcc, 0, v71, vcc
	v_add_co_u32_e32 v34, vcc, s3, v70
	s_mov_b32 s3, 0x4a4000
	s_nop 0
	v_addc_co_u32_e32 v35, vcc, 0, v71, vcc
	v_add_co_u32_e32 v36, vcc, s3, v70
	s_mov_b32 s3, 0x4ad000
	s_nop 0
	v_addc_co_u32_e32 v37, vcc, 0, v71, vcc
	v_add_co_u32_e32 v38, vcc, s3, v70
	s_mov_b32 s3, 0x4b6000
	s_nop 0
	v_addc_co_u32_e32 v39, vcc, 0, v71, vcc
	v_add_co_u32_e32 v40, vcc, s3, v70
	s_mov_b32 s3, 0x4bf000
	s_nop 0
	v_addc_co_u32_e32 v41, vcc, 0, v71, vcc
	v_add_co_u32_e32 v42, vcc, s3, v70
	s_mov_b32 s3, 0x5a0000
	s_nop 0
	v_addc_co_u32_e32 v43, vcc, 0, v71, vcc
	v_add_co_u32_e32 v44, vcc, s3, v70
	s_mov_b32 s3, 0x5a9000
	s_nop 0
	v_addc_co_u32_e32 v45, vcc, 0, v71, vcc
	global_load_dword v115, v[30:31], off nt
	global_load_dword v111, v[32:33], off nt
	global_load_dword v107, v[34:35], off nt
	global_load_dword v103, v[36:37], off nt
	global_load_dword v95, v[38:39], off nt
	global_load_dword v90, v[40:41], off nt
	global_load_dword v83, v[42:43], off nt
	global_load_dword v87, v[44:45], off nt
	v_add_co_u32_e32 v30, vcc, s3, v70
	s_mov_b32 s3, 0x5b2000
	s_nop 0
	v_addc_co_u32_e32 v31, vcc, 0, v71, vcc
	v_add_co_u32_e32 v32, vcc, s3, v70
	s_mov_b32 s3, 0x5bb000
	s_nop 0
	v_addc_co_u32_e32 v33, vcc, 0, v71, vcc
	v_add_co_u32_e32 v34, vcc, s3, v70
	s_mov_b32 s3, 0x5c4000
	s_nop 0
	v_addc_co_u32_e32 v35, vcc, 0, v71, vcc
	v_exp_f32_e32 v29, v29
	v_add_co_u32_e32 v36, vcc, s3, v70
	s_mov_b32 s3, 0x5cd000
	s_nop 0
	v_addc_co_u32_e32 v37, vcc, 0, v71, vcc
	v_add_co_u32_e32 v38, vcc, s3, v70
	s_mov_b32 s3, 0x5d6000
	s_nop 0
	v_addc_co_u32_e32 v39, vcc, 0, v71, vcc
	v_add_f32_e32 v29, 1.0, v29
	v_add_co_u32_e32 v40, vcc, s3, v70
	s_nop 0
	v_addc_co_u32_e32 v41, vcc, 0, v71, vcc
	s_mov_b32 s3, 0x5df000
	v_add_co_u32_e32 v42, vcc, s3, v70
	s_movk_i32 s3, 0x90
	s_nop 0
	v_addc_co_u32_e32 v43, vcc, 0, v71, vcc
	global_load_dword v112, v[30:31], off nt
	global_load_dword v108, v[32:33], off nt
	global_load_dword v104, v[34:35], off nt
	global_load_dword v100, v[36:37], off nt
	global_load_dword v93, v[38:39], off nt
	global_load_dword v91, v[40:41], off nt
	global_load_dword v81, v[42:43], off nt
	v_mul_f32_e32 v32, 0xbfb8aa3b, v15
	v_exp_f32_e32 v32, v32
	s_nop 0
	v_add_f32_e32 v32, 1.0, v32
	v_mul_f32_e32 v31, 0xbfb8aa3b, v16
	v_rcp_f32_e32 v30, v29
	s_nop 0
	v_mul_f32_e32 v29, v14, v30
	v_exp_f32_e32 v31, v31
	s_nop 0
	v_add_f32_e32 v31, 1.0, v31
	v_rcp_f32_e32 v14, v32
	s_nop 0
	v_mul_f32_e32 v30, v15, v14
	v_mul_f32_e32 v32, 0xbfb8aa3b, v17
	v_exp_f32_e32 v32, v32
	s_nop 0
	v_add_f32_e32 v32, 1.0, v32
	v_rcp_f32_e32 v14, v31
	s_nop 0
	v_mul_f32_e32 v31, v16, v14
	v_rcp_f32_e32 v14, v32
	s_nop 0
	v_mul_f32_e32 v17, v17, v14
	v_cvt_pk_bf16_f32 v14, v29, v30
	v_cvt_pk_bf16_f32 v15, v31, v17
	s_nop 0
	v_lshlrev_b32_e32 v16, 16, v14
	v_sub_f32_e32 v16, v29, v16
	v_and_b32_e32 v29, 0xffff0000, v14
	v_sub_f32_e32 v29, v30, v29
	v_cvt_pk_bf16_f32 v16, v16, v29
	v_lshlrev_b32_e32 v29, 16, v15
	v_and_b32_e32 v30, 0xffff0000, v15
	v_sub_f32_e32 v29, v31, v29
	v_sub_f32_e32 v17, v17, v30
	v_cvt_pk_bf16_f32 v17, v29, v17
	s_waitcnt vmcnt(50)
	v_mul_f32_e32 v29, 0xbfb8aa3b, v10
	v_exp_f32_e32 v29, v29
	v_mad_u32_u24 v30, v27, s3, 0
	v_add_u32_e32 v76, v30, v74
	ds_write_b64 v76, v[14:15]
	ds_write_b64 v76, v[16:17] offset:20736
	v_add_f32_e32 v29, 1.0, v29
	v_mul_f32_e32 v16, 0xbfb8aa3b, v11
	v_exp_f32_e32 v16, v16
	s_nop 0
	v_add_f32_e32 v16, 1.0, v16
	v_rcp_f32_e32 v14, v29
	s_nop 0
	v_mul_f32_e32 v14, v10, v14
	v_mul_f32_e32 v29, 0xbfb8aa3b, v12
	v_exp_f32_e32 v29, v29
	s_nop 0
	v_add_f32_e32 v17, 1.0, v29
	v_rcp_f32_e32 v10, v16
	s_nop 0
	v_mul_f32_e32 v15, v11, v10
	v_mul_f32_e32 v16, 0xbfb8aa3b, v13
	v_exp_f32_e32 v16, v16
	s_nop 0
	v_add_f32_e32 v16, 1.0, v16
	v_rcp_f32_e32 v10, v17
	s_nop 0
	v_mul_f32_e32 v17, v12, v10
	v_rcp_f32_e32 v10, v16
	s_nop 0
	v_mul_f32_e32 v13, v13, v10
	s_waitcnt vmcnt(49)
	v_mul_f32_e32 v16, 0xbfb8aa3b, v6
	v_exp_f32_e32 v16, v16
	v_cvt_pk_bf16_f32 v10, v14, v15
	v_cvt_pk_bf16_f32 v11, v17, v13
	s_nop 0
	v_lshlrev_b32_e32 v12, 16, v10
	v_sub_f32_e32 v12, v14, v12
	v_and_b32_e32 v14, 0xffff0000, v10
	v_sub_f32_e32 v14, v15, v14
	v_and_b32_e32 v15, 0xffff0000, v11
	v_cvt_pk_bf16_f32 v12, v12, v14
	v_lshlrev_b32_e32 v14, 16, v11
	v_sub_f32_e32 v13, v13, v15
	v_add_f32_e32 v15, 1.0, v16
	v_sub_f32_e32 v14, v17, v14
	v_cvt_pk_bf16_f32 v13, v14, v13
	v_mad_u32_u24 v14, v28, s3, 0
	v_add_u32_e32 v79, v14, v74
	ds_write_b64 v79, v[10:11]
	ds_write_b64 v79, v[12:13] offset:20736
	v_mul_f32_e32 v12, 0xbfb8aa3b, v7
	v_exp_f32_e32 v12, v12
	s_nop 0
	v_add_f32_e32 v12, 1.0, v12
	v_rcp_f32_e32 v10, v15
	s_nop 0
	v_mul_f32_e32 v10, v6, v10
	v_mul_f32_e32 v15, 0xbfb8aa3b, v8
	v_exp_f32_e32 v15, v15
	s_nop 0
	v_add_f32_e32 v13, 1.0, v15
	v_rcp_f32_e32 v6, v12
	s_nop 0
	v_mul_f32_e32 v11, v7, v6
	v_mul_f32_e32 v12, 0xbfb8aa3b, v9
	v_exp_f32_e32 v12, v12
	s_nop 0
	v_add_f32_e32 v12, 1.0, v12
	v_rcp_f32_e32 v6, v13
	s_nop 0
	v_mul_f32_e32 v13, v8, v6
	s_movk_i32 s3, 0x300
	v_rcp_f32_e32 v6, v12
	s_nop 0
	v_mul_f32_e32 v9, v9, v6
	v_cvt_pk_bf16_f32 v6, v10, v11
	v_cvt_pk_bf16_f32 v7, v13, v9
	v_cmp_gt_u32_e64 s[8:9], s3, v0
	v_lshlrev_b32_e32 v8, 16, v6
	v_sub_f32_e32 v8, v10, v8
	v_and_b32_e32 v10, 0xffff0000, v6
	v_sub_f32_e32 v10, v11, v10
	v_cvt_pk_bf16_f32 v8, v8, v10
	v_lshlrev_b32_e32 v10, 16, v7
	v_and_b32_e32 v11, 0xffff0000, v7
	v_sub_f32_e32 v10, v13, v10
	v_sub_f32_e32 v9, v9, v11
	v_cvt_pk_bf16_f32 v9, v10, v9
	v_add_u32_e32 v10, 0x2400, v30
	v_add_u32_e32 v78, v10, v74
	ds_write_b64 v78, v[6:7]
	ds_write_b64 v78, v[8:9] offset:20736
	s_and_saveexec_b64 s[10:11], s[8:9]
	s_cbranch_execz .LBB0_291
	global_load_dwordx4 v[6:9], v[68:69], off
	s_movk_i32 s3, 0x220
	v_cmp_gt_u32_e64 s[6:7], s3, v0
	s_and_saveexec_b64 s[20:21], s[6:7]
	s_cbranch_execz .LBB0_286
	s_waitcnt vmcnt(0)
	v_mul_f32_e32 v10, 0xbfb8aa3b, v6
	v_exp_f32_e32 v10, v10
	s_nop 0
	v_add_f32_e32 v10, 1.0, v10
	v_rcp_f32_e32 v11, v10
	s_nop 0
	v_mul_f32_e32 v19, v6, v11

.LBB0_668:
	s_and_b64 vcc, exec, s[6:7]
	s_barrier
	s_cbranch_vccnz .LBB0_672
	s_nop 4
	v_mov_b64_e32 v[4:5], s[0:1]
	s_waitcnt vmcnt(0)
	global_load_dwordx2 v[38:39], v[4:5], off offset:80
	s_waitcnt vmcnt(0)
	s_mul_i32 s4, s2, 0x492000
	s_mul_hi_i32 s3, s2, 0x492000
	v_or_b32_e32 v40, s18, v72
	v_mov_b32_e32 v41, 0
	v_mov_b32_e32 v44, 0x9000
	s_add_u32 s4, s94, s4
	v_lshlrev_b64 v[42:43], 2, v[40:41]
	s_addc_u32 s5, s95, s3
	v_mul_u32_u24_e32 v40, 0x24000, v1
	s_mov_b64 s[6:7], 0x5800000
	v_lshl_add_u64 v[4:5], s[4:5], 0, v[42:43]
	v_lshl_add_u64 v[4:5], v[4:5], 0, s[6:7]
	s_mov_b32 s9, 0x12000
	v_lshl_add_u64 v[40:41], v[4:5], 0, v[40:41]
	s_mov_b32 s10, 0x1b000
	s_mov_b32 s8, 0x24000
	s_mov_b32 s11, 0x2d000
	s_mov_b32 s12, 0xa2000
	s_mov_b32 s13, 0xab000
	s_mov_b32 s18, 0xb4000
	s_mov_b32 s19, 0xbd000
	s_mov_b32 s20, 0x132000
	s_mov_b32 s21, 0x13b000
	s_mov_b32 s22, 0x144000
	s_mov_b32 s23, 0x14d000
	s_mov_b32 s24, 0x1c2000
	s_mov_b32 s25, 0x1cb000
	s_mov_b32 s26, 0x1d4000
	s_mov_b32 s27, 0x1dd000
	s_mov_b32 s28, 0x252000
	s_mov_b32 s29, 0x25b000
	s_mov_b32 s30, 0x264000
	s_mov_b32 s31, 0x26d000
	s_mov_b32 s33, 0x2e2000
	s_waitcnt lgkmcnt(0)
	v_mad_i64_i32 v[38:39], s[2:3], s2, v44, v[38:39]
	v_lshl_add_u64 v[38:39], v[38:39], 0, v[42:43]
	global_load_dword v1, v[38:39], off nt
	v_add_co_u32_e32 v38, vcc, s9, v40
	s_mov_b32 s2, 0x2eb000
	s_nop 0
	v_addc_co_u32_e32 v39, vcc, 0, v41, vcc
	v_add_co_u32_e32 v42, vcc, s10, v40
	s_waitcnt vmcnt(0)
	v_add_f32_e32 v30, v30, v1
	v_addc_co_u32_e32 v43, vcc, 0, v41, vcc
	v_add_co_u32_e32 v44, vcc, s8, v40
	v_add_f32_e32 v14, v14, v1
	s_nop 0
	v_addc_co_u32_e32 v45, vcc, 0, v41, vcc
	v_add_co_u32_e32 v46, vcc, s11, v40
	v_add_f32_e32 v31, v31, v1
	s_nop 0
	v_addc_co_u32_e32 v47, vcc, 0, v41, vcc
	v_add_co_u32_e32 v48, vcc, s12, v40
	v_add_f32_e32 v32, v32, v1
	s_nop 0
	v_addc_co_u32_e32 v49, vcc, 0, v41, vcc
	v_add_co_u32_e32 v50, vcc, s13, v40
	v_add_f32_e32 v33, v33, v1
	s_nop 0
	v_addc_co_u32_e32 v51, vcc, 0, v41, vcc
	v_add_co_u32_e32 v52, vcc, s18, v40
	v_add_f32_e32 v15, v15, v1
	s_nop 0
	v_addc_co_u32_e32 v53, vcc, 0, v41, vcc
	v_add_co_u32_e32 v54, vcc, s19, v40
	v_add_f32_e32 v16, v16, v1
	s_nop 0
	v_addc_co_u32_e32 v55, vcc, 0, v41, vcc
	v_add_co_u32_e32 v56, vcc, s20, v40
	v_add_f32_e32 v17, v17, v1
	s_nop 0
	v_addc_co_u32_e32 v57, vcc, 0, v41, vcc
	v_add_co_u32_e32 v58, vcc, s21, v40
	v_add_f32_e32 v34, v34, v1
	s_nop 0
	v_addc_co_u32_e32 v59, vcc, 0, v41, vcc
	v_add_co_u32_e32 v60, vcc, s22, v40
	v_add_f32_e32 v35, v35, v1
	s_nop 0
	v_addc_co_u32_e32 v61, vcc, 0, v41, vcc
	v_add_co_u32_e32 v62, vcc, s23, v40
	v_add_f32_e32 v36, v36, v1
	s_nop 0
	v_addc_co_u32_e32 v63, vcc, 0, v41, vcc
	v_add_co_u32_e32 v64, vcc, s24, v40
	v_add_f32_e32 v37, v37, v1
	s_nop 0
	v_addc_co_u32_e32 v65, vcc, 0, v41, vcc
	v_add_co_u32_e32 v66, vcc, s25, v40
	v_add_f32_e32 v22, v22, v1
	s_nop 0
	v_addc_co_u32_e32 v67, vcc, 0, v41, vcc
	v_add_co_u32_e32 v68, vcc, s26, v40
	v_add_f32_e32 v23, v23, v1
	s_nop 0
	v_addc_co_u32_e32 v69, vcc, 0, v41, vcc
	v_add_co_u32_e32 v70, vcc, s27, v40
	v_add_f32_e32 v24, v24, v1
	s_nop 0
	v_addc_co_u32_e32 v71, vcc, 0, v41, vcc
	v_add_co_u32_e32 v72, vcc, s28, v40
	v_add_f32_e32 v25, v25, v1
	s_nop 0
	v_addc_co_u32_e32 v73, vcc, 0, v41, vcc
	v_add_co_u32_e32 v74, vcc, s29, v40
	v_add_f32_e32 v26, v26, v1
	s_nop 0
	v_addc_co_u32_e32 v75, vcc, 0, v41, vcc
	v_add_co_u32_e32 v76, vcc, s30, v40
	v_add_f32_e32 v27, v27, v1
	s_nop 0
	v_addc_co_u32_e32 v77, vcc, 0, v41, vcc
	v_add_co_u32_e32 v78, vcc, s31, v40
	v_add_f32_e32 v28, v28, v1
	s_nop 0
	v_addc_co_u32_e32 v79, vcc, 0, v41, vcc
	v_add_f32_e32 v29, v29, v1
	global_store_dword v[38:39], v30, off
	global_store_dword v[42:43], v31, off
	global_store_dword v[44:45], v32, off
	global_store_dword v[46:47], v33, off
	global_store_dword v[48:49], v14, off
	global_store_dword v[50:51], v15, off
	global_store_dword v[52:53], v16, off
	global_store_dword v[54:55], v17, off
	global_store_dword v[56:57], v34, off
	global_store_dword v[58:59], v35, off
	global_store_dword v[60:61], v36, off
	global_store_dword v[62:63], v37, off
	global_store_dword v[64:65], v22, off
	global_store_dword v[66:67], v23, off
	global_store_dword v[68:69], v24, off
	global_store_dword v[70:71], v25, off
	global_store_dword v[72:73], v26, off
	global_store_dword v[74:75], v27, off
	global_store_dword v[76:77], v28, off
	global_store_dword v[78:79], v29, off
	v_add_co_u32_e32 v14, vcc, s33, v40
	v_add_f32_e32 v10, v10, v1
	s_nop 0
	v_addc_co_u32_e32 v15, vcc, 0, v41, vcc
	global_store_dword v[14:15], v10, off
	v_add_co_u32_e32 v10, vcc, s2, v40
	v_add_f32_e32 v14, v11, v1
	s_nop 0
	v_addc_co_u32_e32 v11, vcc, 0, v41, vcc
	s_mov_b32 s2, 0x2f4000
	global_store_dword v[10:11], v14, off
	v_add_co_u32_e32 v10, vcc, s2, v40
	v_add_f32_e32 v12, v12, v1
	s_nop 0
	v_addc_co_u32_e32 v11, vcc, 0, v41, vcc
	s_mov_b32 s2, 0x2fd000
	global_store_dword v[10:11], v12, off
	v_add_co_u32_e32 v10, vcc, s2, v40
	v_add_f32_e32 v12, v13, v1
	s_nop 0
	v_addc_co_u32_e32 v11, vcc, 0, v41, vcc
	s_mov_b32 s2, 0x372000
	global_store_dword v[10:11], v12, off
	v_add_co_u32_e32 v10, vcc, s2, v40
	v_add_f32_e32 v12, v18, v1
	s_nop 0
	v_addc_co_u32_e32 v11, vcc, 0, v41, vcc
	s_mov_b32 s2, 0x37b000
	global_store_dword v[10:11], v12, off
	v_add_co_u32_e32 v10, vcc, s2, v40
	v_add_f32_e32 v12, v19, v1
	s_nop 0
	v_addc_co_u32_e32 v11, vcc, 0, v41, vcc
	s_mov_b32 s2, 0x384000
	global_store_dword v[10:11], v12, off
	v_add_co_u32_e32 v10, vcc, s2, v40
	v_add_f32_e32 v12, v20, v1
	s_nop 0
	v_addc_co_u32_e32 v11, vcc, 0, v41, vcc
	s_mov_b32 s2, 0x38d000
	global_store_dword v[10:11], v12, off
	v_add_co_u32_e32 v10, vcc, s2, v40
	v_add_f32_e32 v12, v21, v1
	s_nop 0
	v_addc_co_u32_e32 v11, vcc, 0, v41, vcc
	s_mov_b32 s2, 0x402000
	global_store_dword v[10:11], v12, off
	v_add_co_u32_e32 v10, vcc, s2, v40
	v_add_f32_e32 v6, v6, v1
	s_nop 0
	v_addc_co_u32_e32 v11, vcc, 0, v41, vcc
	s_mov_b32 s2, 0x40b000
	global_store_dword v[10:11], v6, off
	v_add_co_u32_e32 v6, vcc, s2, v40
	v_add_f32_e32 v10, v7, v1
	s_nop 0
	v_addc_co_u32_e32 v7, vcc, 0, v41, vcc
	s_mov_b32 s2, 0x414000
	global_store_dword v[6:7], v10, off
	v_add_co_u32_e32 v6, vcc, s2, v40
	v_add_f32_e32 v8, v8, v1
	s_nop 0
	v_addc_co_u32_e32 v7, vcc, 0, v41, vcc
	global_store_dword v[6:7], v8, off
	v_add_co_u32_e32 v6, vcc, 0x41d000, v40
	v_add_f32_e32 v8, v9, v1
	s_nop 0
	v_addc_co_u32_e32 v7, vcc, 0, v41, vcc
	v_cmp_gt_u32_e32 vcc, 16, v98
	global_store_dword v[6:7], v8, off
	s_and_saveexec_b64 s[6:7], vcc
	s_cbranch_execz .LBB0_671
	v_add_f32_e32 v2, v2, v1
	global_store_dword v[4:5], v2, off
	v_add_co_u32_e32 v2, vcc, 0x9000, v4
	v_add_f32_e32 v1, v3, v1
	s_nop 0
	v_addc_co_u32_e32 v3, vcc, 0, v5, vcc
	global_store_dword v[2:3], v1, off

.LBB0_727:
	v_mov_b32_e32 v130, v0
	s_mov_b64 s[38:39], s[94:95]
	s_mov_b64 s[4:5], s[92:93]
	s_mov_b32 s40, s60
	v_readfirstlane_b32 s2, v130
	v_writelane_b32 v228, s4, 4
	s_ashr_i32 s3, s2, 6
	s_mov_b32 s2, s60
	v_writelane_b32 v228, s5, 5
	v_writelane_b32 v228, s2, 6
	s_mov_b32 s96, 0
	v_and_b32_e32 v132, 63, v130
	v_writelane_b32 v228, s3, 7
	s_lshl_b32 s2, s40, 3
	s_add_i32 s12, s2, s3
	s_add_u32 s4, s38, 0x4000
	v_writelane_b32 v228, s4, 8
	s_addc_u32 s4, s39, 0
	v_writelane_b32 v228, s4, 10
	s_add_i32 s4, s96, 0x20160
	s_add_u32 s42, s38, 0x5800000
	s_addc_u32 s43, s39, 0
	s_cmp_lt_i32 s90, 2
	v_writelane_b32 v228, s4, 12
	s_cselect_b64 s[4:5], -1, 0
	s_cmp_gt_i32 s91, 1
	s_cselect_b64 s[6:7], -1, 0
	s_and_b64 s[4:5], s[4:5], s[6:7]
	s_load_dword s37, s[0:1], 0xe8
	s_andn2_b64 vcc, exec, s[4:5]
	s_waitcnt lgkmcnt(0)
	s_cbranch_vccnz .LBB0_789
	v_mov_b64_e32 v[2:3], s[0:1]
	global_load_dwordx2 v[2:3], v[2:3], off offset:88
	s_waitcnt vmcnt(0)
	s_cmpk_gt_i32 s12, 0x101f
	s_cbranch_scc1 .LBB0_735
	v_mov_b32_e32 v83, 0
	v_lshlrev_b32_e32 v4, 4, v132
	v_mov_b32_e32 v5, v83
	s_waitcnt lgkmcnt(0)
	v_lshl_add_u64 v[18:19], v[2:3], 0, v[4:5]
	global_load_dwordx4 v[2:5], v[18:19], off
	global_load_dwordx4 v[6:9], v[18:19], off offset:1024
	global_load_dwordx4 v[10:13], v[18:19], off offset:2048
	global_load_dwordx4 v[14:17], v[18:19], off offset:3072
	v_mbcnt_lo_u32_b32 v1, -1, 0
	v_mbcnt_hi_u32_b32 v18, -1, v1
	v_and_b32_e32 v1, 64, v18
	v_add_u32_e32 v19, 64, v1
	v_xor_b32_e32 v1, 1, v18
	v_cmp_lt_i32_e32 vcc, v1, v19
	v_xor_b32_e32 v20, 2, v18
	s_add_u32 s8, s0, 8
	v_cndmask_b32_e32 v1, v18, v1, vcc
	v_cmp_lt_i32_e32 vcc, v20, v19
	s_addc_u32 s9, s1, 0
	s_lshl_b32 s10, s12, 2
	v_cndmask_b32_e32 v20, v18, v20, vcc
	v_lshlrev_b32_e32 v97, 2, v20
	v_xor_b32_e32 v20, 4, v18
	v_cmp_lt_i32_e32 vcc, v20, v19
	s_lshl_b32 s16, s37, 5
	s_ashr_i32 s11, s10, 31
	v_cndmask_b32_e32 v20, v18, v20, vcc
	v_lshlrev_b32_e32 v98, 2, v20
	v_xor_b32_e32 v20, 8, v18
	v_cmp_lt_i32_e32 vcc, v20, v19
	v_lshlrev_b32_e32 v82, 3, v132
	s_ashr_i32 s17, s16, 31
	v_cndmask_b32_e32 v20, v18, v20, vcc
	v_lshlrev_b32_e32 v99, 2, v20
	v_xor_b32_e32 v20, 16, v18
	v_cmp_lt_i32_e32 vcc, v20, v19
	s_lshl_b64 s[6:7], s[10:11], 11
	s_mov_b64 s[4:5], 0xba00000
	v_cndmask_b32_e32 v20, v18, v20, vcc
	v_lshlrev_b32_e32 v100, 2, v20
	v_xor_b32_e32 v20, 32, v18
	v_cmp_lt_i32_e32 vcc, v20, v19
	s_add_u32 s6, s38, s6
	s_addc_u32 s7, s39, s7
	v_cndmask_b32_e32 v18, v18, v20, vcc
	v_lshlrev_b32_e32 v101, 2, v18
	v_lshl_add_u64 v[18:19], s[38:39], 0, v[82:83]
	v_lshl_add_u64 v[84:85], v[18:19], 0, s[4:5]
	v_lshlrev_b32_e32 v18, 2, v132
	v_or_b32_e32 v20, 0x100, v18
	v_or_b32_e32 v22, 0x200, v18
	v_or_b32_e32 v24, 0x300, v18
	v_lshl_add_u64 v[26:27], s[6:7], 0, v[82:83]
	s_lshl_b64 s[20:21], s[10:11], 12
	s_mov_b32 s15, 0
	v_lshlrev_b32_e32 v1, 2, v1
	v_lshl_add_u64 v[86:87], v[26:27], 0, s[4:5]
	s_lshl_b64 s[18:19], s[16:17], 11
	s_or_b32 s20, s20, 0x3000
	s_lshl_b64 s[22:23], s[16:17], 12
	v_lshlrev_b32_e32 v82, 4, v132
	v_mov_b32_e32 v102, 0x358637bd
	s_mov_b32 s4, 0xf800000
	v_mov_b32_e32 v103, 0x260
	v_lshlrev_b32_e32 v88, 2, v18
	s_movk_i32 s5, 0x7fff
	s_mov_b32 s13, 0xffff0000
	v_lshlrev_b32_e32 v90, 2, v20
	v_lshlrev_b32_e32 v92, 2, v22
	v_lshlrev_b32_e32 v94, 2, v24
	s_movk_i32 s26, 0x1000
	s_branch .LBB0_731

.LBB0_731:
	s_add_i32 s14, s10, 0xffffc000
	s_cmpk_lt_i32 s10, 0x4000
	s_cselect_b64 s[6:7], -1, 0
	s_and_b64 s[24:25], s[6:7], exec
	s_cselect_b32 s24, s1, s9
	s_cselect_b32 s25, s0, s8
	v_mov_b32_e32 v18, s25
	v_mov_b32_e32 v19, s24
	global_load_dwordx2 v[18:19], v[18:19], off
	s_waitcnt vmcnt(0)
	s_cselect_b32 s25, s11, 0
	s_cselect_b32 s24, s10, s14
	s_lshl_b64 s[24:25], s[24:25], 12
	s_add_u32 s14, s10, 1
	s_addc_u32 s27, s11, 0
	s_add_i32 s30, s10, 0xffffc001
	s_cmpk_lt_i32 s14, 0x4000
	s_cselect_b64 s[48:49], -1, 0
	s_and_b64 s[28:29], s[48:49], exec
	s_cselect_b32 s28, s1, s9
	s_cselect_b32 s29, s0, s8
	v_mov_b32_e32 v20, s29
	v_mov_b32_e32 v21, s28
	s_mov_b64 s[52:53], -1
	s_waitcnt lgkmcnt(0)
	v_lshl_add_u64 v[18:19], v[18:19], 0, s[24:25]
	v_lshl_add_u64 v[18:19], v[18:19], 0, v[82:83]
	global_load_dwordx4 v[78:81], v[18:19], off
	global_load_dwordx4 v[74:77], v[18:19], off offset:1024
	global_load_dwordx4 v[70:73], v[18:19], off offset:2048
	global_load_dwordx4 v[66:69], v[18:19], off offset:3072
	s_nop 0
	global_load_dwordx2 v[18:19], v[20:21], off
	s_waitcnt vmcnt(0)
	s_cselect_b32 s25, s27, 0
	s_cselect_b32 s24, s14, s30
	s_lshl_b64 s[24:25], s[24:25], 12
	s_add_u32 s14, s10, 2
	s_addc_u32 s27, s11, 0
	s_add_i32 s28, s10, 0xffffc002
	s_cmpk_lt_i32 s14, 0x4000
	s_cselect_b64 s[46:47], -1, 0
	s_and_b64 s[30:31], s[46:47], exec
	s_cselect_b32 s29, s1, s9
	s_cselect_b32 s30, s0, s8
	v_mov_b32_e32 v20, s30
	v_mov_b32_e32 v21, s29
	s_waitcnt lgkmcnt(0)
	v_lshl_add_u64 v[18:19], v[18:19], 0, s[24:25]
	v_lshl_add_u64 v[18:19], v[18:19], 0, v[82:83]
	global_load_dwordx4 v[62:65], v[18:19], off
	global_load_dwordx4 v[58:61], v[18:19], off offset:1024
	global_load_dwordx4 v[54:57], v[18:19], off offset:2048
	global_load_dwordx4 v[50:53], v[18:19], off offset:3072
	s_nop 0
	global_load_dwordx2 v[18:19], v[20:21], off
	s_waitcnt vmcnt(0)
	s_cselect_b32 s25, s27, 0
	s_cselect_b32 s24, s14, s28
	s_lshl_b64 s[24:25], s[24:25], 12
	s_add_u32 s50, s10, 3
	s_addc_u32 s51, s11, 0
	s_cmpk_lt_i32 s50, 0x4000
	s_waitcnt lgkmcnt(0)
	v_lshl_add_u64 v[18:19], v[18:19], 0, s[24:25]
	v_lshl_add_u64 v[18:19], v[18:19], 0, v[82:83]
	global_load_dwordx4 v[46:49], v[18:19], off
	global_load_dwordx4 v[38:41], v[18:19], off offset:1024
	global_load_dwordx4 v[30:33], v[18:19], off offset:2048
	s_nop 0
	global_load_dwordx4 v[18:21], v[18:19], off offset:3072
	s_cselect_b64 s[24:25], -1, 0
	s_and_b64 vcc, exec, s[24:25]
	s_cbranch_vccnz .LBB0_733
	v_mov_b64_e32 v[22:23], s[8:9]
	global_load_dwordx2 v[22:23], v[22:23], off
	s_waitcnt vmcnt(0)
	s_add_i32 s14, s10, 0xffffc003
	s_lshl_b64 s[30:31], s[14:15], 12
	s_mov_b32 s44, s50
	s_mov_b32 s45, s15
	s_mov_b64 s[52:53], 0
	s_waitcnt lgkmcnt(0)
	v_lshl_add_u64 v[22:23], v[22:23], 0, s[30:31]
.LBB0_733:
	s_andn2_b64 vcc, exec, s[52:53]
	s_cbranch_vccnz .LBB0_730
	v_mov_b64_e32 v[22:23], s[0:1]
	global_load_dwordx2 v[22:23], v[22:23], off
	s_waitcnt vmcnt(0)
	s_add_i32 s14, s10, 0xffffc003
	s_mov_b64 s[44:45], s[50:51]
	s_waitcnt lgkmcnt(0)
	v_lshl_add_u64 v[22:23], v[22:23], 0, s[20:21]
	s_branch .LBB0_730

.LBB0_789:
	s_waitcnt lgkmcnt(0)
	v_mov_b64_e32 v[2:3], s[0:1]
	global_load_dwordx2 v[134:135], v[2:3], off
	s_waitcnt vmcnt(0)
	global_load_dwordx2 v[136:137], v[2:3], off offset:8
	s_waitcnt vmcnt(0)
	s_cmp_lt_i32 s90, 3
	s_cselect_b64 s[4:5], -1, 0
	s_cmp_gt_i32 s91, 2
	s_cselect_b64 s[6:7], -1, 0
	s_and_b64 s[14:15], s[4:5], s[6:7]
	s_andn2_b64 vcc, exec, s[14:15]
	s_cbranch_vccnz .LBB0_882
	s_add_u32 s4, s38, 0x200000
	s_addc_u32 s5, s39, 0
	s_add_u32 s6, s38, 0x8000
	s_addc_u32 s7, s39, 0
	s_add_u32 s16, s38, 0x10000000
	s_addc_u32 s17, s39, 0
	s_cmp_gt_i32 s40, 21
	s_cbranch_scc1 .LBB0_801
	v_mov_b32_e32 v10, v0
	s_mov_b32 s8, 0x1fffe0
	v_ashrrev_i32_e32 v2, 31, v10
	v_lshrrev_b32_e32 v2, 26, v2
	v_add_u32_e32 v2, v10, v2
	v_ashrrev_i32_e32 v6, 6, v2
	v_bfe_i32 v2, v10, 27, 1
	v_lshlrev_b32_e32 v1, 4, v10
	v_lshrrev_b32_e32 v2, 22, v2
	v_add_u32_e32 v2, v1, v2
	v_and_b32_e32 v2, 0xfffffc00, v2
	v_sub_u32_e32 v2, v1, v2
	v_lshrrev_b32_e32 v3, 4, v2
	v_bitop3_b32 v2, v3, v2, 32 bitop3:0x6c
	v_ashrrev_i32_e32 v4, 31, v2
	v_lshrrev_b32_e32 v4, 26, v4
	v_add_u32_e32 v4, v2, v4
	v_lshlrev_b32_e32 v3, 3, v6
	v_ashrrev_i32_e32 v7, 6, v4
	v_and_b32_e32 v4, 0xc0, v4
	v_and_b32_e32 v3, -16, v3
	v_sub_u32_e32 v2, v2, v4
	v_mov_b32_e32 v4, 1
	v_add_u32_e32 v3, v7, v3
	v_ashrrev_i16_sdwa v2, v4, sext(v2) dst_sel:DWORD dst_unused:UNUSED_PAD src0_sel:DWORD src1_sel:BYTE_0
	v_lshlrev_b32_e32 v5, 5, v6
	v_bfe_i32 v8, v2, 0, 16
	v_lshlrev_b32_e32 v2, 1, v3
	v_lshrrev_b32_e32 v9, 2, v3
	v_and_b32_e32 v11, 3, v7
	v_and_b32_e32 v5, 32, v5
	v_and_b32_e32 v2, 24, v2
	v_and_b32_e32 v9, 4, v9
	v_and_or_b32 v11, v3, s8, v11
	v_or3_b32 v2, v11, v9, v2
	v_add_lshl_u32 v5, v5, v8, 1
	v_add_u32_e32 v1, 0x2000, v1
	v_lshl_add_u32 v140, v2, 11, v5
	v_ashrrev_i32_e32 v2, 31, v1
	v_lshrrev_b32_e32 v2, 22, v2
	v_add_u32_e32 v2, v1, v2
	v_ashrrev_i32_e32 v9, 10, v2
	v_mul_i32_i24_e32 v2, 0x400, v9
	v_sub_u32_e32 v1, v1, v2
	v_lshrrev_b32_e32 v2, 4, v1
	v_bitop3_b32 v1, v2, v1, 32 bitop3:0x6c
	v_lshl_add_u32 v138, v3, 11, v5
	v_ashrrev_i32_e32 v3, 31, v1
	v_lshrrev_b32_e32 v3, 26, v3
	v_add_u32_e32 v3, v1, v3
	v_readfirstlane_b32 s13, v10
	v_lshlrev_b32_e32 v2, 3, v9
	v_ashrrev_i32_e32 v11, 6, v3
	v_and_b32_e32 v3, 0xc0, v3
	v_and_b32_e32 v2, -16, v2
	v_sub_u32_e32 v1, v1, v3
	s_ashr_i32 s19, s13, 6
	s_ashr_i32 s41, s40, 31
	s_ashr_i32 s18, s13, 8
	v_add_u32_e32 v2, v11, v2
	v_ashrrev_i16_sdwa v1, v4, sext(v1) dst_sel:DWORD dst_unused:UNUSED_PAD src0_sel:DWORD src1_sel:BYTE_0
	v_and_b32_e32 v4, 3, v11
	s_lshl_b32 s24, s19, 10
	s_lshl_b64 s[20:21], s[40:41], 19
	v_and_or_b32 v4, v2, s8, v4
	s_add_u32 s8, s4, s20
	s_addc_u32 s9, s5, s21
	s_add_i32 s22, s96, 0x10000
	s_add_i32 s26, s22, s24
	v_lshlrev_b32_e32 v5, 5, v9
	v_bfe_i32 v12, v1, 0, 16
	v_lshlrev_b32_e32 v1, 1, v2
	v_lshrrev_b32_e32 v3, 2, v2
	s_add_i32 s27, s26, 0x2000
	v_and_b32_e32 v5, 32, v5
	v_and_b32_e32 v1, 24, v1
	v_and_b32_e32 v3, 4, v3
	s_add_u32 s10, s8, 0x40000
	v_or3_b32 v1, v4, v3, v1
	v_add_lshl_u32 v3, v5, v12, 1
	s_mov_b32 m0, s26
	s_addc_u32 s11, s9, 0
	s_add_i32 s23, s96, 0x14000
	v_lshl_add_u32 v144, v1, 11, v3
	global_load_lds_dwordx4 v140, s[8:9]
	s_mov_b32 m0, s27
	s_add_i32 s28, s23, s24
	global_load_lds_dwordx4 v144, s[8:9]
	s_mov_b32 m0, s28
	s_add_i32 s29, s28, 0x2000
	global_load_lds_dwordx4 v140, s[10:11]
	s_mov_b32 m0, s29
	v_lshl_add_u32 v142, v2, 11, v3
	global_load_lds_dwordx4 v144, s[10:11]
	s_add_u32 s10, s38, 0xda00000
	s_addc_u32 s11, s39, 0
	s_add_i32 s30, s96, s24
	s_add_i32 s31, s30, 0x2000
	s_mov_b32 m0, s30
	s_add_u32 s44, s38, 0xda40000
	global_load_lds_dwordx4 v138, s[10:11]
	s_mov_b32 m0, s31
	s_addc_u32 s45, s39, 0
	s_add_i32 s33, s30, 0x4000
	global_load_lds_dwordx4 v142, s[10:11]
	s_mov_b32 m0, s33
	s_add_i32 s34, s30, 0x6000
	global_load_lds_dwordx4 v138, s[44:45]
	s_mov_b32 m0, s34
	v_mov_b32_e32 v141, 0
	global_load_lds_dwordx4 v142, s[44:45]
	v_mov_b32_e32 v145, v141
	v_lshl_add_u64 v[4:5], s[8:9], 0, v[140:141]
	v_lshl_add_u64 v[2:3], s[8:9], 0, v[144:145]
	v_mov_b32_e32 v139, v141
	s_cmp_lg_u32 s18, 1
	v_mov_b32_e32 v143, v141
	s_cbranch_scc1 .LBB0_793
	s_barrier

.LBB0_840:
	s_or_b64 exec, exec, s[6:7]
	v_mov_b32_e32 v1, v0
	v_mov_b64_e32 v[2:3], s[0:1]
	s_barrier
	global_load_dwordx2 v[2:3], v[2:3], off offset:88
	s_waitcnt vmcnt(0)
	v_readfirstlane_b32 s6, v1
	s_ashr_i32 s13, s6, 6
	s_cmp_gt_i32 s13, 7
	v_and_b32_e32 v131, 63, v1
	s_cbranch_scc1 .LBB0_843
	v_mov_b32_e32 v91, 0
	v_lshlrev_b32_e32 v90, 4, v131
	s_waitcnt lgkmcnt(0)
	v_lshl_add_u64 v[2:3], v[2:3], 0, v[90:91]
	s_movk_i32 s6, 0x1000
	v_add_co_u32_e32 v18, vcc, s6, v2
	s_lshl_b32 s6, s40, 5
	s_nop 0
	v_addc_co_u32_e32 v19, vcc, 0, v3, vcc
	global_load_dwordx4 v[2:5], v[18:19], off
	global_load_dwordx4 v[6:9], v[18:19], off offset:1024
	global_load_dwordx4 v[10:13], v[18:19], off offset:2048
	global_load_dwordx4 v[14:17], v[18:19], off offset:3072
	v_mbcnt_lo_u32_b32 v18, -1, 0
	v_mbcnt_hi_u32_b32 v18, -1, v18
	v_and_b32_e32 v19, 64, v18
	v_add_u32_e32 v19, 64, v19
	v_xor_b32_e32 v20, 1, v18
	v_cmp_lt_i32_e32 vcc, v20, v19
	s_lshl_b32 s7, s13, 2
	s_add_i32 s26, s6, 0x20a0
	v_cndmask_b32_e32 v20, v18, v20, vcc
	v_lshlrev_b32_e32 v133, 2, v20
	v_xor_b32_e32 v20, 2, v18
	v_cmp_lt_i32_e32 vcc, v20, v19
	s_add_i32 s6, s6, s7
	s_add_i32 s18, s6, 0x2080
	v_cndmask_b32_e32 v20, v18, v20, vcc
	v_lshlrev_b32_e32 v156, 2, v20
	v_xor_b32_e32 v20, 4, v18
	v_cmp_lt_i32_e32 vcc, v20, v19
	s_add_u32 s27, s38, 0x5803000
	s_addc_u32 s28, s39, 0
	v_cndmask_b32_e32 v20, v18, v20, vcc
	v_lshlrev_b32_e32 v157, 2, v20
	v_xor_b32_e32 v20, 8, v18
	v_cmp_lt_i32_e32 vcc, v20, v19
	s_ashr_i32 s19, s18, 31
	s_lshl_b64 s[6:7], s[18:19], 11
	v_cndmask_b32_e32 v20, v18, v20, vcc
	v_lshlrev_b32_e32 v158, 2, v20
	v_xor_b32_e32 v20, 16, v18
	v_cmp_lt_i32_e32 vcc, v20, v19
	v_lshl_or_b32 v92, v131, 3, s6
	v_mov_b32_e32 v93, s7
	v_cndmask_b32_e32 v20, v18, v20, vcc
	v_lshlrev_b32_e32 v159, 2, v20
	v_xor_b32_e32 v20, 32, v18
	v_cmp_lt_i32_e32 vcc, v20, v19
	s_lshl_b64 s[6:7], s[18:19], 12
	v_or_b32_e32 v94, s6, v90
	v_cndmask_b32_e32 v18, v18, v20, vcc
	v_lshlrev_b32_e32 v160, 2, v18
	v_lshlrev_b32_e32 v18, 2, v131
	v_or_b32_e32 v20, 0x100, v18
	v_or_b32_e32 v22, 0x200, v18
	v_or_b32_e32 v24, 0x300, v18
	v_mov_b32_e32 v95, s7
	v_mov_b32_e32 v161, 0x358637bd
	s_mov_b32 s19, 0xf800000
	v_mov_b32_e32 v162, 0x260
	v_lshlrev_b32_e32 v90, 2, v18
	s_movk_i32 s29, 0x7fff
	s_mov_b32 s30, 0xffff0000
	s_mov_b32 s31, 0xba00000
	v_lshlrev_b32_e32 v96, 2, v20
	v_mov_b32_e32 v97, v91
	v_lshlrev_b32_e32 v98, 2, v22
	v_mov_b32_e32 v99, v91
	v_lshlrev_b32_e32 v100, 2, v24
	v_mov_b32_e32 v101, v91
	s_mov_b32 s33, 0xba01000
	s_mov_b64 s[20:21], 0x10000
	s_mov_b64 s[22:23], 0x20000

.LBB0_1002:
	s_or_b64 exec, exec, s[10:11]
	v_mov_b32_e32 v130, v0
	v_mov_b64_e32 v[2:3], s[0:1]
	s_barrier
	global_load_dwordx2 v[2:3], v[2:3], off offset:88
	s_waitcnt vmcnt(0)
	v_readfirstlane_b32 s3, v130
	s_ashr_i32 s3, s3, 6
	s_add_i32 s12, s3, s2
	s_cmp_gt_i32 s3, 15
	v_and_b32_e32 v132, 63, v130
	s_cbranch_scc1 .LBB0_1005
	v_mov_b32_e32 v91, 0
	v_lshlrev_b32_e32 v90, 4, v132
	s_waitcnt lgkmcnt(0)
	v_lshl_add_u64 v[2:3], v[2:3], 0, v[90:91]
	s_movk_i32 s2, 0x1000
	v_add_co_u32_e32 v18, vcc, s2, v2
	v_mbcnt_lo_u32_b32 v1, -1, 0
	s_nop 0
	v_addc_co_u32_e32 v19, vcc, 0, v3, vcc
	global_load_dwordx4 v[2:5], v[18:19], off
	global_load_dwordx4 v[6:9], v[18:19], off offset:1024
	global_load_dwordx4 v[10:13], v[18:19], off offset:2048
	global_load_dwordx4 v[14:17], v[18:19], off offset:3072
	v_mbcnt_hi_u32_b32 v18, -1, v1
	v_and_b32_e32 v1, 64, v18
	v_add_u32_e32 v19, 64, v1
	v_xor_b32_e32 v1, 1, v18
	v_cmp_lt_i32_e32 vcc, v1, v19
	v_xor_b32_e32 v20, 2, v18
	s_lshl_b32 s7, s27, 8
	v_cndmask_b32_e32 v1, v18, v1, vcc
	v_cmp_lt_i32_e32 vcc, v20, v19
	s_lshl_b32 s2, s26, 6
	s_add_i32 s8, s7, s2
	v_cndmask_b32_e32 v20, v18, v20, vcc
	v_lshlrev_b32_e32 v131, 2, v20
	v_xor_b32_e32 v20, 4, v18
	v_cmp_lt_i32_e32 vcc, v20, v19
	s_lshl_b32 s9, s3, 2
	s_add_i32 s6, s9, s8
	v_cndmask_b32_e32 v20, v18, v20, vcc
	v_lshlrev_b32_e32 v133, 2, v20
	v_xor_b32_e32 v20, 8, v18
	v_cmp_lt_i32_e32 vcc, v20, v19
	s_add_u32 s2, s38, 0x5803000
	s_addc_u32 s13, s39, 0
	v_cndmask_b32_e32 v20, v18, v20, vcc
	v_lshlrev_b32_e32 v152, 2, v20
	v_xor_b32_e32 v20, 16, v18
	v_cmp_lt_i32_e32 vcc, v20, v19
	s_lshl_b32 s5, s5, 6
	s_add_i32 s5, s7, s5
	v_cndmask_b32_e32 v20, v18, v20, vcc
	v_lshlrev_b32_e32 v153, 2, v20
	v_xor_b32_e32 v20, 32, v18
	v_cmp_lt_i32_e32 vcc, v20, v19
	s_add_i32 s5, s5, s9
	s_lshl_b32 s4, s4, 6
	v_cndmask_b32_e32 v18, v18, v20, vcc
	s_sub_i32 s4, s5, s4
	s_ashr_i32 s7, s6, 31
	v_lshlrev_b32_e32 v154, 2, v18
	s_or_b32 s22, s8, 32
	v_lshlrev_b32_e32 v18, 2, v132
	s_sub_i32 s8, s4, 32
	s_lshl_b64 s[4:5], s[6:7], 11
	v_or_b32_e32 v20, 0x100, v18
	v_or_b32_e32 v22, 0x200, v18
	v_or_b32_e32 v24, 0x300, v18
	v_lshl_or_b32 v92, v132, 3, s4
	v_mov_b32_e32 v93, s5
	s_lshl_b64 s[4:5], s[6:7], 12
	v_lshlrev_b32_e32 v1, 2, v1
	v_or_b32_e32 v94, s4, v90
	v_mov_b32_e32 v95, s5
	v_mov_b32_e32 v155, 0x358637bd
	s_mov_b32 s4, 0xf800000
	v_mov_b32_e32 v156, 0x260
	v_lshlrev_b32_e32 v90, 2, v18
	s_movk_i32 s5, 0x7fff
	s_mov_b32 s23, 0xffff0000
	s_mov_b32 s24, 0xba00000
	v_lshlrev_b32_e32 v96, 2, v20
	v_mov_b32_e32 v97, v91
	v_lshlrev_b32_e32 v98, 2, v22
	v_mov_b32_e32 v99, v91
	v_lshlrev_b32_e32 v100, 2, v24
	v_mov_b32_e32 v101, v91
	s_mov_b32 s25, 0xba01000
	s_mov_b64 s[16:17], 0x10000
	s_mov_b64 s[18:19], 0x20000

.LBB0_1591:
	v_mov_b32_e32 v180, v0
	s_mov_b64 s[6:7], -1
	v_readfirstlane_b32 s22, v180
	s_ashr_i32 s10, s22, 6
	v_and_b32_e32 v182, 63, v180
	s_cmp_lg_u32 s5, s33
	s_cbranch_scc0 .LBB0_1597
	s_waitcnt lgkmcnt(0)
	v_mov_b64_e32 v[2:3], s[0:1]
	global_load_dwordx2 v[4:5], v[2:3], off offset:64
	s_waitcnt vmcnt(0)
	global_load_dwordx2 v[8:9], v[2:3], off offset:32
	s_waitcnt vmcnt(0)
	v_ashrrev_i32_e32 v41, 5, v180
	v_lshlrev_b32_e32 v2, 14, v41
	v_and_b32_e32 v178, 0x1c000, v2
	s_mov_b32 s83, s57
	v_lshlrev_b32_e32 v40, 4, v180
	v_and_b32_e32 v6, 0xf0, v40
	v_mov_b32_e32 v7, v179
	s_lshl_b32 s5, s10, 5
	s_and_b32 s6, s5, 0xffffffc0
	s_lshl_b32 s5, s10, 7
	v_and_b32_e32 v203, 31, v180
	s_and_b32 s11, s5, 0x80
	s_mov_b32 s5, 0x20000
	v_lshrrev_b32_e32 v181, 5, v182
	s_mov_b64 s[8:9], 0
	s_waitcnt lgkmcnt(0)
	v_lshl_add_u64 v[26:27], s[54:55], 2, v[4:5]
	v_lshl_add_u64 v[2:3], v[8:9], 0, v[178:179]
	v_lshl_add_u64 v[4:5], v[2:3], 0, s[82:83]
	v_and_b32_e32 v2, 0x100, v40
	v_mov_b32_e32 v3, v179
	v_lshl_add_u64 v[10:11], v[4:5], 0, v[2:3]
	v_ashrrev_i32_e32 v4, 8, v180
	v_ashrrev_i32_e32 v5, 31, v4
	v_lshl_add_u64 v[4:5], v[4:5], 2, v[26:27]
	global_load_dword v4, v[4:5], off
	v_add_u32_e32 v3, 16, v41
	v_lshl_add_u64 v[8:9], v[8:9], 0, s[76:77]
	s_waitcnt vmcnt(0)
	v_ashrrev_i32_e32 v5, 31, v4
	v_lshlrev_b64 v[4:5], 17, v[4:5]
	v_lshl_add_u64 v[12:13], v[10:11], 0, v[4:5]
	v_lshl_add_u64 v[18:19], v[12:13], 0, v[6:7]
	v_ashrrev_i32_e32 v12, 3, v3
	v_ashrrev_i32_e32 v13, 31, v12
	v_lshl_add_u64 v[12:13], v[12:13], 2, v[26:27]
	global_load_dword v12, v[12:13], off
	v_add_u32_e32 v3, 32, v41
	v_or_b32_e32 v4, v4, v178
	v_or3_b32 v4, v4, v2, v6
	v_lshl_add_u64 v[200:201], v[8:9], 0, v[4:5]
	s_waitcnt vmcnt(0)
	v_ashrrev_i32_e32 v13, 31, v12
	v_lshlrev_b64 v[12:13], 17, v[12:13]
	v_lshl_add_u64 v[14:15], v[10:11], 0, v[12:13]
	v_lshl_add_u64 v[22:23], v[14:15], 0, v[6:7]
	v_ashrrev_i32_e32 v14, 3, v3
	v_ashrrev_i32_e32 v15, 31, v14
	v_lshl_add_u64 v[14:15], v[14:15], 2, v[26:27]
	global_load_dword v14, v[14:15], off
	v_add_u32_e32 v3, 48, v41
	v_or_b32_e32 v12, v12, v178
	v_or3_b32 v12, v12, v2, v6
	v_lshl_add_u64 v[198:199], v[8:9], 0, v[12:13]
	s_waitcnt vmcnt(0)
	v_ashrrev_i32_e32 v15, 31, v14
	v_lshlrev_b64 v[14:15], 17, v[14:15]
	v_lshl_add_u64 v[16:17], v[10:11], 0, v[14:15]
	v_lshl_add_u64 v[28:29], v[16:17], 0, v[6:7]
	v_ashrrev_i32_e32 v16, 3, v3
	v_ashrrev_i32_e32 v17, 31, v16
	v_lshl_add_u64 v[16:17], v[16:17], 2, v[26:27]
	global_load_dword v16, v[16:17], off
	v_add_u32_e32 v3, 64, v41
	v_or_b32_e32 v14, v14, v178
	v_or3_b32 v14, v14, v2, v6
	v_lshl_add_u64 v[196:197], v[8:9], 0, v[14:15]
	s_waitcnt vmcnt(0)
	v_ashrrev_i32_e32 v17, 31, v16
	v_lshlrev_b64 v[16:17], 17, v[16:17]
	v_lshl_add_u64 v[20:21], v[10:11], 0, v[16:17]
	v_lshl_add_u64 v[32:33], v[20:21], 0, v[6:7]
	v_ashrrev_i32_e32 v20, 3, v3
	v_ashrrev_i32_e32 v21, 31, v20
	v_lshl_add_u64 v[20:21], v[20:21], 2, v[26:27]
	global_load_dword v20, v[20:21], off
	v_add_u32_e32 v3, 0x50, v41
	v_or_b32_e32 v16, v16, v178
	v_or3_b32 v16, v16, v2, v6
	v_lshl_add_u64 v[194:195], v[8:9], 0, v[16:17]
	s_waitcnt vmcnt(0)
	v_ashrrev_i32_e32 v21, 31, v20
	v_lshlrev_b64 v[20:21], 17, v[20:21]
	v_lshl_add_u64 v[24:25], v[10:11], 0, v[20:21]
	v_lshl_add_u64 v[34:35], v[24:25], 0, v[6:7]
	v_ashrrev_i32_e32 v24, 3, v3
	v_ashrrev_i32_e32 v25, 31, v24
	v_lshl_add_u64 v[24:25], v[24:25], 2, v[26:27]
	global_load_dword v24, v[24:25], off
	v_add_u32_e32 v3, 0x60, v41
	v_or_b32_e32 v20, v20, v178
	v_or3_b32 v20, v20, v2, v6
	v_lshl_add_u64 v[192:193], v[8:9], 0, v[20:21]
	s_waitcnt vmcnt(0)
	v_ashrrev_i32_e32 v25, 31, v24
	v_lshlrev_b64 v[24:25], 17, v[24:25]
	v_lshl_add_u64 v[30:31], v[10:11], 0, v[24:25]
	v_lshl_add_u64 v[36:37], v[30:31], 0, v[6:7]
	v_ashrrev_i32_e32 v30, 3, v3
	v_add_u32_e32 v3, 0x70, v41
	v_ashrrev_i32_e32 v42, 3, v3
	v_ashrrev_i32_e32 v31, 31, v30
	v_ashrrev_i32_e32 v43, 31, v42
	v_lshl_add_u64 v[30:31], v[30:31], 2, v[26:27]
	v_lshl_add_u64 v[26:27], v[42:43], 2, v[26:27]
	global_load_dword v30, v[30:31], off
	v_lshrrev_b32_e32 v3, 4, v180
	global_load_dword v26, v[26:27], off
	v_mul_lo_u32 v41, v3, s48
	v_lshlrev_b32_e32 v3, 3, v180
	v_and_b32_e32 v48, 0x78, v3
	v_or_b32_e32 v3, s6, v203
	s_waitcnt vmcnt(1)
	v_ashrrev_i32_e32 v31, 31, v30
	v_lshlrev_b64 v[30:31], 17, v[30:31]
	s_waitcnt vmcnt(0)
	v_ashrrev_i32_e32 v27, 31, v26
	v_lshlrev_b64 v[26:27], 17, v[26:27]
	v_lshl_add_u64 v[38:39], v[10:11], 0, v[30:31]
	v_lshl_add_u64 v[10:11], v[10:11], 0, v[26:27]
	v_lshl_add_u64 v[42:43], v[10:11], 0, v[6:7]
	v_ashrrev_i32_e32 v10, 3, v180
	v_ashrrev_i32_e32 v11, 31, v10
	v_lshl_add_u64 v[38:39], v[38:39], 0, v[6:7]
	v_lshlrev_b64 v[44:45], 11, v[10:11]
	v_or_b32_e32 v7, s11, v203
	v_mov_b32_e32 v11, s96
	v_lshl_add_u64 v[46:47], s[58:59], 0, v[44:45]
	v_mul_lo_u32 v49, v10, s48
	v_and_b32_e32 v10, 0x70, v40
	v_mad_u32_u24 v7, v7, s48, v11
	v_mov_b32_e32 v11, v179
	global_load_dwordx4 v[130:133], v[18:19], off nt
	global_load_dwordx4 v[134:137], v[22:23], off nt
	global_load_dwordx4 v[138:141], v[28:29], off nt
	global_load_dwordx4 v[142:145], v[32:33], off nt
	global_load_dwordx4 v[146:149], v[34:35], off nt
	global_load_dwordx4 v[150:153], v[36:37], off nt
	global_load_dwordx4 v[154:157], v[38:39], off nt
	global_load_dwordx4 v[158:161], v[42:43], off nt
	v_lshl_add_u64 v[22:23], v[46:47], 0, v[10:11]
	v_add_co_u32_e32 v28, vcc, s5, v22
	s_mov_b32 s5, 0x40000
	s_nop 0
	v_addc_co_u32_e32 v29, vcc, 0, v23, vcc
	global_load_dwordx4 v[162:165], v[22:23], off
	global_load_dwordx4 v[166:169], v[28:29], off
	v_add_co_u32_e32 v28, vcc, s5, v22
	s_mov_b32 s5, 0x60000
	s_nop 0
	v_addc_co_u32_e32 v29, vcc, 0, v23, vcc
	v_add_co_u32_e32 v22, vcc, s5, v22
	global_load_dwordx4 v[170:173], v[28:29], off
	s_nop 0
	v_addc_co_u32_e32 v23, vcc, 0, v23, vcc
	global_load_dwordx4 v[174:177], v[22:23], off
	v_or_b32_e32 v22, v26, v178
	v_or3_b32 v26, v22, v2, v6
	v_or_b32_e32 v22, v30, v178
	v_mul_lo_u32 v40, v3, s48
	v_or3_b32 v30, v22, v2, v6
	v_or_b32_e32 v22, v24, v178
	v_lshlrev_b32_e32 v3, 4, v181
	v_add_u32_e32 v19, s96, v41
	v_add_u32_e32 v11, s96, v49
	v_add_u32_e32 v18, s96, v40
	v_or_b32_e32 v44, v44, v10
	v_or3_b32 v24, v22, v2, v6
	v_mov_b32_e32 v2, 0
	v_lshl_add_u64 v[184:185], s[74:75], 0, v[44:45]
	v_lshl_add_u64 v[186:187], v[8:9], 0, v[26:27]
	v_lshl_add_u64 v[188:189], v[8:9], 0, v[30:31]
	v_lshl_add_u64 v[190:191], v[8:9], 0, v[24:25]
	v_add_u32_e32 v178, v19, v48
	v_add_u32_e32 v204, v11, v10
	v_add_u32_e32 v205, v18, v3
	v_add_u32_e32 v206, v7, v3
	v_mov_b32_e32 v3, v2
	v_mov_b32_e32 v4, v2
	v_mov_b32_e32 v5, v2
	v_mov_b32_e32 v6, v2
	v_mov_b32_e32 v7, v2
	v_mov_b32_e32 v8, v2
	v_mov_b32_e32 v9, v2
	v_mov_b32_e32 v10, v2
	v_mov_b32_e32 v11, v2
	v_mov_b32_e32 v12, v2
	v_mov_b32_e32 v13, v2
	v_mov_b32_e32 v14, v2
	v_mov_b32_e32 v15, v2
	v_mov_b32_e32 v16, v2
	v_mov_b32_e32 v17, v2
	v_mov_b32_e32 v18, v2
	v_mov_b32_e32 v19, v2
	v_mov_b32_e32 v20, v2
	v_mov_b32_e32 v21, v2
	v_mov_b32_e32 v22, v2
	v_mov_b32_e32 v23, v2
	v_mov_b32_e32 v24, v2
	v_mov_b32_e32 v25, v2
	v_mov_b32_e32 v26, v2
	v_mov_b32_e32 v27, v2
	v_mov_b32_e32 v28, v2
	v_mov_b32_e32 v29, v2
	v_mov_b32_e32 v30, v2
	v_mov_b32_e32 v31, v2
	v_mov_b32_e32 v32, v2
	v_mov_b32_e32 v33, v2
	v_mov_b32_e32 v34, v2
	v_mov_b32_e32 v35, v2
	v_mov_b32_e32 v36, v2
	v_mov_b32_e32 v37, v2
	v_mov_b32_e32 v38, v2
	v_mov_b32_e32 v39, v2
	v_mov_b32_e32 v40, v2
	v_mov_b32_e32 v41, v2
	v_mov_b32_e32 v42, v2
	v_mov_b32_e32 v43, v2
	v_mov_b32_e32 v44, v2
	v_mov_b32_e32 v45, v2
	v_mov_b32_e32 v46, v2
	v_mov_b32_e32 v47, v2
	v_mov_b32_e32 v48, v2
	v_mov_b32_e32 v49, v2
	v_mov_b32_e32 v50, v2
	v_mov_b32_e32 v51, v2
	v_mov_b32_e32 v52, v2
	v_mov_b32_e32 v53, v2
	v_mov_b32_e32 v54, v2
	v_mov_b32_e32 v55, v2
	v_mov_b32_e32 v56, v2
	v_mov_b32_e32 v57, v2
	v_mov_b32_e32 v58, v2
	v_mov_b32_e32 v59, v2
	v_mov_b32_e32 v60, v2
	v_mov_b32_e32 v61, v2
	v_mov_b32_e32 v62, v2
	v_mov_b32_e32 v63, v2
	v_mov_b32_e32 v64, v2
	v_mov_b32_e32 v65, v2
	v_mov_b32_e32 v66, v2
	v_mov_b32_e32 v67, v2
	v_mov_b32_e32 v68, v2
	v_mov_b32_e32 v69, v2
	v_mov_b32_e32 v70, v2
	v_mov_b32_e32 v71, v2
	v_mov_b32_e32 v72, v2
	v_mov_b32_e32 v73, v2
	v_mov_b32_e32 v74, v2
	v_mov_b32_e32 v75, v2
	v_mov_b32_e32 v76, v2
	v_mov_b32_e32 v77, v2
	v_mov_b32_e32 v78, v2
	v_mov_b32_e32 v79, v2
	v_mov_b32_e32 v80, v2
	v_mov_b32_e32 v81, v2
	v_mov_b32_e32 v82, v2
	v_mov_b32_e32 v83, v2
	v_mov_b32_e32 v84, v2
	v_mov_b32_e32 v85, v2
	v_mov_b32_e32 v86, v2
	v_mov_b32_e32 v87, v2
	v_mov_b32_e32 v88, v2
	v_mov_b32_e32 v89, v2
	v_mov_b32_e32 v90, v2
	v_mov_b32_e32 v91, v2
	v_mov_b32_e32 v92, v2
	v_mov_b32_e32 v93, v2
	v_mov_b32_e32 v94, v2
	v_mov_b32_e32 v95, v2
	v_mov_b32_e32 v96, v2
	v_mov_b32_e32 v97, v2
	v_mov_b32_e32 v98, v2
	v_mov_b32_e32 v99, v2
	v_mov_b32_e32 v100, v2
	v_mov_b32_e32 v101, v2
	v_mov_b32_e32 v102, v2
	v_mov_b32_e32 v103, v2
	v_mov_b32_e32 v104, v2
	v_mov_b32_e32 v105, v2
	v_mov_b32_e32 v106, v2
	v_mov_b32_e32 v107, v2
	v_mov_b32_e32 v108, v2
	v_mov_b32_e32 v109, v2
	v_mov_b32_e32 v110, v2
	v_mov_b32_e32 v111, v2
	v_mov_b32_e32 v112, v2
	v_mov_b32_e32 v113, v2
	v_mov_b32_e32 v114, v2
	v_mov_b32_e32 v115, v2
	v_mov_b32_e32 v116, v2
	v_mov_b32_e32 v117, v2
	v_mov_b32_e32 v118, v2
	v_mov_b32_e32 v119, v2
	v_mov_b32_e32 v120, v2
	v_mov_b32_e32 v121, v2
	v_mov_b32_e32 v122, v2
	v_mov_b32_e32 v123, v2
	v_mov_b32_e32 v124, v2
	v_mov_b32_e32 v125, v2
	v_mov_b32_e32 v126, v2
	v_mov_b32_e32 v127, v2
	v_mov_b32_e32 v128, v2
	v_mov_b32_e32 v129, v2
	s_branch .LBB0_1594

.LBB0_1602:
	s_lshl_b32 s24, s86, 4
	s_lshl_b32 s25, s86, 6
	s_and_b32 s24, s24, 0xffffe000
	s_and_b32 s25, s25, 0x1fc0
	s_or_b32 s90, s24, s25
	s_bfe_u32 s87, s86, 0x20007
	s_lshl_b32 s91, s87, 6
	s_load_dwordx2 s[98:99], s[0:1], 0x98
	s_load_dwordx2 s[100:101], s[0:1], 0xa0
	v_lshlrev_b32_e32 v178, 2, v182
	v_ashrrev_i32_e32 v150, 4, v180
	v_add_u32_e32 v152, s90, v150
	v_mad_i64_i32 v[152:153], vcc, v152, s62, v[22:23]
	global_load_dword v170, v[152:153], off
	v_add_u32_e32 v151, 0x200, v180
	v_ashrrev_i32_e32 v151, 4, v151
	v_add_u32_e32 v154, s90, v151
	v_mad_i64_i32 v[154:155], vcc, v154, s62, v[22:23]
	global_load_dword v171, v[154:155], off
	v_lshl_add_u32 v174, v150, 2, v59
	v_lshl_add_u32 v175, v151, 2, v59
	s_waitcnt lgkmcnt(0)
	s_lshl_b32 s56, s91, 2
	v_and_b32_e32 v156, 0xffffff00, v43
	v_ashrrev_i32_e32 v157, 31, v156
	v_lshl_add_u64 v[158:159], v[156:157], 2, s[98:99]
	v_lshl_add_u64 v[158:159], v[158:159], 0, s[56:57]
	v_lshl_add_u64 v[158:159], v[158:159], 0, v[178:179]
	global_load_dword v172, v[158:159], off
	v_add_u32_e32 v176, s4, v43
	v_add_u32_e32 v160, 0x800, v43
	v_and_b32_e32 v156, 0xffffff00, v160
	v_ashrrev_i32_e32 v157, 31, v156
	v_lshl_add_u64 v[162:163], v[156:157], 2, s[98:99]
	v_lshl_add_u64 v[162:163], v[162:163], 0, s[56:57]
	v_lshl_add_u64 v[162:163], v[162:163], 0, v[178:179]
	global_load_dword v173, v[162:163], off
	v_add_u32_e32 v177, s4, v160
	v_ashrrev_i32_e32 v90, 6, v180
	v_add_u32_e32 v164, s91, v90
	v_ashrrev_i32_e32 v165, 31, v164
	v_lshl_add_u64 v[166:167], v[164:165], 2, s[100:101]
	global_load_dword v132, v[166:167], off
	v_add_u32_e32 v164, 0x200, v180
	v_ashrrev_i32_e32 v91, 6, v164
	v_add_u32_e32 v164, s91, v91
	v_ashrrev_i32_e32 v165, 31, v164
	v_lshl_add_u64 v[166:167], v[164:165], 2, s[100:101]
	global_load_dword v133, v[166:167], off
	v_add_u32_e32 v164, 0x400, v180
	v_ashrrev_i32_e32 v92, 6, v164
	v_add_u32_e32 v164, s91, v92
	v_ashrrev_i32_e32 v165, 31, v164
	v_lshl_add_u64 v[166:167], v[164:165], 2, s[100:101]
	global_load_dword v134, v[166:167], off
	v_add_u32_e32 v164, 0x600, v180
	v_ashrrev_i32_e32 v93, 6, v164
	v_add_u32_e32 v164, s91, v93
	v_ashrrev_i32_e32 v165, 31, v164
	v_lshl_add_u64 v[166:167], v[164:165], 2, s[100:101]
	global_load_dword v135, v[166:167], off
	v_add_u32_e32 v164, 0x800, v180
	v_ashrrev_i32_e32 v94, 6, v164
	v_add_u32_e32 v164, s91, v94
	v_ashrrev_i32_e32 v165, 31, v164
	v_lshl_add_u64 v[166:167], v[164:165], 2, s[100:101]
	global_load_dword v136, v[166:167], off
	v_add_u32_e32 v164, 0xa00, v180
	v_ashrrev_i32_e32 v95, 6, v164
	v_add_u32_e32 v164, s91, v95
	v_ashrrev_i32_e32 v165, 31, v164
	v_lshl_add_u64 v[166:167], v[164:165], 2, s[100:101]
	global_load_dword v137, v[166:167], off
	v_add_u32_e32 v164, 0xc00, v180
	v_ashrrev_i32_e32 v96, 6, v164
	v_add_u32_e32 v164, s91, v96
	v_ashrrev_i32_e32 v165, 31, v164
	v_lshl_add_u64 v[166:167], v[164:165], 2, s[100:101]
	global_load_dword v138, v[166:167], off
	v_add_u32_e32 v164, 0xe00, v180
	v_ashrrev_i32_e32 v97, 6, v164
	v_add_u32_e32 v164, s91, v97
	v_ashrrev_i32_e32 v165, 31, v164
	v_lshl_add_u64 v[166:167], v[164:165], 2, s[100:101]
	global_load_dword v139, v[166:167], off
	s_lshl_b32 s24, s86, 4
	s_lshl_b32 s25, s86, 6
	s_and_b32 s24, s24, 0xffffe000
	s_and_b32 s25, s25, 0x1fc0
	s_or_b32 s90, s24, s25
	s_bfe_u32 s87, s86, 0x20007
	v_add_u32_e32 v2, s90, v35
	v_mov_b64_e32 v[10:11], s[46:47]
	v_mad_i64_i32 v[2:3], s[24:25], v2, s62, v[10:11]
	s_lshl_b32 s56, s87, 8
	v_lshl_add_u64 v[2:3], v[2:3], 0, s[56:57]
	v_lshlrev_b32_e32 v178, 2, v182
	v_add_u32_e32 v4, s90, v36
	v_lshl_add_u64 v[2:3], v[2:3], 0, v[178:179]
	v_mad_i64_i32 v[4:5], s[24:25], v4, s62, v[10:11]
	v_add_co_u32_e32 v2, vcc, s50, v2
	v_lshl_add_u64 v[4:5], v[4:5], 0, s[56:57]
	v_add_u32_e32 v6, s90, v37
	v_addc_co_u32_e32 v3, vcc, 0, v3, vcc
	v_lshl_add_u64 v[4:5], v[4:5], 0, v[178:179]
	v_mad_i64_i32 v[6:7], s[24:25], v6, s62, v[10:11]
	v_add_co_u32_e32 v4, vcc, s50, v4
	v_lshl_add_u64 v[6:7], v[6:7], 0, s[56:57]
	v_add_u32_e32 v8, s90, v38
	v_addc_co_u32_e32 v5, vcc, 0, v5, vcc
	v_lshl_add_u64 v[6:7], v[6:7], 0, v[178:179]
	v_mad_i64_i32 v[8:9], s[24:25], v8, s62, v[10:11]
	v_add_co_u32_e32 v6, vcc, s50, v6
	v_lshl_add_u64 v[8:9], v[8:9], 0, s[56:57]
	v_add_u32_e32 v12, s90, v39
	v_addc_co_u32_e32 v7, vcc, 0, v7, vcc
	v_lshl_add_u64 v[8:9], v[8:9], 0, v[178:179]
	v_mad_i64_i32 v[12:13], s[24:25], v12, s62, v[10:11]
	v_add_co_u32_e32 v8, vcc, s50, v8
	v_lshl_add_u64 v[12:13], v[12:13], 0, s[56:57]
	v_add_u32_e32 v14, s90, v40
	v_addc_co_u32_e32 v9, vcc, 0, v9, vcc
	v_lshl_add_u64 v[12:13], v[12:13], 0, v[178:179]
	v_mad_i64_i32 v[14:15], s[24:25], v14, s62, v[10:11]
	v_add_co_u32_e32 v12, vcc, s50, v12
	v_lshl_add_u64 v[14:15], v[14:15], 0, s[56:57]
	v_add_u32_e32 v16, s90, v41
	v_addc_co_u32_e32 v13, vcc, 0, v13, vcc
	v_lshl_add_u64 v[14:15], v[14:15], 0, v[178:179]
	v_mad_i64_i32 v[16:17], s[24:25], v16, s62, v[10:11]
	v_add_co_u32_e32 v14, vcc, s50, v14
	v_lshl_add_u64 v[16:17], v[16:17], 0, s[56:57]
	v_add_u32_e32 v29, s90, v42
	v_addc_co_u32_e32 v15, vcc, 0, v15, vcc
	v_lshl_add_u64 v[16:17], v[16:17], 0, v[178:179]
	v_mad_i64_i32 v[66:67], s[24:25], v29, s62, v[10:11]
	v_add_co_u32_e32 v16, vcc, s50, v16
	v_lshl_add_u64 v[66:67], v[66:67], 0, s[56:57]
	s_nop 0
	v_addc_co_u32_e32 v17, vcc, 0, v17, vcc
	v_lshl_add_u64 v[66:67], v[66:67], 0, v[178:179]
	v_add_co_u32_e32 v74, vcc, s50, v66
	s_lshl_b32 s56, s87, 9
	s_nop 0
	v_addc_co_u32_e32 v75, vcc, 0, v67, vcc
	global_load_dword v72, v[2:3], off offset:2144
	global_load_dword v71, v[4:5], off offset:2144
	global_load_dword v70, v[6:7], off offset:2144
	global_load_dword v69, v[8:9], off offset:2144
	global_load_dword v68, v[12:13], off offset:2144
	global_load_dword v67, v[14:15], off offset:2144
	global_load_dword v66, v[16:17], off offset:2144
	global_load_dword v65, v[74:75], off offset:2144
	v_add_u32_e32 v2, s90, v44
	v_mad_i64_i32 v[2:3], s[24:25], v2, s62, v[10:11]
	v_lshl_add_u64 v[2:3], v[2:3], 0, s[56:57]
	v_mov_b32_e32 v29, v179
	v_add_u32_e32 v4, s90, v45
	v_lshl_add_u64 v[2:3], v[2:3], 0, v[28:29]
	v_mad_i64_i32 v[4:5], s[24:25], v4, s62, v[10:11]
	v_add_co_u32_e32 v2, vcc, s50, v2
	v_lshl_add_u64 v[4:5], v[4:5], 0, s[56:57]
	v_add_u32_e32 v12, s90, v46
	v_addc_co_u32_e32 v3, vcc, 0, v3, vcc
	v_lshl_add_u64 v[4:5], v[4:5], 0, v[28:29]
	v_mad_i64_i32 v[12:13], s[24:25], v12, s62, v[10:11]
	v_add_co_u32_e32 v6, vcc, s50, v4
	v_lshl_add_u64 v[12:13], v[12:13], 0, s[56:57]
	v_add_u32_e32 v14, s90, v47
	v_addc_co_u32_e32 v7, vcc, 0, v5, vcc
	v_lshl_add_u64 v[12:13], v[12:13], 0, v[28:29]
	v_mad_i64_i32 v[10:11], s[24:25], v14, s62, v[10:11]
	v_add_co_u32_e32 v12, vcc, s50, v12
	v_lshl_add_u64 v[10:11], v[10:11], 0, s[56:57]
	s_nop 0
	v_addc_co_u32_e32 v13, vcc, 0, v13, vcc
	v_lshl_add_u64 v[10:11], v[10:11], 0, v[28:29]
	v_add_co_u32_e32 v14, vcc, 0x1000, v10
	global_load_dwordx4 v[2:5], v[2:3], off offset:3168
	s_nop 0
	global_load_dwordx4 v[6:9], v[6:7], off offset:3168
	v_addc_co_u32_e32 v15, vcc, 0, v11, vcc
	global_load_dwordx4 v[10:13], v[12:13], off offset:3168
	s_nop 0
	global_load_dwordx4 v[14:17], v[14:15], off offset:3168
	s_lshl_b32 s87, s87, 6
	s_waitcnt lgkmcnt(0)
	s_barrier
	s_waitcnt vmcnt(20)
	ds_write_b32 v174, v170
	ds_write_b32 v175, v171
	ds_write_b32 v176, v172
	ds_write_b32 v177, v173
	s_waitcnt lgkmcnt(0)
	s_barrier
	ds_read2st64_b32 v[100:101], v60 offset1:1
	ds_read2st64_b32 v[102:103], v60 offset0:2 offset1:3
	ds_read2st64_b32 v[104:105], v60 offset0:4 offset1:5
	ds_read2st64_b32 v[106:107], v60 offset0:6 offset1:7
	ds_read2st64_b32 v[108:109], v60 offset0:8 offset1:9
	ds_read2st64_b32 v[110:111], v60 offset0:10 offset1:11
	ds_read2st64_b32 v[112:113], v60 offset0:12 offset1:13
	ds_read2st64_b32 v[114:115], v60 offset0:14 offset1:15
	v_lshl_add_u32 v143, v90, 2, s4
	ds_read2st64_b32 v[116:117], v143 offset1:1
	ds_read2st64_b32 v[118:119], v143 offset0:2 offset1:3
	ds_read2st64_b32 v[120:121], v143 offset0:4 offset1:5
	ds_read2st64_b32 v[122:123], v143 offset0:6 offset1:7
	ds_read2st64_b32 v[124:125], v143 offset0:8 offset1:9
	ds_read2st64_b32 v[126:127], v143 offset0:10 offset1:11
	ds_read2st64_b32 v[128:129], v143 offset0:12 offset1:13
	ds_read2st64_b32 v[130:131], v143 offset0:14 offset1:15
	s_waitcnt vmcnt(12)
	s_waitcnt lgkmcnt(0)
	v_lshl_add_u32 v143, v91, 2, s4
	ds_read2st64_b32 v[204:205], v143 offset1:1
	ds_read2st64_b32 v[206:207], v143 offset0:2 offset1:3
	ds_read2st64_b32 v[208:209], v143 offset0:4 offset1:5
	ds_read2st64_b32 v[210:211], v143 offset0:6 offset1:7
	ds_read2st64_b32 v[212:213], v143 offset0:8 offset1:9
	ds_read2st64_b32 v[214:215], v143 offset0:10 offset1:11
	ds_read2st64_b32 v[216:217], v143 offset0:12 offset1:13
	ds_read2st64_b32 v[218:219], v143 offset0:14 offset1:15
	v_fmac_f32_e32 v132, v100, v116
	v_fmac_f32_e32 v132, v101, v117
	v_fmac_f32_e32 v132, v102, v118
	v_fmac_f32_e32 v132, v103, v119
	v_fmac_f32_e32 v132, v104, v120
	v_fmac_f32_e32 v132, v105, v121
	v_mul_f32_e32 v140, v106, v122
	v_mul_f32_e32 v141, v107, v123
	v_add_f32_e32 v132, v132, v140
	v_add_f32_e32 v132, v132, v141
	v_mul_f32_e32 v140, v108, v124
	v_mul_f32_e32 v141, v109, v125
	v_add_f32_e32 v132, v132, v140
	v_add_f32_e32 v132, v132, v141
	v_mul_f32_e32 v140, v110, v126
	v_mul_f32_e32 v141, v111, v127
	v_add_f32_e32 v132, v132, v140
	v_add_f32_e32 v132, v132, v141
	v_mul_f32_e32 v140, v112, v128
	v_mul_f32_e32 v141, v113, v129
	v_add_f32_e32 v132, v132, v140
	v_add_f32_e32 v132, v132, v141
	v_mul_f32_e32 v140, v114, v130
	v_mul_f32_e32 v141, v115, v131
	v_add_f32_e32 v132, v132, v140
	v_add_f32_e32 v132, v132, v141
	s_mov_b32 s24, 0xbfb8aa3b
	v_min_f32_e32 v141, 0, v132
	v_mul_f32_e64 v140, |v132|, s24
	v_exp_f32_e32 v140, v140
	s_mov_b32 s24, 0x800000
	v_add_f32_e32 v140, 1.0, v140
	v_cmp_gt_f32_e32 vcc, s24, v140
	s_mov_b32 s24, 0x3f317217
	s_nop 0
	v_cndmask_b32_e64 v142, 0, 32, vcc
	v_ldexp_f32 v140, v140, v142
	v_log_f32_e32 v140, v140
	s_nop 0
	v_mul_f32_e32 v142, 0x3f317217, v140
	v_fma_f32 v142, v140, s24, -v142
	v_fmac_f32_e32 v142, 0x3377d1cf, v140
	s_mov_b32 s24, 0x7f800000
	v_fmac_f32_e32 v142, 0x3f317217, v140
	v_cmp_lt_f32_e64 s[24:25], |v140|, s24
	s_nop 1
	v_cndmask_b32_e64 v140, v140, v142, s[24:25]
	v_cndmask_b32_e32 v142, 0, v183, vcc
	v_sub_f32_e32 v140, v140, v142
	v_sub_f32_e32 v140, v141, v140
	v_mul_f32_e32 v142, 0x3d800000, v140
	v_mad_u64_u32 v[144:145], s[24:25], v90, s51, v[18:19]
	ds_write_b32 v144, v142
	s_waitcnt lgkmcnt(1)
	v_lshl_add_u32 v143, v92, 2, s4
	ds_read2st64_b32 v[116:117], v143 offset1:1
	ds_read2st64_b32 v[118:119], v143 offset0:2 offset1:3
	ds_read2st64_b32 v[120:121], v143 offset0:4 offset1:5
	ds_read2st64_b32 v[122:123], v143 offset0:6 offset1:7
	ds_read2st64_b32 v[124:125], v143 offset0:8 offset1:9
	ds_read2st64_b32 v[126:127], v143 offset0:10 offset1:11
	ds_read2st64_b32 v[128:129], v143 offset0:12 offset1:13
	ds_read2st64_b32 v[130:131], v143 offset0:14 offset1:15
	v_fmac_f32_e32 v133, v100, v204
	v_fmac_f32_e32 v133, v101, v205
	v_fmac_f32_e32 v133, v102, v206
	v_fmac_f32_e32 v133, v103, v207
	v_fmac_f32_e32 v133, v104, v208
	v_fmac_f32_e32 v133, v105, v209
	v_mul_f32_e32 v140, v106, v210
	v_mul_f32_e32 v141, v107, v211
	v_add_f32_e32 v133, v133, v140
	v_add_f32_e32 v133, v133, v141
	v_mul_f32_e32 v140, v108, v212
	v_mul_f32_e32 v141, v109, v213
	v_add_f32_e32 v133, v133, v140
	v_add_f32_e32 v133, v133, v141
	v_mul_f32_e32 v140, v110, v214
	v_mul_f32_e32 v141, v111, v215
	v_add_f32_e32 v133, v133, v140
	v_add_f32_e32 v133, v133, v141
	v_mul_f32_e32 v140, v112, v216
	v_mul_f32_e32 v141, v113, v217
	v_add_f32_e32 v133, v133, v140
	v_add_f32_e32 v133, v133, v141
	v_mul_f32_e32 v140, v114, v218
	v_mul_f32_e32 v141, v115, v219
	v_add_f32_e32 v133, v133, v140
	v_add_f32_e32 v133, v133, v141
	s_mov_b32 s24, 0xbfb8aa3b
	v_min_f32_e32 v141, 0, v133
	v_mul_f32_e64 v140, |v133|, s24
	v_exp_f32_e32 v140, v140
	s_mov_b32 s24, 0x800000
	v_add_f32_e32 v140, 1.0, v140
	v_cmp_gt_f32_e32 vcc, s24, v140
	s_mov_b32 s24, 0x3f317217
	s_nop 0
	v_cndmask_b32_e64 v142, 0, 32, vcc
	v_ldexp_f32 v140, v140, v142
	v_log_f32_e32 v140, v140
	s_nop 0
	v_mul_f32_e32 v142, 0x3f317217, v140
	v_fma_f32 v142, v140, s24, -v142
	v_fmac_f32_e32 v142, 0x3377d1cf, v140
	s_mov_b32 s24, 0x7f800000
	v_fmac_f32_e32 v142, 0x3f317217, v140
	v_cmp_lt_f32_e64 s[24:25], |v140|, s24
	s_nop 1
	v_cndmask_b32_e64 v140, v140, v142, s[24:25]
	v_cndmask_b32_e32 v142, 0, v183, vcc
	v_sub_f32_e32 v140, v140, v142
	v_sub_f32_e32 v140, v141, v140
	v_mul_f32_e32 v142, 0x3d800000, v140
	v_mad_u64_u32 v[144:145], s[24:25], v91, s51, v[18:19]
	ds_write_b32 v144, v142
	s_waitcnt lgkmcnt(1)
	v_lshl_add_u32 v143, v93, 2, s4
	ds_read2st64_b32 v[204:205], v143 offset1:1
	ds_read2st64_b32 v[206:207], v143 offset0:2 offset1:3
	ds_read2st64_b32 v[208:209], v143 offset0:4 offset1:5
	ds_read2st64_b32 v[210:211], v143 offset0:6 offset1:7
	ds_read2st64_b32 v[212:213], v143 offset0:8 offset1:9
	ds_read2st64_b32 v[214:215], v143 offset0:10 offset1:11
	ds_read2st64_b32 v[216:217], v143 offset0:12 offset1:13
	ds_read2st64_b32 v[218:219], v143 offset0:14 offset1:15
	v_fmac_f32_e32 v134, v100, v116
	v_fmac_f32_e32 v134, v101, v117
	v_fmac_f32_e32 v134, v102, v118
	v_fmac_f32_e32 v134, v103, v119
	v_fmac_f32_e32 v134, v104, v120
	v_fmac_f32_e32 v134, v105, v121
	v_mul_f32_e32 v140, v106, v122
	v_mul_f32_e32 v141, v107, v123
	v_add_f32_e32 v134, v134, v140
	v_add_f32_e32 v134, v134, v141
	v_mul_f32_e32 v140, v108, v124
	v_mul_f32_e32 v141, v109, v125
	v_add_f32_e32 v134, v134, v140
	v_add_f32_e32 v134, v134, v141
	v_mul_f32_e32 v140, v110, v126
	v_mul_f32_e32 v141, v111, v127
	v_add_f32_e32 v134, v134, v140
	v_add_f32_e32 v134, v134, v141
	v_mul_f32_e32 v140, v112, v128
	v_mul_f32_e32 v141, v113, v129
	v_add_f32_e32 v134, v134, v140
	v_add_f32_e32 v134, v134, v141
	v_mul_f32_e32 v140, v114, v130
	v_mul_f32_e32 v141, v115, v131
	v_add_f32_e32 v134, v134, v140
	v_add_f32_e32 v134, v134, v141
	s_mov_b32 s24, 0xbfb8aa3b
	v_min_f32_e32 v141, 0, v134
	v_mul_f32_e64 v140, |v134|, s24
	v_exp_f32_e32 v140, v140
	s_mov_b32 s24, 0x800000
	v_add_f32_e32 v140, 1.0, v140
	v_cmp_gt_f32_e32 vcc, s24, v140
	s_mov_b32 s24, 0x3f317217
	s_nop 0
	v_cndmask_b32_e64 v142, 0, 32, vcc
	v_ldexp_f32 v140, v140, v142
	v_log_f32_e32 v140, v140
	s_nop 0
	v_mul_f32_e32 v142, 0x3f317217, v140
	v_fma_f32 v142, v140, s24, -v142
	v_fmac_f32_e32 v142, 0x3377d1cf, v140
	s_mov_b32 s24, 0x7f800000
	v_fmac_f32_e32 v142, 0x3f317217, v140
	v_cmp_lt_f32_e64 s[24:25], |v140|, s24
	s_nop 1
	v_cndmask_b32_e64 v140, v140, v142, s[24:25]
	v_cndmask_b32_e32 v142, 0, v183, vcc
	v_sub_f32_e32 v140, v140, v142
	v_sub_f32_e32 v140, v141, v140
	v_mul_f32_e32 v142, 0x3d800000, v140
	v_mad_u64_u32 v[144:145], s[24:25], v92, s51, v[18:19]
	ds_write_b32 v144, v142
	s_waitcnt lgkmcnt(1)
	v_lshl_add_u32 v143, v94, 2, s4
	ds_read2st64_b32 v[116:117], v143 offset1:1
	ds_read2st64_b32 v[118:119], v143 offset0:2 offset1:3
	ds_read2st64_b32 v[120:121], v143 offset0:4 offset1:5
	ds_read2st64_b32 v[122:123], v143 offset0:6 offset1:7
	ds_read2st64_b32 v[124:125], v143 offset0:8 offset1:9
	ds_read2st64_b32 v[126:127], v143 offset0:10 offset1:11
	ds_read2st64_b32 v[128:129], v143 offset0:12 offset1:13
	ds_read2st64_b32 v[130:131], v143 offset0:14 offset1:15
	v_fmac_f32_e32 v135, v100, v204
	v_fmac_f32_e32 v135, v101, v205
	v_fmac_f32_e32 v135, v102, v206
	v_fmac_f32_e32 v135, v103, v207
	v_fmac_f32_e32 v135, v104, v208
	v_fmac_f32_e32 v135, v105, v209
	v_mul_f32_e32 v140, v106, v210
	v_mul_f32_e32 v141, v107, v211
	v_add_f32_e32 v135, v135, v140
	v_add_f32_e32 v135, v135, v141
	v_mul_f32_e32 v140, v108, v212
	v_mul_f32_e32 v141, v109, v213
	v_add_f32_e32 v135, v135, v140
	v_add_f32_e32 v135, v135, v141
	v_mul_f32_e32 v140, v110, v214
	v_mul_f32_e32 v141, v111, v215
	v_add_f32_e32 v135, v135, v140
	v_add_f32_e32 v135, v135, v141
	v_mul_f32_e32 v140, v112, v216
	v_mul_f32_e32 v141, v113, v217
	v_add_f32_e32 v135, v135, v140
	v_add_f32_e32 v135, v135, v141
	v_mul_f32_e32 v140, v114, v218
	v_mul_f32_e32 v141, v115, v219
	v_add_f32_e32 v135, v135, v140
	v_add_f32_e32 v135, v135, v141
	s_mov_b32 s24, 0xbfb8aa3b
	v_min_f32_e32 v141, 0, v135
	v_mul_f32_e64 v140, |v135|, s24
	v_exp_f32_e32 v140, v140
	s_mov_b32 s24, 0x800000
	v_add_f32_e32 v140, 1.0, v140
	v_cmp_gt_f32_e32 vcc, s24, v140
	s_mov_b32 s24, 0x3f317217
	s_nop 0
	v_cndmask_b32_e64 v142, 0, 32, vcc
	v_ldexp_f32 v140, v140, v142
	v_log_f32_e32 v140, v140
	s_nop 0
	v_mul_f32_e32 v142, 0x3f317217, v140
	v_fma_f32 v142, v140, s24, -v142
	v_fmac_f32_e32 v142, 0x3377d1cf, v140
	s_mov_b32 s24, 0x7f800000
	v_fmac_f32_e32 v142, 0x3f317217, v140
	v_cmp_lt_f32_e64 s[24:25], |v140|, s24
	s_nop 1
	v_cndmask_b32_e64 v140, v140, v142, s[24:25]
	v_cndmask_b32_e32 v142, 0, v183, vcc
	v_sub_f32_e32 v140, v140, v142
	v_sub_f32_e32 v140, v141, v140
	v_mul_f32_e32 v142, 0x3d800000, v140
	v_mad_u64_u32 v[144:145], s[24:25], v93, s51, v[18:19]
	ds_write_b32 v144, v142
	s_waitcnt lgkmcnt(1)
	v_lshl_add_u32 v143, v95, 2, s4
	ds_read2st64_b32 v[204:205], v143 offset1:1
	ds_read2st64_b32 v[206:207], v143 offset0:2 offset1:3
	ds_read2st64_b32 v[208:209], v143 offset0:4 offset1:5
	ds_read2st64_b32 v[210:211], v143 offset0:6 offset1:7
	ds_read2st64_b32 v[212:213], v143 offset0:8 offset1:9
	ds_read2st64_b32 v[214:215], v143 offset0:10 offset1:11
	ds_read2st64_b32 v[216:217], v143 offset0:12 offset1:13
	ds_read2st64_b32 v[218:219], v143 offset0:14 offset1:15
	v_fmac_f32_e32 v136, v100, v116
	v_fmac_f32_e32 v136, v101, v117
	v_fmac_f32_e32 v136, v102, v118
	v_fmac_f32_e32 v136, v103, v119
	v_fmac_f32_e32 v136, v104, v120
	v_fmac_f32_e32 v136, v105, v121
	v_mul_f32_e32 v140, v106, v122
	v_mul_f32_e32 v141, v107, v123
	v_add_f32_e32 v136, v136, v140
	v_add_f32_e32 v136, v136, v141
	v_mul_f32_e32 v140, v108, v124
	v_mul_f32_e32 v141, v109, v125
	v_add_f32_e32 v136, v136, v140
	v_add_f32_e32 v136, v136, v141
	v_mul_f32_e32 v140, v110, v126
	v_mul_f32_e32 v141, v111, v127
	v_add_f32_e32 v136, v136, v140
	v_add_f32_e32 v136, v136, v141
	v_mul_f32_e32 v140, v112, v128
	v_mul_f32_e32 v141, v113, v129
	v_add_f32_e32 v136, v136, v140
	v_add_f32_e32 v136, v136, v141
	v_mul_f32_e32 v140, v114, v130
	v_mul_f32_e32 v141, v115, v131
	v_add_f32_e32 v136, v136, v140
	v_add_f32_e32 v136, v136, v141
	s_mov_b32 s24, 0xbfb8aa3b
	v_min_f32_e32 v141, 0, v136
	v_mul_f32_e64 v140, |v136|, s24
	v_exp_f32_e32 v140, v140
	s_mov_b32 s24, 0x800000
	v_add_f32_e32 v140, 1.0, v140
	v_cmp_gt_f32_e32 vcc, s24, v140
	s_mov_b32 s24, 0x3f317217
	s_nop 0
	v_cndmask_b32_e64 v142, 0, 32, vcc
	v_ldexp_f32 v140, v140, v142
	v_log_f32_e32 v140, v140
	s_nop 0
	v_mul_f32_e32 v142, 0x3f317217, v140
	v_fma_f32 v142, v140, s24, -v142
	v_fmac_f32_e32 v142, 0x3377d1cf, v140
	s_mov_b32 s24, 0x7f800000
	v_fmac_f32_e32 v142, 0x3f317217, v140
	v_cmp_lt_f32_e64 s[24:25], |v140|, s24
	s_nop 1
	v_cndmask_b32_e64 v140, v140, v142, s[24:25]
	v_cndmask_b32_e32 v142, 0, v183, vcc
	v_sub_f32_e32 v140, v140, v142
	v_sub_f32_e32 v140, v141, v140
	v_mul_f32_e32 v142, 0x3d800000, v140
	v_mad_u64_u32 v[144:145], s[24:25], v94, s51, v[18:19]
	ds_write_b32 v144, v142
	s_waitcnt lgkmcnt(1)
	v_lshl_add_u32 v143, v96, 2, s4
	ds_read2st64_b32 v[116:117], v143 offset1:1
	ds_read2st64_b32 v[118:119], v143 offset0:2 offset1:3
	ds_read2st64_b32 v[120:121], v143 offset0:4 offset1:5
	ds_read2st64_b32 v[122:123], v143 offset0:6 offset1:7
	ds_read2st64_b32 v[124:125], v143 offset0:8 offset1:9
	ds_read2st64_b32 v[126:127], v143 offset0:10 offset1:11
	ds_read2st64_b32 v[128:129], v143 offset0:12 offset1:13
	ds_read2st64_b32 v[130:131], v143 offset0:14 offset1:15
	v_fmac_f32_e32 v137, v100, v204
	v_fmac_f32_e32 v137, v101, v205
	v_fmac_f32_e32 v137, v102, v206
	v_fmac_f32_e32 v137, v103, v207
	v_fmac_f32_e32 v137, v104, v208
	v_fmac_f32_e32 v137, v105, v209
	v_mul_f32_e32 v140, v106, v210
	v_mul_f32_e32 v141, v107, v211
	v_add_f32_e32 v137, v137, v140
	v_add_f32_e32 v137, v137, v141
	v_mul_f32_e32 v140, v108, v212
	v_mul_f32_e32 v141, v109, v213
	v_add_f32_e32 v137, v137, v140
	v_add_f32_e32 v137, v137, v141
	v_mul_f32_e32 v140, v110, v214
	v_mul_f32_e32 v141, v111, v215
	v_add_f32_e32 v137, v137, v140
	v_add_f32_e32 v137, v137, v141
	v_mul_f32_e32 v140, v112, v216
	v_mul_f32_e32 v141, v113, v217
	v_add_f32_e32 v137, v137, v140
	v_add_f32_e32 v137, v137, v141
	v_mul_f32_e32 v140, v114, v218
	v_mul_f32_e32 v141, v115, v219
	v_add_f32_e32 v137, v137, v140
	v_add_f32_e32 v137, v137, v141
	s_mov_b32 s24, 0xbfb8aa3b
	v_min_f32_e32 v141, 0, v137
	v_mul_f32_e64 v140, |v137|, s24
	v_exp_f32_e32 v140, v140
	s_mov_b32 s24, 0x800000
	v_add_f32_e32 v140, 1.0, v140
	v_cmp_gt_f32_e32 vcc, s24, v140
	s_mov_b32 s24, 0x3f317217
	s_nop 0
	v_cndmask_b32_e64 v142, 0, 32, vcc
	v_ldexp_f32 v140, v140, v142
	v_log_f32_e32 v140, v140
	s_nop 0
	v_mul_f32_e32 v142, 0x3f317217, v140
	v_fma_f32 v142, v140, s24, -v142
	v_fmac_f32_e32 v142, 0x3377d1cf, v140
	s_mov_b32 s24, 0x7f800000
	v_fmac_f32_e32 v142, 0x3f317217, v140
	v_cmp_lt_f32_e64 s[24:25], |v140|, s24
	s_nop 1
	v_cndmask_b32_e64 v140, v140, v142, s[24:25]
	v_cndmask_b32_e32 v142, 0, v183, vcc
	v_sub_f32_e32 v140, v140, v142
	v_sub_f32_e32 v140, v141, v140
	v_mul_f32_e32 v142, 0x3d800000, v140
	v_mad_u64_u32 v[144:145], s[24:25], v95, s51, v[18:19]
	ds_write_b32 v144, v142
	s_waitcnt lgkmcnt(1)
	v_lshl_add_u32 v143, v97, 2, s4
	ds_read2st64_b32 v[204:205], v143 offset1:1
	ds_read2st64_b32 v[206:207], v143 offset0:2 offset1:3
	ds_read2st64_b32 v[208:209], v143 offset0:4 offset1:5
	ds_read2st64_b32 v[210:211], v143 offset0:6 offset1:7
	ds_read2st64_b32 v[212:213], v143 offset0:8 offset1:9
	ds_read2st64_b32 v[214:215], v143 offset0:10 offset1:11
	ds_read2st64_b32 v[216:217], v143 offset0:12 offset1:13
	ds_read2st64_b32 v[218:219], v143 offset0:14 offset1:15
	v_fmac_f32_e32 v138, v100, v116
	v_fmac_f32_e32 v138, v101, v117
	v_fmac_f32_e32 v138, v102, v118
	v_fmac_f32_e32 v138, v103, v119
	v_fmac_f32_e32 v138, v104, v120
	v_fmac_f32_e32 v138, v105, v121
	v_mul_f32_e32 v140, v106, v122
	v_mul_f32_e32 v141, v107, v123
	v_add_f32_e32 v138, v138, v140
	v_add_f32_e32 v138, v138, v141
	v_mul_f32_e32 v140, v108, v124
	v_mul_f32_e32 v141, v109, v125
	v_add_f32_e32 v138, v138, v140
	v_add_f32_e32 v138, v138, v141
	v_mul_f32_e32 v140, v110, v126
	v_mul_f32_e32 v141, v111, v127
	v_add_f32_e32 v138, v138, v140
	v_add_f32_e32 v138, v138, v141
	v_mul_f32_e32 v140, v112, v128
	v_mul_f32_e32 v141, v113, v129
	v_add_f32_e32 v138, v138, v140
	v_add_f32_e32 v138, v138, v141
	v_mul_f32_e32 v140, v114, v130
	v_mul_f32_e32 v141, v115, v131
	v_add_f32_e32 v138, v138, v140
	v_add_f32_e32 v138, v138, v141
	s_mov_b32 s24, 0xbfb8aa3b
	v_min_f32_e32 v141, 0, v138
	v_mul_f32_e64 v140, |v138|, s24
	v_exp_f32_e32 v140, v140
	s_mov_b32 s24, 0x800000
	v_add_f32_e32 v140, 1.0, v140
	v_cmp_gt_f32_e32 vcc, s24, v140
	s_mov_b32 s24, 0x3f317217
	s_nop 0
	v_cndmask_b32_e64 v142, 0, 32, vcc
	v_ldexp_f32 v140, v140, v142
	v_log_f32_e32 v140, v140
	s_nop 0
	v_mul_f32_e32 v142, 0x3f317217, v140
	v_fma_f32 v142, v140, s24, -v142
	v_fmac_f32_e32 v142, 0x3377d1cf, v140
	s_mov_b32 s24, 0x7f800000
	v_fmac_f32_e32 v142, 0x3f317217, v140
	v_cmp_lt_f32_e64 s[24:25], |v140|, s24
	s_nop 1
	v_cndmask_b32_e64 v140, v140, v142, s[24:25]
	v_cndmask_b32_e32 v142, 0, v183, vcc
	v_sub_f32_e32 v140, v140, v142
	v_sub_f32_e32 v140, v141, v140
	v_mul_f32_e32 v142, 0x3d800000, v140
	v_mad_u64_u32 v[144:145], s[24:25], v96, s51, v[18:19]
	ds_write_b32 v144, v142
	s_waitcnt lgkmcnt(1)
	v_fmac_f32_e32 v139, v100, v204
	v_fmac_f32_e32 v139, v101, v205
	v_fmac_f32_e32 v139, v102, v206
	v_fmac_f32_e32 v139, v103, v207
	v_fmac_f32_e32 v139, v104, v208
	v_fmac_f32_e32 v139, v105, v209
	v_mul_f32_e32 v140, v106, v210
	v_mul_f32_e32 v141, v107, v211
	v_add_f32_e32 v139, v139, v140
	v_add_f32_e32 v139, v139, v141
	v_mul_f32_e32 v140, v108, v212
	v_mul_f32_e32 v141, v109, v213
	v_add_f32_e32 v139, v139, v140
	v_add_f32_e32 v139, v139, v141
	v_mul_f32_e32 v140, v110, v214
	v_mul_f32_e32 v141, v111, v215
	v_add_f32_e32 v139, v139, v140
	v_add_f32_e32 v139, v139, v141
	v_mul_f32_e32 v140, v112, v216
	v_mul_f32_e32 v141, v113, v217
	v_add_f32_e32 v139, v139, v140
	v_add_f32_e32 v139, v139, v141
	v_mul_f32_e32 v140, v114, v218
	v_mul_f32_e32 v141, v115, v219
	v_add_f32_e32 v139, v139, v140
	v_add_f32_e32 v139, v139, v141
	s_mov_b32 s24, 0xbfb8aa3b
	v_min_f32_e32 v141, 0, v139
	v_mul_f32_e64 v140, |v139|, s24
	v_exp_f32_e32 v140, v140
	s_mov_b32 s24, 0x800000
	v_add_f32_e32 v140, 1.0, v140
	v_cmp_gt_f32_e32 vcc, s24, v140
	s_mov_b32 s24, 0x3f317217
	s_nop 0
	v_cndmask_b32_e64 v142, 0, 32, vcc
	v_ldexp_f32 v140, v140, v142
	v_log_f32_e32 v140, v140
	s_nop 0
	v_mul_f32_e32 v142, 0x3f317217, v140
	v_fma_f32 v142, v140, s24, -v142
	v_fmac_f32_e32 v142, 0x3377d1cf, v140
	s_mov_b32 s24, 0x7f800000
	v_fmac_f32_e32 v142, 0x3f317217, v140
	v_cmp_lt_f32_e64 s[24:25], |v140|, s24
	s_nop 1
	v_cndmask_b32_e64 v140, v140, v142, s[24:25]
	v_cndmask_b32_e32 v142, 0, v183, vcc
	v_sub_f32_e32 v140, v140, v142
	v_sub_f32_e32 v140, v141, v140
	v_mul_f32_e32 v142, 0x3d800000, v140
	v_mad_u64_u32 v[144:145], s[24:25], v97, s51, v[18:19]
	ds_write_b32 v144, v142
	s_waitcnt vmcnt(0)

.LBB0_1627:
	global_load_dwordx2 v[44:45], v[24:25], off offset:152
	s_waitcnt vmcnt(0)
	v_and_b32_e32 v46, 0xffffff00, v43
	v_ashrrev_i32_e32 v47, 31, v46
	v_add_u32_e32 v21, 0x200, v21
	v_cmp_lt_i32_e32 vcc, s13, v21
	s_or_b64 s[8:9], vcc, s[8:9]
	s_waitcnt lgkmcnt(0)
	v_lshl_add_u64 v[44:45], v[46:47], 2, v[44:45]
	v_lshl_add_u64 v[44:45], v[44:45], 0, s[10:11]
	v_lshl_add_u64 v[44:45], v[44:45], 0, v[22:23]
	global_load_dword v44, v[44:45], off
	v_add_u32_e32 v45, s4, v43
	v_add_u32_e32 v43, 0x800, v43
	s_waitcnt vmcnt(0)
	ds_write_b32 v45, v44
	s_andn2_b64 exec, exec, s[8:9]
	s_cbranch_execnz .LBB0_1627

.LBB0_1630:
	global_load_dwordx2 v[44:45], v[24:25], off offset:160
	s_waitcnt vmcnt(0)
	v_ashrrev_i32_e32 v60, 6, v43
	v_add_u32_e32 v46, s3, v60
	v_ashrrev_i32_e32 v47, 31, v46
	v_add_u32_e32 v79, 0x200, v43
	v_cmp_lt_i32_e32 vcc, s14, v43
	v_lshl_add_u32 v43, v60, 2, s4
	s_or_b64 s[8:9], vcc, s[8:9]
	v_mad_u64_u32 v[60:61], s[18:19], v60, s13, v[22:23]
	s_waitcnt lgkmcnt(0)
	v_lshl_add_u64 v[44:45], v[46:47], 2, v[44:45]
	global_load_dword v78, v[44:45], off
	ds_read2st64_b32 v[44:45], v21 offset1:1
	ds_read2st64_b32 v[46:47], v21 offset0:2 offset1:3
	ds_read2st64_b32 v[48:49], v21 offset0:4 offset1:5
	ds_read2st64_b32 v[50:51], v21 offset0:6 offset1:7
	ds_read2st64_b32 v[52:53], v21 offset0:8 offset1:9
	ds_read2st64_b32 v[54:55], v21 offset0:10 offset1:11
	ds_read2st64_b32 v[56:57], v21 offset0:12 offset1:13
	ds_read2st64_b32 v[58:59], v21 offset0:14 offset1:15
	ds_read2st64_b32 v[62:63], v43 offset1:1
	ds_read2st64_b32 v[64:65], v43 offset0:2 offset1:3
	ds_read2st64_b32 v[66:67], v43 offset0:4 offset1:5
	ds_read2st64_b32 v[68:69], v43 offset0:6 offset1:7
	ds_read2st64_b32 v[70:71], v43 offset0:8 offset1:9
	ds_read2st64_b32 v[72:73], v43 offset0:10 offset1:11
	ds_read2st64_b32 v[74:75], v43 offset0:12 offset1:13
	ds_read2st64_b32 v[76:77], v43 offset0:14 offset1:15
	s_waitcnt lgkmcnt(4)
	v_pk_mul_f32 v[50:51], v[50:51], v[68:69]
	s_waitcnt lgkmcnt(3)
	v_pk_mul_f32 v[52:53], v[52:53], v[70:71]
	s_waitcnt lgkmcnt(2)
	v_pk_mul_f32 v[54:55], v[54:55], v[72:73]
	s_waitcnt lgkmcnt(1)
	v_pk_mul_f32 v[56:57], v[56:57], v[74:75]
	s_waitcnt lgkmcnt(0)
	v_pk_mul_f32 v[58:59], v[58:59], v[76:77]
	s_waitcnt vmcnt(0)
	v_fmac_f32_e32 v78, v44, v62
	v_fmac_f32_e32 v78, v45, v63
	v_fmac_f32_e32 v78, v46, v64
	v_fmac_f32_e32 v78, v47, v65
	v_fmac_f32_e32 v78, v48, v66
	v_fmac_f32_e32 v78, v49, v67
	v_add_f32_e32 v43, v78, v50
	v_add_f32_e32 v43, v43, v51
	v_add_f32_e32 v43, v43, v52
	v_add_f32_e32 v43, v43, v53
	v_add_f32_e32 v43, v43, v54
	v_add_f32_e32 v43, v43, v55
	v_add_f32_e32 v43, v43, v56
	v_add_f32_e32 v43, v43, v57
	v_add_f32_e32 v43, v43, v58
	v_add_f32_e32 v44, v43, v59
	v_mul_f32_e64 v43, |v44|, s5
	v_exp_f32_e32 v45, v43
	v_min_f32_e32 v44, 0, v44
	v_mov_b32_e32 v43, v79
	v_add_f32_e32 v45, 1.0, v45
	v_cmp_gt_f32_e32 vcc, s10, v45
	s_nop 1
	v_cndmask_b32_e64 v46, 0, 32, vcc
	v_ldexp_f32 v45, v45, v46
	v_log_f32_e32 v45, v45
	v_cndmask_b32_e32 v46, 0, v23, vcc
	v_mul_f32_e32 v47, 0x3f317217, v45
	v_fma_f32 v47, v45, s11, -v47
	v_fmac_f32_e32 v47, 0x3377d1cf, v45
	v_fmac_f32_e32 v47, 0x3f317217, v45
	v_cmp_lt_f32_e64 vcc, |v45|, s12
	s_nop 1
	v_cndmask_b32_e32 v45, v45, v47, vcc
	v_sub_f32_e32 v45, v45, v46
	v_sub_f32_e32 v44, v44, v45
	v_mul_f32_e32 v44, 0x3d800000, v44
	ds_write_b32 v60, v44
	s_andn2_b64 exec, exec, s[8:9]
	s_cbranch_execnz .LBB0_1630

.LBB0_1644:
	s_andn2_saveexec_b64 s[24:25], s[16:17]
	s_cbranch_execz .LBB0_1648
	v_mov_b64_e32 v[42:43], s[0:1]
	global_load_dwordx2 v[58:59], v[42:43], off offset:152
	s_waitcnt vmcnt(0)
	global_load_dwordx2 v[60:61], v[42:43], off offset:160
	s_waitcnt vmcnt(0)
	v_mov_b32_e32 v41, s22
	s_mov_b32 s21, s19
	v_mov_b32_e32 v46, s23
	v_add_co_u32_e32 v54, vcc, 0x2000, v41
	v_lshl_add_u64 v[42:43], v[10:11], 2, s[22:23]
	v_lshl_add_u64 v[44:45], v[12:13], 2, s[22:23]
	v_addc_co_u32_e32 v55, vcc, 0, v46, vcc
	global_load_dword v41, v[42:43], off
	global_load_dword v66, v[44:45], off
	s_nop 0
	global_load_dwordx4 v[42:45], v[54:55], off offset:1120
	global_load_dwordx4 v[46:49], v[54:55], off offset:1136
	global_load_dwordx4 v[50:53], v[54:55], off offset:1152
	s_nop 0
	global_load_dwordx4 v[54:57], v[54:55], off offset:1168
	v_xor_b32_e32 v80, 32, v1
	s_waitcnt lgkmcnt(0)
	v_lshl_add_u64 v[58:59], v[58:59], 0, s[20:21]
	v_lshl_add_u64 v[60:61], v[8:9], 2, v[60:61]
	v_lshl_add_u64 v[58:59], v[130:131], 2, v[58:59]
	global_load_dword v67, v[60:61], off
	global_load_dword v68, v[58:59], off
	global_load_dword v69, v[58:59], off offset:1024
	global_load_dword v70, v[58:59], off offset:2048
	global_load_dword v71, v[58:59], off offset:3072
	v_add_co_u32_e64 v62, s[16:17], s30, v58
	v_add_co_u32_e32 v60, vcc, s31, v58
	s_nop 0
	v_addc_co_u32_e64 v63, s[16:17], 0, v59, s[16:17]
	v_add_co_u32_e64 v64, s[16:17], s29, v58
	v_addc_co_u32_e32 v61, vcc, 0, v59, vcc
	s_nop 0
	v_addc_co_u32_e64 v65, s[16:17], 0, v59, s[16:17]
	global_load_dword v58, v[62:63], off offset:-4096
	global_load_dword v59, v[60:61], off offset:1024
	global_load_dword v72, v[60:61], off offset:2048
	s_nop 0
	global_load_dword v60, v[60:61], off offset:3072
	s_nop 0
	global_load_dword v61, v[62:63], off
	global_load_dword v73, v[62:63], off offset:1024
	global_load_dword v74, v[62:63], off offset:2048
	s_nop 0
	global_load_dword v62, v[62:63], off offset:3072
	s_nop 0
	global_load_dword v63, v[64:65], off
	global_load_dword v75, v[64:65], off offset:1024
	global_load_dword v76, v[64:65], off offset:2048
	s_nop 0
	global_load_dword v64, v[64:65], off offset:3072
	v_cmp_lt_i32_e32 vcc, v36, v35
	s_waitcnt vmcnt(0)
	v_mul_f32_e32 v77, 0x3e000000, v41
	v_mul_f32_e32 v41, v77, v66
	v_cndmask_b32_e32 v65, v1, v36, vcc
	v_lshlrev_b32_e32 v65, 2, v65
	ds_bpermute_b32 v41, v65, v41
	v_cmp_lt_i32_e32 vcc, v37, v35
	s_waitcnt lgkmcnt(0)
	v_fmac_f32_e32 v41, v77, v66
	v_cndmask_b32_e32 v65, v1, v37, vcc
	v_lshlrev_b32_e32 v65, 2, v65
	ds_bpermute_b32 v65, v65, v41
	v_cmp_lt_i32_e32 vcc, v38, v35
	s_waitcnt lgkmcnt(0)
	v_add_f32_e32 v41, v41, v65
	v_cndmask_b32_e32 v78, v1, v38, vcc
	v_cmp_lt_i32_e32 vcc, v39, v35
	v_lshlrev_b32_e32 v78, 2, v78
	ds_bpermute_b32 v65, v78, v41
	v_cndmask_b32_e32 v79, v1, v39, vcc
	v_cmp_lt_i32_e32 vcc, v40, v35
	v_lshlrev_b32_e32 v79, 2, v79
	s_waitcnt lgkmcnt(0)
	v_add_f32_e32 v41, v41, v65
	v_cndmask_b32_e32 v78, v1, v40, vcc
	v_cmp_lt_i32_e32 vcc, v80, v35
	ds_bpermute_b32 v65, v79, v41
	v_lshlrev_b32_e32 v78, 2, v78
	s_waitcnt lgkmcnt(0)
	v_add_f32_e32 v41, v41, v65
	v_fmac_f32_e32 v67, v42, v68
	v_fmac_f32_e32 v67, v43, v69
	v_fmac_f32_e32 v67, v44, v70
	v_fmac_f32_e32 v67, v45, v71
	v_cndmask_b32_e32 v43, v1, v80, vcc
	v_fmac_f32_e32 v67, v46, v58
	v_fmac_f32_e32 v67, v47, v59
	v_fmac_f32_e32 v67, v48, v72
	v_fmac_f32_e32 v67, v49, v60
	v_fmac_f32_e32 v67, v50, v61
	v_fmac_f32_e32 v67, v51, v73
	v_fmac_f32_e32 v67, v52, v74
	v_fmac_f32_e32 v67, v53, v62
	v_fmac_f32_e32 v67, v54, v63
	v_fmac_f32_e32 v67, v55, v75
	v_fmac_f32_e32 v67, v56, v76
	v_fmac_f32_e32 v67, v57, v64
	v_mul_f32_e64 v42, |v67|, s33
	v_exp_f32_e32 v42, v42
	v_min_f32_e32 v45, 0, v67
	v_lshlrev_b32_e32 v43, 2, v43
	v_add_f32_e32 v42, 1.0, v42
	v_cmp_gt_f32_e32 vcc, s34, v42
	s_nop 1
	v_cndmask_b32_e64 v44, 0, 32, vcc
	v_ldexp_f32 v42, v42, v44
	v_log_f32_e32 v42, v42
	ds_bpermute_b32 v44, v78, v41
	v_cndmask_b32_e32 v46, 0, v34, vcc
	v_mul_f32_e32 v47, 0x3f317217, v42
	v_fma_f32 v47, v42, s35, -v47
	v_fmac_f32_e32 v47, 0x3377d1cf, v42
	v_fmac_f32_e32 v47, 0x3f317217, v42
	v_cmp_lt_f32_e64 vcc, |v42|, s36
	s_waitcnt lgkmcnt(0)
	v_add_f32_e32 v41, v41, v44
	v_cndmask_b32_e32 v42, v42, v47, vcc
	v_sub_f32_e32 v42, v42, v46
	v_sub_f32_e32 v42, v45, v42
	v_mul_f32_e32 v42, 0x3d800000, v42
	v_mul_f32_e32 v42, 0x3fb8aa3b, v42
	v_exp_f32_e32 v45, v42
	ds_bpermute_b32 v42, v43, v41
	v_mul_f32_e32 v43, v77, v45
	ds_write2st64_b32 v6, v43, v66 offset0:128 offset1:129
	ds_write_b32 v6, v45 offset:33280
	s_and_saveexec_b64 s[16:17], s[12:13]
	s_cbranch_execz .LBB0_1647
	s_waitcnt lgkmcnt(2)
	v_add_f32_e32 v41, v41, v42
	v_mov_b32_e32 v42, s96
	ds_write_b32 v42, v41 offset:34048

.LBB0_1648:
	s_or_b64 exec, exec, s[24:25]
	s_waitcnt lgkmcnt(0)
	v_mov_b64_e32 v[42:43], s[0:1]
	s_waitcnt lgkmcnt(0)
	s_barrier
	global_load_dwordx2 v[42:43], v[42:43], off offset:56
	s_waitcnt vmcnt(0)
	s_and_b32 s16, s2, 0x7ffffffc
	s_mov_b32 s17, s19
	s_or_b32 s16, s4, s16
	s_lshl_b64 s[16:17], s[16:17], 15
	v_mov_b32_e32 v41, 0
	s_waitcnt lgkmcnt(0)
	v_lshl_add_u64 v[50:51], v[42:43], 0, s[16:17]
	v_lshl_add_u64 v[42:43], v[50:51], 0, v[18:19]
	global_load_dwordx4 v[42:45], v[42:43], off
	s_add_u32 s16, s5, s16
	s_addc_u32 s17, s26, s17
	v_lshl_add_u64 v[54:55], s[16:17], 0, v[18:19]
	v_lshl_add_u64 v[56:57], v[50:51], 0, v[20:21]
	s_waitcnt vmcnt(0)
	ds_write_b128 v2, v[42:45]
	ds_read_b128 v[46:49], v3 offset:33536
	ds_read2st64_b32 v[52:53], v26 offset0:129 offset1:130
	s_waitcnt lgkmcnt(0)
	v_pk_mul_f32 v[48:49], v[48:49], v[52:53] op_sel_hi:[1,0]
	v_pk_mul_f32 v[46:47], v[46:47], v[52:53] op_sel_hi:[1,0]
	v_mov_b32_e32 v52, v53
	v_pk_fma_f32 v[44:45], v[44:45], v[52:53], v[48:49] op_sel_hi:[1,0,1]
	v_pk_fma_f32 v[42:43], v[42:43], v[52:53], v[46:47] op_sel_hi:[1,0,1]
	global_store_dwordx4 v[54:55], v[42:45], off
	global_load_dwordx4 v[42:45], v[56:57], off
	v_lshl_add_u64 v[54:55], s[16:17], 0, v[20:21]
	v_lshl_add_u64 v[56:57], v[50:51], 0, v[22:23]
	v_lshl_add_u64 v[50:51], v[50:51], 0, v[24:25]
	s_waitcnt vmcnt(0)
	ds_write_b128 v7, v[42:45]
	ds_read_b128 v[46:49], v3 offset:33536
	ds_read2st64_b32 v[52:53], v27 offset0:129 offset1:130
	s_waitcnt lgkmcnt(0)
	v_pk_mul_f32 v[48:49], v[48:49], v[52:53] op_sel_hi:[1,0]
	v_pk_mul_f32 v[46:47], v[46:47], v[52:53] op_sel_hi:[1,0]
	v_mov_b32_e32 v52, v53
	v_pk_fma_f32 v[44:45], v[44:45], v[52:53], v[48:49] op_sel_hi:[1,0,1]
	v_pk_fma_f32 v[42:43], v[42:43], v[52:53], v[46:47] op_sel_hi:[1,0,1]
	global_store_dwordx4 v[54:55], v[42:45], off
	global_load_dwordx4 v[42:45], v[56:57], off
	v_lshl_add_u64 v[54:55], s[16:17], 0, v[22:23]
	s_waitcnt vmcnt(0)
	ds_write_b128 v30, v[42:45]
	ds_read_b128 v[46:49], v3 offset:33536
	ds_read2st64_b32 v[52:53], v28 offset0:129 offset1:130
	s_waitcnt lgkmcnt(0)
	v_pk_mul_f32 v[48:49], v[48:49], v[52:53] op_sel_hi:[1,0]
	v_pk_mul_f32 v[46:47], v[46:47], v[52:53] op_sel_hi:[1,0]
	v_mov_b32_e32 v52, v53
	v_pk_fma_f32 v[44:45], v[44:45], v[52:53], v[48:49] op_sel_hi:[1,0,1]
	v_pk_fma_f32 v[42:43], v[42:43], v[52:53], v[46:47] op_sel_hi:[1,0,1]
	global_store_dwordx4 v[54:55], v[42:45], off
	global_load_dwordx4 v[42:45], v[50:51], off
	v_lshl_add_u64 v[52:53], s[16:17], 0, v[24:25]
	s_waitcnt vmcnt(0)
	ds_write_b128 v31, v[42:45]
	ds_read_b128 v[46:49], v3 offset:33536
	ds_read2st64_b32 v[50:51], v29 offset0:129 offset1:130
	s_waitcnt lgkmcnt(0)
	v_pk_mul_f32 v[48:49], v[48:49], v[50:51] op_sel_hi:[1,0]
	v_pk_mul_f32 v[46:47], v[46:47], v[50:51] op_sel_hi:[1,0]
	v_mov_b32_e32 v50, v51
	v_pk_fma_f32 v[44:45], v[44:45], v[50:51], v[48:49] op_sel_hi:[1,0,1]
	v_pk_fma_f32 v[42:43], v[42:43], v[50:51], v[46:47] op_sel_hi:[1,0,1]
	global_store_dwordx4 v[52:53], v[42:45], off
	s_waitcnt lgkmcnt(0)
	s_barrier
	s_and_saveexec_b64 s[16:17], s[8:9]
	s_cbranch_execz .LBB0_1654
	v_mov_b32_e32 v41, 0
	s_mov_b32 s21, 0
	s_mov_b32 s24, s28

.LBB0_1654:
	s_or_b64 exec, exec, s[16:17]
	s_waitcnt lgkmcnt(0)
	s_barrier
	s_and_saveexec_b64 s[24:25], s[8:9]
	s_cbranch_execz .LBB0_1639
	v_mov_b32_e32 v42, s37
	v_mov_b64_e32 v[44:45], s[0:1]
	ds_read2_b32 v[42:43], v42 offset1:1
	global_load_dwordx2 v[44:45], v[44:45], off offset:168
	s_waitcnt vmcnt(0)
	v_lshl_add_u64 v[46:47], v[14:15], 2, s[22:23]
	global_load_dword v46, v[46:47], off
	s_waitcnt lgkmcnt(0)
	v_add_f32_e32 v42, v42, v43
	v_fmamk_f32 v42, v42, 0x3c000000, v32
	v_mul_f32_e32 v43, 0x4f800000, v42
	v_cmp_gt_f32_e32 vcc, s41, v42
	v_lshl_add_u64 v[44:45], v[130:131], 2, v[44:45]
	global_load_dword v44, v[44:45], off
	v_cndmask_b32_e32 v42, v42, v43, vcc
	v_sqrt_f32_e32 v43, v42
	s_nop 0
	v_add_u32_e32 v45, -1, v43
	v_add_u32_e32 v47, 1, v43
	v_fma_f32 v48, -v45, v43, v42
	v_fma_f32 v49, -v47, v43, v42
	v_cmp_ge_f32_e64 s[16:17], 0, v48
	s_nop 1
	v_cndmask_b32_e64 v43, v43, v45, s[16:17]
	v_cmp_lt_f32_e64 s[16:17], 0, v49
	s_nop 1
	v_cndmask_b32_e64 v43, v43, v47, s[16:17]
	v_mul_f32_e32 v45, 0x37800000, v43
	v_cndmask_b32_e32 v43, v43, v45, vcc
	v_cmp_class_f32_e32 vcc, v42, v33
	s_nop 1
	v_cndmask_b32_e32 v42, v43, v42, vcc
	v_div_scale_f32 v43, s[16:17], v42, v42, 1.0
	v_rcp_f32_e32 v45, v43
	v_div_scale_f32 v47, vcc, 1.0, v42, 1.0
	s_lshl_b64 s[16:17], s[18:19], 11
	v_fma_f32 v48, -v43, v45, 1.0
	v_fmac_f32_e32 v45, v48, v45
	v_mul_f32_e32 v48, v47, v45
	v_fma_f32 v49, -v43, v48, v47
	v_fmac_f32_e32 v48, v49, v45
	v_fma_f32 v43, -v43, v48, v47
	s_waitcnt vmcnt(0)
	v_mul_f32_e32 v47, 0xbfb8aa3b, v46
	v_exp_f32_e32 v47, v47
	v_div_fmas_f32 v43, v43, v45, v48
	v_div_fixup_f32 v42, v43, v42, 1.0
	v_mul_f32_e32 v41, v41, v42
	v_add_f32_e32 v43, 1.0, v47
	v_div_scale_f32 v45, s[22:23], v43, v43, v46
	v_rcp_f32_e32 v47, v45
	v_div_scale_f32 v42, vcc, v46, v43, v46
	v_fma_f32 v48, -v45, v47, 1.0
	v_fmac_f32_e32 v47, v48, v47
	v_mul_f32_e32 v48, v42, v47
	v_fma_f32 v49, -v45, v48, v42
	v_fmac_f32_e32 v48, v49, v47
	v_fma_f32 v42, -v45, v48, v42
	v_div_fmas_f32 v42, v42, v47, v48
	v_div_fixup_f32 v42, v42, v43, v46
	v_mul_f32_e32 v41, v44, v41
	v_mul_f32_e32 v41, v41, v42
	v_bfe_u32 v42, v41, 16, 1
	v_add3_u32 v41, v41, v42, s44
	v_lshl_add_u64 v[42:43], v[16:17], 0, s[16:17]
	global_store_short_d16_hi v[42:43], v41, off
	s_branch .LBB0_1639

.LBB0_1714:
	v_mov_b64_e32 v[8:9], s[0:1]
	global_load_dwordx2 v[8:9], v[8:9], off offset:144
	s_waitcnt vmcnt(0)
	v_add_u32_e32 v5, 0x200, v5
	v_cmp_lt_i32_e32 vcc, s7, v5
	s_or_b64 s[72:73], vcc, s[72:73]
	s_waitcnt lgkmcnt(0)
	v_lshl_add_u64 v[8:9], v[8:9], 0, v[2:3]
	global_load_dword v7, v[8:9], off nt
	v_lshl_add_u64 v[2:3], v[2:3], 0, s[14:15]
	s_waitcnt vmcnt(0)
	ds_write_b32 v6, v7
	v_add_u32_e32 v6, 0x800, v6
	s_andn2_b64 exec, exec, s[72:73]
	s_cbranch_execnz .LBB0_1714
.LBB0_1715:
	s_or_b64 exec, exec, s[68:69]
	s_movk_i32 s7, 0x7f
	v_cmp_lt_i32_e32 vcc, s7, v130
	s_and_saveexec_b64 s[14:15], vcc
	s_xor_b64 s[14:15], exec, s[14:15]
	s_lshl_b32 s7, s5, 7
	s_or_saveexec_b64 s[14:15], s[14:15]
	v_mov_b32_e32 v58, s7
	s_xor_b64 exec, exec, s[14:15]
	s_cbranch_execz .LBB0_1721
	v_mov_b64_e32 v[2:3], s[0:1]
	global_load_dwordx2 v[6:7], v[2:3], off offset:136
	s_waitcnt vmcnt(0)
	s_lshl_b32 s7, s5, 7
	v_add_u32_e32 v2, s7, v130
	v_ashrrev_i32_e32 v3, 31, v2
	s_add_u32 s68, s38, 0x6200000
	s_addc_u32 s69, s39, 0
	s_mov_b32 s9, 0
	s_waitcnt lgkmcnt(0)
	v_lshl_add_u64 v[6:7], v[2:3], 2, v[6:7]
	global_load_dword v3, v[6:7], off nt

.LBB0_2725:
	v_mov_b64_e32 v[4:5], s[0:1]
	s_waitcnt lgkmcnt(0)
	s_barrier
	global_load_dwordx2 v[2:3], v[4:5], off offset:40
	s_waitcnt vmcnt(0)
	global_load_dwordx2 v[10:11], v[4:5], off offset:48
	s_waitcnt vmcnt(0)
	global_load_dwordx2 v[4:5], v[4:5], off offset:64
	s_waitcnt vmcnt(0)
	s_lshl_b32 s6, s5, 2
	s_add_i32 s6, s36, s6
	v_mov_b32_e32 v6, s6
	v_add_u32_e32 v6, 0xc00, v6
	ds_read2_b32 v[6:7], v6 offset1:8
	s_mov_b64 s[8:9], -1
	s_waitcnt lgkmcnt(0)
	v_cmp_lt_i32_e32 vcc, 31, v6
	v_readfirstlane_b32 s10, v6
	v_readfirstlane_b32 s11, v7
	s_cbranch_vccz .LBB0_2745
	s_add_u32 s6, s18, 0xc00
	s_addc_u32 s7, s19, 0
	v_lshl_add_u64 v[4:5], s[58:59], 2, v[4:5]
	v_mov_b64_e32 v[6:7], s[6:7]
	s_cbranch_execz .LBB0_2746

.LBB0_2935:
	s_or_b64 exec, exec, s[6:7]
	v_mov_b32_e32 v1, v0
	v_mov_b64_e32 v[2:3], s[0:1]
	s_barrier
	global_load_dwordx2 v[2:3], v[2:3], off offset:88
	s_waitcnt vmcnt(0)
	v_readfirstlane_b32 s2, v1
	s_ashr_i32 s2, s2, 4
	s_and_b32 s3, s2, -4
	s_cmp_gt_i32 s3, 31
	s_cbranch_scc1 .LBB0_2938
	v_and_b32_e32 v21, 63, v1
	v_mov_b32_e32 v91, 0
	v_lshlrev_b32_e32 v90, 4, v21
	s_waitcnt lgkmcnt(0)
	v_lshl_add_u64 v[2:3], v[2:3], 0, v[90:91]
	s_movk_i32 s2, 0x2000
	v_add_co_u32_e32 v18, vcc, s2, v2
	v_and_b32_e32 v1, 64, v166
	s_nop 0
	v_addc_co_u32_e32 v19, vcc, 0, v3, vcc
	global_load_dwordx4 v[2:5], v[18:19], off
	global_load_dwordx4 v[6:9], v[18:19], off offset:1024
	global_load_dwordx4 v[10:13], v[18:19], off offset:2048
	global_load_dwordx4 v[14:17], v[18:19], off offset:3072
	v_add_u32_e32 v18, 64, v1
	v_xor_b32_e32 v1, 1, v166
	v_cmp_lt_i32_e32 vcc, v1, v18
	v_xor_b32_e32 v19, 2, v166
	s_lshl_b32 s4, s40, 5
	v_cndmask_b32_e32 v1, v166, v1, vcc
	v_cmp_lt_i32_e32 vcc, v19, v18
	s_add_i32 s3, s4, s3
	s_add_i32 s2, s4, 0x20a0
	v_cndmask_b32_e32 v19, v166, v19, vcc
	v_lshlrev_b32_e32 v167, 2, v19
	v_xor_b32_e32 v19, 4, v166
	v_cmp_lt_i32_e32 vcc, v19, v18
	s_add_i32 s12, s3, 0x2080
	s_add_u32 s3, s68, 0x5800000
	v_cndmask_b32_e32 v19, v166, v19, vcc
	v_lshlrev_b32_e32 v168, 2, v19
	v_xor_b32_e32 v19, 8, v166
	v_cmp_lt_i32_e32 vcc, v19, v18
	s_addc_u32 s4, s69, 0
	s_ashr_i32 s13, s12, 31
	v_cndmask_b32_e32 v19, v166, v19, vcc
	v_lshlrev_b32_e32 v169, 2, v19
	v_xor_b32_e32 v19, 16, v166
	v_cmp_lt_i32_e32 vcc, v19, v18
	s_lshl_b64 s[6:7], s[12:13], 11
	v_lshl_or_b32 v92, v21, 3, s6
	v_cndmask_b32_e32 v19, v166, v19, vcc
	v_lshlrev_b32_e32 v170, 2, v19
	v_xor_b32_e32 v19, 32, v166
	v_cmp_lt_i32_e32 vcc, v19, v18
	v_mov_b32_e32 v93, s7
	s_lshl_b64 s[6:7], s[12:13], 12
	v_cndmask_b32_e32 v18, v166, v19, vcc
	v_lshlrev_b32_e32 v171, 2, v18
	v_lshlrev_b32_e32 v18, 2, v21
	v_or_b32_e32 v20, 0x100, v18
	v_or_b32_e32 v22, 0x200, v18
	v_or_b32_e32 v24, 0x300, v18
	v_lshlrev_b32_e32 v1, 2, v1
	v_or_b32_e32 v94, s6, v90
	v_mov_b32_e32 v95, s7
	v_mov_b32_e32 v172, 0x358637bd
	s_mov_b32 s13, 0xf800000
	v_mov_b32_e32 v173, 0x260
	v_lshlrev_b32_e32 v90, 2, v18
	s_movk_i32 s22, 0x7fff
	s_mov_b32 s23, 0xffff0000
	s_mov_b32 s24, 0xba00000
	v_lshlrev_b32_e32 v96, 2, v20
	v_lshlrev_b32_e32 v98, 2, v22
	v_mov_b32_e32 v99, v91
	v_lshlrev_b32_e32 v100, 2, v24
	v_mov_b32_e32 v101, v91
	s_mov_b32 s25, 0xba01000
	s_mov_b64 s[14:15], 0x10000
	s_mov_b64 s[16:17], 0x20000
	v_mov_b32_e32 v97, v91

.LBB0_2948:
	s_or_b64 exec, exec, s[8:9]
	s_ashr_i32 s28, s16, 6
	s_add_i32 s29, s5, 0xc300
	s_add_i32 s14, s5, 0x14300
	v_add_u32_e32 v6, 0x800, v2
	s_add_u32 s12, s68, 0x16000000
	v_ashrrev_i32_e32 v71, 6, v6
	v_add_u32_e32 v6, 0xa00, v2
	s_addc_u32 s13, s69, 0
	s_lshl_b32 s3, s28, 3
	v_ashrrev_i32_e32 v72, 6, v6
	v_add_u32_e32 v6, 0xc00, v2
	s_and_b32 s4, s3, 0xfffffe0
	s_lshl_b32 s3, s28, 7
	v_ashrrev_i32_e32 v73, 6, v6
	v_add_u32_e32 v6, 0xe00, v2
	s_add_i32 s2, s96, 0x20180
	s_and_b32 s30, s3, 0x180
	v_ashrrev_i32_e32 v74, 6, v6
	v_lshlrev_b32_e32 v6, 2, v2
	v_bfe_u32 v7, v2, 5, 1
	v_and_b32_e32 v10, 31, v2
	s_cmp_lt_u32 s28, 4
	v_and_b32_e32 v6, 0x7c, v6
	v_lshlrev_b32_e32 v11, 2, v10
	v_lshlrev_b32_e32 v12, 2, v7
	s_cselect_b32 s3, 16, 32
	s_add_i32 s8, s30, s5
	v_mov_b32_e32 v43, 0
	v_lshlrev_b32_e32 v42, 2, v6
	v_and_b32_e32 v4, 63, v2
	v_add_u32_e32 v13, s8, v11
	v_or_b32_e32 v3, s4, v12
	v_ashrrev_i32_e32 v67, 6, v2
	v_add_u32_e32 v5, 0x200, v2
	v_lshl_add_u64 v[8:9], s[68:69], 0, v[42:43]
	s_mov_b64 s[8:9], 0x24400000
	s_movk_i32 s4, 0x41
	v_ashrrev_i32_e32 v68, 6, v5
	v_add_u32_e32 v15, 0x400, v2
	v_lshl_add_u64 v[44:45], v[8:9], 0, s[8:9]
	v_mad_u64_u32 v[8:9], s[8:9], v67, s4, v[4:5]
	v_ashrrev_i32_e32 v69, 6, v15
	v_add_u32_e32 v16, 0x600, v2
	v_lshl_add_u32 v79, v8, 2, s5
	v_mad_u64_u32 v[8:9], s[8:9], v68, s4, v[4:5]
	v_ashrrev_i32_e32 v70, 6, v16
	v_lshl_add_u32 v80, v8, 2, s5
	v_mad_u64_u32 v[8:9], s[8:9], v69, s4, v[4:5]
	v_lshl_add_u32 v81, v8, 2, s5
	v_mad_u64_u32 v[8:9], s[8:9], v70, s4, v[4:5]
	s_waitcnt vmcnt(0)
	v_lshl_add_u32 v82, v8, 2, s5
	v_mad_u64_u32 v[8:9], s[8:9], v71, s4, v[4:5]
	v_lshl_add_u32 v83, v8, 2, s5
	v_mad_u64_u32 v[8:9], s[8:9], v72, s4, v[4:5]
	v_add_u32_e32 v55, 0x518, v4
	v_add_u32_e32 v66, 0x618, v4
	v_ashrrev_i32_e32 v76, 5, v5
	v_lshl_add_u32 v84, v8, 2, s5
	v_mad_u64_u32 v[8:9], s[8:9], v73, s4, v[4:5]
	v_mad_u64_u32 v[4:5], s[8:9], v74, s4, v[4:5]
	v_lshl_add_u32 v86, v4, 2, s5
	v_lshlrev_b32_e32 v4, 4, v2
	v_add_u32_e32 v5, 0x4000, v4
	s_cmp_gt_i32 s28, 3
	v_add_u32_e32 v90, s29, v5
	v_add_u32_e32 v91, s14, v5
	v_add_u32_e32 v5, 0x6000, v4
	s_cselect_b64 s[8:9], -1, 0
	s_cmp_eq_u32 s28, 1
	v_add_u32_e32 v88, s14, v4
	v_add_u32_e32 v93, s14, v5
	s_cselect_b64 s[14:15], -1, 0
	s_ashr_i32 s33, s16, 2
	s_lshl_b32 s16, s28, 5
	v_ashrrev_i32_e32 v77, 5, v15
	v_mov_b32_e32 v15, s5
	v_add_u32_e32 v92, s29, v5
	s_or_b64 s[8:9], s[8:9], s[14:15]
	s_and_b32 s18, s33, 0xffffffe0
	v_and_or_b32 v5, s16, 32, v10
	s_movk_i32 s34, 0x104
	s_xor_b64 s[14:15], s[8:9], -1
	v_mad_u32_u24 v9, v5, s34, v15
	v_or_b32_e32 v15, s18, v12
	s_cmp_lt_i32 s28, 4
	v_cmp_gt_i32_e32 vcc, v5, v15
	v_or_b32_e32 v17, 1, v15
	s_cselect_b64 s[16:17], -1, 0
	s_or_b64 s[18:19], s[8:9], vcc
	v_cmp_gt_i32_e32 vcc, v5, v17
	v_or_b32_e32 v17, 2, v15
	s_or_b64 s[20:21], s[8:9], vcc
	v_cmp_gt_i32_e32 vcc, v5, v17
	v_or_b32_e32 v17, 3, v15
	s_or_b64 s[22:23], s[8:9], vcc
	v_cmp_gt_i32_e32 vcc, v5, v17
	v_or_b32_e32 v17, 8, v15
	s_or_b64 s[24:25], s[8:9], vcc
	v_cmp_gt_i32_e32 vcc, v5, v17
	v_or_b32_e32 v17, 9, v15
	s_or_b64 s[26:27], s[8:9], vcc
	v_cmp_gt_i32_e32 vcc, v5, v17
	v_or_b32_e32 v17, 10, v15
	s_or_b64 s[46:47], s[8:9], vcc
	v_cmp_gt_i32_e32 vcc, v5, v17
	v_or_b32_e32 v17, 11, v15
	s_or_b64 s[48:49], s[8:9], vcc
	v_cmp_gt_i32_e32 vcc, v5, v17
	v_or_b32_e32 v17, 16, v15
	s_or_b64 s[50:51], s[8:9], vcc
	v_cmp_gt_i32_e32 vcc, v5, v17
	v_or_b32_e32 v17, 17, v15
	s_or_b64 s[52:53], s[8:9], vcc
	v_cmp_gt_i32_e32 vcc, v5, v17
	v_or_b32_e32 v17, 18, v15
	s_or_b64 s[54:55], s[8:9], vcc
	v_cmp_gt_i32_e32 vcc, v5, v17
	v_or_b32_e32 v17, 19, v15
	s_or_b64 s[56:57], s[8:9], vcc
	v_cmp_gt_i32_e32 vcc, v5, v17
	v_or_b32_e32 v17, 24, v15
	s_or_b64 s[58:59], s[8:9], vcc
	v_cmp_gt_i32_e32 vcc, v5, v17
	v_or_b32_e32 v17, 25, v15
	v_ashrrev_i32_e32 v78, 5, v16
	v_lshlrev_b32_e32 v16, 8, v5
	s_or_b64 s[60:61], s[8:9], vcc
	v_cmp_gt_i32_e32 vcc, v5, v17
	v_or_b32_e32 v17, 26, v15
	s_movk_i32 s31, 0x210
	v_sub_u32_e32 v9, v9, v16
	v_mul_lo_u32 v16, v15, s34
	s_or_b64 s[62:63], s[8:9], vcc
	v_cmp_gt_i32_e32 vcc, v5, v17
	v_or_b32_e32 v15, 27, v15
	v_mul_lo_u32 v14, v3, s31
	v_ashrrev_i32_e32 v3, 31, v2
	s_or_b64 s[64:65], s[8:9], vcc
	v_cmp_gt_i32_e32 vcc, v5, v15
	v_ashrrev_i32_e32 v75, 5, v2
	s_or_b64 s[66:67], s[8:9], vcc
	v_ashrrev_i32_e32 v94, 3, v2
	v_lshl_add_u64 v[2:3], v[2:3], 2, s[68:69]
	s_mov_b64 s[8:9], 0x35c00000
	v_lshl_add_u64 v[56:57], v[2:3], 0, s[8:9]
	v_lshlrev_b32_e32 v2, 9, v7
	s_lshr_b32 s8, s28, 2
	v_or3_b32 v96, v2, s30, v11
	s_mulk_i32 s8, 0x2080
	v_mul_u32_u24_e32 v2, 0x104, v10
	v_lshl_add_u32 v85, v8, 2, s5
	v_mul_u32_u24_e32 v8, 0x104, v5
	v_add3_u32 v2, s8, v2, v12
	s_lshr_b32 s8, s33, 5
	v_add3_u32 v3, v8, v12, s5
	s_mulk_i32 s8, 0x2080
	v_add_u32_e32 v98, 0x8200, v3
	v_mov_b32_e32 v3, s8
	v_and_b32_e32 v54, 0x70, v4
	v_mad_u32_u24 v3, v10, s34, v3
	v_lshlrev_b32_e32 v46, 7, v75
	v_lshlrev_b32_e32 v48, 7, v76
	v_lshlrev_b32_e32 v50, 7, v77
	v_lshlrev_b32_e32 v52, 7, v78
	v_add_u32_e32 v87, s5, v4
	v_mul_lo_u32 v4, v94, s31
	v_lshlrev_b32_e32 v5, 2, v54
	v_add3_u32 v3, v3, v12, s5
	v_ashrrev_i32_e32 v47, 31, v46
	v_ashrrev_i32_e32 v49, 31, v48
	v_ashrrev_i32_e32 v51, 31, v50
	v_ashrrev_i32_e32 v53, 31, v52
	s_movk_i32 s4, 0x2000
	v_add_u32_e32 v89, 0x2000, v88
	v_add3_u32 v95, s5, v4, v5
	v_add_u32_e32 v97, 0x4100, v2
	v_add_u32_e32 v99, 0x4100, v3
	v_add_u32_e32 v100, s29, v96
	v_add_u32_e32 v101, s5, v2
	s_movk_i32 s28, 0x3ff
	s_mov_b32 s71, 0
	s_movk_i32 s29, 0x3000
	s_movk_i32 s30, 0x1000
	v_lshlrev_b32_e32 v58, 2, v6
	v_add_u32_e32 v102, v9, v16
	v_add_u32_e32 v103, v13, v14
	v_mov_b32_e32 v104, 0x358637bd
	s_mov_b32 s31, 0xf800000
	v_mov_b32_e32 v105, 0x260
	s_mov_b64 s[72:73], 0x24a0
	s_movk_i32 s33, 0x7fff
	s_mov_b32 s34, 0xffff0000
	s_mov_b64 s[74:75], 0xdc00400
	v_mov_b32_e32 v229, v1
	s_branch .LBB0_2950

.LBB0_2950:
	s_barrier
	s_and_saveexec_b64 s[8:9], s[6:7]
	v_mov_b32_e32 v2, s2
	ds_write_b32 v2, v1
	s_or_b64 exec, exec, s[8:9]
	v_mov_b32_e32 v2, s2
	s_waitcnt lgkmcnt(0)
	s_barrier
	ds_read_b32 v2, v2
	s_mov_b64 s[76:77], -1
	s_waitcnt lgkmcnt(0)
	v_cmp_lt_i32_e32 vcc, s28, v2
	v_readfirstlane_b32 s8, v2
	s_cbranch_vccnz .LBB0_2949
	s_and_saveexec_b64 s[76:77], s[6:7]
	s_cbranch_execz .LBB0_2957
	s_mov_b64 s[80:81], exec
	v_mbcnt_lo_u32_b32 v1, s80, 0
	v_mbcnt_hi_u32_b32 v1, s81, v1
	v_cmp_eq_u32_e32 vcc, 0, v1
	s_and_saveexec_b64 s[78:79], vcc
	s_cbranch_execz .LBB0_2956
	s_bcnt1_i32_b64 s9, s[80:81]
	v_mov_b32_e32 v2, s9
	global_atomic_add v229, v43, v2, s[10:11] sc0

.LBB0_2957:
	s_or_b64 exec, exec, s[76:77]
	s_lshl_b32 s9, s8, 4
	s_lshl_b32 s36, s8, 6
	s_and_b32 s9, s9, 0xffffe000
	s_and_b32 s36, s36, 0x1fc0
	s_or_b32 s36, s9, s36
	s_ashr_i32 s9, s8, 31
	s_bfe_u32 s35, s8, 0x20007
	s_lshl_b64 s[44:45], s[8:9], 14
	s_lshl_b32 s37, s35, 6
	v_add_u32_e32 v2, s36, v67
	v_mov_b64_e32 v[26:27], s[12:13]
	v_lshl_add_u64 v[4:5], v[56:57], 0, s[44:45]
	v_add_u32_e32 v10, s36, v68
	v_mad_i64_i32 v[2:3], s[76:77], v2, s29, v[26:27]
	v_add_lshl_u32 v42, v55, s37, 2
	v_add_lshl_u32 v8, v66, s37, 2
	v_mov_b32_e32 v9, v43
	v_mad_i64_i32 v[10:11], s[44:45], v10, s29, v[26:27]
	v_add_co_u32_e32 v14, vcc, s30, v4
	v_lshl_add_u64 v[6:7], v[2:3], 0, v[42:43]
	v_lshl_add_u64 v[2:3], v[2:3], 0, v[8:9]
	v_lshl_add_u64 v[12:13], v[10:11], 0, v[42:43]
	v_lshl_add_u64 v[10:11], v[10:11], 0, v[8:9]
	v_addc_co_u32_e32 v15, vcc, 0, v5, vcc
	global_load_dword v34, v[4:5], off
	global_load_dword v35, v[6:7], off
	global_load_dword v36, v[2:3], off
	global_load_dword v37, v[12:13], off
	global_load_dword v38, v[10:11], off
	global_load_dword v39, v[14:15], off
	global_load_dword v40, v[14:15], off offset:2048
	global_load_dword v41, v[4:5], off offset:2048
	v_add_u32_e32 v2, s36, v69
	v_mad_i64_i32 v[2:3], s[44:45], v2, s29, v[26:27]
	v_add_u32_e32 v10, s36, v70
	v_add_u32_e32 v14, s36, v71
	v_lshl_add_u64 v[6:7], v[2:3], 0, v[42:43]
	v_mad_i64_i32 v[10:11], s[44:45], v10, s29, v[26:27]
	v_mad_i64_i32 v[14:15], s[44:45], v14, s29, v[26:27]
	v_add_co_u32_e32 v16, vcc, s4, v4
	v_lshl_add_u64 v[2:3], v[2:3], 0, v[8:9]
	v_lshl_add_u64 v[12:13], v[10:11], 0, v[42:43]
	v_lshl_add_u64 v[10:11], v[10:11], 0, v[8:9]
	v_addc_co_u32_e32 v17, vcc, 0, v5, vcc
	v_lshl_add_u64 v[18:19], v[14:15], 0, v[42:43]
	v_lshl_add_u64 v[14:15], v[14:15], 0, v[8:9]
	global_load_dword v60, v[6:7], off
	global_load_dword v61, v[2:3], off
	global_load_dword v62, v[12:13], off
	global_load_dword v63, v[10:11], off
	global_load_dword v64, v[16:17], off
	global_load_dword v65, v[18:19], off
	global_load_dword v106, v[14:15], off
	global_load_dword v107, v[16:17], off offset:2048
	v_add_u32_e32 v20, s36, v72
	v_mad_i64_i32 v[20:21], s[44:45], v20, s29, v[26:27]
	v_add_u32_e32 v10, s36, v73
	v_add_u32_e32 v14, s36, v74
	v_lshl_add_u64 v[2:3], v[20:21], 0, v[42:43]
	v_mad_i64_i32 v[10:11], s[44:45], v10, s29, v[26:27]
	v_add_co_u32_e32 v4, vcc, s29, v4
	v_mad_i64_i32 v[14:15], s[44:45], v14, s29, v[26:27]
	v_lshl_add_u64 v[6:7], v[20:21], 0, v[8:9]
	v_addc_co_u32_e32 v5, vcc, 0, v5, vcc
	v_lshl_add_u64 v[12:13], v[10:11], 0, v[42:43]
	v_lshl_add_u64 v[10:11], v[10:11], 0, v[8:9]
	v_lshl_add_u64 v[16:17], v[14:15], 0, v[42:43]
	v_lshl_add_u64 v[8:9], v[14:15], 0, v[8:9]
	global_load_dword v42, v[2:3], off
	global_load_dword v108, v[6:7], off
	global_load_dword v109, v[4:5], off
	global_load_dword v110, v[12:13], off
	global_load_dword v111, v[10:11], off
	global_load_dword v112, v[16:17], off
	global_load_dword v113, v[8:9], off
	global_load_dword v114, v[4:5], off offset:2048
	s_lshl_b64 s[8:9], s[8:9], 15
	v_add_u32_e32 v2, s36, v75
	v_lshl_add_u64 v[28:29], v[44:45], 0, s[8:9]
	v_mad_i64_i32 v[2:3], s[8:9], v2, s29, v[26:27]
	s_lshl_b32 s70, s35, 9
	v_lshl_add_u64 v[2:3], v[2:3], 0, s[70:71]
	v_mov_b32_e32 v59, v43
	v_add_u32_e32 v10, s36, v76
	v_lshl_add_u64 v[2:3], v[2:3], 0, v[58:59]
	v_mad_i64_i32 v[10:11], s[8:9], v10, s29, v[26:27]
	v_add_co_u32_e32 v2, vcc, s30, v2
	v_lshl_add_u64 v[10:11], v[10:11], 0, s[70:71]
	v_add_u32_e32 v18, s36, v77
	v_addc_co_u32_e32 v3, vcc, 0, v3, vcc
	v_lshl_add_u64 v[10:11], v[10:11], 0, v[58:59]
	v_mad_i64_i32 v[18:19], s[8:9], v18, s29, v[26:27]
	v_add_co_u32_e32 v10, vcc, s30, v10
	v_lshl_add_u64 v[18:19], v[18:19], 0, s[70:71]
	v_add_u32_e32 v30, s36, v78
	v_addc_co_u32_e32 v11, vcc, 0, v11, vcc
	v_lshl_add_u64 v[18:19], v[18:19], 0, v[58:59]
	v_mad_i64_i32 v[26:27], s[8:9], v30, s29, v[26:27]
	v_add_co_u32_e32 v18, vcc, s30, v18
	v_lshl_add_u64 v[26:27], v[26:27], 0, s[70:71]
	s_nop 0
	v_addc_co_u32_e32 v19, vcc, 0, v19, vcc
	v_lshl_add_u64 v[26:27], v[26:27], 0, v[58:59]
	v_add_co_u32_e32 v26, vcc, s30, v26
	v_lshl_add_u64 v[6:7], v[46:47], 2, v[28:29]
	v_lshl_add_u64 v[14:15], v[48:49], 2, v[28:29]
	v_lshl_add_u64 v[22:23], v[50:51], 2, v[28:29]
	v_addc_co_u32_e32 v27, vcc, 0, v27, vcc
	v_lshl_add_u64 v[30:31], v[52:53], 2, v[28:29]
	global_load_dwordx4 v[2:5], v[2:3], off offset:3168
	s_nop 0
	global_load_dwordx4 v[6:9], v[6:7], off
	s_nop 0
	global_load_dwordx4 v[10:13], v[10:11], off offset:3168
	s_nop 0
	global_load_dwordx4 v[14:17], v[14:15], off
	s_nop 0
	global_load_dwordx4 v[18:21], v[18:19], off offset:3168
	s_nop 0
	global_load_dwordx4 v[22:25], v[22:23], off
	s_nop 0
	global_load_dwordx4 v[26:29], v[26:27], off offset:3168
	s_nop 0
	global_load_dwordx4 v[30:33], v[30:31], off
	s_waitcnt vmcnt(0) lgkmcnt(0)
	v_mul_f32_e32 v59, 0x3fb8aa3b, v34
	v_mul_f32_e32 v34, 0xbfb8aa3b, v34
	v_exp_f32_e32 v34, v34
	v_exp_f32_e32 v59, v59
	v_mul_f32_e32 v35, 0x3e000000, v35
	v_mul_f32_e32 v34, v36, v34
	v_mul_f32_e32 v36, 0x3fb8aa3b, v41
	v_exp_f32_e32 v36, v36
	v_mul_f32_e32 v35, v35, v59
	v_mul_f32_e32 v41, 0xbfb8aa3b, v41
	s_barrier
	v_add_u32_e32 v232, s36, v94
	v_mov_b64_e32 v[234:235], s[12:13]
	s_lshl_b32 s98, s35, 2
	s_mov_b32 s99, 0
	v_lshlrev_b32_e32 v230, 2, v54
	v_mov_b32_e32 v231, 0
	v_mad_i64_i32 v[234:235], s[100:101], v232, s29, v[234:235]
	v_lshl_add_u64 v[234:235], v[234:235], 0, s[98:99]
	v_lshl_add_u64 v[234:235], v[234:235], 0, v[230:231]
	v_lshl_add_u64 v[234:235], v[234:235], 0, s[72:73]
	global_load_dword v236, v[234:235], off
	v_exp_f32_e32 v41, v41
	ds_write2st64_b32 v79, v35, v34 offset0:65 offset1:130
	v_mul_f32_e32 v34, 0x3e000000, v37
	v_mul_f32_e32 v34, v34, v36
	v_mul_f32_e32 v36, 0x3fb8aa3b, v39
	v_mul_f32_e32 v37, 0xbfb8aa3b, v39
	v_exp_f32_e32 v36, v36
	v_exp_f32_e32 v37, v37
	v_mul_f32_e32 v35, v38, v41
	ds_write2st64_b32 v80, v34, v35 offset0:65 offset1:130
	v_mul_f32_e32 v34, 0x3e000000, v60
	v_mul_f32_e32 v34, v34, v36
	v_mul_f32_e32 v35, v61, v37
	v_mul_f32_e32 v36, 0x3fb8aa3b, v40
	v_mul_f32_e32 v37, 0xbfb8aa3b, v40
	v_exp_f32_e32 v36, v36
	v_exp_f32_e32 v37, v37
	ds_write2st64_b32 v81, v34, v35 offset0:65 offset1:130
	v_mul_f32_e32 v34, 0x3e000000, v62
	v_mul_f32_e32 v34, v34, v36
	v_mul_f32_e32 v35, v63, v37
	v_mul_f32_e32 v36, 0x3fb8aa3b, v64
	v_mul_f32_e32 v37, 0xbfb8aa3b, v64
	v_exp_f32_e32 v36, v36
	v_exp_f32_e32 v37, v37
	ds_write2st64_b32 v82, v34, v35 offset0:65 offset1:130
	v_mul_f32_e32 v34, 0x3e000000, v65
	v_mul_f32_e32 v34, v34, v36
	v_mul_f32_e32 v35, v106, v37
	v_mul_f32_e32 v36, 0x3fb8aa3b, v107
	v_mul_f32_e32 v37, 0xbfb8aa3b, v107
	v_exp_f32_e32 v36, v36
	v_exp_f32_e32 v37, v37
	ds_write2st64_b32 v83, v34, v35 offset0:65 offset1:130
	v_mul_f32_e32 v34, 0x3e000000, v42
	v_mul_f32_e32 v34, v34, v36
	v_mul_f32_e32 v35, v108, v37
	v_mul_f32_e32 v36, 0x3fb8aa3b, v109
	v_mul_f32_e32 v37, 0xbfb8aa3b, v109
	v_exp_f32_e32 v36, v36
	v_exp_f32_e32 v37, v37
	ds_write2st64_b32 v84, v34, v35 offset0:65 offset1:130
	v_mul_f32_e32 v34, 0x3e000000, v110
	v_mul_f32_e32 v34, v34, v36
	v_mul_f32_e32 v35, v111, v37
	v_mul_f32_e32 v36, 0x3fb8aa3b, v114
	v_mul_f32_e32 v37, 0xbfb8aa3b, v114
	v_exp_f32_e32 v36, v36
	v_exp_f32_e32 v37, v37
	ds_write2st64_b32 v85, v34, v35 offset0:65 offset1:130
	v_mul_f32_e32 v34, 0x3e000000, v112
	v_mul_f32_e32 v34, v34, v36
	v_mul_f32_e32 v35, v113, v37
	ds_write2st64_b32 v86, v34, v35 offset0:65 offset1:130
	ds_write_b128 v87, v[2:5] offset:49920
	ds_write_b128 v88, v[6:9]
	ds_write_b128 v87, v[10:13] offset:58112
	ds_write_b128 v89, v[14:17]
	ds_write_b128 v90, v[18:21]
	ds_write_b128 v91, v[22:25]
	ds_write_b128 v92, v[26:29]
	ds_write_b128 v93, v[30:33]
	v_mov_b32_e32 v2, 0
	s_lshl_b32 s35, s35, 7
	s_mov_b32 s8, 32
	v_mov_b32_e32 v18, v97
	v_mov_b32_e32 v19, v96
	v_mov_b32_e32 v3, v2
	v_mov_b32_e32 v4, v2
	v_mov_b32_e32 v5, v2
	v_mov_b32_e32 v6, v2
	v_mov_b32_e32 v7, v2
	v_mov_b32_e32 v8, v2
	v_mov_b32_e32 v9, v2
	v_mov_b32_e32 v10, v2
	v_mov_b32_e32 v11, v2
	v_mov_b32_e32 v12, v2
	v_mov_b32_e32 v13, v2
	v_mov_b32_e32 v14, v2
	v_mov_b32_e32 v15, v2
	v_mov_b32_e32 v16, v2
	v_mov_b32_e32 v17, v2
	s_waitcnt lgkmcnt(0)
	s_barrier

.LBB0_2965:
	ds_read2_b32 v[20:21], v18 offset1:2
	ds_read2st64_b32 v[22:23], v19 offset1:4
	s_add_i32 s8, s8, -8
	s_cmp_eq_u32 s8, 0
	s_waitcnt lgkmcnt(0)
	v_mfma_f32_32x32x2_f32 v[2:17], v20, v22, v[2:17]
	v_mfma_f32_32x32x2_f32 v[2:17], v21, v23, v[2:17]
	ds_read2_b32 v[20:21], v18 offset0:4 offset1:6
	ds_read2st64_b32 v[22:23], v19 offset0:8 offset1:12
	s_waitcnt lgkmcnt(0)
	v_mfma_f32_32x32x2_f32 v[2:17], v20, v22, v[2:17]
	v_mfma_f32_32x32x2_f32 v[2:17], v21, v23, v[2:17]
	ds_read2_b32 v[20:21], v18 offset0:8 offset1:10
	ds_read2st64_b32 v[22:23], v19 offset0:16 offset1:20
	s_waitcnt lgkmcnt(0)
	v_mfma_f32_32x32x2_f32 v[2:17], v20, v22, v[2:17]
	v_mfma_f32_32x32x2_f32 v[2:17], v21, v23, v[2:17]
	ds_read2_b32 v[20:21], v18 offset0:12 offset1:14
	ds_read2st64_b32 v[22:23], v19 offset0:24 offset1:28
	v_add_u32_e32 v19, 0x2000, v19
	v_add_u32_e32 v18, 64, v18
	s_waitcnt lgkmcnt(0)
	v_mfma_f32_32x32x2_f32 v[2:17], v20, v22, v[2:17]
	v_mfma_f32_32x32x2_f32 v[2:17], v21, v23, v[2:17]
	s_cbranch_scc0 .LBB0_2965
	v_add_u32_e32 v18, 0xc200, v103
	s_barrier
	s_nop 14
	ds_write2_b32 v18, v2, v3 offset0:64 offset1:196
	v_add_u32_e32 v2, 0xc600, v103
	ds_write2_b32 v2, v4, v5 offset0:72 offset1:204
	v_add_u32_e32 v2, 0xd200, v103
	ds_write2_b32 v2, v6, v7 offset0:96 offset1:228
	v_add_u32_e32 v2, 0xd600, v103
	ds_write2_b32 v2, v8, v9 offset0:104 offset1:236
	v_add_u32_e32 v2, 0xe400, v103
	ds_write2_b32 v2, v10, v11 offset1:132
	v_add_u32_e32 v2, 0xe800, v103
	ds_write2_b32 v2, v12, v13 offset0:8 offset1:140
	v_add_u32_e32 v2, 0xf400, v103
	ds_write2_b32 v2, v14, v15 offset0:32 offset1:164
	v_add_u32_e32 v2, 0xf800, v103
	v_mov_b64_e32 v[18:19], s[0:1]
	ds_write2_b32 v2, v16, v17 offset0:40 offset1:172
	s_waitcnt lgkmcnt(0)
	s_barrier
	ds_read_b128 v[14:17], v95 offset:49920
	ds_read_b128 v[10:13], v95 offset:49936
	ds_read_b128 v[6:9], v95 offset:49952
	ds_read_b128 v[2:5], v95 offset:49968
	global_load_dwordx2 v[22:23], v[18:19], off offset:168
	s_waitcnt vmcnt(0)
	v_mov_b32_e32 v1, v229
	v_add_u32_e32 v60, s36, v94
	v_mov_b64_e32 v[18:19], s[12:13]
	v_and_b32_e32 v21, 64, v166
	s_lshl_b32 s70, s35, 2
	v_mad_i64_i32 v[18:19], s[8:9], v60, s29, v[18:19]
	v_xor_b32_e32 v20, 1, v166
	v_lshlrev_b32_e32 v42, 2, v54
	v_add_u32_e32 v59, 64, v21
	v_lshl_add_u64 v[18:19], v[18:19], 0, s[70:71]
	v_cmp_lt_i32_e32 vcc, v20, v59
	v_lshl_add_u64 v[30:31], v[18:19], 0, v[42:43]
	s_waitcnt lgkmcnt(0)
	v_mov_b32_e32 v26, v15
	v_cndmask_b32_e32 v20, v166, v20, vcc
	v_add_co_u32_e32 v18, vcc, s4, v30
	v_lshlrev_b32_e32 v61, 2, v20
	s_nop 0
	v_addc_co_u32_e32 v19, vcc, 0, v31, vcc
	global_load_dwordx4 v[18:21], v[18:19], off offset:1184
	v_mov_b32_e32 v27, v11
	v_mov_b32_e32 v24, v14
	v_mov_b32_e32 v25, v10
	v_mov_b32_e32 v36, v7
	v_mov_b32_e32 v37, v3
	v_pk_mul_f32 v[26:27], v[26:27], v[26:27]
	v_mov_b32_e32 v28, v16
	v_mov_b32_e32 v29, v12
	v_mov_b32_e32 v34, v6
	v_mov_b32_e32 v35, v2
	v_pk_mul_f32 v[36:37], v[36:37], v[36:37]
	v_pk_fma_f32 v[24:25], v[24:25], v[24:25], v[26:27]
	v_mov_b32_e32 v32, v17
	v_mov_b32_e32 v33, v13
	v_mov_b32_e32 v38, v8
	v_mov_b32_e32 v39, v4
	v_pk_fma_f32 v[26:27], v[34:35], v[34:35], v[36:37]
	v_pk_fma_f32 v[24:25], v[28:29], v[28:29], v[24:25]
	v_mov_b32_e32 v40, v9
	v_mov_b32_e32 v41, v5
	v_pk_fma_f32 v[26:27], v[38:39], v[38:39], v[26:27]
	v_pk_fma_f32 v[24:25], v[32:33], v[32:33], v[24:25]
	v_pk_fma_f32 v[26:27], v[40:41], v[40:41], v[26:27]
	v_add_f32_e32 v24, v24, v25
	v_add_f32_e32 v24, v24, v26
	v_add_f32_e32 v24, v24, v27
	ds_bpermute_b32 v25, v61, v24
	v_xor_b32_e32 v26, 2, v166
	v_cmp_lt_i32_e32 vcc, v26, v59
	v_lshl_add_u64 v[62:63], v[30:31], 0, s[72:73]
	v_mov_b32_e32 v38, v14
	v_cndmask_b32_e32 v26, v166, v26, vcc
	v_lshlrev_b32_e32 v26, 2, v26
	s_waitcnt lgkmcnt(0)
	v_add_f32_e32 v24, v24, v25
	ds_bpermute_b32 v25, v26, v24
	v_ashrrev_i32_e32 v61, 31, v60
	s_lshl_b32 s70, s35, 1
	s_mov_b64 s[76:77], 0
	s_waitcnt lgkmcnt(0)
	v_add_f32_e32 v32, v24, v25
	v_lshl_add_u64 v[64:65], v[22:23], 0, v[42:43]
	global_load_dwordx4 v[26:29], v[64:65], off
	v_xor_b32_e32 v22, 4, v166
	v_cmp_lt_i32_e32 vcc, v22, v59
	s_nop 1
	v_cndmask_b32_e32 v22, v166, v22, vcc
	v_lshlrev_b32_e32 v22, 2, v22
	ds_bpermute_b32 v33, v22, v32
	global_load_dwordx4 v[22:25], v[64:65], off offset:16
	s_waitcnt lgkmcnt(0)
	v_add_f32_e32 v30, v32, v33
	v_fmamk_f32 v30, v30, 0x3c000000, v104
	v_mul_f32_e32 v31, 0x4f800000, v30
	v_cmp_gt_f32_e32 vcc, s31, v30
	s_nop 1
	v_cndmask_b32_e32 v39, v30, v31, vcc
	v_sqrt_f32_e32 v40, v39
	global_load_dwordx4 v[30:33], v[62:63], off offset:16
	global_load_dwordx4 v[34:37], v[62:63], off offset:48
	v_add_u32_e32 v14, -1, v40
	v_add_u32_e32 v41, 1, v40
	v_fma_f32 v42, -v14, v40, v39
	v_fma_f32 v59, -v41, v40, v39
	v_cmp_ge_f32_e64 s[8:9], 0, v42
	s_nop 1
	v_cndmask_b32_e64 v14, v40, v14, s[8:9]
	v_cmp_lt_f32_e64 s[8:9], 0, v59
	s_nop 1
	v_cndmask_b32_e64 v14, v14, v41, s[8:9]
	v_mul_f32_e32 v40, 0x37800000, v14
	v_cndmask_b32_e32 v14, v14, v40, vcc
	v_cmp_class_f32_e32 vcc, v39, v105
	s_nop 1
	v_cndmask_b32_e32 v14, v14, v39, vcc
	v_div_scale_f32 v40, s[8:9], v14, v14, 1.0
	v_rcp_f32_e32 v41, v40
	v_mov_b32_e32 v39, v16
	v_div_scale_f32 v16, vcc, 1.0, v14, 1.0
	v_fma_f32 v42, -v40, v41, 1.0
	v_fmac_f32_e32 v41, v42, v41
	v_mul_f32_e32 v42, v16, v41
	v_fma_f32 v59, -v40, v42, v16
	v_fmac_f32_e32 v42, v59, v41
	v_fma_f32 v16, -v40, v42, v16
	v_div_fmas_f32 v16, v16, v41, v42
	v_div_fixup_f32 v14, v16, v14, 1.0
	v_pk_mul_f32 v[110:111], v[38:39], v[14:15] op_sel_hi:[1,0]
	s_waitcnt vmcnt(0)
	v_mul_f32_e32 v16, 0xbfb8aa3b, v18
	v_mul_f32_e32 v38, 0xbfb8aa3b, v20
	v_exp_f32_e32 v112, v16
	v_exp_f32_e32 v113, v38
	v_mul_f32_e32 v16, 0xbfb8aa3b, v19
	global_load_dwordx4 v[38:41], v[64:65], off offset:48
	global_load_dwordx4 v[106:109], v[64:65], off offset:32
	v_exp_f32_e32 v64, v16
	v_pk_add_f32 v[112:113], v[112:113], 1.0 op_sel_hi:[1,0]
	s_nop 0
	v_div_scale_f32 v16, s[8:9], v113, v113, v20
	v_rcp_f32_e32 v65, v16
	v_div_scale_f32 v59, s[8:9], v112, v112, v18
	v_rcp_f32_e32 v116, v59
	v_fma_f32 v114, -v16, v65, 1.0
	v_div_scale_f32 v42, vcc, v20, v113, v20
	v_fmac_f32_e32 v65, v114, v65
	v_fma_f32 v115, -v59, v116, 1.0
	v_mul_f32_e32 v114, v42, v65
	v_fmac_f32_e32 v116, v115, v116
	v_fma_f32 v115, -v16, v114, v42
	v_fmac_f32_e32 v114, v115, v65
	v_fma_f32 v16, -v16, v114, v42
	v_div_fmas_f32 v16, v16, v65, v114
	v_div_scale_f32 v117, s[8:9], v18, v112, v18
	v_div_fixup_f32 v113, v16, v113, v20
	v_mul_f32_e32 v20, 0xbfb8aa3b, v21
	v_mul_f32_e32 v118, v117, v116
	v_exp_f32_e32 v65, v20
	v_fma_f32 v119, -v59, v118, v117
	v_fmac_f32_e32 v118, v119, v116
	v_fma_f32 v16, -v59, v118, v117
	s_mov_b64 vcc, s[8:9]
	v_div_fmas_f32 v16, v16, v116, v118
	v_pk_add_f32 v[64:65], v[64:65], 1.0 op_sel_hi:[1,0]
	v_div_fixup_f32 v112, v16, v112, v18
	v_mov_b32_e32 v16, v15
	v_div_scale_f32 v15, s[8:9], v65, v65, v21
	v_rcp_f32_e32 v18, v15
	v_mov_b32_e32 v114, v26
	v_mov_b32_e32 v115, v28
	v_mov_b32_e32 v28, v27
	v_fma_f32 v20, -v15, v18, 1.0
	v_fmac_f32_e32 v18, v20, v18
	v_div_scale_f32 v20, vcc, v21, v65, v21
	v_mul_f32_e32 v26, v20, v18
	v_fma_f32 v27, -v15, v26, v20
	v_fmac_f32_e32 v26, v27, v18
	v_pk_mul_f32 v[16:17], v[16:17], v[14:15] op_sel_hi:[1,0]
	v_fma_f32 v15, -v15, v26, v20
	v_div_scale_f32 v20, s[8:9], v64, v64, v19
	v_rcp_f32_e32 v27, v20
	v_div_fmas_f32 v15, v15, v18, v26
	v_div_fixup_f32 v21, v15, v65, v21
	v_pk_mul_f32 v[16:17], v[28:29], v[16:17]
	v_fma_f32 v15, -v20, v27, 1.0
	v_fmac_f32_e32 v27, v15, v27
	v_div_scale_f32 v15, vcc, v19, v64, v19
	v_mul_f32_e32 v18, v15, v27
	v_fma_f32 v26, -v20, v18, v15
	v_fmac_f32_e32 v18, v26, v27
	v_fma_f32 v15, -v20, v18, v15
	v_div_fmas_f32 v15, v15, v27, v18
	v_div_fixup_f32 v20, v15, v64, v19
	v_pk_mul_f32 v[20:21], v[20:21], v[16:17]
	global_load_dwordx4 v[16:19], v[62:63], off offset:32
	s_waitcnt lgkmcnt(0)
	v_mul_f32_e32 v15, 0xbfb8aa3b, v30
	v_exp_f32_e32 v26, v15
	v_mul_f32_e32 v15, 0xbfb8aa3b, v31
	v_exp_f32_e32 v28, v15
	v_mul_f32_e32 v15, 0xbfb8aa3b, v32
	v_exp_f32_e32 v27, v15
	v_mov_b32_e32 v62, v10
	v_mov_b32_e32 v63, v12
	v_pk_mul_f32 v[62:63], v[62:63], v[14:15] op_sel_hi:[1,0]
	v_pk_add_f32 v[26:27], v[26:27], 1.0 op_sel_hi:[1,0]
	v_mov_b32_e32 v64, v22
	v_div_scale_f32 v10, s[8:9], v27, v27, v32
	v_rcp_f32_e32 v12, v10
	v_mov_b32_e32 v65, v24
	v_pk_mul_f32 v[110:111], v[114:115], v[110:111]
	v_pk_mul_f32 v[62:63], v[62:63], v[64:65]
	v_fma_f32 v15, -v10, v12, 1.0
	v_fmac_f32_e32 v12, v15, v12
	v_div_scale_f32 v15, vcc, v32, v27, v32
	v_mul_f32_e32 v22, v15, v12
	v_fma_f32 v24, -v10, v22, v15
	v_fmac_f32_e32 v22, v24, v12
	v_fma_f32 v10, -v10, v22, v15
	v_div_scale_f32 v15, s[8:9], v26, v26, v30
	v_rcp_f32_e32 v24, v15
	v_div_fmas_f32 v10, v10, v12, v22
	v_div_fixup_f32 v27, v10, v27, v32
	v_pk_mul_f32 v[110:111], v[112:113], v[110:111]
	v_fma_f32 v10, -v15, v24, 1.0
	v_fmac_f32_e32 v24, v10, v24
	v_div_scale_f32 v10, vcc, v30, v26, v30
	v_mul_f32_e32 v12, v10, v24
	v_fma_f32 v22, -v15, v12, v10
	v_fmac_f32_e32 v12, v22, v24
	v_fma_f32 v10, -v15, v12, v10
	v_div_fmas_f32 v10, v10, v24, v12
	v_mul_f32_e32 v12, 0xbfb8aa3b, v33
	v_exp_f32_e32 v29, v12
	v_div_fixup_f32 v26, v10, v26, v30
	v_mov_b32_e32 v12, v11
	v_mov_b32_e32 v24, v23
	v_pk_add_f32 v[10:11], v[28:29], 1.0 op_sel_hi:[1,0]
	v_pk_mul_f32 v[26:27], v[62:63], v[26:27]
	v_div_scale_f32 v15, s[8:9], v11, v11, v33
	v_rcp_f32_e32 v22, v15
	v_pk_mul_f32 v[12:13], v[12:13], v[14:15] op_sel_hi:[1,0]
	v_lshlrev_b32_e32 v42, 1, v54
	v_pk_mul_f32 v[12:13], v[12:13], v[24:25]
	v_fma_f32 v23, -v15, v22, 1.0
	v_fmac_f32_e32 v22, v23, v22
	v_div_scale_f32 v23, vcc, v33, v11, v33
	v_mul_f32_e32 v24, v23, v22
	v_fma_f32 v25, -v15, v24, v23
	v_fmac_f32_e32 v24, v25, v22
	v_fma_f32 v15, -v15, v24, v23
	v_div_scale_f32 v23, s[8:9], v10, v10, v31
	v_rcp_f32_e32 v25, v23
	v_div_fmas_f32 v15, v15, v22, v24
	v_div_fixup_f32 v11, v15, v11, v33
	v_fma_f32 v15, -v23, v25, 1.0
	v_fmac_f32_e32 v25, v15, v25
	v_div_scale_f32 v15, vcc, v31, v10, v31
	v_mul_f32_e32 v22, v15, v25
	v_fma_f32 v24, -v23, v22, v15
	v_fmac_f32_e32 v22, v24, v25
	v_fma_f32 v15, -v23, v22, v15
	v_div_fmas_f32 v15, v15, v25, v22
	v_div_fixup_f32 v10, v15, v10, v31
	v_pk_mul_f32 v[10:11], v[12:13], v[10:11]
	v_cvt_pk_bf16_f32 v13, v27, v11
	v_cvt_pk_bf16_f32 v11, v111, v21
	s_waitcnt vmcnt(0)
	v_mul_f32_e32 v15, 0xbfb8aa3b, v16
	v_cvt_pk_bf16_f32 v12, v26, v10
	v_cvt_pk_bf16_f32 v10, v110, v20
	v_exp_f32_e32 v20, v15
	v_mul_f32_e32 v15, 0xbfb8aa3b, v17
	v_exp_f32_e32 v22, v15
	v_mul_f32_e32 v15, 0xbfb8aa3b, v18
	v_exp_f32_e32 v21, v15
	v_mov_b32_e32 v24, v6
	v_mov_b32_e32 v25, v8
	v_pk_mul_f32 v[24:25], v[24:25], v[14:15] op_sel_hi:[1,0]
	v_pk_add_f32 v[20:21], v[20:21], 1.0 op_sel_hi:[1,0]
	v_mov_b32_e32 v26, v106
	v_div_scale_f32 v6, s[8:9], v21, v21, v18
	v_rcp_f32_e32 v8, v6
	v_mov_b32_e32 v27, v108
	v_pk_mul_f32 v[24:25], v[24:25], v[26:27]
	v_mov_b32_e32 v108, v107
	v_fma_f32 v15, -v6, v8, 1.0
	v_fmac_f32_e32 v8, v15, v8
	v_div_scale_f32 v15, vcc, v18, v21, v18
	v_mul_f32_e32 v23, v15, v8
	v_fma_f32 v26, -v6, v23, v15
	v_fmac_f32_e32 v23, v26, v8
	v_fma_f32 v6, -v6, v23, v15
	v_div_scale_f32 v15, s[8:9], v20, v20, v16
	v_rcp_f32_e32 v26, v15
	v_div_fmas_f32 v6, v6, v8, v23
	v_div_fixup_f32 v21, v6, v21, v18
	v_fma_f32 v6, -v15, v26, 1.0
	v_fmac_f32_e32 v26, v6, v26
	v_div_scale_f32 v6, vcc, v16, v20, v16
	v_mul_f32_e32 v8, v6, v26
	v_fma_f32 v18, -v15, v8, v6
	v_fmac_f32_e32 v8, v18, v26
	v_fma_f32 v6, -v15, v8, v6
	v_div_fmas_f32 v6, v6, v26, v8
	v_mul_f32_e32 v8, 0xbfb8aa3b, v19
	v_exp_f32_e32 v23, v8
	v_div_fixup_f32 v20, v6, v20, v16
	v_mov_b32_e32 v8, v7
	v_pk_mul_f32 v[20:21], v[24:25], v[20:21]
	v_pk_add_f32 v[6:7], v[22:23], 1.0 op_sel_hi:[1,0]
	s_nop 0
	v_div_scale_f32 v15, s[8:9], v7, v7, v19
	v_rcp_f32_e32 v16, v15
	v_pk_mul_f32 v[8:9], v[8:9], v[14:15] op_sel_hi:[1,0]
	v_fma_f32 v18, -v15, v16, 1.0
	v_fmac_f32_e32 v16, v18, v16
	v_div_scale_f32 v18, vcc, v19, v7, v19
	v_mul_f32_e32 v22, v18, v16
	v_fma_f32 v23, -v15, v22, v18
	v_fmac_f32_e32 v22, v23, v16
	v_fma_f32 v15, -v15, v22, v18
	v_div_scale_f32 v18, s[8:9], v6, v6, v17
	v_rcp_f32_e32 v23, v18
	v_div_fmas_f32 v15, v15, v16, v22
	v_div_fixup_f32 v7, v15, v7, v19
	v_pk_mul_f32 v[8:9], v[8:9], v[108:109]
	v_fma_f32 v15, -v18, v23, 1.0
	v_fmac_f32_e32 v23, v15, v23
	v_div_scale_f32 v15, vcc, v17, v6, v17
	v_mul_f32_e32 v16, v15, v23
	v_fma_f32 v19, -v18, v16, v15
	v_fmac_f32_e32 v16, v19, v23
	v_fma_f32 v15, -v18, v16, v15
	v_div_fmas_f32 v15, v15, v23, v16
	v_div_fixup_f32 v6, v15, v6, v17
	v_pk_mul_f32 v[6:7], v[8:9], v[6:7]
	v_mul_f32_e32 v9, 0xbfb8aa3b, v35
	v_mul_f32_e32 v8, 0xbfb8aa3b, v34
	v_exp_f32_e32 v16, v9
	v_mul_f32_e32 v9, 0xbfb8aa3b, v36
	v_exp_f32_e32 v8, v8
	v_exp_f32_e32 v9, v9
	v_mov_b32_e32 v18, v2
	v_mov_b32_e32 v19, v4
	v_pk_mul_f32 v[18:19], v[18:19], v[14:15] op_sel_hi:[1,0]
	v_pk_add_f32 v[8:9], v[8:9], 1.0 op_sel_hi:[1,0]
	v_mov_b32_e32 v22, v38
	v_div_scale_f32 v2, s[8:9], v9, v9, v36
	v_rcp_f32_e32 v4, v2
	v_mov_b32_e32 v23, v40
	v_pk_mul_f32 v[18:19], v[18:19], v[22:23]
	v_mov_b32_e32 v40, v39
	v_fma_f32 v15, -v2, v4, 1.0
	v_fmac_f32_e32 v4, v15, v4
	v_div_scale_f32 v15, vcc, v36, v9, v36
	v_mul_f32_e32 v17, v15, v4
	v_fma_f32 v22, -v2, v17, v15
	v_fmac_f32_e32 v17, v22, v4
	v_fma_f32 v2, -v2, v17, v15
	v_div_scale_f32 v15, s[8:9], v8, v8, v34
	v_rcp_f32_e32 v22, v15
	v_div_fmas_f32 v2, v2, v4, v17
	v_div_fixup_f32 v9, v2, v9, v36
	v_fma_f32 v2, -v15, v22, 1.0
	v_fmac_f32_e32 v22, v2, v22
	v_div_scale_f32 v2, vcc, v34, v8, v34
	v_mul_f32_e32 v4, v2, v22
	v_fma_f32 v17, -v15, v4, v2
	v_fmac_f32_e32 v4, v17, v22
	v_fma_f32 v2, -v15, v4, v2
	v_div_fmas_f32 v2, v2, v22, v4
	v_mul_f32_e32 v4, 0xbfb8aa3b, v37
	v_exp_f32_e32 v17, v4
	v_div_fixup_f32 v8, v2, v8, v34
	v_mov_b32_e32 v4, v3
	v_pk_mul_f32 v[8:9], v[18:19], v[8:9]
	v_pk_add_f32 v[2:3], v[16:17], 1.0 op_sel_hi:[1,0]
	s_nop 0
	v_div_scale_f32 v15, s[8:9], v3, v3, v37
	v_rcp_f32_e32 v16, v15
	v_pk_mul_f32 v[4:5], v[4:5], v[14:15] op_sel_hi:[1,0]
	v_fma_f32 v14, -v15, v16, 1.0
	v_fmac_f32_e32 v16, v14, v16
	v_div_scale_f32 v14, vcc, v37, v3, v37
	v_mul_f32_e32 v17, v14, v16
	v_fma_f32 v18, -v15, v17, v14
	v_fmac_f32_e32 v17, v18, v16
	v_fma_f32 v14, -v15, v17, v14
	v_div_scale_f32 v15, s[8:9], v2, v2, v35
	v_rcp_f32_e32 v18, v15
	v_div_fmas_f32 v14, v14, v16, v17
	v_div_fixup_f32 v3, v14, v3, v37
	v_pk_mul_f32 v[4:5], v[4:5], v[40:41]
	v_fma_f32 v14, -v15, v18, 1.0
	v_fmac_f32_e32 v18, v14, v18
	v_div_scale_f32 v14, vcc, v35, v2, v35
	v_mul_f32_e32 v16, v14, v18
	v_fma_f32 v17, -v15, v16, v14
	v_fmac_f32_e32 v16, v17, v18
	v_fma_f32 v14, -v15, v16, v14
	v_div_fmas_f32 v14, v14, v18, v16
	v_div_fixup_f32 v2, v14, v2, v35
	v_pk_mul_f32 v[2:3], v[4:5], v[2:3]
	v_bfe_u32 v5, v2, 16, 1
	v_add3_u32 v2, v2, v5, s33
	v_bfe_u32 v14, v8, 16, 1
	v_add3_u32 v8, v8, v14, s33
	v_lshrrev_b32_e32 v4, 16, v8
	v_cvt_pk_bf16_f32 v5, v9, v3
	v_and_or_b32 v4, v2, s34, v4
	v_cvt_pk_bf16_f32 v3, v21, v7
	v_cvt_pk_bf16_f32 v2, v20, v6
	v_lshlrev_b64 v[6:7], 11, v[60:61]
	v_lshl_add_u64 v[6:7], s[68:69], 0, v[6:7]
	v_lshl_add_u64 v[6:7], v[6:7], 0, s[70:71]
	v_lshl_add_u64 v[6:7], v[6:7], 0, v[42:43]
	v_lshl_add_u64 v[8:9], v[6:7], 0, s[74:75]
	v_add_co_u32_e32 v6, vcc, 0xdc00000, v6
	s_nop 1
	v_addc_co_u32_e32 v7, vcc, 0, v7, vcc
	global_store_dwordx4 v[6:7], v[10:13], off offset:1024
	global_store_dwordx4 v[8:9], v[2:5], off offset:16
	s_branch .LBB0_2949

.LBB0_3084:
	s_or_b64 exec, exec, s[10:11]
	v_mov_b32_e32 v1, v0
	v_mov_b64_e32 v[2:3], s[0:1]
	s_barrier
	global_load_dwordx2 v[2:3], v[2:3], off offset:88
	s_waitcnt vmcnt(0)
	v_readfirstlane_b32 s5, v1
	s_ashr_i32 s5, s5, 4
	s_and_b32 s6, s5, -4
	s_cmp_gt_i32 s6, 63
	s_cbranch_scc1 .LBB0_3087
	v_and_b32_e32 v21, 63, v1
	v_mov_b32_e32 v91, 0
	v_lshlrev_b32_e32 v90, 4, v21
	s_waitcnt lgkmcnt(0)
	v_lshl_add_u64 v[2:3], v[2:3], 0, v[90:91]
	s_movk_i32 s5, 0x2000
	v_add_co_u32_e32 v18, vcc, s5, v2
	v_mbcnt_lo_u32_b32 v1, -1, 0
	s_nop 0
	v_addc_co_u32_e32 v19, vcc, 0, v3, vcc
	global_load_dwordx4 v[2:5], v[18:19], off
	global_load_dwordx4 v[6:9], v[18:19], off offset:1024
	global_load_dwordx4 v[10:13], v[18:19], off offset:2048
	global_load_dwordx4 v[14:17], v[18:19], off offset:3072
	v_mbcnt_hi_u32_b32 v18, -1, v1
	v_and_b32_e32 v1, 64, v18
	v_add_u32_e32 v19, 64, v1
	v_xor_b32_e32 v1, 1, v18
	v_cmp_lt_i32_e32 vcc, v1, v19
	v_xor_b32_e32 v20, 2, v18
	s_lshl_b32 s7, s28, 8
	v_cndmask_b32_e32 v1, v18, v1, vcc
	v_cmp_lt_i32_e32 vcc, v20, v19
	s_lshl_b32 s4, s4, 6
	s_add_i32 s8, s7, s4
	v_cndmask_b32_e32 v20, v18, v20, vcc
	v_lshlrev_b32_e32 v166, 2, v20
	v_xor_b32_e32 v20, 4, v18
	v_cmp_lt_i32_e32 vcc, v20, v19
	s_add_i32 s10, s6, s8
	s_add_u32 s4, s68, 0x5800000
	v_cndmask_b32_e32 v20, v18, v20, vcc
	v_lshlrev_b32_e32 v167, 2, v20
	v_xor_b32_e32 v20, 8, v18
	v_cmp_lt_i32_e32 vcc, v20, v19
	s_addc_u32 s5, s69, 0
	s_lshl_b32 s3, s3, 6
	v_cndmask_b32_e32 v20, v18, v20, vcc
	v_lshlrev_b32_e32 v168, 2, v20
	v_xor_b32_e32 v20, 16, v18
	v_cmp_lt_i32_e32 vcc, v20, v19
	s_add_i32 s3, s7, s3
	s_add_i32 s3, s3, s6
	v_cndmask_b32_e32 v20, v18, v20, vcc
	v_lshlrev_b32_e32 v169, 2, v20
	v_xor_b32_e32 v20, 32, v18
	v_cmp_lt_i32_e32 vcc, v20, v19
	s_lshl_b32 s2, s2, 6
	s_sub_i32 s2, s3, s2
	v_cndmask_b32_e32 v18, v18, v20, vcc
	s_ashr_i32 s11, s10, 31
	v_lshlrev_b32_e32 v170, 2, v18
	v_lshlrev_b32_e32 v18, 2, v21
	s_or_b32 s20, s8, 32
	s_sub_i32 s8, s2, 32
	s_lshl_b64 s[2:3], s[10:11], 11
	v_or_b32_e32 v20, 0x100, v18
	v_or_b32_e32 v22, 0x200, v18
	v_or_b32_e32 v24, 0x300, v18
	v_lshl_or_b32 v92, v21, 3, s2
	v_mov_b32_e32 v93, s3
	s_lshl_b64 s[2:3], s[10:11], 12
	v_lshlrev_b32_e32 v1, 2, v1
	v_or_b32_e32 v94, s2, v90
	v_mov_b32_e32 v95, s3
	v_mov_b32_e32 v171, 0x358637bd
	s_mov_b32 s2, 0xf800000
	v_mov_b32_e32 v172, 0x260
	v_lshlrev_b32_e32 v90, 2, v18
	s_movk_i32 s3, 0x7fff
	s_mov_b32 s21, 0xffff0000
	s_mov_b32 s22, 0xba00000
	v_lshlrev_b32_e32 v96, 2, v20
	v_lshlrev_b32_e32 v98, 2, v22
	v_mov_b32_e32 v99, v91
	v_lshlrev_b32_e32 v100, 2, v24
	v_mov_b32_e32 v101, v91
	s_mov_b32 s23, 0xba01000
	s_mov_b64 s[12:13], 0x10000
	s_mov_b64 s[14:15], 0x20000
	v_mov_b32_e32 v97, v91

.LBB0_3192:
	s_or_b64 exec, exec, s[6:7]
	v_mov_b32_e32 v1, v0
	v_mov_b64_e32 v[2:3], s[0:1]
	s_barrier
	global_load_dwordx2 v[2:3], v[2:3], off offset:88
	s_waitcnt vmcnt(0)
	v_readfirstlane_b32 s5, v1
	s_ashr_i32 s6, s5, 6
	s_cmp_gt_i32 s6, 7
	s_cbranch_scc1 .LBB0_3195
	v_and_b32_e32 v21, 63, v1
	v_mov_b32_e32 v91, 0
	v_lshlrev_b32_e32 v90, 4, v21
	s_waitcnt lgkmcnt(0)
	v_lshl_add_u64 v[2:3], v[2:3], 0, v[90:91]
	s_movk_i32 s5, 0x3000
	v_add_co_u32_e32 v18, vcc, s5, v2
	v_mbcnt_lo_u32_b32 v1, -1, 0
	s_nop 0
	v_addc_co_u32_e32 v19, vcc, 0, v3, vcc
	global_load_dwordx4 v[2:5], v[18:19], off
	global_load_dwordx4 v[6:9], v[18:19], off offset:1024
	global_load_dwordx4 v[10:13], v[18:19], off offset:2048
	global_load_dwordx4 v[14:17], v[18:19], off offset:3072
	v_mbcnt_hi_u32_b32 v18, -1, v1
	v_and_b32_e32 v1, 64, v18
	v_add_u32_e32 v19, 64, v1
	v_xor_b32_e32 v1, 1, v18
	v_cmp_lt_i32_e32 vcc, v1, v19
	v_xor_b32_e32 v20, 2, v18
	s_lshl_b32 s7, s16, 5
	v_cndmask_b32_e32 v1, v18, v1, vcc
	v_cmp_lt_i32_e32 vcc, v20, v19
	s_lshl_b32 s6, s6, 2
	s_add_i32 s6, s7, s6
	v_cndmask_b32_e32 v20, v18, v20, vcc
	v_lshlrev_b32_e32 v148, 2, v20
	v_xor_b32_e32 v20, 4, v18
	v_cmp_lt_i32_e32 vcc, v20, v19
	s_add_i32 s24, s6, 0x2080
	s_ashr_i32 s25, s24, 31
	v_cndmask_b32_e32 v20, v18, v20, vcc
	v_lshlrev_b32_e32 v149, 2, v20
	v_xor_b32_e32 v20, 8, v18
	v_cmp_lt_i32_e32 vcc, v20, v19
	s_add_i32 s5, s7, 0x20a0
	s_lshl_b64 s[6:7], s[24:25], 11
	v_cndmask_b32_e32 v20, v18, v20, vcc
	v_lshlrev_b32_e32 v150, 2, v20
	v_xor_b32_e32 v20, 16, v18
	v_cmp_lt_i32_e32 vcc, v20, v19
	v_lshl_or_b32 v92, v21, 3, s6
	v_mov_b32_e32 v93, s7
	v_cndmask_b32_e32 v20, v18, v20, vcc
	v_lshlrev_b32_e32 v151, 2, v20
	v_xor_b32_e32 v20, 32, v18
	v_cmp_lt_i32_e32 vcc, v20, v19
	s_lshl_b64 s[6:7], s[24:25], 12
	v_lshlrev_b32_e32 v1, 2, v1
	v_cndmask_b32_e32 v18, v18, v20, vcc
	v_lshlrev_b32_e32 v152, 2, v18
	v_lshlrev_b32_e32 v18, 2, v21
	v_or_b32_e32 v20, 0x100, v18
	v_or_b32_e32 v22, 0x200, v18
	v_or_b32_e32 v24, 0x300, v18
	v_or_b32_e32 v94, s6, v90
	v_mov_b32_e32 v95, s7
	v_mov_b32_e32 v153, 0x358637bd
	s_mov_b32 s17, 0xf800000
	v_mov_b32_e32 v154, 0x260
	v_lshlrev_b32_e32 v90, 2, v18
	s_movk_i32 s25, 0x7fff
	s_mov_b32 s28, 0xffff0000
	s_mov_b32 s29, 0xba00000
	v_lshlrev_b32_e32 v96, 2, v20
	v_lshlrev_b32_e32 v98, 2, v22
	v_mov_b32_e32 v99, v91
	v_lshlrev_b32_e32 v100, 2, v24
	v_mov_b32_e32 v101, v91
	s_mov_b32 s30, 0xba01000
	s_mov_b64 s[26:27], 0x10000
	s_mov_b64 s[38:39], 0x20000
	v_mov_b32_e32 v97, v91

.LBB0_3339:
	s_or_b64 exec, exec, s[10:11]
	v_mov_b32_e32 v1, v0
	v_mov_b64_e32 v[2:3], s[0:1]
	s_barrier
	global_load_dwordx2 v[2:3], v[2:3], off offset:88
	s_waitcnt vmcnt(0)
	v_readfirstlane_b32 s6, v1
	s_ashr_i32 s6, s6, 6
	s_cmp_gt_i32 s6, 15
	s_cbranch_scc1 .LBB0_3342
	v_and_b32_e32 v21, 63, v1
	v_mov_b32_e32 v91, 0
	v_lshlrev_b32_e32 v90, 4, v21
	s_waitcnt lgkmcnt(0)
	v_lshl_add_u64 v[2:3], v[2:3], 0, v[90:91]
	s_movk_i32 s7, 0x3000
	v_add_co_u32_e32 v18, vcc, s7, v2
	v_mbcnt_lo_u32_b32 v1, -1, 0
	s_nop 0
	v_addc_co_u32_e32 v19, vcc, 0, v3, vcc
	global_load_dwordx4 v[2:5], v[18:19], off
	global_load_dwordx4 v[6:9], v[18:19], off offset:1024
	global_load_dwordx4 v[10:13], v[18:19], off offset:2048
	global_load_dwordx4 v[14:17], v[18:19], off offset:3072
	v_mbcnt_hi_u32_b32 v18, -1, v1
	v_and_b32_e32 v1, 64, v18
	v_add_u32_e32 v19, 64, v1
	v_xor_b32_e32 v1, 1, v18
	v_cmp_lt_i32_e32 vcc, v1, v19
	v_xor_b32_e32 v20, 2, v18
	s_lshl_b32 s7, s31, 8
	v_cndmask_b32_e32 v1, v18, v1, vcc
	v_cmp_lt_i32_e32 vcc, v20, v19
	s_lshl_b32 s8, s30, 6
	s_add_i32 s8, s7, s8
	v_cndmask_b32_e32 v20, v18, v20, vcc
	v_lshlrev_b32_e32 v148, 2, v20
	v_xor_b32_e32 v20, 4, v18
	v_cmp_lt_i32_e32 vcc, v20, v19
	s_lshl_b32 s9, s6, 2
	s_add_i32 s6, s9, s8
	v_cndmask_b32_e32 v20, v18, v20, vcc
	v_lshlrev_b32_e32 v149, 2, v20
	v_xor_b32_e32 v20, 8, v18
	v_cmp_lt_i32_e32 vcc, v20, v19
	s_or_b32 s24, s8, 32
	s_lshl_b32 s8, s29, 6
	v_cndmask_b32_e32 v20, v18, v20, vcc
	v_lshlrev_b32_e32 v150, 2, v20
	v_xor_b32_e32 v20, 16, v18
	v_cmp_lt_i32_e32 vcc, v20, v19
	s_add_i32 s7, s7, s8
	s_add_i32 s7, s7, s9
	v_cndmask_b32_e32 v20, v18, v20, vcc
	v_lshlrev_b32_e32 v151, 2, v20
	v_xor_b32_e32 v20, 32, v18
	v_cmp_lt_i32_e32 vcc, v20, v19
	s_lshl_b32 s8, s28, 6
	s_sub_i32 s7, s7, s8
	v_cndmask_b32_e32 v18, v18, v20, vcc
	v_lshlrev_b32_e32 v152, 2, v18
	v_lshlrev_b32_e32 v18, 2, v21
	s_sub_i32 s8, s7, 32
	s_ashr_i32 s7, s6, 31
	v_or_b32_e32 v20, 0x100, v18
	v_or_b32_e32 v22, 0x200, v18
	v_or_b32_e32 v24, 0x300, v18
	s_lshl_b64 s[10:11], s[6:7], 11
	s_lshl_b64 s[6:7], s[6:7], 12
	v_lshlrev_b32_e32 v1, 2, v1
	v_lshl_or_b32 v92, v21, 3, s10
	v_mov_b32_e32 v93, s11
	v_or_b32_e32 v94, s6, v90
	v_mov_b32_e32 v95, s7
	v_mov_b32_e32 v153, 0x358637bd
	s_mov_b32 s25, 0xf800000
	v_mov_b32_e32 v154, 0x260
	v_lshlrev_b32_e32 v90, 2, v18
	s_movk_i32 s26, 0x7fff
	s_mov_b32 s27, 0xffff0000
	s_mov_b32 s28, 0xba00000
	v_lshlrev_b32_e32 v96, 2, v20
	v_lshlrev_b32_e32 v98, 2, v22
	v_mov_b32_e32 v99, v91
	v_lshlrev_b32_e32 v100, 2, v24
	v_mov_b32_e32 v101, v91
	s_mov_b32 s29, 0xba01000
	s_mov_b64 s[16:17], 0x10000
	s_mov_b64 s[18:19], 0x20000
	v_mov_b32_e32 v97, v91

.LBB0_3447:
	s_or_b64 exec, exec, s[6:7]
	v_mov_b32_e32 v1, v0
	v_mov_b64_e32 v[2:3], s[0:1]
	s_barrier
	global_load_dwordx2 v[2:3], v[2:3], off offset:88
	s_waitcnt vmcnt(0)
	v_readfirstlane_b32 s5, v1
	s_ashr_i32 s5, s5, 6
	s_cmp_gt_i32 s5, 7
	v_and_b32_e32 v131, 63, v1
	s_cbranch_scc1 .LBB0_3450
	v_mov_b32_e32 v91, 0
	v_lshlrev_b32_e32 v90, 4, v131
	s_waitcnt lgkmcnt(0)
	v_lshl_add_u64 v[2:3], v[2:3], 0, v[90:91]
	s_movk_i32 s6, 0x4000
	v_add_co_u32_e32 v18, vcc, s6, v2
	s_lshl_b32 s6, s40, 5
	s_nop 0
	v_addc_co_u32_e32 v19, vcc, 0, v3, vcc
	global_load_dwordx4 v[2:5], v[18:19], off
	global_load_dwordx4 v[6:9], v[18:19], off offset:1024
	global_load_dwordx4 v[10:13], v[18:19], off offset:2048
	global_load_dwordx4 v[14:17], v[18:19], off offset:3072
	v_mbcnt_lo_u32_b32 v18, -1, 0
	v_mbcnt_hi_u32_b32 v18, -1, v18
	v_and_b32_e32 v19, 64, v18
	v_add_u32_e32 v19, 64, v19
	v_xor_b32_e32 v20, 1, v18
	v_cmp_lt_i32_e32 vcc, v20, v19
	s_lshl_b32 s7, s5, 2
	s_add_i32 s13, s6, 0x20a0
	v_cndmask_b32_e32 v20, v18, v20, vcc
	v_lshlrev_b32_e32 v133, 2, v20
	v_xor_b32_e32 v20, 2, v18
	v_cmp_lt_i32_e32 vcc, v20, v19
	s_add_i32 s6, s6, s7
	s_add_i32 s20, s6, 0x2080
	v_cndmask_b32_e32 v20, v18, v20, vcc
	v_lshlrev_b32_e32 v152, 2, v20
	v_xor_b32_e32 v20, 4, v18
	v_cmp_lt_i32_e32 vcc, v20, v19
	s_add_u32 s26, s38, 0x5803000
	s_addc_u32 s27, s39, 0
	v_cndmask_b32_e32 v20, v18, v20, vcc
	v_lshlrev_b32_e32 v153, 2, v20
	v_xor_b32_e32 v20, 8, v18
	v_cmp_lt_i32_e32 vcc, v20, v19
	s_ashr_i32 s21, s20, 31
	s_lshl_b64 s[6:7], s[20:21], 11
	v_cndmask_b32_e32 v20, v18, v20, vcc
	v_lshlrev_b32_e32 v154, 2, v20
	v_xor_b32_e32 v20, 16, v18
	v_cmp_lt_i32_e32 vcc, v20, v19
	v_lshl_or_b32 v92, v131, 3, s6
	v_mov_b32_e32 v93, s7
	v_cndmask_b32_e32 v20, v18, v20, vcc
	v_lshlrev_b32_e32 v155, 2, v20
	v_xor_b32_e32 v20, 32, v18
	v_cmp_lt_i32_e32 vcc, v20, v19
	s_lshl_b64 s[6:7], s[20:21], 12
	v_or_b32_e32 v94, s6, v90
	v_cndmask_b32_e32 v18, v18, v20, vcc
	v_lshlrev_b32_e32 v156, 2, v18
	v_lshlrev_b32_e32 v18, 2, v131
	v_or_b32_e32 v20, 0x100, v18
	v_or_b32_e32 v22, 0x200, v18
	v_or_b32_e32 v24, 0x300, v18
	v_mov_b32_e32 v95, s7
	v_mov_b32_e32 v157, 0x358637bd
	s_mov_b32 s21, 0xf800000
	v_mov_b32_e32 v158, 0x260
	v_lshlrev_b32_e32 v90, 2, v18
	s_movk_i32 s28, 0x7fff
	s_mov_b32 s29, 0xffff0000
	s_mov_b32 s30, 0xba00000
	v_lshlrev_b32_e32 v96, 2, v20
	v_mov_b32_e32 v97, v91
	v_lshlrev_b32_e32 v98, 2, v22
	v_mov_b32_e32 v99, v91
	v_lshlrev_b32_e32 v100, 2, v24
	v_mov_b32_e32 v101, v91
	s_mov_b32 s31, 0xba01000
	s_mov_b64 s[22:23], 0x10000
	s_mov_b64 s[24:25], 0x20000

.LBB0_3609:
	s_or_b64 exec, exec, s[10:11]
	v_mov_b32_e32 v130, v0
	v_mov_b64_e32 v[2:3], s[0:1]
	s_barrier
	global_load_dwordx2 v[2:3], v[2:3], off offset:88
	s_waitcnt vmcnt(0)
	v_readfirstlane_b32 s6, v130
	s_ashr_i32 s96, s6, 6
	s_add_i32 s12, s96, s2
	s_cmp_gt_i32 s96, 15
	v_and_b32_e32 v132, 63, v130
	s_cbranch_scc1 .LBB0_3612
	v_mov_b32_e32 v91, 0
	v_lshlrev_b32_e32 v90, 4, v132
	s_waitcnt lgkmcnt(0)
	v_lshl_add_u64 v[2:3], v[2:3], 0, v[90:91]
	s_movk_i32 s2, 0x4000
	v_add_co_u32_e32 v18, vcc, s2, v2
	v_mbcnt_lo_u32_b32 v1, -1, 0
	s_nop 0
	v_addc_co_u32_e32 v19, vcc, 0, v3, vcc
	global_load_dwordx4 v[2:5], v[18:19], off
	global_load_dwordx4 v[6:9], v[18:19], off offset:1024
	global_load_dwordx4 v[10:13], v[18:19], off offset:2048
	global_load_dwordx4 v[14:17], v[18:19], off offset:3072
	v_mbcnt_hi_u32_b32 v18, -1, v1
	v_and_b32_e32 v1, 64, v18
	v_add_u32_e32 v19, 64, v1
	v_xor_b32_e32 v1, 1, v18
	v_cmp_lt_i32_e32 vcc, v1, v19
	v_xor_b32_e32 v20, 2, v18
	s_lshl_b32 s7, s26, 8
	v_cndmask_b32_e32 v1, v18, v1, vcc
	v_cmp_lt_i32_e32 vcc, v20, v19
	s_lshl_b32 s2, s5, 6
	s_add_i32 s8, s7, s2
	v_cndmask_b32_e32 v20, v18, v20, vcc
	v_lshlrev_b32_e32 v131, 2, v20
	v_xor_b32_e32 v20, 4, v18
	v_cmp_lt_i32_e32 vcc, v20, v19
	s_lshl_b32 s9, s96, 2
	s_add_i32 s6, s9, s8
	v_cndmask_b32_e32 v20, v18, v20, vcc
	v_lshlrev_b32_e32 v133, 2, v20
	v_xor_b32_e32 v20, 8, v18
	v_cmp_lt_i32_e32 vcc, v20, v19
	s_add_u32 s2, s38, 0x5803000
	s_addc_u32 s5, s39, 0
	v_cndmask_b32_e32 v20, v18, v20, vcc
	v_lshlrev_b32_e32 v152, 2, v20
	v_xor_b32_e32 v20, 16, v18
	v_cmp_lt_i32_e32 vcc, v20, v19
	s_lshl_b32 s4, s4, 6
	s_add_i32 s4, s7, s4
	v_cndmask_b32_e32 v20, v18, v20, vcc
	v_lshlrev_b32_e32 v153, 2, v20
	v_xor_b32_e32 v20, 32, v18
	v_cmp_lt_i32_e32 vcc, v20, v19
	s_add_i32 s4, s4, s9
	s_lshl_b32 s3, s3, 6
	v_cndmask_b32_e32 v18, v18, v20, vcc
	v_lshlrev_b32_e32 v154, 2, v18
	v_lshlrev_b32_e32 v18, 2, v132
	s_ashr_i32 s7, s6, 31
	v_or_b32_e32 v20, 0x100, v18
	v_or_b32_e32 v22, 0x200, v18
	v_or_b32_e32 v24, 0x300, v18
	s_sub_i32 s3, s4, s3
	s_lshl_b64 s[10:11], s[6:7], 11
	s_lshl_b64 s[6:7], s[6:7], 12
	v_lshlrev_b32_e32 v1, 2, v1
	s_or_b32 s13, s8, 32
	s_sub_i32 s8, s3, 32
	v_lshl_or_b32 v92, v132, 3, s10
	v_mov_b32_e32 v93, s11
	v_or_b32_e32 v94, s6, v90
	v_mov_b32_e32 v95, s7
	v_mov_b32_e32 v155, 0x358637bd
	s_mov_b32 s3, 0xf800000
	v_mov_b32_e32 v156, 0x260
	v_lshlrev_b32_e32 v90, 2, v18
	s_movk_i32 s4, 0x7fff
	s_mov_b32 s22, 0xffff0000
	s_mov_b32 s23, 0xba00000
	v_lshlrev_b32_e32 v96, 2, v20
	v_mov_b32_e32 v97, v91
	v_lshlrev_b32_e32 v98, 2, v22
	v_mov_b32_e32 v99, v91
	v_lshlrev_b32_e32 v100, 2, v24
	v_mov_b32_e32 v101, v91
	s_mov_b32 s24, 0xba01000
	s_mov_b64 s[14:15], 0x10000
	s_mov_b64 s[18:19], 0x20000

.LBB0_4198:
	v_mov_b32_e32 v180, v0
	s_mov_b64 s[6:7], -1
	v_readfirstlane_b32 s22, v180
	s_ashr_i32 s10, s22, 6
	v_and_b32_e32 v182, 63, v180
	s_cmp_eq_u32 s2, s33
	s_cbranch_scc1 .LBB0_4204
	s_waitcnt lgkmcnt(0)
	v_mov_b64_e32 v[2:3], s[0:1]
	global_load_dwordx2 v[4:5], v[2:3], off offset:64
	s_waitcnt vmcnt(0)
	global_load_dwordx2 v[8:9], v[2:3], off offset:32
	s_waitcnt vmcnt(0)
	v_ashrrev_i32_e32 v41, 5, v180
	v_lshlrev_b32_e32 v2, 14, v41
	v_and_b32_e32 v178, 0x1c000, v2
	s_mov_b32 s81, s57
	v_lshlrev_b32_e32 v40, 4, v180
	s_mov_b64 s[6:7], 0x14000000
	v_and_b32_e32 v6, 0xf0, v40
	v_mov_b32_e32 v7, v179
	s_lshl_b32 s2, s10, 5
	v_and_b32_e32 v203, 31, v180
	v_lshrrev_b32_e32 v181, 5, v182
	s_mov_b64 s[8:9], 0
	s_waitcnt lgkmcnt(0)
	v_lshl_add_u64 v[24:25], s[54:55], 2, v[4:5]
	v_lshl_add_u64 v[2:3], v[8:9], 0, v[178:179]
	v_lshl_add_u64 v[4:5], v[2:3], 0, s[80:81]
	v_and_b32_e32 v2, 0x100, v40
	v_mov_b32_e32 v3, v179
	v_lshl_add_u64 v[4:5], v[4:5], 0, v[2:3]
	v_lshl_add_u64 v[10:11], v[4:5], 0, s[6:7]
	v_ashrrev_i32_e32 v4, 8, v180
	v_ashrrev_i32_e32 v5, 31, v4
	v_lshl_add_u64 v[4:5], v[4:5], 2, v[24:25]
	global_load_dword v4, v[4:5], off
	v_add_u32_e32 v3, 16, v41
	s_and_b32 s6, s2, 0xffffffc0
	s_lshl_b32 s2, s10, 7
	s_and_b32 s11, s2, 0x80
	s_mov_b32 s2, 0x20000
	v_lshl_add_u64 v[8:9], v[8:9], 0, s[76:77]
	s_waitcnt vmcnt(0)
	v_ashrrev_i32_e32 v5, 31, v4
	v_lshlrev_b64 v[4:5], 17, v[4:5]
	v_lshl_add_u64 v[12:13], v[10:11], 0, v[4:5]
	v_lshl_add_u64 v[18:19], v[12:13], 0, v[6:7]
	v_ashrrev_i32_e32 v12, 3, v3
	v_ashrrev_i32_e32 v13, 31, v12
	v_lshl_add_u64 v[12:13], v[12:13], 2, v[24:25]
	global_load_dword v12, v[12:13], off
	v_add_u32_e32 v3, 32, v41
	v_or_b32_e32 v4, v4, v178
	v_or3_b32 v4, v4, v2, v6
	v_lshl_add_u64 v[200:201], v[8:9], 0, v[4:5]
	s_waitcnt vmcnt(0)
	v_ashrrev_i32_e32 v13, 31, v12
	v_lshlrev_b64 v[12:13], 17, v[12:13]
	v_lshl_add_u64 v[14:15], v[10:11], 0, v[12:13]
	v_lshl_add_u64 v[22:23], v[14:15], 0, v[6:7]
	v_ashrrev_i32_e32 v14, 3, v3
	v_ashrrev_i32_e32 v15, 31, v14
	v_lshl_add_u64 v[14:15], v[14:15], 2, v[24:25]
	global_load_dword v14, v[14:15], off
	v_add_u32_e32 v3, 48, v41
	v_or_b32_e32 v12, v12, v178
	v_or3_b32 v12, v12, v2, v6
	v_lshl_add_u64 v[198:199], v[8:9], 0, v[12:13]
	s_waitcnt vmcnt(0)
	v_ashrrev_i32_e32 v15, 31, v14
	v_lshlrev_b64 v[14:15], 17, v[14:15]
	v_lshl_add_u64 v[16:17], v[10:11], 0, v[14:15]
	v_lshl_add_u64 v[28:29], v[16:17], 0, v[6:7]
	v_ashrrev_i32_e32 v16, 3, v3
	v_ashrrev_i32_e32 v17, 31, v16
	v_lshl_add_u64 v[16:17], v[16:17], 2, v[24:25]
	global_load_dword v16, v[16:17], off
	v_add_u32_e32 v3, 64, v41
	v_or_b32_e32 v14, v14, v178
	v_or3_b32 v14, v14, v2, v6
	v_lshl_add_u64 v[196:197], v[8:9], 0, v[14:15]
	s_waitcnt vmcnt(0)
	v_ashrrev_i32_e32 v17, 31, v16
	v_lshlrev_b64 v[16:17], 17, v[16:17]
	v_lshl_add_u64 v[20:21], v[10:11], 0, v[16:17]
	v_lshl_add_u64 v[32:33], v[20:21], 0, v[6:7]
	v_ashrrev_i32_e32 v20, 3, v3
	v_ashrrev_i32_e32 v21, 31, v20
	v_lshl_add_u64 v[20:21], v[20:21], 2, v[24:25]
	global_load_dword v20, v[20:21], off
	v_add_u32_e32 v3, 0x50, v41
	v_or_b32_e32 v16, v16, v178
	v_or3_b32 v16, v16, v2, v6
	v_lshl_add_u64 v[194:195], v[8:9], 0, v[16:17]
	s_waitcnt vmcnt(0)
	v_ashrrev_i32_e32 v21, 31, v20
	v_lshlrev_b64 v[20:21], 17, v[20:21]
	v_lshl_add_u64 v[26:27], v[10:11], 0, v[20:21]
	v_lshl_add_u64 v[34:35], v[26:27], 0, v[6:7]
	v_ashrrev_i32_e32 v26, 3, v3
	v_ashrrev_i32_e32 v27, 31, v26
	v_lshl_add_u64 v[26:27], v[26:27], 2, v[24:25]
	global_load_dword v26, v[26:27], off
	v_add_u32_e32 v3, 0x60, v41
	v_or_b32_e32 v20, v20, v178
	v_or3_b32 v20, v20, v2, v6
	v_lshl_add_u64 v[192:193], v[8:9], 0, v[20:21]
	s_waitcnt vmcnt(0)
	v_ashrrev_i32_e32 v27, 31, v26
	v_lshlrev_b64 v[26:27], 17, v[26:27]
	v_lshl_add_u64 v[30:31], v[10:11], 0, v[26:27]
	v_lshl_add_u64 v[36:37], v[30:31], 0, v[6:7]
	v_ashrrev_i32_e32 v30, 3, v3
	v_add_u32_e32 v3, 0x70, v41
	v_ashrrev_i32_e32 v42, 3, v3
	v_ashrrev_i32_e32 v31, 31, v30
	v_ashrrev_i32_e32 v43, 31, v42
	v_lshl_add_u64 v[30:31], v[30:31], 2, v[24:25]
	v_lshl_add_u64 v[24:25], v[42:43], 2, v[24:25]
	global_load_dword v30, v[30:31], off
	v_lshrrev_b32_e32 v3, 4, v180
	global_load_dword v24, v[24:25], off
	v_mul_lo_u32 v41, v3, s48
	v_lshlrev_b32_e32 v3, 3, v180
	v_and_b32_e32 v3, 0x78, v3
	s_waitcnt vmcnt(1)
	v_ashrrev_i32_e32 v31, 31, v30
	v_lshlrev_b64 v[30:31], 17, v[30:31]
	s_waitcnt vmcnt(0)
	v_ashrrev_i32_e32 v25, 31, v24
	v_lshlrev_b64 v[24:25], 17, v[24:25]
	v_lshl_add_u64 v[38:39], v[10:11], 0, v[30:31]
	v_lshl_add_u64 v[10:11], v[10:11], 0, v[24:25]
	v_lshl_add_u64 v[42:43], v[10:11], 0, v[6:7]
	v_ashrrev_i32_e32 v10, 3, v180
	v_ashrrev_i32_e32 v11, 31, v10
	v_lshlrev_b64 v[44:45], 11, v[10:11]
	v_mul_lo_u32 v48, v10, s48
	v_and_b32_e32 v10, 0x70, v40
	v_or_b32_e32 v11, s11, v203
	v_mov_b32_e32 v40, s94
	v_lshl_add_u64 v[46:47], s[58:59], 0, v[44:45]
	v_mad_u32_u24 v40, v11, s48, v40
	v_mov_b32_e32 v11, v179
	v_lshl_add_u64 v[38:39], v[38:39], 0, v[6:7]
	global_load_dwordx4 v[130:133], v[18:19], off nt
	global_load_dwordx4 v[134:137], v[22:23], off nt
	global_load_dwordx4 v[138:141], v[28:29], off nt
	global_load_dwordx4 v[142:145], v[32:33], off nt
	global_load_dwordx4 v[146:149], v[34:35], off nt
	global_load_dwordx4 v[150:153], v[36:37], off nt
	global_load_dwordx4 v[154:157], v[38:39], off nt
	global_load_dwordx4 v[158:161], v[42:43], off nt
	v_lshl_add_u64 v[22:23], v[46:47], 0, v[10:11]
	v_add_co_u32_e32 v28, vcc, s2, v22
	s_mov_b32 s2, 0x40000
	s_nop 0
	v_addc_co_u32_e32 v29, vcc, 0, v23, vcc
	global_load_dwordx4 v[162:165], v[22:23], off
	global_load_dwordx4 v[166:169], v[28:29], off
	v_add_co_u32_e32 v28, vcc, s2, v22
	s_mov_b32 s2, 0x60000
	s_nop 0
	v_addc_co_u32_e32 v29, vcc, 0, v23, vcc
	v_add_co_u32_e32 v22, vcc, s2, v22
	global_load_dwordx4 v[170:173], v[28:29], off
	s_nop 0
	v_addc_co_u32_e32 v23, vcc, 0, v23, vcc
	global_load_dwordx4 v[174:177], v[22:23], off
	v_or_b32_e32 v22, v24, v178
	v_or_b32_e32 v7, s6, v203
	v_or3_b32 v24, v22, v2, v6
	v_or_b32_e32 v22, v30, v178
	v_mul_lo_u32 v49, v7, s48
	v_or3_b32 v30, v22, v2, v6
	v_or_b32_e32 v22, v26, v178
	v_lshlrev_b32_e32 v7, 4, v181
	v_add_u32_e32 v11, s94, v41
	v_add_u32_e32 v18, s94, v48
	v_add_u32_e32 v19, s94, v49
	v_or_b32_e32 v44, v44, v10
	v_or3_b32 v26, v22, v2, v6
	v_mov_b32_e32 v2, 0
	v_lshl_add_u64 v[184:185], s[74:75], 0, v[44:45]
	v_lshl_add_u64 v[186:187], v[8:9], 0, v[24:25]
	v_lshl_add_u64 v[188:189], v[8:9], 0, v[30:31]
	v_lshl_add_u64 v[190:191], v[8:9], 0, v[26:27]
	v_add_u32_e32 v178, v11, v3
	v_add_u32_e32 v204, v18, v10
	v_add_u32_e32 v205, v19, v7
	v_add_u32_e32 v206, v40, v7
	v_mov_b32_e32 v3, v2
	v_mov_b32_e32 v4, v2
	v_mov_b32_e32 v5, v2
	v_mov_b32_e32 v6, v2
	v_mov_b32_e32 v7, v2
	v_mov_b32_e32 v8, v2
	v_mov_b32_e32 v9, v2
	v_mov_b32_e32 v10, v2
	v_mov_b32_e32 v11, v2
	v_mov_b32_e32 v12, v2
	v_mov_b32_e32 v13, v2
	v_mov_b32_e32 v14, v2
	v_mov_b32_e32 v15, v2
	v_mov_b32_e32 v16, v2
	v_mov_b32_e32 v17, v2
	v_mov_b32_e32 v18, v2
	v_mov_b32_e32 v19, v2
	v_mov_b32_e32 v20, v2
	v_mov_b32_e32 v21, v2
	v_mov_b32_e32 v22, v2
	v_mov_b32_e32 v23, v2
	v_mov_b32_e32 v24, v2
	v_mov_b32_e32 v25, v2
	v_mov_b32_e32 v26, v2
	v_mov_b32_e32 v27, v2
	v_mov_b32_e32 v28, v2
	v_mov_b32_e32 v29, v2
	v_mov_b32_e32 v30, v2
	v_mov_b32_e32 v31, v2
	v_mov_b32_e32 v32, v2
	v_mov_b32_e32 v33, v2
	v_mov_b32_e32 v34, v2
	v_mov_b32_e32 v35, v2
	v_mov_b32_e32 v36, v2
	v_mov_b32_e32 v37, v2
	v_mov_b32_e32 v38, v2
	v_mov_b32_e32 v39, v2
	v_mov_b32_e32 v40, v2
	v_mov_b32_e32 v41, v2
	v_mov_b32_e32 v42, v2
	v_mov_b32_e32 v43, v2
	v_mov_b32_e32 v44, v2
	v_mov_b32_e32 v45, v2
	v_mov_b32_e32 v46, v2
	v_mov_b32_e32 v47, v2
	v_mov_b32_e32 v48, v2
	v_mov_b32_e32 v49, v2
	v_mov_b32_e32 v50, v2
	v_mov_b32_e32 v51, v2
	v_mov_b32_e32 v52, v2
	v_mov_b32_e32 v53, v2
	v_mov_b32_e32 v54, v2
	v_mov_b32_e32 v55, v2
	v_mov_b32_e32 v56, v2
	v_mov_b32_e32 v57, v2
	v_mov_b32_e32 v58, v2
	v_mov_b32_e32 v59, v2
	v_mov_b32_e32 v60, v2
	v_mov_b32_e32 v61, v2
	v_mov_b32_e32 v62, v2
	v_mov_b32_e32 v63, v2
	v_mov_b32_e32 v64, v2
	v_mov_b32_e32 v65, v2
	v_mov_b32_e32 v66, v2
	v_mov_b32_e32 v67, v2
	v_mov_b32_e32 v68, v2
	v_mov_b32_e32 v69, v2
	v_mov_b32_e32 v70, v2
	v_mov_b32_e32 v71, v2
	v_mov_b32_e32 v72, v2
	v_mov_b32_e32 v73, v2
	v_mov_b32_e32 v74, v2
	v_mov_b32_e32 v75, v2
	v_mov_b32_e32 v76, v2
	v_mov_b32_e32 v77, v2
	v_mov_b32_e32 v78, v2
	v_mov_b32_e32 v79, v2
	v_mov_b32_e32 v80, v2
	v_mov_b32_e32 v81, v2
	v_mov_b32_e32 v82, v2
	v_mov_b32_e32 v83, v2
	v_mov_b32_e32 v84, v2
	v_mov_b32_e32 v85, v2
	v_mov_b32_e32 v86, v2
	v_mov_b32_e32 v87, v2
	v_mov_b32_e32 v88, v2
	v_mov_b32_e32 v89, v2
	v_mov_b32_e32 v90, v2
	v_mov_b32_e32 v91, v2
	v_mov_b32_e32 v92, v2
	v_mov_b32_e32 v93, v2
	v_mov_b32_e32 v94, v2
	v_mov_b32_e32 v95, v2
	v_mov_b32_e32 v96, v2
	v_mov_b32_e32 v97, v2
	v_mov_b32_e32 v98, v2
	v_mov_b32_e32 v99, v2
	v_mov_b32_e32 v100, v2
	v_mov_b32_e32 v101, v2
	v_mov_b32_e32 v102, v2
	v_mov_b32_e32 v103, v2
	v_mov_b32_e32 v104, v2
	v_mov_b32_e32 v105, v2
	v_mov_b32_e32 v106, v2
	v_mov_b32_e32 v107, v2
	v_mov_b32_e32 v108, v2
	v_mov_b32_e32 v109, v2
	v_mov_b32_e32 v110, v2
	v_mov_b32_e32 v111, v2
	v_mov_b32_e32 v112, v2
	v_mov_b32_e32 v113, v2
	v_mov_b32_e32 v114, v2
	v_mov_b32_e32 v115, v2
	v_mov_b32_e32 v116, v2
	v_mov_b32_e32 v117, v2
	v_mov_b32_e32 v118, v2
	v_mov_b32_e32 v119, v2
	v_mov_b32_e32 v120, v2
	v_mov_b32_e32 v121, v2
	v_mov_b32_e32 v122, v2
	v_mov_b32_e32 v123, v2
	v_mov_b32_e32 v124, v2
	v_mov_b32_e32 v125, v2
	v_mov_b32_e32 v126, v2
	v_mov_b32_e32 v127, v2
	v_mov_b32_e32 v128, v2
	v_mov_b32_e32 v129, v2
	s_branch .LBB0_4201

.LBB0_4209:
	s_lshl_b32 s24, s86, 4
	s_lshl_b32 s25, s86, 6
	s_and_b32 s24, s24, 0xffffe000
	s_and_b32 s25, s25, 0x1fc0
	s_or_b32 s87, s24, s25
	s_bfe_u32 s88, s86, 0x20007
	s_lshl_b32 s91, s88, 6
	s_load_dwordx2 s[98:99], s[0:1], 0x98
	s_load_dwordx2 s[100:101], s[0:1], 0xa0
	v_lshlrev_b32_e32 v178, 2, v182
	v_ashrrev_i32_e32 v150, 4, v180
	v_add_u32_e32 v152, s87, v150
	v_mad_i64_i32 v[152:153], vcc, v152, s62, v[22:23]
	global_load_dword v170, v[152:153], off
	v_add_u32_e32 v151, 0x200, v180
	v_ashrrev_i32_e32 v151, 4, v151
	v_add_u32_e32 v154, s87, v151
	v_mad_i64_i32 v[154:155], vcc, v154, s62, v[22:23]
	global_load_dword v171, v[154:155], off
	v_lshl_add_u32 v174, v150, 2, v59
	v_lshl_add_u32 v175, v151, 2, v59
	s_waitcnt lgkmcnt(0)
	s_lshl_b32 s56, s91, 2
	v_and_b32_e32 v156, 0xffffff00, v43
	v_ashrrev_i32_e32 v157, 31, v156
	v_lshl_add_u64 v[158:159], v[156:157], 2, s[98:99]
	v_lshl_add_u64 v[158:159], v[158:159], 0, s[56:57]
	v_lshl_add_u64 v[158:159], v[158:159], 0, v[178:179]
	s_mov_b32 s24, 0x4000
	s_mov_b32 s25, 0
	v_lshl_add_u64 v[158:159], v[158:159], 0, s[24:25]
	global_load_dword v172, v[158:159], off
	v_add_u32_e32 v176, s4, v43
	v_add_u32_e32 v160, 0x800, v43
	v_and_b32_e32 v156, 0xffffff00, v160
	v_ashrrev_i32_e32 v157, 31, v156
	v_lshl_add_u64 v[162:163], v[156:157], 2, s[98:99]
	v_lshl_add_u64 v[162:163], v[162:163], 0, s[56:57]
	v_lshl_add_u64 v[162:163], v[162:163], 0, v[178:179]
	v_lshl_add_u64 v[162:163], v[162:163], 0, s[24:25]
	global_load_dword v173, v[162:163], off
	v_add_u32_e32 v177, s4, v160
	v_ashrrev_i32_e32 v90, 6, v180
	v_add_u32_e32 v164, s91, v90
	v_ashrrev_i32_e32 v165, 31, v164
	v_lshl_add_u64 v[166:167], v[164:165], 2, s[100:101]
	global_load_dword v132, v[166:167], off offset:1024
	v_add_u32_e32 v164, 0x200, v180
	v_ashrrev_i32_e32 v91, 6, v164
	v_add_u32_e32 v164, s91, v91
	v_ashrrev_i32_e32 v165, 31, v164
	v_lshl_add_u64 v[166:167], v[164:165], 2, s[100:101]
	global_load_dword v133, v[166:167], off offset:1024
	v_add_u32_e32 v164, 0x400, v180
	v_ashrrev_i32_e32 v92, 6, v164
	v_add_u32_e32 v164, s91, v92
	v_ashrrev_i32_e32 v165, 31, v164
	v_lshl_add_u64 v[166:167], v[164:165], 2, s[100:101]
	global_load_dword v134, v[166:167], off offset:1024
	v_add_u32_e32 v164, 0x600, v180
	v_ashrrev_i32_e32 v93, 6, v164
	v_add_u32_e32 v164, s91, v93
	v_ashrrev_i32_e32 v165, 31, v164
	v_lshl_add_u64 v[166:167], v[164:165], 2, s[100:101]
	global_load_dword v135, v[166:167], off offset:1024
	v_add_u32_e32 v164, 0x800, v180
	v_ashrrev_i32_e32 v94, 6, v164
	v_add_u32_e32 v164, s91, v94
	v_ashrrev_i32_e32 v165, 31, v164
	v_lshl_add_u64 v[166:167], v[164:165], 2, s[100:101]
	global_load_dword v136, v[166:167], off offset:1024
	v_add_u32_e32 v164, 0xa00, v180
	v_ashrrev_i32_e32 v95, 6, v164
	v_add_u32_e32 v164, s91, v95
	v_ashrrev_i32_e32 v165, 31, v164
	v_lshl_add_u64 v[166:167], v[164:165], 2, s[100:101]
	global_load_dword v137, v[166:167], off offset:1024
	v_add_u32_e32 v164, 0xc00, v180
	v_ashrrev_i32_e32 v96, 6, v164
	v_add_u32_e32 v164, s91, v96
	v_ashrrev_i32_e32 v165, 31, v164
	v_lshl_add_u64 v[166:167], v[164:165], 2, s[100:101]
	global_load_dword v138, v[166:167], off offset:1024
	v_add_u32_e32 v164, 0xe00, v180
	v_ashrrev_i32_e32 v97, 6, v164
	v_add_u32_e32 v164, s91, v97
	v_ashrrev_i32_e32 v165, 31, v164
	v_lshl_add_u64 v[166:167], v[164:165], 2, s[100:101]
	global_load_dword v139, v[166:167], off offset:1024
	s_lshl_b32 s24, s86, 4
	s_lshl_b32 s25, s86, 6
	s_and_b32 s24, s24, 0xffffe000
	s_and_b32 s25, s25, 0x1fc0
	s_or_b32 s87, s24, s25
	s_bfe_u32 s88, s86, 0x20007
	v_add_u32_e32 v2, s87, v35
	v_mov_b64_e32 v[10:11], s[46:47]
	v_mad_i64_i32 v[2:3], s[24:25], v2, s62, v[10:11]
	s_lshl_b32 s56, s88, 8
	v_lshl_add_u64 v[2:3], v[2:3], 0, s[56:57]
	v_lshlrev_b32_e32 v178, 2, v182
	v_add_u32_e32 v4, s87, v36
	v_lshl_add_u64 v[2:3], v[2:3], 0, v[178:179]
	v_mad_i64_i32 v[4:5], s[24:25], v4, s62, v[10:11]
	v_add_co_u32_e32 v2, vcc, s30, v2
	v_lshl_add_u64 v[4:5], v[4:5], 0, s[56:57]
	v_add_u32_e32 v6, s87, v37
	v_addc_co_u32_e32 v3, vcc, 0, v3, vcc
	v_lshl_add_u64 v[4:5], v[4:5], 0, v[178:179]
	v_mad_i64_i32 v[6:7], s[24:25], v6, s62, v[10:11]
	v_add_co_u32_e32 v4, vcc, s30, v4
	v_lshl_add_u64 v[6:7], v[6:7], 0, s[56:57]
	v_add_u32_e32 v8, s87, v38
	v_addc_co_u32_e32 v5, vcc, 0, v5, vcc
	v_lshl_add_u64 v[6:7], v[6:7], 0, v[178:179]
	v_mad_i64_i32 v[8:9], s[24:25], v8, s62, v[10:11]
	v_add_co_u32_e32 v6, vcc, s30, v6
	v_lshl_add_u64 v[8:9], v[8:9], 0, s[56:57]
	v_add_u32_e32 v12, s87, v39
	v_addc_co_u32_e32 v7, vcc, 0, v7, vcc
	v_lshl_add_u64 v[8:9], v[8:9], 0, v[178:179]
	v_mad_i64_i32 v[12:13], s[24:25], v12, s62, v[10:11]
	v_add_co_u32_e32 v8, vcc, s30, v8
	v_lshl_add_u64 v[12:13], v[12:13], 0, s[56:57]
	v_add_u32_e32 v14, s87, v40
	v_addc_co_u32_e32 v9, vcc, 0, v9, vcc
	v_lshl_add_u64 v[12:13], v[12:13], 0, v[178:179]
	v_mad_i64_i32 v[14:15], s[24:25], v14, s62, v[10:11]
	v_add_co_u32_e32 v12, vcc, s30, v12
	v_lshl_add_u64 v[14:15], v[14:15], 0, s[56:57]
	v_add_u32_e32 v16, s87, v41
	v_addc_co_u32_e32 v13, vcc, 0, v13, vcc
	v_lshl_add_u64 v[14:15], v[14:15], 0, v[178:179]
	v_mad_i64_i32 v[16:17], s[24:25], v16, s62, v[10:11]
	v_add_co_u32_e32 v14, vcc, s30, v14
	v_lshl_add_u64 v[16:17], v[16:17], 0, s[56:57]
	v_add_u32_e32 v29, s87, v42
	v_addc_co_u32_e32 v15, vcc, 0, v15, vcc
	v_lshl_add_u64 v[16:17], v[16:17], 0, v[178:179]
	v_mad_i64_i32 v[66:67], s[24:25], v29, s62, v[10:11]
	v_add_co_u32_e32 v16, vcc, s30, v16
	v_lshl_add_u64 v[66:67], v[66:67], 0, s[56:57]
	s_nop 0
	v_addc_co_u32_e32 v17, vcc, 0, v17, vcc
	v_lshl_add_u64 v[66:67], v[66:67], 0, v[178:179]
	v_add_co_u32_e32 v74, vcc, s30, v66
	s_lshl_b32 s56, s88, 9
	s_nop 0
	v_addc_co_u32_e32 v75, vcc, 0, v67, vcc
	global_load_dword v72, v[2:3], off offset:2144
	global_load_dword v71, v[4:5], off offset:2144
	global_load_dword v70, v[6:7], off offset:2144
	global_load_dword v69, v[8:9], off offset:2144
	global_load_dword v68, v[12:13], off offset:2144
	global_load_dword v67, v[14:15], off offset:2144
	global_load_dword v66, v[16:17], off offset:2144
	global_load_dword v65, v[74:75], off offset:2144
	v_add_u32_e32 v2, s87, v44
	v_mad_i64_i32 v[2:3], s[24:25], v2, s62, v[10:11]
	v_lshl_add_u64 v[2:3], v[2:3], 0, s[56:57]
	v_mov_b32_e32 v29, v179
	v_add_u32_e32 v4, s87, v45
	v_lshl_add_u64 v[2:3], v[2:3], 0, v[28:29]
	v_mad_i64_i32 v[4:5], s[24:25], v4, s62, v[10:11]
	v_add_co_u32_e32 v2, vcc, s30, v2
	v_lshl_add_u64 v[4:5], v[4:5], 0, s[56:57]
	v_add_u32_e32 v12, s87, v46
	v_addc_co_u32_e32 v3, vcc, 0, v3, vcc
	v_lshl_add_u64 v[4:5], v[4:5], 0, v[28:29]
	v_mad_i64_i32 v[12:13], s[24:25], v12, s62, v[10:11]
	v_add_co_u32_e32 v6, vcc, s30, v4
	v_lshl_add_u64 v[12:13], v[12:13], 0, s[56:57]
	v_add_u32_e32 v14, s87, v47
	v_addc_co_u32_e32 v7, vcc, 0, v5, vcc
	v_lshl_add_u64 v[12:13], v[12:13], 0, v[28:29]
	v_mad_i64_i32 v[10:11], s[24:25], v14, s62, v[10:11]
	v_add_co_u32_e32 v12, vcc, s30, v12
	v_lshl_add_u64 v[10:11], v[10:11], 0, s[56:57]
	s_nop 0
	v_addc_co_u32_e32 v13, vcc, 0, v13, vcc
	v_lshl_add_u64 v[10:11], v[10:11], 0, v[28:29]
	v_add_co_u32_e32 v14, vcc, 0x1000, v10
	global_load_dwordx4 v[2:5], v[2:3], off offset:3168
	s_nop 0
	global_load_dwordx4 v[6:9], v[6:7], off offset:3168
	v_addc_co_u32_e32 v15, vcc, 0, v11, vcc
	global_load_dwordx4 v[10:13], v[12:13], off offset:3168
	s_nop 0
	global_load_dwordx4 v[14:17], v[14:15], off offset:3168
	s_lshl_b32 s88, s88, 6
	s_mov_b32 s89, s57
	s_waitcnt lgkmcnt(0)
	s_barrier
	s_waitcnt vmcnt(20)
	ds_write_b32 v174, v170
	ds_write_b32 v175, v171
	ds_write_b32 v176, v172
	ds_write_b32 v177, v173
	s_waitcnt lgkmcnt(0)
	s_barrier
	ds_read2st64_b32 v[100:101], v60 offset1:1
	ds_read2st64_b32 v[102:103], v60 offset0:2 offset1:3
	ds_read2st64_b32 v[104:105], v60 offset0:4 offset1:5
	ds_read2st64_b32 v[106:107], v60 offset0:6 offset1:7
	ds_read2st64_b32 v[108:109], v60 offset0:8 offset1:9
	ds_read2st64_b32 v[110:111], v60 offset0:10 offset1:11
	ds_read2st64_b32 v[112:113], v60 offset0:12 offset1:13
	ds_read2st64_b32 v[114:115], v60 offset0:14 offset1:15
	v_lshl_add_u32 v143, v90, 2, s4
	ds_read2st64_b32 v[116:117], v143 offset1:1
	ds_read2st64_b32 v[118:119], v143 offset0:2 offset1:3
	ds_read2st64_b32 v[120:121], v143 offset0:4 offset1:5
	ds_read2st64_b32 v[122:123], v143 offset0:6 offset1:7
	ds_read2st64_b32 v[124:125], v143 offset0:8 offset1:9
	ds_read2st64_b32 v[126:127], v143 offset0:10 offset1:11
	ds_read2st64_b32 v[128:129], v143 offset0:12 offset1:13
	ds_read2st64_b32 v[130:131], v143 offset0:14 offset1:15
	s_waitcnt vmcnt(12)
	s_waitcnt lgkmcnt(0)
	v_lshl_add_u32 v143, v91, 2, s4
	ds_read2st64_b32 v[204:205], v143 offset1:1
	ds_read2st64_b32 v[206:207], v143 offset0:2 offset1:3
	ds_read2st64_b32 v[208:209], v143 offset0:4 offset1:5
	ds_read2st64_b32 v[210:211], v143 offset0:6 offset1:7
	ds_read2st64_b32 v[212:213], v143 offset0:8 offset1:9
	ds_read2st64_b32 v[214:215], v143 offset0:10 offset1:11
	ds_read2st64_b32 v[216:217], v143 offset0:12 offset1:13
	ds_read2st64_b32 v[218:219], v143 offset0:14 offset1:15
	v_fmac_f32_e32 v132, v100, v116
	v_fmac_f32_e32 v132, v101, v117
	v_fmac_f32_e32 v132, v102, v118
	v_fmac_f32_e32 v132, v103, v119
	v_fmac_f32_e32 v132, v104, v120
	v_fmac_f32_e32 v132, v105, v121
	v_mul_f32_e32 v140, v106, v122
	v_mul_f32_e32 v141, v107, v123
	v_add_f32_e32 v132, v132, v140
	v_add_f32_e32 v132, v132, v141
	v_mul_f32_e32 v140, v108, v124
	v_mul_f32_e32 v141, v109, v125
	v_add_f32_e32 v132, v132, v140
	v_add_f32_e32 v132, v132, v141
	v_mul_f32_e32 v140, v110, v126
	v_mul_f32_e32 v141, v111, v127
	v_add_f32_e32 v132, v132, v140
	v_add_f32_e32 v132, v132, v141
	v_mul_f32_e32 v140, v112, v128
	v_mul_f32_e32 v141, v113, v129
	v_add_f32_e32 v132, v132, v140
	v_add_f32_e32 v132, v132, v141
	v_mul_f32_e32 v140, v114, v130
	v_mul_f32_e32 v141, v115, v131
	v_add_f32_e32 v132, v132, v140
	v_add_f32_e32 v132, v132, v141
	s_mov_b32 s24, 0xbfb8aa3b
	v_min_f32_e32 v141, 0, v132
	v_mul_f32_e64 v140, |v132|, s24
	v_exp_f32_e32 v140, v140
	s_mov_b32 s24, 0x800000
	v_add_f32_e32 v140, 1.0, v140
	v_cmp_gt_f32_e32 vcc, s24, v140
	s_mov_b32 s24, 0x3f317217
	s_nop 0
	v_cndmask_b32_e64 v142, 0, 32, vcc
	v_ldexp_f32 v140, v140, v142
	v_log_f32_e32 v140, v140
	s_nop 0
	v_mul_f32_e32 v142, 0x3f317217, v140
	v_fma_f32 v142, v140, s24, -v142
	v_fmac_f32_e32 v142, 0x3377d1cf, v140
	s_mov_b32 s24, 0x7f800000
	v_fmac_f32_e32 v142, 0x3f317217, v140
	v_cmp_lt_f32_e64 s[24:25], |v140|, s24
	s_nop 1
	v_cndmask_b32_e64 v140, v140, v142, s[24:25]
	v_cndmask_b32_e32 v142, 0, v183, vcc
	v_sub_f32_e32 v140, v140, v142
	v_sub_f32_e32 v140, v141, v140
	v_mul_f32_e32 v142, 0x3d800000, v140
	v_mad_u64_u32 v[144:145], s[24:25], v90, s31, v[18:19]
	ds_write_b32 v144, v142
	s_waitcnt lgkmcnt(1)
	v_lshl_add_u32 v143, v92, 2, s4
	ds_read2st64_b32 v[116:117], v143 offset1:1
	ds_read2st64_b32 v[118:119], v143 offset0:2 offset1:3
	ds_read2st64_b32 v[120:121], v143 offset0:4 offset1:5
	ds_read2st64_b32 v[122:123], v143 offset0:6 offset1:7
	ds_read2st64_b32 v[124:125], v143 offset0:8 offset1:9
	ds_read2st64_b32 v[126:127], v143 offset0:10 offset1:11
	ds_read2st64_b32 v[128:129], v143 offset0:12 offset1:13
	ds_read2st64_b32 v[130:131], v143 offset0:14 offset1:15
	v_fmac_f32_e32 v133, v100, v204
	v_fmac_f32_e32 v133, v101, v205
	v_fmac_f32_e32 v133, v102, v206
	v_fmac_f32_e32 v133, v103, v207
	v_fmac_f32_e32 v133, v104, v208
	v_fmac_f32_e32 v133, v105, v209
	v_mul_f32_e32 v140, v106, v210
	v_mul_f32_e32 v141, v107, v211
	v_add_f32_e32 v133, v133, v140
	v_add_f32_e32 v133, v133, v141
	v_mul_f32_e32 v140, v108, v212
	v_mul_f32_e32 v141, v109, v213
	v_add_f32_e32 v133, v133, v140
	v_add_f32_e32 v133, v133, v141
	v_mul_f32_e32 v140, v110, v214
	v_mul_f32_e32 v141, v111, v215
	v_add_f32_e32 v133, v133, v140
	v_add_f32_e32 v133, v133, v141
	v_mul_f32_e32 v140, v112, v216
	v_mul_f32_e32 v141, v113, v217
	v_add_f32_e32 v133, v133, v140
	v_add_f32_e32 v133, v133, v141
	v_mul_f32_e32 v140, v114, v218
	v_mul_f32_e32 v141, v115, v219
	v_add_f32_e32 v133, v133, v140
	v_add_f32_e32 v133, v133, v141
	s_mov_b32 s24, 0xbfb8aa3b
	v_min_f32_e32 v141, 0, v133
	v_mul_f32_e64 v140, |v133|, s24
	v_exp_f32_e32 v140, v140
	s_mov_b32 s24, 0x800000
	v_add_f32_e32 v140, 1.0, v140
	v_cmp_gt_f32_e32 vcc, s24, v140
	s_mov_b32 s24, 0x3f317217
	s_nop 0
	v_cndmask_b32_e64 v142, 0, 32, vcc
	v_ldexp_f32 v140, v140, v142
	v_log_f32_e32 v140, v140
	s_nop 0
	v_mul_f32_e32 v142, 0x3f317217, v140
	v_fma_f32 v142, v140, s24, -v142
	v_fmac_f32_e32 v142, 0x3377d1cf, v140
	s_mov_b32 s24, 0x7f800000
	v_fmac_f32_e32 v142, 0x3f317217, v140
	v_cmp_lt_f32_e64 s[24:25], |v140|, s24
	s_nop 1
	v_cndmask_b32_e64 v140, v140, v142, s[24:25]
	v_cndmask_b32_e32 v142, 0, v183, vcc
	v_sub_f32_e32 v140, v140, v142
	v_sub_f32_e32 v140, v141, v140
	v_mul_f32_e32 v142, 0x3d800000, v140
	v_mad_u64_u32 v[144:145], s[24:25], v91, s31, v[18:19]
	ds_write_b32 v144, v142
	s_waitcnt lgkmcnt(1)
	v_lshl_add_u32 v143, v93, 2, s4
	ds_read2st64_b32 v[204:205], v143 offset1:1
	ds_read2st64_b32 v[206:207], v143 offset0:2 offset1:3
	ds_read2st64_b32 v[208:209], v143 offset0:4 offset1:5
	ds_read2st64_b32 v[210:211], v143 offset0:6 offset1:7
	ds_read2st64_b32 v[212:213], v143 offset0:8 offset1:9
	ds_read2st64_b32 v[214:215], v143 offset0:10 offset1:11
	ds_read2st64_b32 v[216:217], v143 offset0:12 offset1:13
	ds_read2st64_b32 v[218:219], v143 offset0:14 offset1:15
	v_fmac_f32_e32 v134, v100, v116
	v_fmac_f32_e32 v134, v101, v117
	v_fmac_f32_e32 v134, v102, v118
	v_fmac_f32_e32 v134, v103, v119
	v_fmac_f32_e32 v134, v104, v120
	v_fmac_f32_e32 v134, v105, v121
	v_mul_f32_e32 v140, v106, v122
	v_mul_f32_e32 v141, v107, v123
	v_add_f32_e32 v134, v134, v140
	v_add_f32_e32 v134, v134, v141
	v_mul_f32_e32 v140, v108, v124
	v_mul_f32_e32 v141, v109, v125
	v_add_f32_e32 v134, v134, v140
	v_add_f32_e32 v134, v134, v141
	v_mul_f32_e32 v140, v110, v126
	v_mul_f32_e32 v141, v111, v127
	v_add_f32_e32 v134, v134, v140
	v_add_f32_e32 v134, v134, v141
	v_mul_f32_e32 v140, v112, v128
	v_mul_f32_e32 v141, v113, v129
	v_add_f32_e32 v134, v134, v140
	v_add_f32_e32 v134, v134, v141
	v_mul_f32_e32 v140, v114, v130
	v_mul_f32_e32 v141, v115, v131
	v_add_f32_e32 v134, v134, v140
	v_add_f32_e32 v134, v134, v141
	s_mov_b32 s24, 0xbfb8aa3b
	v_min_f32_e32 v141, 0, v134
	v_mul_f32_e64 v140, |v134|, s24
	v_exp_f32_e32 v140, v140
	s_mov_b32 s24, 0x800000
	v_add_f32_e32 v140, 1.0, v140
	v_cmp_gt_f32_e32 vcc, s24, v140
	s_mov_b32 s24, 0x3f317217
	s_nop 0
	v_cndmask_b32_e64 v142, 0, 32, vcc
	v_ldexp_f32 v140, v140, v142
	v_log_f32_e32 v140, v140
	s_nop 0
	v_mul_f32_e32 v142, 0x3f317217, v140
	v_fma_f32 v142, v140, s24, -v142
	v_fmac_f32_e32 v142, 0x3377d1cf, v140
	s_mov_b32 s24, 0x7f800000
	v_fmac_f32_e32 v142, 0x3f317217, v140
	v_cmp_lt_f32_e64 s[24:25], |v140|, s24
	s_nop 1
	v_cndmask_b32_e64 v140, v140, v142, s[24:25]
	v_cndmask_b32_e32 v142, 0, v183, vcc
	v_sub_f32_e32 v140, v140, v142
	v_sub_f32_e32 v140, v141, v140
	v_mul_f32_e32 v142, 0x3d800000, v140
	v_mad_u64_u32 v[144:145], s[24:25], v92, s31, v[18:19]
	ds_write_b32 v144, v142
	s_waitcnt lgkmcnt(1)
	v_lshl_add_u32 v143, v94, 2, s4
	ds_read2st64_b32 v[116:117], v143 offset1:1
	ds_read2st64_b32 v[118:119], v143 offset0:2 offset1:3
	ds_read2st64_b32 v[120:121], v143 offset0:4 offset1:5
	ds_read2st64_b32 v[122:123], v143 offset0:6 offset1:7
	ds_read2st64_b32 v[124:125], v143 offset0:8 offset1:9
	ds_read2st64_b32 v[126:127], v143 offset0:10 offset1:11
	ds_read2st64_b32 v[128:129], v143 offset0:12 offset1:13
	ds_read2st64_b32 v[130:131], v143 offset0:14 offset1:15
	v_fmac_f32_e32 v135, v100, v204
	v_fmac_f32_e32 v135, v101, v205
	v_fmac_f32_e32 v135, v102, v206
	v_fmac_f32_e32 v135, v103, v207
	v_fmac_f32_e32 v135, v104, v208
	v_fmac_f32_e32 v135, v105, v209
	v_mul_f32_e32 v140, v106, v210
	v_mul_f32_e32 v141, v107, v211
	v_add_f32_e32 v135, v135, v140
	v_add_f32_e32 v135, v135, v141
	v_mul_f32_e32 v140, v108, v212
	v_mul_f32_e32 v141, v109, v213
	v_add_f32_e32 v135, v135, v140
	v_add_f32_e32 v135, v135, v141
	v_mul_f32_e32 v140, v110, v214
	v_mul_f32_e32 v141, v111, v215
	v_add_f32_e32 v135, v135, v140
	v_add_f32_e32 v135, v135, v141
	v_mul_f32_e32 v140, v112, v216
	v_mul_f32_e32 v141, v113, v217
	v_add_f32_e32 v135, v135, v140
	v_add_f32_e32 v135, v135, v141
	v_mul_f32_e32 v140, v114, v218
	v_mul_f32_e32 v141, v115, v219
	v_add_f32_e32 v135, v135, v140
	v_add_f32_e32 v135, v135, v141
	s_mov_b32 s24, 0xbfb8aa3b
	v_min_f32_e32 v141, 0, v135
	v_mul_f32_e64 v140, |v135|, s24
	v_exp_f32_e32 v140, v140
	s_mov_b32 s24, 0x800000
	v_add_f32_e32 v140, 1.0, v140
	v_cmp_gt_f32_e32 vcc, s24, v140
	s_mov_b32 s24, 0x3f317217
	s_nop 0
	v_cndmask_b32_e64 v142, 0, 32, vcc
	v_ldexp_f32 v140, v140, v142
	v_log_f32_e32 v140, v140
	s_nop 0
	v_mul_f32_e32 v142, 0x3f317217, v140
	v_fma_f32 v142, v140, s24, -v142
	v_fmac_f32_e32 v142, 0x3377d1cf, v140
	s_mov_b32 s24, 0x7f800000
	v_fmac_f32_e32 v142, 0x3f317217, v140
	v_cmp_lt_f32_e64 s[24:25], |v140|, s24
	s_nop 1
	v_cndmask_b32_e64 v140, v140, v142, s[24:25]
	v_cndmask_b32_e32 v142, 0, v183, vcc
	v_sub_f32_e32 v140, v140, v142
	v_sub_f32_e32 v140, v141, v140
	v_mul_f32_e32 v142, 0x3d800000, v140
	v_mad_u64_u32 v[144:145], s[24:25], v93, s31, v[18:19]
	ds_write_b32 v144, v142
	s_waitcnt lgkmcnt(1)
	v_lshl_add_u32 v143, v95, 2, s4
	ds_read2st64_b32 v[204:205], v143 offset1:1
	ds_read2st64_b32 v[206:207], v143 offset0:2 offset1:3
	ds_read2st64_b32 v[208:209], v143 offset0:4 offset1:5
	ds_read2st64_b32 v[210:211], v143 offset0:6 offset1:7
	ds_read2st64_b32 v[212:213], v143 offset0:8 offset1:9
	ds_read2st64_b32 v[214:215], v143 offset0:10 offset1:11
	ds_read2st64_b32 v[216:217], v143 offset0:12 offset1:13
	ds_read2st64_b32 v[218:219], v143 offset0:14 offset1:15
	v_fmac_f32_e32 v136, v100, v116
	v_fmac_f32_e32 v136, v101, v117
	v_fmac_f32_e32 v136, v102, v118
	v_fmac_f32_e32 v136, v103, v119
	v_fmac_f32_e32 v136, v104, v120
	v_fmac_f32_e32 v136, v105, v121
	v_mul_f32_e32 v140, v106, v122
	v_mul_f32_e32 v141, v107, v123
	v_add_f32_e32 v136, v136, v140
	v_add_f32_e32 v136, v136, v141
	v_mul_f32_e32 v140, v108, v124
	v_mul_f32_e32 v141, v109, v125
	v_add_f32_e32 v136, v136, v140
	v_add_f32_e32 v136, v136, v141
	v_mul_f32_e32 v140, v110, v126
	v_mul_f32_e32 v141, v111, v127
	v_add_f32_e32 v136, v136, v140
	v_add_f32_e32 v136, v136, v141
	v_mul_f32_e32 v140, v112, v128
	v_mul_f32_e32 v141, v113, v129
	v_add_f32_e32 v136, v136, v140
	v_add_f32_e32 v136, v136, v141
	v_mul_f32_e32 v140, v114, v130
	v_mul_f32_e32 v141, v115, v131
	v_add_f32_e32 v136, v136, v140
	v_add_f32_e32 v136, v136, v141
	s_mov_b32 s24, 0xbfb8aa3b
	v_min_f32_e32 v141, 0, v136
	v_mul_f32_e64 v140, |v136|, s24
	v_exp_f32_e32 v140, v140
	s_mov_b32 s24, 0x800000
	v_add_f32_e32 v140, 1.0, v140
	v_cmp_gt_f32_e32 vcc, s24, v140
	s_mov_b32 s24, 0x3f317217
	s_nop 0
	v_cndmask_b32_e64 v142, 0, 32, vcc
	v_ldexp_f32 v140, v140, v142
	v_log_f32_e32 v140, v140
	s_nop 0
	v_mul_f32_e32 v142, 0x3f317217, v140
	v_fma_f32 v142, v140, s24, -v142
	v_fmac_f32_e32 v142, 0x3377d1cf, v140
	s_mov_b32 s24, 0x7f800000
	v_fmac_f32_e32 v142, 0x3f317217, v140
	v_cmp_lt_f32_e64 s[24:25], |v140|, s24
	s_nop 1
	v_cndmask_b32_e64 v140, v140, v142, s[24:25]
	v_cndmask_b32_e32 v142, 0, v183, vcc
	v_sub_f32_e32 v140, v140, v142
	v_sub_f32_e32 v140, v141, v140
	v_mul_f32_e32 v142, 0x3d800000, v140
	v_mad_u64_u32 v[144:145], s[24:25], v94, s31, v[18:19]
	ds_write_b32 v144, v142
	s_waitcnt lgkmcnt(1)
	v_lshl_add_u32 v143, v96, 2, s4
	ds_read2st64_b32 v[116:117], v143 offset1:1
	ds_read2st64_b32 v[118:119], v143 offset0:2 offset1:3
	ds_read2st64_b32 v[120:121], v143 offset0:4 offset1:5
	ds_read2st64_b32 v[122:123], v143 offset0:6 offset1:7
	ds_read2st64_b32 v[124:125], v143 offset0:8 offset1:9
	ds_read2st64_b32 v[126:127], v143 offset0:10 offset1:11
	ds_read2st64_b32 v[128:129], v143 offset0:12 offset1:13
	ds_read2st64_b32 v[130:131], v143 offset0:14 offset1:15
	v_fmac_f32_e32 v137, v100, v204
	v_fmac_f32_e32 v137, v101, v205
	v_fmac_f32_e32 v137, v102, v206
	v_fmac_f32_e32 v137, v103, v207
	v_fmac_f32_e32 v137, v104, v208
	v_fmac_f32_e32 v137, v105, v209
	v_mul_f32_e32 v140, v106, v210
	v_mul_f32_e32 v141, v107, v211
	v_add_f32_e32 v137, v137, v140
	v_add_f32_e32 v137, v137, v141
	v_mul_f32_e32 v140, v108, v212
	v_mul_f32_e32 v141, v109, v213
	v_add_f32_e32 v137, v137, v140
	v_add_f32_e32 v137, v137, v141
	v_mul_f32_e32 v140, v110, v214
	v_mul_f32_e32 v141, v111, v215
	v_add_f32_e32 v137, v137, v140
	v_add_f32_e32 v137, v137, v141
	v_mul_f32_e32 v140, v112, v216
	v_mul_f32_e32 v141, v113, v217
	v_add_f32_e32 v137, v137, v140
	v_add_f32_e32 v137, v137, v141
	v_mul_f32_e32 v140, v114, v218
	v_mul_f32_e32 v141, v115, v219
	v_add_f32_e32 v137, v137, v140
	v_add_f32_e32 v137, v137, v141
	s_mov_b32 s24, 0xbfb8aa3b
	v_min_f32_e32 v141, 0, v137
	v_mul_f32_e64 v140, |v137|, s24
	v_exp_f32_e32 v140, v140
	s_mov_b32 s24, 0x800000
	v_add_f32_e32 v140, 1.0, v140
	v_cmp_gt_f32_e32 vcc, s24, v140
	s_mov_b32 s24, 0x3f317217
	s_nop 0
	v_cndmask_b32_e64 v142, 0, 32, vcc
	v_ldexp_f32 v140, v140, v142
	v_log_f32_e32 v140, v140
	s_nop 0
	v_mul_f32_e32 v142, 0x3f317217, v140
	v_fma_f32 v142, v140, s24, -v142
	v_fmac_f32_e32 v142, 0x3377d1cf, v140
	s_mov_b32 s24, 0x7f800000
	v_fmac_f32_e32 v142, 0x3f317217, v140
	v_cmp_lt_f32_e64 s[24:25], |v140|, s24
	s_nop 1
	v_cndmask_b32_e64 v140, v140, v142, s[24:25]
	v_cndmask_b32_e32 v142, 0, v183, vcc
	v_sub_f32_e32 v140, v140, v142
	v_sub_f32_e32 v140, v141, v140
	v_mul_f32_e32 v142, 0x3d800000, v140
	v_mad_u64_u32 v[144:145], s[24:25], v95, s31, v[18:19]
	ds_write_b32 v144, v142
	s_waitcnt lgkmcnt(1)
	v_lshl_add_u32 v143, v97, 2, s4
	ds_read2st64_b32 v[204:205], v143 offset1:1
	ds_read2st64_b32 v[206:207], v143 offset0:2 offset1:3
	ds_read2st64_b32 v[208:209], v143 offset0:4 offset1:5
	ds_read2st64_b32 v[210:211], v143 offset0:6 offset1:7
	ds_read2st64_b32 v[212:213], v143 offset0:8 offset1:9
	ds_read2st64_b32 v[214:215], v143 offset0:10 offset1:11
	ds_read2st64_b32 v[216:217], v143 offset0:12 offset1:13
	ds_read2st64_b32 v[218:219], v143 offset0:14 offset1:15
	v_fmac_f32_e32 v138, v100, v116
	v_fmac_f32_e32 v138, v101, v117
	v_fmac_f32_e32 v138, v102, v118
	v_fmac_f32_e32 v138, v103, v119
	v_fmac_f32_e32 v138, v104, v120
	v_fmac_f32_e32 v138, v105, v121
	v_mul_f32_e32 v140, v106, v122
	v_mul_f32_e32 v141, v107, v123
	v_add_f32_e32 v138, v138, v140
	v_add_f32_e32 v138, v138, v141
	v_mul_f32_e32 v140, v108, v124
	v_mul_f32_e32 v141, v109, v125
	v_add_f32_e32 v138, v138, v140
	v_add_f32_e32 v138, v138, v141
	v_mul_f32_e32 v140, v110, v126
	v_mul_f32_e32 v141, v111, v127
	v_add_f32_e32 v138, v138, v140
	v_add_f32_e32 v138, v138, v141
	v_mul_f32_e32 v140, v112, v128
	v_mul_f32_e32 v141, v113, v129
	v_add_f32_e32 v138, v138, v140
	v_add_f32_e32 v138, v138, v141
	v_mul_f32_e32 v140, v114, v130
	v_mul_f32_e32 v141, v115, v131
	v_add_f32_e32 v138, v138, v140
	v_add_f32_e32 v138, v138, v141
	s_mov_b32 s24, 0xbfb8aa3b
	v_min_f32_e32 v141, 0, v138
	v_mul_f32_e64 v140, |v138|, s24
	v_exp_f32_e32 v140, v140
	s_mov_b32 s24, 0x800000
	v_add_f32_e32 v140, 1.0, v140
	v_cmp_gt_f32_e32 vcc, s24, v140
	s_mov_b32 s24, 0x3f317217
	s_nop 0
	v_cndmask_b32_e64 v142, 0, 32, vcc
	v_ldexp_f32 v140, v140, v142
	v_log_f32_e32 v140, v140
	s_nop 0
	v_mul_f32_e32 v142, 0x3f317217, v140
	v_fma_f32 v142, v140, s24, -v142
	v_fmac_f32_e32 v142, 0x3377d1cf, v140
	s_mov_b32 s24, 0x7f800000
	v_fmac_f32_e32 v142, 0x3f317217, v140
	v_cmp_lt_f32_e64 s[24:25], |v140|, s24
	s_nop 1
	v_cndmask_b32_e64 v140, v140, v142, s[24:25]
	v_cndmask_b32_e32 v142, 0, v183, vcc
	v_sub_f32_e32 v140, v140, v142
	v_sub_f32_e32 v140, v141, v140
	v_mul_f32_e32 v142, 0x3d800000, v140
	v_mad_u64_u32 v[144:145], s[24:25], v96, s31, v[18:19]
	ds_write_b32 v144, v142
	s_waitcnt lgkmcnt(1)
	v_fmac_f32_e32 v139, v100, v204
	v_fmac_f32_e32 v139, v101, v205
	v_fmac_f32_e32 v139, v102, v206
	v_fmac_f32_e32 v139, v103, v207
	v_fmac_f32_e32 v139, v104, v208
	v_fmac_f32_e32 v139, v105, v209
	v_mul_f32_e32 v140, v106, v210
	v_mul_f32_e32 v141, v107, v211
	v_add_f32_e32 v139, v139, v140
	v_add_f32_e32 v139, v139, v141
	v_mul_f32_e32 v140, v108, v212
	v_mul_f32_e32 v141, v109, v213
	v_add_f32_e32 v139, v139, v140
	v_add_f32_e32 v139, v139, v141
	v_mul_f32_e32 v140, v110, v214
	v_mul_f32_e32 v141, v111, v215
	v_add_f32_e32 v139, v139, v140
	v_add_f32_e32 v139, v139, v141
	v_mul_f32_e32 v140, v112, v216
	v_mul_f32_e32 v141, v113, v217
	v_add_f32_e32 v139, v139, v140
	v_add_f32_e32 v139, v139, v141
	v_mul_f32_e32 v140, v114, v218
	v_mul_f32_e32 v141, v115, v219
	v_add_f32_e32 v139, v139, v140
	v_add_f32_e32 v139, v139, v141
	s_mov_b32 s24, 0xbfb8aa3b
	v_min_f32_e32 v141, 0, v139
	v_mul_f32_e64 v140, |v139|, s24
	v_exp_f32_e32 v140, v140
	s_mov_b32 s24, 0x800000
	v_add_f32_e32 v140, 1.0, v140
	v_cmp_gt_f32_e32 vcc, s24, v140
	s_mov_b32 s24, 0x3f317217
	s_nop 0
	v_cndmask_b32_e64 v142, 0, 32, vcc
	v_ldexp_f32 v140, v140, v142
	v_log_f32_e32 v140, v140
	s_nop 0
	v_mul_f32_e32 v142, 0x3f317217, v140
	v_fma_f32 v142, v140, s24, -v142
	v_fmac_f32_e32 v142, 0x3377d1cf, v140
	s_mov_b32 s24, 0x7f800000
	v_fmac_f32_e32 v142, 0x3f317217, v140
	v_cmp_lt_f32_e64 s[24:25], |v140|, s24
	s_nop 1
	v_cndmask_b32_e64 v140, v140, v142, s[24:25]
	v_cndmask_b32_e32 v142, 0, v183, vcc
	v_sub_f32_e32 v140, v140, v142
	v_sub_f32_e32 v140, v141, v140
	v_mul_f32_e32 v142, 0x3d800000, v140
	v_mad_u64_u32 v[144:145], s[24:25], v97, s31, v[18:19]
	ds_write_b32 v144, v142
	s_waitcnt vmcnt(0)

.LBB0_4234:
	global_load_dwordx2 v[44:45], v[24:25], off offset:152
	s_waitcnt vmcnt(0)
	v_and_b32_e32 v46, 0xffffff00, v43
	v_ashrrev_i32_e32 v47, 31, v46
	v_add_u32_e32 v21, 0x200, v21
	s_waitcnt lgkmcnt(0)
	v_lshl_add_u64 v[44:45], v[46:47], 2, v[44:45]
	v_lshl_add_u64 v[44:45], v[44:45], 0, s[12:13]
	v_lshl_add_u64 v[44:45], v[44:45], 0, v[22:23]
	v_add_co_u32_e32 v44, vcc, 0x4000, v44
	s_nop 1
	v_addc_co_u32_e32 v45, vcc, 0, v45, vcc
	global_load_dword v44, v[44:45], off
	v_cmp_lt_i32_e32 vcc, s14, v21
	v_add_u32_e32 v45, s4, v43
	v_add_u32_e32 v43, 0x800, v43
	s_or_b64 s[10:11], vcc, s[10:11]
	s_waitcnt vmcnt(0)
	ds_write_b32 v45, v44
	s_andn2_b64 exec, exec, s[10:11]
	s_cbranch_execnz .LBB0_4234

.LBB0_4237:
	global_load_dwordx2 v[44:45], v[24:25], off offset:160
	s_waitcnt vmcnt(0)
	v_ashrrev_i32_e32 v46, 6, v43
	v_ashrrev_i32_e32 v47, 31, v46
	v_lshl_add_u64 v[48:49], s[6:7], 0, v[46:47]
	v_add_u32_e32 v79, 0x200, v43
	v_cmp_lt_i32_e32 vcc, s15, v43
	v_lshl_add_u32 v43, v46, 2, s4
	v_mad_u64_u32 v[46:47], s[18:19], v46, s14, v[22:23]
	s_or_b64 s[10:11], vcc, s[10:11]
	s_waitcnt lgkmcnt(0)
	v_lshl_add_u64 v[44:45], v[48:49], 2, v[44:45]
	global_load_dword v78, v[44:45], off offset:1024
	ds_read2st64_b32 v[44:45], v21 offset1:1
	ds_read2st64_b32 v[48:49], v21 offset0:2 offset1:3
	ds_read2st64_b32 v[50:51], v21 offset0:4 offset1:5
	ds_read2st64_b32 v[52:53], v21 offset0:6 offset1:7
	ds_read2st64_b32 v[54:55], v21 offset0:8 offset1:9
	ds_read2st64_b32 v[56:57], v21 offset0:10 offset1:11
	ds_read2st64_b32 v[58:59], v21 offset0:12 offset1:13
	ds_read2st64_b32 v[60:61], v21 offset0:14 offset1:15
	ds_read2st64_b32 v[62:63], v43 offset1:1
	ds_read2st64_b32 v[64:65], v43 offset0:2 offset1:3
	ds_read2st64_b32 v[66:67], v43 offset0:4 offset1:5
	ds_read2st64_b32 v[68:69], v43 offset0:6 offset1:7
	ds_read2st64_b32 v[70:71], v43 offset0:8 offset1:9
	ds_read2st64_b32 v[72:73], v43 offset0:10 offset1:11
	ds_read2st64_b32 v[74:75], v43 offset0:12 offset1:13
	ds_read2st64_b32 v[76:77], v43 offset0:14 offset1:15
	s_waitcnt lgkmcnt(4)
	v_pk_mul_f32 v[52:53], v[52:53], v[68:69]
	s_waitcnt lgkmcnt(3)
	v_pk_mul_f32 v[54:55], v[54:55], v[70:71]
	s_waitcnt lgkmcnt(2)
	v_pk_mul_f32 v[56:57], v[56:57], v[72:73]
	s_waitcnt lgkmcnt(1)
	v_pk_mul_f32 v[58:59], v[58:59], v[74:75]
	s_waitcnt lgkmcnt(0)
	v_pk_mul_f32 v[60:61], v[60:61], v[76:77]
	s_waitcnt vmcnt(0)
	v_fmac_f32_e32 v78, v44, v62
	v_fmac_f32_e32 v78, v45, v63
	v_fmac_f32_e32 v78, v48, v64
	v_fmac_f32_e32 v78, v49, v65
	v_fmac_f32_e32 v78, v50, v66
	v_fmac_f32_e32 v78, v51, v67
	v_add_f32_e32 v43, v78, v52
	v_add_f32_e32 v43, v43, v53
	v_add_f32_e32 v43, v43, v54
	v_add_f32_e32 v43, v43, v55
	v_add_f32_e32 v43, v43, v56
	v_add_f32_e32 v43, v43, v57
	v_add_f32_e32 v43, v43, v58
	v_add_f32_e32 v43, v43, v59
	v_add_f32_e32 v43, v43, v60
	v_add_f32_e32 v44, v43, v61
	v_mul_f32_e64 v43, |v44|, s3
	v_exp_f32_e32 v45, v43
	v_min_f32_e32 v44, 0, v44
	v_mov_b32_e32 v43, v79
	v_add_f32_e32 v45, 1.0, v45
	v_cmp_gt_f32_e32 vcc, s5, v45
	s_nop 1
	v_cndmask_b32_e64 v47, 0, 32, vcc
	v_ldexp_f32 v45, v45, v47
	v_log_f32_e32 v45, v45
	v_cndmask_b32_e32 v47, 0, v23, vcc
	v_mul_f32_e32 v48, 0x3f317217, v45
	v_fma_f32 v48, v45, s12, -v48
	v_fmac_f32_e32 v48, 0x3377d1cf, v45
	v_fmac_f32_e32 v48, 0x3f317217, v45
	v_cmp_lt_f32_e64 vcc, |v45|, s13
	s_nop 1
	v_cndmask_b32_e32 v45, v45, v48, vcc
	v_sub_f32_e32 v45, v45, v47
	v_sub_f32_e32 v44, v44, v45
	v_mul_f32_e32 v44, 0x3d800000, v44
	ds_write_b32 v46, v44
	s_andn2_b64 exec, exec, s[10:11]
	s_cbranch_execnz .LBB0_4237

.LBB0_4251:
	s_andn2_saveexec_b64 s[24:25], s[16:17]
	s_cbranch_execz .LBB0_4255
	v_mov_b64_e32 v[42:43], s[0:1]
	global_load_dwordx2 v[58:59], v[42:43], off offset:152
	s_waitcnt vmcnt(0)
	global_load_dwordx2 v[60:61], v[42:43], off offset:160
	s_waitcnt vmcnt(0)
	v_mov_b32_e32 v46, s22
	v_mov_b32_e32 v47, s23
	v_add_co_u32_e32 v54, vcc, 0x2000, v46
	v_lshl_add_u64 v[42:43], v[8:9], 2, s[22:23]
	v_lshl_add_u64 v[44:45], v[10:11], 2, s[22:23]
	v_addc_co_u32_e32 v55, vcc, 0, v47, vcc
	global_load_dword v66, v[42:43], off
	global_load_dword v67, v[44:45], off
	s_nop 0
	global_load_dwordx4 v[42:45], v[54:55], off offset:1120
	global_load_dwordx4 v[46:49], v[54:55], off offset:1136
	global_load_dwordx4 v[50:53], v[54:55], off offset:1152
	s_nop 0
	global_load_dwordx4 v[54:57], v[54:55], off offset:1168
	s_mov_b32 s21, s19
	s_waitcnt lgkmcnt(0)
	v_lshl_add_u64 v[58:59], v[58:59], 0, s[20:21]
	v_lshl_add_u64 v[60:61], v[16:17], 2, v[60:61]
	global_load_dword v68, v[60:61], off offset:1024
	v_lshl_add_u64 v[58:59], v[130:131], 2, v[58:59]
	v_add_co_u32_e32 v60, vcc, s28, v58
	v_add_co_u32_e64 v62, s[16:17], s30, v58
	s_nop 0
	v_addc_co_u32_e32 v61, vcc, 0, v59, vcc
	v_addc_co_u32_e64 v63, s[16:17], 0, v59, s[16:17]
	v_add_co_u32_e64 v64, s[16:17], s31, v58
	v_add_co_u32_e32 v58, vcc, s29, v58
	s_nop 0
	v_addc_co_u32_e64 v65, s[16:17], 0, v59, s[16:17]
	v_addc_co_u32_e32 v59, vcc, 0, v59, vcc
	global_load_dword v69, v[58:59], off offset:-4096
	global_load_dword v70, v[60:61], off offset:1024
	global_load_dword v71, v[60:61], off offset:2048
	s_nop 0
	global_load_dword v60, v[60:61], off offset:3072
	s_nop 0
	global_load_dword v61, v[58:59], off
	global_load_dword v72, v[58:59], off offset:1024
	global_load_dword v73, v[58:59], off offset:2048
	s_nop 0
	global_load_dword v58, v[58:59], off offset:3072
	s_nop 0
	global_load_dword v59, v[64:65], off offset:-4096
	global_load_dword v74, v[62:63], off offset:1024
	global_load_dword v75, v[62:63], off offset:2048
	s_nop 0
	global_load_dword v62, v[62:63], off offset:3072
	s_nop 0
	global_load_dword v63, v[64:65], off
	global_load_dword v76, v[64:65], off offset:1024
	global_load_dword v77, v[64:65], off offset:2048
	s_nop 0
	global_load_dword v64, v[64:65], off offset:3072
	v_cmp_lt_i32_e32 vcc, v36, v35
	s_waitcnt vmcnt(0)
	v_mul_f32_e32 v66, 0x3e000000, v66
	v_mul_f32_e32 v78, v66, v67
	v_cndmask_b32_e32 v65, v1, v36, vcc
	v_lshlrev_b32_e32 v65, 2, v65
	ds_bpermute_b32 v65, v65, v78
	v_cmp_lt_i32_e32 vcc, v37, v35
	s_waitcnt lgkmcnt(0)
	v_fmac_f32_e32 v65, v66, v67
	v_cndmask_b32_e32 v78, v1, v37, vcc
	v_lshlrev_b32_e32 v78, 2, v78
	ds_bpermute_b32 v78, v78, v65
	v_cmp_lt_i32_e32 vcc, v38, v35
	s_waitcnt lgkmcnt(0)
	v_add_f32_e32 v65, v65, v78
	v_cndmask_b32_e32 v79, v1, v38, vcc
	v_cmp_lt_i32_e32 vcc, v39, v35
	v_lshlrev_b32_e32 v79, 2, v79
	ds_bpermute_b32 v78, v79, v65
	v_cndmask_b32_e32 v80, v1, v39, vcc
	v_cmp_lt_i32_e32 vcc, v40, v35
	v_lshlrev_b32_e32 v80, 2, v80
	s_waitcnt lgkmcnt(0)
	v_add_f32_e32 v65, v65, v78
	v_cndmask_b32_e32 v79, v1, v40, vcc
	v_cmp_lt_i32_e32 vcc, v41, v35
	ds_bpermute_b32 v78, v80, v65
	v_fmac_f32_e32 v68, v42, v69
	v_fmac_f32_e32 v68, v43, v70
	v_fmac_f32_e32 v68, v44, v71
	v_fmac_f32_e32 v68, v45, v60
	v_fmac_f32_e32 v68, v46, v61
	v_fmac_f32_e32 v68, v47, v72
	v_fmac_f32_e32 v68, v48, v73
	v_fmac_f32_e32 v68, v49, v58
	v_fmac_f32_e32 v68, v50, v59
	v_fmac_f32_e32 v68, v51, v74
	v_fmac_f32_e32 v68, v52, v75
	v_fmac_f32_e32 v68, v53, v62
	v_fmac_f32_e32 v68, v54, v63
	v_fmac_f32_e32 v68, v55, v76
	v_fmac_f32_e32 v68, v56, v77
	v_fmac_f32_e32 v68, v57, v64
	v_mul_f32_e64 v42, |v68|, s33
	v_exp_f32_e32 v42, v42
	v_cndmask_b32_e32 v81, v1, v41, vcc
	v_lshlrev_b32_e32 v43, 2, v79
	s_waitcnt lgkmcnt(0)
	v_add_f32_e32 v45, v65, v78
	v_add_f32_e32 v42, 1.0, v42
	v_cmp_gt_f32_e32 vcc, s34, v42
	ds_bpermute_b32 v43, v43, v45
	v_lshlrev_b32_e32 v44, 2, v81
	v_cndmask_b32_e64 v46, 0, 32, vcc
	v_ldexp_f32 v42, v42, v46
	v_log_f32_e32 v42, v42
	v_cndmask_b32_e32 v47, 0, v34, vcc
	v_min_f32_e32 v46, 0, v68
	v_mul_f32_e32 v48, 0x3f317217, v42
	v_fma_f32 v48, v42, s35, -v48
	v_fmac_f32_e32 v48, 0x3377d1cf, v42
	v_fmac_f32_e32 v48, 0x3f317217, v42
	v_cmp_lt_f32_e64 vcc, |v42|, s36
	s_nop 1
	v_cndmask_b32_e32 v42, v42, v48, vcc
	v_sub_f32_e32 v42, v42, v47
	v_sub_f32_e32 v42, v46, v42
	v_mul_f32_e32 v42, 0x3d800000, v42
	v_mul_f32_e32 v42, 0x3fb8aa3b, v42
	v_exp_f32_e32 v46, v42
	s_waitcnt lgkmcnt(0)
	v_add_f32_e32 v42, v45, v43
	ds_bpermute_b32 v43, v44, v42
	v_mul_f32_e32 v44, v66, v46
	ds_write2st64_b32 v6, v44, v67 offset0:128 offset1:129
	ds_write_b32 v6, v46 offset:33280
	s_and_saveexec_b64 s[16:17], s[12:13]
	s_cbranch_execz .LBB0_4254
	s_waitcnt lgkmcnt(2)
	v_add_f32_e32 v42, v42, v43
	v_mov_b32_e32 v43, s94
	ds_write_b32 v43, v42 offset:34048

.LBB0_4255:
	s_or_b64 exec, exec, s[24:25]
	s_waitcnt lgkmcnt(0)
	v_mov_b64_e32 v[42:43], s[0:1]
	s_waitcnt lgkmcnt(0)
	s_barrier
	global_load_dwordx2 v[42:43], v[42:43], off offset:56
	s_waitcnt vmcnt(0)
	s_and_b32 s16, s2, 0x7ffffffc
	s_mov_b32 s17, s19
	s_add_i32 s16, s3, s16
	s_lshl_b64 s[16:17], s[16:17], 15
	s_waitcnt lgkmcnt(0)
	v_lshl_add_u64 v[50:51], v[42:43], 0, s[16:17]
	v_lshl_add_u64 v[42:43], v[50:51], 0, v[18:19]
	global_load_dwordx4 v[42:45], v[42:43], off
	s_add_u32 s16, s4, s16
	s_addc_u32 s17, s5, s17
	v_lshl_add_u64 v[54:55], s[16:17], 0, v[18:19]
	v_lshl_add_u64 v[56:57], v[50:51], 0, v[20:21]
	s_waitcnt vmcnt(0)
	ds_write_b128 v2, v[42:45]
	ds_read_b128 v[46:49], v3 offset:33536
	ds_read2st64_b32 v[52:53], v26 offset0:129 offset1:130
	s_waitcnt lgkmcnt(0)
	v_pk_mul_f32 v[48:49], v[48:49], v[52:53] op_sel_hi:[1,0]
	v_pk_mul_f32 v[46:47], v[46:47], v[52:53] op_sel_hi:[1,0]
	v_mov_b32_e32 v52, v53
	v_pk_fma_f32 v[44:45], v[44:45], v[52:53], v[48:49] op_sel_hi:[1,0,1]
	v_pk_fma_f32 v[42:43], v[42:43], v[52:53], v[46:47] op_sel_hi:[1,0,1]
	global_store_dwordx4 v[54:55], v[42:45], off
	global_load_dwordx4 v[42:45], v[56:57], off
	v_lshl_add_u64 v[54:55], s[16:17], 0, v[20:21]
	v_lshl_add_u64 v[56:57], v[50:51], 0, v[22:23]
	v_lshl_add_u64 v[50:51], v[50:51], 0, v[24:25]
	s_waitcnt vmcnt(0)
	ds_write_b128 v7, v[42:45]
	ds_read_b128 v[46:49], v3 offset:33536
	ds_read2st64_b32 v[52:53], v27 offset0:129 offset1:130
	s_waitcnt lgkmcnt(0)
	v_pk_mul_f32 v[48:49], v[48:49], v[52:53] op_sel_hi:[1,0]
	v_pk_mul_f32 v[46:47], v[46:47], v[52:53] op_sel_hi:[1,0]
	v_mov_b32_e32 v52, v53
	v_pk_fma_f32 v[44:45], v[44:45], v[52:53], v[48:49] op_sel_hi:[1,0,1]
	v_pk_fma_f32 v[42:43], v[42:43], v[52:53], v[46:47] op_sel_hi:[1,0,1]
	global_store_dwordx4 v[54:55], v[42:45], off
	global_load_dwordx4 v[42:45], v[56:57], off
	v_lshl_add_u64 v[54:55], s[16:17], 0, v[22:23]
	s_waitcnt vmcnt(0)
	ds_write_b128 v30, v[42:45]
	ds_read_b128 v[46:49], v3 offset:33536
	ds_read2st64_b32 v[52:53], v28 offset0:129 offset1:130
	s_waitcnt lgkmcnt(0)
	v_pk_mul_f32 v[48:49], v[48:49], v[52:53] op_sel_hi:[1,0]
	v_pk_mul_f32 v[46:47], v[46:47], v[52:53] op_sel_hi:[1,0]
	v_mov_b32_e32 v52, v53
	v_pk_fma_f32 v[44:45], v[44:45], v[52:53], v[48:49] op_sel_hi:[1,0,1]
	v_pk_fma_f32 v[42:43], v[42:43], v[52:53], v[46:47] op_sel_hi:[1,0,1]
	global_store_dwordx4 v[54:55], v[42:45], off
	global_load_dwordx4 v[42:45], v[50:51], off
	v_lshl_add_u64 v[52:53], s[16:17], 0, v[24:25]
	s_waitcnt vmcnt(0)
	ds_write_b128 v31, v[42:45]
	ds_read_b128 v[46:49], v3 offset:33536
	ds_read2st64_b32 v[50:51], v29 offset0:129 offset1:130
	s_waitcnt lgkmcnt(0)
	v_pk_mul_f32 v[48:49], v[48:49], v[50:51] op_sel_hi:[1,0]
	v_pk_mul_f32 v[46:47], v[46:47], v[50:51] op_sel_hi:[1,0]
	v_mov_b32_e32 v50, v51
	v_pk_fma_f32 v[44:45], v[44:45], v[50:51], v[48:49] op_sel_hi:[1,0,1]
	v_pk_fma_f32 v[42:43], v[42:43], v[50:51], v[46:47] op_sel_hi:[1,0,1]
	global_store_dwordx4 v[52:53], v[42:45], off
	s_waitcnt lgkmcnt(0)
	s_barrier
	v_mov_b32_e32 v42, 0
	s_and_saveexec_b64 s[16:17], s[8:9]
	s_cbranch_execz .LBB0_4261
	v_mov_b32_e32 v42, 0
	s_mov_b32 s21, 0
	s_mov_b32 s24, s27

.LBB0_4261:
	s_or_b64 exec, exec, s[16:17]
	s_waitcnt lgkmcnt(0)
	s_barrier
	s_and_saveexec_b64 s[24:25], s[8:9]
	s_cbranch_execz .LBB0_4246
	v_mov_b32_e32 v43, s37
	v_mov_b64_e32 v[46:47], s[0:1]
	ds_read2_b32 v[44:45], v43 offset1:1
	global_load_dwordx2 v[46:47], v[46:47], off offset:168
	s_waitcnt vmcnt(0)
	v_lshl_add_u64 v[48:49], v[12:13], 2, s[22:23]
	global_load_dword v43, v[48:49], off
	s_waitcnt lgkmcnt(0)
	v_add_f32_e32 v44, v44, v45
	v_fmamk_f32 v44, v44, 0x3c000000, v32
	v_mul_f32_e32 v45, 0x4f800000, v44
	v_cmp_gt_f32_e32 vcc, s41, v44
	v_lshl_add_u64 v[46:47], v[130:131], 2, v[46:47]
	global_load_dword v46, v[46:47], off offset:512
	v_cndmask_b32_e32 v44, v44, v45, vcc
	v_sqrt_f32_e32 v45, v44
	s_nop 0
	v_add_u32_e32 v47, -1, v45
	v_add_u32_e32 v48, 1, v45
	v_fma_f32 v49, -v47, v45, v44
	v_fma_f32 v50, -v48, v45, v44
	v_cmp_ge_f32_e64 s[16:17], 0, v49
	s_nop 1
	v_cndmask_b32_e64 v45, v45, v47, s[16:17]
	v_cmp_lt_f32_e64 s[16:17], 0, v50
	s_nop 1
	v_cndmask_b32_e64 v45, v45, v48, s[16:17]
	v_mul_f32_e32 v47, 0x37800000, v45
	v_cndmask_b32_e32 v45, v45, v47, vcc
	v_cmp_class_f32_e32 vcc, v44, v33
	s_nop 1
	v_cndmask_b32_e32 v44, v45, v44, vcc
	v_div_scale_f32 v45, s[16:17], v44, v44, 1.0
	v_rcp_f32_e32 v47, v45
	v_div_scale_f32 v48, vcc, 1.0, v44, 1.0
	s_lshl_b64 s[16:17], s[18:19], 11
	v_fma_f32 v49, -v45, v47, 1.0
	v_fmac_f32_e32 v47, v49, v47
	v_mul_f32_e32 v49, v48, v47
	v_fma_f32 v50, -v45, v49, v48
	v_fmac_f32_e32 v49, v50, v47
	v_fma_f32 v45, -v45, v49, v48
	s_waitcnt vmcnt(0)
	v_mul_f32_e32 v48, 0xbfb8aa3b, v43
	v_exp_f32_e32 v48, v48
	v_div_fmas_f32 v45, v45, v47, v49
	v_div_fixup_f32 v44, v45, v44, 1.0
	v_mul_f32_e32 v42, v42, v44
	v_add_f32_e32 v45, 1.0, v48
	v_div_scale_f32 v47, s[22:23], v45, v45, v43
	v_rcp_f32_e32 v48, v47
	v_div_scale_f32 v44, vcc, v43, v45, v43
	v_fma_f32 v49, -v47, v48, 1.0
	v_fmac_f32_e32 v48, v49, v48
	v_mul_f32_e32 v49, v44, v48
	v_fma_f32 v50, -v47, v49, v44
	v_fmac_f32_e32 v49, v50, v48
	v_fma_f32 v44, -v47, v49, v44
	v_div_fmas_f32 v44, v44, v48, v49
	v_div_fixup_f32 v43, v44, v45, v43
	v_mul_f32_e32 v42, v46, v42
	v_mul_f32_e32 v42, v42, v43
	v_bfe_u32 v43, v42, 16, 1
	v_add3_u32 v44, v42, v43, s42
	v_lshl_add_u64 v[42:43], v[14:15], 0, s[16:17]
	global_store_short_d16_hi v[42:43], v44, off
	s_branch .LBB0_4246

.LBB0_4321:
	v_mov_b64_e32 v[8:9], s[0:1]
	global_load_dwordx2 v[8:9], v[8:9], off offset:144
	s_waitcnt vmcnt(0)
	v_add_u32_e32 v5, 0x200, v5
	v_cmp_lt_i32_e32 vcc, s4, v5
	s_or_b64 s[90:91], vcc, s[90:91]
	s_waitcnt lgkmcnt(0)
	v_lshl_add_u64 v[8:9], v[8:9], 0, v[2:3]
	global_load_dword v7, v[8:9], off nt
	v_lshl_add_u64 v[2:3], v[2:3], 0, s[14:15]
	s_waitcnt vmcnt(0)
	ds_write_b32 v6, v7
	v_add_u32_e32 v6, 0x800, v6
	s_andn2_b64 exec, exec, s[90:91]
	s_cbranch_execnz .LBB0_4321
.LBB0_4322:
	s_or_b64 exec, exec, s[72:73]
	s_movk_i32 s4, 0x7f
	s_and_b32 s26, s40, 1
	v_cmp_lt_i32_e32 vcc, s4, v130
	s_and_saveexec_b64 s[14:15], vcc
	s_xor_b64 s[14:15], exec, s[14:15]
	s_lshl_b32 s4, s26, 7
	s_or_saveexec_b64 s[14:15], s[14:15]
	v_mov_b32_e32 v59, s4
	s_xor_b64 exec, exec, s[14:15]
	s_cbranch_execz .LBB0_4328
	v_mov_b64_e32 v[2:3], s[0:1]
	global_load_dwordx2 v[6:7], v[2:3], off offset:136
	s_waitcnt vmcnt(0)
	s_lshl_b32 s4, s26, 7
	v_add_u32_e32 v2, s4, v130
	v_add_u32_e32 v8, 0x100, v2
	v_ashrrev_i32_e32 v9, 31, v8
	s_add_u32 s72, s38, 0x6200000
	s_addc_u32 s73, s39, 0
	s_mov_b32 s5, 0
	s_waitcnt lgkmcnt(0)
	v_lshl_add_u64 v[6:7], v[8:9], 2, v[6:7]
	global_load_dword v3, v[6:7], off nt

.LBB0_5332:
	v_mov_b64_e32 v[4:5], s[0:1]
	s_waitcnt lgkmcnt(0)
	s_barrier
	global_load_dwordx2 v[2:3], v[4:5], off offset:40
	s_waitcnt vmcnt(0)
	global_load_dwordx2 v[10:11], v[4:5], off offset:48
	s_waitcnt vmcnt(0)
	global_load_dwordx2 v[4:5], v[4:5], off offset:64
	s_waitcnt vmcnt(0)
	s_lshl_b32 s6, s5, 2
	s_add_i32 s6, s3, s6
	v_mov_b32_e32 v6, s6
	v_add_u32_e32 v6, 0xc00, v6
	ds_read2_b32 v[6:7], v6 offset1:8
	s_mov_b64 s[8:9], -1
	s_waitcnt lgkmcnt(0)
	v_cmp_gt_i32_e32 vcc, 32, v6
	v_readfirstlane_b32 s10, v6
	v_readfirstlane_b32 s11, v7
	s_cbranch_vccnz .LBB0_5334
	s_add_u32 s6, s18, 0xc00
	s_addc_u32 s7, s19, 0
	s_mov_b64 s[8:9], 0

.LBB0_5542:
	s_or_b64 exec, exec, s[6:7]
	v_mov_b32_e32 v1, v0
	v_mov_b64_e32 v[2:3], s[0:1]
	s_barrier
	global_load_dwordx2 v[2:3], v[2:3], off offset:88
	s_waitcnt vmcnt(0)
	v_readfirstlane_b32 s2, v1
	s_ashr_i32 s2, s2, 4
	s_and_b32 s3, s2, -4
	s_cmp_gt_i32 s3, 31
	s_cbranch_scc1 .LBB0_5545
	v_and_b32_e32 v21, 63, v1
	v_mov_b32_e32 v91, 0
	v_lshlrev_b32_e32 v90, 4, v21
	s_waitcnt lgkmcnt(0)
	v_lshl_add_u64 v[2:3], v[2:3], 0, v[90:91]
	s_movk_i32 s2, 0x5000
	v_add_co_u32_e32 v18, vcc, s2, v2
	v_and_b32_e32 v1, 64, v166
	s_nop 0
	v_addc_co_u32_e32 v19, vcc, 0, v3, vcc
	global_load_dwordx4 v[2:5], v[18:19], off
	global_load_dwordx4 v[6:9], v[18:19], off offset:1024
	global_load_dwordx4 v[10:13], v[18:19], off offset:2048
	global_load_dwordx4 v[14:17], v[18:19], off offset:3072
	v_add_u32_e32 v18, 64, v1
	v_xor_b32_e32 v1, 1, v166
	v_cmp_lt_i32_e32 vcc, v1, v18
	v_xor_b32_e32 v19, 2, v166
	s_lshl_b32 s4, s40, 5
	v_cndmask_b32_e32 v1, v166, v1, vcc
	v_cmp_lt_i32_e32 vcc, v19, v18
	s_add_i32 s3, s4, s3
	s_add_i32 s2, s4, 0x20a0
	v_cndmask_b32_e32 v19, v166, v19, vcc
	v_lshlrev_b32_e32 v167, 2, v19
	v_xor_b32_e32 v19, 4, v166
	v_cmp_lt_i32_e32 vcc, v19, v18
	s_add_i32 s12, s3, 0x2080
	s_add_u32 s3, s68, 0x5800000
	v_cndmask_b32_e32 v19, v166, v19, vcc
	v_lshlrev_b32_e32 v168, 2, v19
	v_xor_b32_e32 v19, 8, v166
	v_cmp_lt_i32_e32 vcc, v19, v18
	s_addc_u32 s4, s69, 0
	s_ashr_i32 s13, s12, 31
	v_cndmask_b32_e32 v19, v166, v19, vcc
	v_lshlrev_b32_e32 v169, 2, v19
	v_xor_b32_e32 v19, 16, v166
	v_cmp_lt_i32_e32 vcc, v19, v18
	s_lshl_b64 s[6:7], s[12:13], 11
	v_lshl_or_b32 v92, v21, 3, s6
	v_cndmask_b32_e32 v19, v166, v19, vcc
	v_lshlrev_b32_e32 v170, 2, v19
	v_xor_b32_e32 v19, 32, v166
	v_cmp_lt_i32_e32 vcc, v19, v18
	v_mov_b32_e32 v93, s7
	s_lshl_b64 s[6:7], s[12:13], 12
	v_cndmask_b32_e32 v18, v166, v19, vcc
	v_lshlrev_b32_e32 v171, 2, v18
	v_lshlrev_b32_e32 v18, 2, v21
	v_or_b32_e32 v20, 0x100, v18
	v_or_b32_e32 v22, 0x200, v18
	v_or_b32_e32 v24, 0x300, v18
	v_lshlrev_b32_e32 v1, 2, v1
	v_or_b32_e32 v94, s6, v90
	v_mov_b32_e32 v95, s7
	v_mov_b32_e32 v172, 0x358637bd
	s_mov_b32 s13, 0xf800000
	v_mov_b32_e32 v173, 0x260
	v_lshlrev_b32_e32 v90, 2, v18
	s_movk_i32 s22, 0x7fff
	s_mov_b32 s23, 0xffff0000
	s_mov_b32 s24, 0xba00000
	v_lshlrev_b32_e32 v96, 2, v20
	v_lshlrev_b32_e32 v98, 2, v22
	v_mov_b32_e32 v99, v91
	v_lshlrev_b32_e32 v100, 2, v24
	v_mov_b32_e32 v101, v91
	s_mov_b32 s25, 0xba01000
	s_mov_b64 s[14:15], 0x10000
	s_mov_b64 s[16:17], 0x20000
	v_mov_b32_e32 v97, v91

.LBB0_5555:
	s_or_b64 exec, exec, s[8:9]
	s_ashr_i32 s29, s16, 6
	s_add_i32 s30, s5, 0xc300
	s_add_i32 s14, s5, 0x14300
	v_add_u32_e32 v6, 0x800, v2
	s_add_u32 s12, s68, 0x16000000
	v_ashrrev_i32_e32 v71, 6, v6
	v_add_u32_e32 v6, 0xa00, v2
	s_addc_u32 s13, s69, 0
	s_lshl_b32 s3, s29, 3
	v_ashrrev_i32_e32 v72, 6, v6
	v_add_u32_e32 v6, 0xc00, v2
	s_and_b32 s4, s3, 0xfffffe0
	s_lshl_b32 s3, s29, 7
	v_ashrrev_i32_e32 v73, 6, v6
	v_add_u32_e32 v6, 0xe00, v2
	s_add_i32 s2, s94, 0x20180
	s_and_b32 s31, s3, 0x180
	v_ashrrev_i32_e32 v74, 6, v6
	v_lshlrev_b32_e32 v6, 2, v2
	v_and_b32_e32 v10, 31, v2
	s_cmp_lt_u32 s29, 4
	v_and_b32_e32 v6, 0x7c, v6
	v_lshlrev_b32_e32 v11, 2, v10
	s_cselect_b32 s3, 16, 32
	s_add_i32 s8, s31, s5
	v_mov_b32_e32 v43, 0
	v_lshlrev_b32_e32 v42, 2, v6
	v_and_b32_e32 v4, 63, v2
	v_add_u32_e32 v13, s8, v11
	v_ashrrev_i32_e32 v67, 6, v2
	v_add_u32_e32 v5, 0x200, v2
	v_lshl_add_u64 v[8:9], s[68:69], 0, v[42:43]
	s_mov_b64 s[8:9], 0x24400000
	s_movk_i32 s15, 0x41
	v_ashrrev_i32_e32 v68, 6, v5
	v_add_u32_e32 v15, 0x400, v2
	v_lshl_add_u64 v[44:45], v[8:9], 0, s[8:9]
	v_mad_u64_u32 v[8:9], s[8:9], v67, s15, v[4:5]
	v_ashrrev_i32_e32 v69, 6, v15
	v_add_u32_e32 v16, 0x600, v2
	v_lshl_add_u32 v79, v8, 2, s5
	v_mad_u64_u32 v[8:9], s[8:9], v68, s15, v[4:5]
	v_ashrrev_i32_e32 v70, 6, v16
	v_lshl_add_u32 v80, v8, 2, s5
	v_mad_u64_u32 v[8:9], s[8:9], v69, s15, v[4:5]
	v_lshl_add_u32 v81, v8, 2, s5
	v_mad_u64_u32 v[8:9], s[8:9], v70, s15, v[4:5]
	s_waitcnt vmcnt(0)
	v_lshl_add_u32 v82, v8, 2, s5
	v_mad_u64_u32 v[8:9], s[8:9], v71, s15, v[4:5]
	v_lshl_add_u32 v83, v8, 2, s5
	v_mad_u64_u32 v[8:9], s[8:9], v72, s15, v[4:5]
	v_add_u32_e32 v55, 0x518, v4
	v_add_u32_e32 v66, 0x618, v4
	v_ashrrev_i32_e32 v76, 5, v5
	v_lshl_add_u32 v84, v8, 2, s5
	v_mad_u64_u32 v[8:9], s[8:9], v73, s15, v[4:5]
	v_mad_u64_u32 v[4:5], s[8:9], v74, s15, v[4:5]
	v_lshl_add_u32 v86, v4, 2, s5
	v_lshlrev_b32_e32 v4, 4, v2
	v_add_u32_e32 v5, 0x4000, v4
	s_cmp_gt_i32 s29, 3
	v_add_u32_e32 v90, s30, v5
	v_add_u32_e32 v91, s14, v5
	v_add_u32_e32 v5, 0x6000, v4
	s_cselect_b64 s[8:9], -1, 0
	s_cmp_eq_u32 s29, 1
	v_bfe_u32 v7, v2, 5, 1
	v_add_u32_e32 v88, s14, v4
	v_add_u32_e32 v93, s14, v5
	s_cselect_b64 s[14:15], -1, 0
	s_ashr_i32 s34, s16, 2
	s_lshl_b32 s16, s29, 5
	v_lshlrev_b32_e32 v12, 2, v7
	v_ashrrev_i32_e32 v77, 5, v15
	v_mov_b32_e32 v15, s5
	v_add_u32_e32 v92, s30, v5
	s_or_b64 s[8:9], s[8:9], s[14:15]
	s_and_b32 s18, s34, 0xffffffe0
	v_and_or_b32 v5, s16, 32, v10
	s_movk_i32 s35, 0x104
	s_xor_b64 s[14:15], s[8:9], -1
	v_mad_u32_u24 v9, v5, s35, v15
	v_or_b32_e32 v15, s18, v12
	s_cmp_lt_i32 s29, 4
	v_cmp_gt_i32_e32 vcc, v5, v15
	v_or_b32_e32 v17, 1, v15
	s_cselect_b64 s[16:17], -1, 0
	s_or_b64 s[18:19], s[8:9], vcc
	v_cmp_gt_i32_e32 vcc, v5, v17
	v_or_b32_e32 v17, 2, v15
	s_or_b64 s[20:21], s[8:9], vcc
	v_cmp_gt_i32_e32 vcc, v5, v17
	v_or_b32_e32 v17, 3, v15
	s_or_b64 s[22:23], s[8:9], vcc
	v_cmp_gt_i32_e32 vcc, v5, v17
	v_or_b32_e32 v17, 8, v15
	s_or_b64 s[24:25], s[8:9], vcc
	v_cmp_gt_i32_e32 vcc, v5, v17
	v_or_b32_e32 v17, 9, v15
	s_or_b64 s[26:27], s[8:9], vcc
	v_cmp_gt_i32_e32 vcc, v5, v17
	v_or_b32_e32 v17, 10, v15
	s_or_b64 s[46:47], s[8:9], vcc
	v_cmp_gt_i32_e32 vcc, v5, v17
	v_or_b32_e32 v17, 11, v15
	s_or_b64 s[48:49], s[8:9], vcc
	v_cmp_gt_i32_e32 vcc, v5, v17
	v_or_b32_e32 v17, 16, v15
	s_or_b64 s[50:51], s[8:9], vcc
	v_cmp_gt_i32_e32 vcc, v5, v17
	v_or_b32_e32 v17, 17, v15
	s_or_b64 s[52:53], s[8:9], vcc
	v_cmp_gt_i32_e32 vcc, v5, v17
	v_or_b32_e32 v17, 18, v15
	s_or_b64 s[54:55], s[8:9], vcc
	v_cmp_gt_i32_e32 vcc, v5, v17
	v_or_b32_e32 v17, 19, v15
	s_or_b64 s[56:57], s[8:9], vcc
	v_cmp_gt_i32_e32 vcc, v5, v17
	v_or_b32_e32 v17, 24, v15
	s_or_b64 s[58:59], s[8:9], vcc
	v_cmp_gt_i32_e32 vcc, v5, v17
	v_or_b32_e32 v17, 25, v15
	v_ashrrev_i32_e32 v78, 5, v16
	v_lshlrev_b32_e32 v16, 8, v5
	s_or_b64 s[60:61], s[8:9], vcc
	v_cmp_gt_i32_e32 vcc, v5, v17
	v_or_b32_e32 v17, 26, v15
	v_or_b32_e32 v3, s4, v12
	s_movk_i32 s33, 0x210
	v_sub_u32_e32 v9, v9, v16
	v_mul_lo_u32 v16, v15, s35
	s_or_b64 s[62:63], s[8:9], vcc
	v_cmp_gt_i32_e32 vcc, v5, v17
	v_or_b32_e32 v15, 27, v15
	v_mul_lo_u32 v14, v3, s33
	v_ashrrev_i32_e32 v3, 31, v2
	s_or_b64 s[64:65], s[8:9], vcc
	v_cmp_gt_i32_e32 vcc, v5, v15
	v_ashrrev_i32_e32 v75, 5, v2
	s_or_b64 s[66:67], s[8:9], vcc
	v_ashrrev_i32_e32 v94, 3, v2
	v_lshl_add_u64 v[2:3], v[2:3], 2, s[68:69]
	s_mov_b64 s[8:9], 0x35c00000
	v_lshl_add_u64 v[56:57], v[2:3], 0, s[8:9]
	v_lshlrev_b32_e32 v2, 9, v7
	s_lshr_b32 s8, s29, 2
	v_or3_b32 v96, v2, s31, v11
	s_mulk_i32 s8, 0x2080
	v_mul_u32_u24_e32 v2, 0x104, v10
	v_lshl_add_u32 v85, v8, 2, s5
	v_mul_u32_u24_e32 v8, 0x104, v5
	v_add3_u32 v2, s8, v2, v12
	s_lshr_b32 s8, s34, 5
	v_add3_u32 v3, v8, v12, s5
	s_mulk_i32 s8, 0x2080
	v_add_u32_e32 v98, 0x8200, v3
	v_mov_b32_e32 v3, s8
	v_and_b32_e32 v54, 0x70, v4
	v_mad_u32_u24 v3, v10, s35, v3
	v_lshlrev_b32_e32 v46, 7, v75
	v_lshlrev_b32_e32 v48, 7, v76
	v_lshlrev_b32_e32 v50, 7, v77
	v_lshlrev_b32_e32 v52, 7, v78
	v_add_u32_e32 v87, s5, v4
	v_mul_lo_u32 v4, v94, s33
	v_lshlrev_b32_e32 v5, 2, v54
	v_add3_u32 v3, v3, v12, s5
	s_movk_i32 s4, 0x400
	v_ashrrev_i32_e32 v47, 31, v46
	v_ashrrev_i32_e32 v49, 31, v48
	v_ashrrev_i32_e32 v51, 31, v50
	v_ashrrev_i32_e32 v53, 31, v52
	s_movk_i32 s28, 0x2000
	v_add_u32_e32 v89, 0x2000, v88
	v_add3_u32 v95, s5, v4, v5
	v_add_u32_e32 v97, 0x4100, v2
	v_add_u32_e32 v99, 0x4100, v3
	v_add_u32_e32 v100, s30, v96
	v_add_u32_e32 v101, s5, v2
	s_mov_b32 s71, 0
	s_movk_i32 s29, 0x3000
	s_movk_i32 s30, 0x1000
	v_lshlrev_b32_e32 v58, 2, v6
	v_add_u32_e32 v102, v9, v16
	v_add_u32_e32 v103, v13, v14
	v_mov_b32_e32 v104, 0x358637bd
	s_mov_b32 s31, 0xf800000
	v_mov_b32_e32 v105, 0x260
	s_mov_b64 s[72:73], 0x24a0
	s_movk_i32 s33, 0x7fff
	s_mov_b32 s34, 0xffff0000
	s_mov_b64 s[74:75], 0xdc00400
	v_mov_b32_e32 v229, v1
	s_branch .LBB0_5557

.LBB0_5557:
	s_barrier
	s_and_saveexec_b64 s[8:9], s[6:7]
	v_mov_b32_e32 v2, s2
	ds_write_b32 v2, v1
	s_or_b64 exec, exec, s[8:9]
	v_mov_b32_e32 v2, s2
	s_waitcnt lgkmcnt(0)
	s_barrier
	ds_read_b32 v2, v2
	s_mov_b64 s[76:77], -1
	s_waitcnt lgkmcnt(0)
	v_cmp_gt_i32_e32 vcc, s4, v2
	v_readfirstlane_b32 s8, v2
	s_cbranch_vccz .LBB0_5556
	s_and_saveexec_b64 s[76:77], s[6:7]
	s_cbranch_execz .LBB0_5564
	s_mov_b64 s[80:81], exec
	v_mbcnt_lo_u32_b32 v1, s80, 0
	v_mbcnt_hi_u32_b32 v1, s81, v1
	v_cmp_eq_u32_e32 vcc, 0, v1
	s_and_saveexec_b64 s[78:79], vcc
	s_cbranch_execz .LBB0_5563
	s_bcnt1_i32_b64 s9, s[80:81]
	v_mov_b32_e32 v2, s9
	global_atomic_add v229, v43, v2, s[10:11] sc0

.LBB0_5564:
	s_or_b64 exec, exec, s[76:77]
	s_lshl_b32 s9, s8, 4
	s_lshl_b32 s36, s8, 6
	s_and_b32 s9, s9, 0xffffe000
	s_and_b32 s36, s36, 0x1fc0
	s_or_b32 s36, s9, s36
	s_ashr_i32 s9, s8, 31
	s_bfe_u32 s35, s8, 0x20007
	s_lshl_b64 s[42:43], s[8:9], 14
	s_lshl_b32 s37, s35, 6
	v_add_u32_e32 v2, s36, v67
	v_mov_b64_e32 v[26:27], s[12:13]
	v_lshl_add_u64 v[4:5], v[56:57], 0, s[42:43]
	v_add_u32_e32 v10, s36, v68
	v_mad_i64_i32 v[2:3], s[44:45], v2, s29, v[26:27]
	v_add_lshl_u32 v42, v55, s37, 2
	v_add_lshl_u32 v8, v66, s37, 2
	v_mov_b32_e32 v9, v43
	v_mad_i64_i32 v[10:11], s[42:43], v10, s29, v[26:27]
	v_add_co_u32_e32 v14, vcc, s30, v4
	v_lshl_add_u64 v[6:7], v[2:3], 0, v[42:43]
	v_lshl_add_u64 v[2:3], v[2:3], 0, v[8:9]
	v_lshl_add_u64 v[12:13], v[10:11], 0, v[42:43]
	v_lshl_add_u64 v[10:11], v[10:11], 0, v[8:9]
	v_addc_co_u32_e32 v15, vcc, 0, v5, vcc
	global_load_dword v34, v[4:5], off
	global_load_dword v35, v[6:7], off
	global_load_dword v36, v[2:3], off
	global_load_dword v37, v[12:13], off
	global_load_dword v38, v[10:11], off
	global_load_dword v39, v[14:15], off
	global_load_dword v40, v[14:15], off offset:2048
	global_load_dword v41, v[4:5], off offset:2048
	v_add_u32_e32 v2, s36, v69
	v_mad_i64_i32 v[2:3], s[42:43], v2, s29, v[26:27]
	v_add_u32_e32 v10, s36, v70
	v_add_u32_e32 v14, s36, v71
	v_lshl_add_u64 v[6:7], v[2:3], 0, v[42:43]
	v_mad_i64_i32 v[10:11], s[42:43], v10, s29, v[26:27]
	v_mad_i64_i32 v[14:15], s[42:43], v14, s29, v[26:27]
	v_add_co_u32_e32 v16, vcc, s28, v4
	v_lshl_add_u64 v[2:3], v[2:3], 0, v[8:9]
	v_lshl_add_u64 v[12:13], v[10:11], 0, v[42:43]
	v_lshl_add_u64 v[10:11], v[10:11], 0, v[8:9]
	v_addc_co_u32_e32 v17, vcc, 0, v5, vcc
	v_lshl_add_u64 v[18:19], v[14:15], 0, v[42:43]
	v_lshl_add_u64 v[14:15], v[14:15], 0, v[8:9]
	global_load_dword v60, v[6:7], off
	global_load_dword v61, v[2:3], off
	global_load_dword v62, v[12:13], off
	global_load_dword v63, v[10:11], off
	global_load_dword v64, v[16:17], off
	global_load_dword v65, v[18:19], off
	global_load_dword v106, v[14:15], off
	global_load_dword v107, v[16:17], off offset:2048
	v_add_u32_e32 v20, s36, v72
	v_mad_i64_i32 v[20:21], s[42:43], v20, s29, v[26:27]
	v_add_u32_e32 v10, s36, v73
	v_add_u32_e32 v14, s36, v74
	v_lshl_add_u64 v[2:3], v[20:21], 0, v[42:43]
	v_mad_i64_i32 v[10:11], s[42:43], v10, s29, v[26:27]
	v_add_co_u32_e32 v4, vcc, s29, v4
	v_mad_i64_i32 v[14:15], s[42:43], v14, s29, v[26:27]
	v_lshl_add_u64 v[6:7], v[20:21], 0, v[8:9]
	v_addc_co_u32_e32 v5, vcc, 0, v5, vcc
	v_lshl_add_u64 v[12:13], v[10:11], 0, v[42:43]
	v_lshl_add_u64 v[10:11], v[10:11], 0, v[8:9]
	v_lshl_add_u64 v[16:17], v[14:15], 0, v[42:43]
	v_lshl_add_u64 v[8:9], v[14:15], 0, v[8:9]
	global_load_dword v42, v[2:3], off
	global_load_dword v108, v[6:7], off
	global_load_dword v109, v[4:5], off
	global_load_dword v110, v[12:13], off
	global_load_dword v111, v[10:11], off
	global_load_dword v112, v[16:17], off
	global_load_dword v113, v[8:9], off
	global_load_dword v114, v[4:5], off offset:2048
	s_lshl_b64 s[8:9], s[8:9], 15
	v_add_u32_e32 v2, s36, v75
	v_lshl_add_u64 v[28:29], v[44:45], 0, s[8:9]
	v_mad_i64_i32 v[2:3], s[8:9], v2, s29, v[26:27]
	s_lshl_b32 s70, s35, 9
	v_lshl_add_u64 v[2:3], v[2:3], 0, s[70:71]
	v_mov_b32_e32 v59, v43
	v_add_u32_e32 v10, s36, v76
	v_lshl_add_u64 v[2:3], v[2:3], 0, v[58:59]
	v_mad_i64_i32 v[10:11], s[8:9], v10, s29, v[26:27]
	v_add_co_u32_e32 v2, vcc, s30, v2
	v_lshl_add_u64 v[10:11], v[10:11], 0, s[70:71]
	v_add_u32_e32 v18, s36, v77
	v_addc_co_u32_e32 v3, vcc, 0, v3, vcc
	v_lshl_add_u64 v[10:11], v[10:11], 0, v[58:59]
	v_mad_i64_i32 v[18:19], s[8:9], v18, s29, v[26:27]
	v_add_co_u32_e32 v10, vcc, s30, v10
	v_lshl_add_u64 v[18:19], v[18:19], 0, s[70:71]
	v_add_u32_e32 v30, s36, v78
	v_addc_co_u32_e32 v11, vcc, 0, v11, vcc
	v_lshl_add_u64 v[18:19], v[18:19], 0, v[58:59]
	v_mad_i64_i32 v[26:27], s[8:9], v30, s29, v[26:27]
	v_add_co_u32_e32 v18, vcc, s30, v18
	v_lshl_add_u64 v[26:27], v[26:27], 0, s[70:71]
	s_nop 0
	v_addc_co_u32_e32 v19, vcc, 0, v19, vcc
	v_lshl_add_u64 v[26:27], v[26:27], 0, v[58:59]
	v_add_co_u32_e32 v26, vcc, s30, v26
	v_lshl_add_u64 v[6:7], v[46:47], 2, v[28:29]
	v_lshl_add_u64 v[14:15], v[48:49], 2, v[28:29]
	v_lshl_add_u64 v[22:23], v[50:51], 2, v[28:29]
	v_addc_co_u32_e32 v27, vcc, 0, v27, vcc
	v_lshl_add_u64 v[30:31], v[52:53], 2, v[28:29]
	global_load_dwordx4 v[2:5], v[2:3], off offset:3168
	s_nop 0
	global_load_dwordx4 v[6:9], v[6:7], off
	s_nop 0
	global_load_dwordx4 v[10:13], v[10:11], off offset:3168
	s_nop 0
	global_load_dwordx4 v[14:17], v[14:15], off
	s_nop 0
	global_load_dwordx4 v[18:21], v[18:19], off offset:3168
	s_nop 0
	global_load_dwordx4 v[22:25], v[22:23], off
	s_nop 0
	global_load_dwordx4 v[26:29], v[26:27], off offset:3168
	s_nop 0
	global_load_dwordx4 v[30:33], v[30:31], off
	s_waitcnt vmcnt(0) lgkmcnt(0)
	v_mul_f32_e32 v59, 0x3fb8aa3b, v34
	v_mul_f32_e32 v34, 0xbfb8aa3b, v34
	v_exp_f32_e32 v34, v34
	v_exp_f32_e32 v59, v59
	v_mul_f32_e32 v35, 0x3e000000, v35
	v_mul_f32_e32 v34, v36, v34
	v_mul_f32_e32 v36, 0x3fb8aa3b, v41
	v_exp_f32_e32 v36, v36
	v_mul_f32_e32 v35, v35, v59
	v_mul_f32_e32 v41, 0xbfb8aa3b, v41
	s_barrier
	v_add_u32_e32 v232, s36, v94
	v_mov_b64_e32 v[234:235], s[12:13]
	s_lshl_b32 s98, s35, 2
	s_mov_b32 s99, 0
	v_lshlrev_b32_e32 v230, 2, v54
	v_mov_b32_e32 v231, 0
	v_mad_i64_i32 v[234:235], s[100:101], v232, s29, v[234:235]
	v_lshl_add_u64 v[234:235], v[234:235], 0, s[98:99]
	v_lshl_add_u64 v[234:235], v[234:235], 0, v[230:231]
	v_lshl_add_u64 v[234:235], v[234:235], 0, s[72:73]
	global_load_dword v236, v[234:235], off
	v_exp_f32_e32 v41, v41
	ds_write2st64_b32 v79, v35, v34 offset0:65 offset1:130
	v_mul_f32_e32 v34, 0x3e000000, v37
	v_mul_f32_e32 v34, v34, v36
	v_mul_f32_e32 v36, 0x3fb8aa3b, v39
	v_mul_f32_e32 v37, 0xbfb8aa3b, v39
	v_exp_f32_e32 v36, v36
	v_exp_f32_e32 v37, v37
	v_mul_f32_e32 v35, v38, v41
	ds_write2st64_b32 v80, v34, v35 offset0:65 offset1:130
	v_mul_f32_e32 v34, 0x3e000000, v60
	v_mul_f32_e32 v34, v34, v36
	v_mul_f32_e32 v35, v61, v37
	v_mul_f32_e32 v36, 0x3fb8aa3b, v40
	v_mul_f32_e32 v37, 0xbfb8aa3b, v40
	v_exp_f32_e32 v36, v36
	v_exp_f32_e32 v37, v37
	ds_write2st64_b32 v81, v34, v35 offset0:65 offset1:130
	v_mul_f32_e32 v34, 0x3e000000, v62
	v_mul_f32_e32 v34, v34, v36
	v_mul_f32_e32 v35, v63, v37
	v_mul_f32_e32 v36, 0x3fb8aa3b, v64
	v_mul_f32_e32 v37, 0xbfb8aa3b, v64
	v_exp_f32_e32 v36, v36
	v_exp_f32_e32 v37, v37
	ds_write2st64_b32 v82, v34, v35 offset0:65 offset1:130
	v_mul_f32_e32 v34, 0x3e000000, v65
	v_mul_f32_e32 v34, v34, v36
	v_mul_f32_e32 v35, v106, v37
	v_mul_f32_e32 v36, 0x3fb8aa3b, v107
	v_mul_f32_e32 v37, 0xbfb8aa3b, v107
	v_exp_f32_e32 v36, v36
	v_exp_f32_e32 v37, v37
	ds_write2st64_b32 v83, v34, v35 offset0:65 offset1:130
	v_mul_f32_e32 v34, 0x3e000000, v42
	v_mul_f32_e32 v34, v34, v36
	v_mul_f32_e32 v35, v108, v37
	v_mul_f32_e32 v36, 0x3fb8aa3b, v109
	v_mul_f32_e32 v37, 0xbfb8aa3b, v109
	v_exp_f32_e32 v36, v36
	v_exp_f32_e32 v37, v37
	ds_write2st64_b32 v84, v34, v35 offset0:65 offset1:130
	v_mul_f32_e32 v34, 0x3e000000, v110
	v_mul_f32_e32 v34, v34, v36
	v_mul_f32_e32 v35, v111, v37
	v_mul_f32_e32 v36, 0x3fb8aa3b, v114
	v_mul_f32_e32 v37, 0xbfb8aa3b, v114
	v_exp_f32_e32 v36, v36
	v_exp_f32_e32 v37, v37
	ds_write2st64_b32 v85, v34, v35 offset0:65 offset1:130
	v_mul_f32_e32 v34, 0x3e000000, v112
	v_mul_f32_e32 v34, v34, v36
	v_mul_f32_e32 v35, v113, v37
	ds_write2st64_b32 v86, v34, v35 offset0:65 offset1:130
	ds_write_b128 v87, v[2:5] offset:49920
	ds_write_b128 v88, v[6:9]
	ds_write_b128 v87, v[10:13] offset:58112
	ds_write_b128 v89, v[14:17]
	ds_write_b128 v90, v[18:21]
	ds_write_b128 v91, v[22:25]
	ds_write_b128 v92, v[26:29]
	ds_write_b128 v93, v[30:33]
	v_mov_b32_e32 v2, 0
	s_lshl_b32 s35, s35, 7
	s_mov_b32 s8, 32
	v_mov_b32_e32 v18, v97
	v_mov_b32_e32 v19, v96
	v_mov_b32_e32 v3, v2
	v_mov_b32_e32 v4, v2
	v_mov_b32_e32 v5, v2
	v_mov_b32_e32 v6, v2
	v_mov_b32_e32 v7, v2
	v_mov_b32_e32 v8, v2
	v_mov_b32_e32 v9, v2
	v_mov_b32_e32 v10, v2
	v_mov_b32_e32 v11, v2
	v_mov_b32_e32 v12, v2
	v_mov_b32_e32 v13, v2
	v_mov_b32_e32 v14, v2
	v_mov_b32_e32 v15, v2
	v_mov_b32_e32 v16, v2
	v_mov_b32_e32 v17, v2
	s_waitcnt lgkmcnt(0)
	s_barrier

.LBB0_5572:
	ds_read2_b32 v[20:21], v18 offset1:2
	ds_read2st64_b32 v[22:23], v19 offset1:4
	s_add_i32 s8, s8, -8
	s_cmp_lg_u32 s8, 0
	s_waitcnt lgkmcnt(0)
	v_mfma_f32_32x32x2_f32 v[2:17], v20, v22, v[2:17]
	v_mfma_f32_32x32x2_f32 v[2:17], v21, v23, v[2:17]
	ds_read2_b32 v[20:21], v18 offset0:4 offset1:6
	ds_read2st64_b32 v[22:23], v19 offset0:8 offset1:12
	s_waitcnt lgkmcnt(0)
	v_mfma_f32_32x32x2_f32 v[2:17], v20, v22, v[2:17]
	v_mfma_f32_32x32x2_f32 v[2:17], v21, v23, v[2:17]
	ds_read2_b32 v[20:21], v18 offset0:8 offset1:10
	ds_read2st64_b32 v[22:23], v19 offset0:16 offset1:20
	s_waitcnt lgkmcnt(0)
	v_mfma_f32_32x32x2_f32 v[2:17], v20, v22, v[2:17]
	v_mfma_f32_32x32x2_f32 v[2:17], v21, v23, v[2:17]
	ds_read2_b32 v[20:21], v18 offset0:12 offset1:14
	ds_read2st64_b32 v[22:23], v19 offset0:24 offset1:28
	v_add_u32_e32 v19, 0x2000, v19
	v_add_u32_e32 v18, 64, v18
	s_waitcnt lgkmcnt(0)
	v_mfma_f32_32x32x2_f32 v[2:17], v20, v22, v[2:17]
	v_mfma_f32_32x32x2_f32 v[2:17], v21, v23, v[2:17]
	s_cbranch_scc1 .LBB0_5572
	v_add_u32_e32 v18, 0xc200, v103
	s_barrier
	s_nop 14
	ds_write2_b32 v18, v2, v3 offset0:64 offset1:196
	v_add_u32_e32 v2, 0xc600, v103
	ds_write2_b32 v2, v4, v5 offset0:72 offset1:204
	v_add_u32_e32 v2, 0xd200, v103
	ds_write2_b32 v2, v6, v7 offset0:96 offset1:228
	v_add_u32_e32 v2, 0xd600, v103
	ds_write2_b32 v2, v8, v9 offset0:104 offset1:236
	v_add_u32_e32 v2, 0xe400, v103
	ds_write2_b32 v2, v10, v11 offset1:132
	v_add_u32_e32 v2, 0xe800, v103
	ds_write2_b32 v2, v12, v13 offset0:8 offset1:140
	v_add_u32_e32 v2, 0xf400, v103
	ds_write2_b32 v2, v14, v15 offset0:32 offset1:164
	v_add_u32_e32 v2, 0xf800, v103
	v_mov_b64_e32 v[18:19], s[0:1]
	ds_write2_b32 v2, v16, v17 offset0:40 offset1:172
	s_waitcnt lgkmcnt(0)
	s_barrier
	ds_read_b128 v[14:17], v95 offset:49920
	ds_read_b128 v[10:13], v95 offset:49936
	ds_read_b128 v[6:9], v95 offset:49952
	ds_read_b128 v[2:5], v95 offset:49968
	global_load_dwordx2 v[22:23], v[18:19], off offset:168
	s_waitcnt vmcnt(0)
	v_mov_b32_e32 v1, v229
	v_add_u32_e32 v60, s36, v94
	v_mov_b64_e32 v[18:19], s[12:13]
	v_and_b32_e32 v21, 64, v166
	s_lshl_b32 s70, s35, 2
	v_mad_i64_i32 v[18:19], s[8:9], v60, s29, v[18:19]
	v_xor_b32_e32 v20, 1, v166
	v_lshlrev_b32_e32 v42, 2, v54
	v_add_u32_e32 v59, 64, v21
	v_lshl_add_u64 v[18:19], v[18:19], 0, s[70:71]
	v_cmp_lt_i32_e32 vcc, v20, v59
	v_lshl_add_u64 v[30:31], v[18:19], 0, v[42:43]
	s_waitcnt lgkmcnt(0)
	v_mov_b32_e32 v26, v15
	v_cndmask_b32_e32 v20, v166, v20, vcc
	v_add_co_u32_e32 v18, vcc, s28, v30
	v_lshlrev_b32_e32 v61, 2, v20
	s_nop 0
	v_addc_co_u32_e32 v19, vcc, 0, v31, vcc
	global_load_dwordx4 v[18:21], v[18:19], off offset:1184
	v_mov_b32_e32 v27, v11
	v_mov_b32_e32 v24, v14
	v_mov_b32_e32 v25, v10
	v_mov_b32_e32 v36, v7
	v_mov_b32_e32 v37, v3
	v_pk_mul_f32 v[26:27], v[26:27], v[26:27]
	v_mov_b32_e32 v28, v16
	v_mov_b32_e32 v29, v12
	v_mov_b32_e32 v34, v6
	v_mov_b32_e32 v35, v2
	v_pk_mul_f32 v[36:37], v[36:37], v[36:37]
	v_pk_fma_f32 v[24:25], v[24:25], v[24:25], v[26:27]
	v_mov_b32_e32 v32, v17
	v_mov_b32_e32 v33, v13
	v_mov_b32_e32 v38, v8
	v_mov_b32_e32 v39, v4
	v_pk_fma_f32 v[26:27], v[34:35], v[34:35], v[36:37]
	v_pk_fma_f32 v[24:25], v[28:29], v[28:29], v[24:25]
	v_mov_b32_e32 v40, v9
	v_mov_b32_e32 v41, v5
	v_pk_fma_f32 v[26:27], v[38:39], v[38:39], v[26:27]
	v_pk_fma_f32 v[24:25], v[32:33], v[32:33], v[24:25]
	v_pk_fma_f32 v[26:27], v[40:41], v[40:41], v[26:27]
	v_add_f32_e32 v24, v24, v25
	v_add_f32_e32 v24, v24, v26
	v_add_f32_e32 v24, v24, v27
	ds_bpermute_b32 v25, v61, v24
	v_xor_b32_e32 v26, 2, v166
	v_cmp_lt_i32_e32 vcc, v26, v59
	v_lshl_add_u64 v[62:63], v[30:31], 0, s[72:73]
	v_mov_b32_e32 v38, v14
	v_cndmask_b32_e32 v26, v166, v26, vcc
	v_lshlrev_b32_e32 v26, 2, v26
	s_waitcnt lgkmcnt(0)
	v_add_f32_e32 v24, v24, v25
	ds_bpermute_b32 v25, v26, v24
	v_ashrrev_i32_e32 v61, 31, v60
	s_lshl_b32 s70, s35, 1
	s_mov_b64 s[76:77], 0
	s_waitcnt lgkmcnt(0)
	v_add_f32_e32 v32, v24, v25
	v_lshl_add_u64 v[64:65], v[22:23], 0, v[42:43]
	global_load_dwordx4 v[26:29], v[64:65], off offset:512
	v_xor_b32_e32 v22, 4, v166
	v_cmp_lt_i32_e32 vcc, v22, v59
	s_nop 1
	v_cndmask_b32_e32 v22, v166, v22, vcc
	v_lshlrev_b32_e32 v22, 2, v22
	ds_bpermute_b32 v33, v22, v32
	global_load_dwordx4 v[22:25], v[64:65], off offset:528
	s_waitcnt lgkmcnt(0)
	v_add_f32_e32 v30, v32, v33
	v_fmamk_f32 v30, v30, 0x3c000000, v104
	v_mul_f32_e32 v31, 0x4f800000, v30
	v_cmp_gt_f32_e32 vcc, s31, v30
	s_nop 1
	v_cndmask_b32_e32 v39, v30, v31, vcc
	v_sqrt_f32_e32 v40, v39
	global_load_dwordx4 v[30:33], v[62:63], off offset:16
	global_load_dwordx4 v[34:37], v[62:63], off offset:48
	v_add_u32_e32 v14, -1, v40
	v_add_u32_e32 v41, 1, v40
	v_fma_f32 v42, -v14, v40, v39
	v_fma_f32 v59, -v41, v40, v39
	v_cmp_ge_f32_e64 s[8:9], 0, v42
	s_nop 1
	v_cndmask_b32_e64 v14, v40, v14, s[8:9]
	v_cmp_lt_f32_e64 s[8:9], 0, v59
	s_nop 1
	v_cndmask_b32_e64 v14, v14, v41, s[8:9]
	v_mul_f32_e32 v40, 0x37800000, v14
	v_cndmask_b32_e32 v14, v14, v40, vcc
	v_cmp_class_f32_e32 vcc, v39, v105
	s_nop 1
	v_cndmask_b32_e32 v14, v14, v39, vcc
	v_div_scale_f32 v40, s[8:9], v14, v14, 1.0
	v_rcp_f32_e32 v41, v40
	v_mov_b32_e32 v39, v16
	v_div_scale_f32 v16, vcc, 1.0, v14, 1.0
	v_fma_f32 v42, -v40, v41, 1.0
	v_fmac_f32_e32 v41, v42, v41
	v_mul_f32_e32 v42, v16, v41
	v_fma_f32 v59, -v40, v42, v16
	v_fmac_f32_e32 v42, v59, v41
	v_fma_f32 v16, -v40, v42, v16
	v_div_fmas_f32 v16, v16, v41, v42
	v_div_fixup_f32 v14, v16, v14, 1.0
	v_pk_mul_f32 v[110:111], v[38:39], v[14:15] op_sel_hi:[1,0]
	s_waitcnt vmcnt(0)
	v_mul_f32_e32 v16, 0xbfb8aa3b, v18
	v_mul_f32_e32 v38, 0xbfb8aa3b, v20
	v_exp_f32_e32 v112, v16
	v_exp_f32_e32 v113, v38
	v_mul_f32_e32 v16, 0xbfb8aa3b, v19
	global_load_dwordx4 v[38:41], v[64:65], off offset:560
	global_load_dwordx4 v[106:109], v[64:65], off offset:544
	v_exp_f32_e32 v64, v16
	v_pk_add_f32 v[112:113], v[112:113], 1.0 op_sel_hi:[1,0]
	s_nop 0
	v_div_scale_f32 v16, s[8:9], v113, v113, v20
	v_rcp_f32_e32 v65, v16
	v_div_scale_f32 v59, s[8:9], v112, v112, v18
	v_rcp_f32_e32 v116, v59
	v_fma_f32 v114, -v16, v65, 1.0
	v_div_scale_f32 v42, vcc, v20, v113, v20
	v_fmac_f32_e32 v65, v114, v65
	v_fma_f32 v115, -v59, v116, 1.0
	v_mul_f32_e32 v114, v42, v65
	v_fmac_f32_e32 v116, v115, v116
	v_fma_f32 v115, -v16, v114, v42
	v_fmac_f32_e32 v114, v115, v65
	v_fma_f32 v16, -v16, v114, v42
	v_div_fmas_f32 v16, v16, v65, v114
	v_div_scale_f32 v117, s[8:9], v18, v112, v18
	v_div_fixup_f32 v113, v16, v113, v20
	v_mul_f32_e32 v20, 0xbfb8aa3b, v21
	v_mul_f32_e32 v118, v117, v116
	v_exp_f32_e32 v65, v20
	v_fma_f32 v119, -v59, v118, v117
	v_fmac_f32_e32 v118, v119, v116
	v_fma_f32 v16, -v59, v118, v117
	s_mov_b64 vcc, s[8:9]
	v_div_fmas_f32 v16, v16, v116, v118
	v_pk_add_f32 v[64:65], v[64:65], 1.0 op_sel_hi:[1,0]
	v_div_fixup_f32 v112, v16, v112, v18
	v_mov_b32_e32 v16, v15
	v_div_scale_f32 v15, s[8:9], v65, v65, v21
	v_rcp_f32_e32 v18, v15
	v_mov_b32_e32 v114, v26
	v_mov_b32_e32 v115, v28
	v_mov_b32_e32 v28, v27
	v_fma_f32 v20, -v15, v18, 1.0
	v_fmac_f32_e32 v18, v20, v18
	v_div_scale_f32 v20, vcc, v21, v65, v21
	v_mul_f32_e32 v26, v20, v18
	v_fma_f32 v27, -v15, v26, v20
	v_fmac_f32_e32 v26, v27, v18
	v_pk_mul_f32 v[16:17], v[16:17], v[14:15] op_sel_hi:[1,0]
	v_fma_f32 v15, -v15, v26, v20
	v_div_scale_f32 v20, s[8:9], v64, v64, v19
	v_rcp_f32_e32 v27, v20
	v_div_fmas_f32 v15, v15, v18, v26
	v_div_fixup_f32 v21, v15, v65, v21
	v_pk_mul_f32 v[16:17], v[28:29], v[16:17]
	v_fma_f32 v15, -v20, v27, 1.0
	v_fmac_f32_e32 v27, v15, v27
	v_div_scale_f32 v15, vcc, v19, v64, v19
	v_mul_f32_e32 v18, v15, v27
	v_fma_f32 v26, -v20, v18, v15
	v_fmac_f32_e32 v18, v26, v27
	v_fma_f32 v15, -v20, v18, v15
	v_div_fmas_f32 v15, v15, v27, v18
	v_div_fixup_f32 v20, v15, v64, v19
	v_pk_mul_f32 v[20:21], v[20:21], v[16:17]
	global_load_dwordx4 v[16:19], v[62:63], off offset:32
	s_waitcnt lgkmcnt(0)
	v_mul_f32_e32 v15, 0xbfb8aa3b, v30
	v_exp_f32_e32 v26, v15
	v_mul_f32_e32 v15, 0xbfb8aa3b, v31
	v_exp_f32_e32 v28, v15
	v_mul_f32_e32 v15, 0xbfb8aa3b, v32
	v_exp_f32_e32 v27, v15
	v_mov_b32_e32 v62, v10
	v_mov_b32_e32 v63, v12
	v_pk_mul_f32 v[62:63], v[62:63], v[14:15] op_sel_hi:[1,0]
	v_pk_add_f32 v[26:27], v[26:27], 1.0 op_sel_hi:[1,0]
	v_mov_b32_e32 v64, v22
	v_div_scale_f32 v10, s[8:9], v27, v27, v32
	v_rcp_f32_e32 v12, v10
	v_mov_b32_e32 v65, v24
	v_pk_mul_f32 v[110:111], v[114:115], v[110:111]
	v_pk_mul_f32 v[62:63], v[62:63], v[64:65]
	v_fma_f32 v15, -v10, v12, 1.0
	v_fmac_f32_e32 v12, v15, v12
	v_div_scale_f32 v15, vcc, v32, v27, v32
	v_mul_f32_e32 v22, v15, v12
	v_fma_f32 v24, -v10, v22, v15
	v_fmac_f32_e32 v22, v24, v12
	v_fma_f32 v10, -v10, v22, v15
	v_div_scale_f32 v15, s[8:9], v26, v26, v30
	v_rcp_f32_e32 v24, v15
	v_div_fmas_f32 v10, v10, v12, v22
	v_div_fixup_f32 v27, v10, v27, v32
	v_pk_mul_f32 v[110:111], v[112:113], v[110:111]
	v_fma_f32 v10, -v15, v24, 1.0
	v_fmac_f32_e32 v24, v10, v24
	v_div_scale_f32 v10, vcc, v30, v26, v30
	v_mul_f32_e32 v12, v10, v24
	v_fma_f32 v22, -v15, v12, v10
	v_fmac_f32_e32 v12, v22, v24
	v_fma_f32 v10, -v15, v12, v10
	v_div_fmas_f32 v10, v10, v24, v12
	v_mul_f32_e32 v12, 0xbfb8aa3b, v33
	v_exp_f32_e32 v29, v12
	v_div_fixup_f32 v26, v10, v26, v30
	v_mov_b32_e32 v12, v11
	v_mov_b32_e32 v24, v23
	v_pk_add_f32 v[10:11], v[28:29], 1.0 op_sel_hi:[1,0]
	v_pk_mul_f32 v[26:27], v[62:63], v[26:27]
	v_div_scale_f32 v15, s[8:9], v11, v11, v33
	v_rcp_f32_e32 v22, v15
	v_pk_mul_f32 v[12:13], v[12:13], v[14:15] op_sel_hi:[1,0]
	v_lshlrev_b32_e32 v42, 1, v54
	v_pk_mul_f32 v[12:13], v[12:13], v[24:25]
	v_fma_f32 v23, -v15, v22, 1.0
	v_fmac_f32_e32 v22, v23, v22
	v_div_scale_f32 v23, vcc, v33, v11, v33
	v_mul_f32_e32 v24, v23, v22
	v_fma_f32 v25, -v15, v24, v23
	v_fmac_f32_e32 v24, v25, v22
	v_fma_f32 v15, -v15, v24, v23
	v_div_scale_f32 v23, s[8:9], v10, v10, v31
	v_rcp_f32_e32 v25, v23
	v_div_fmas_f32 v15, v15, v22, v24
	v_div_fixup_f32 v11, v15, v11, v33
	v_fma_f32 v15, -v23, v25, 1.0
	v_fmac_f32_e32 v25, v15, v25
	v_div_scale_f32 v15, vcc, v31, v10, v31
	v_mul_f32_e32 v22, v15, v25
	v_fma_f32 v24, -v23, v22, v15
	v_fmac_f32_e32 v22, v24, v25
	v_fma_f32 v15, -v23, v22, v15
	v_div_fmas_f32 v15, v15, v25, v22
	v_div_fixup_f32 v10, v15, v10, v31
	v_pk_mul_f32 v[10:11], v[12:13], v[10:11]
	v_cvt_pk_bf16_f32 v13, v27, v11
	v_cvt_pk_bf16_f32 v11, v111, v21
	s_waitcnt vmcnt(0)
	v_mul_f32_e32 v15, 0xbfb8aa3b, v16
	v_cvt_pk_bf16_f32 v12, v26, v10
	v_cvt_pk_bf16_f32 v10, v110, v20
	v_exp_f32_e32 v20, v15
	v_mul_f32_e32 v15, 0xbfb8aa3b, v17
	v_exp_f32_e32 v22, v15
	v_mul_f32_e32 v15, 0xbfb8aa3b, v18
	v_exp_f32_e32 v21, v15
	v_mov_b32_e32 v24, v6
	v_mov_b32_e32 v25, v8
	v_pk_mul_f32 v[24:25], v[24:25], v[14:15] op_sel_hi:[1,0]
	v_pk_add_f32 v[20:21], v[20:21], 1.0 op_sel_hi:[1,0]
	v_mov_b32_e32 v26, v106
	v_div_scale_f32 v6, s[8:9], v21, v21, v18
	v_rcp_f32_e32 v8, v6
	v_mov_b32_e32 v27, v108
	v_pk_mul_f32 v[24:25], v[24:25], v[26:27]
	v_mov_b32_e32 v108, v107
	v_fma_f32 v15, -v6, v8, 1.0
	v_fmac_f32_e32 v8, v15, v8
	v_div_scale_f32 v15, vcc, v18, v21, v18
	v_mul_f32_e32 v23, v15, v8
	v_fma_f32 v26, -v6, v23, v15
	v_fmac_f32_e32 v23, v26, v8
	v_fma_f32 v6, -v6, v23, v15
	v_div_scale_f32 v15, s[8:9], v20, v20, v16
	v_rcp_f32_e32 v26, v15
	v_div_fmas_f32 v6, v6, v8, v23
	v_div_fixup_f32 v21, v6, v21, v18
	v_fma_f32 v6, -v15, v26, 1.0
	v_fmac_f32_e32 v26, v6, v26
	v_div_scale_f32 v6, vcc, v16, v20, v16
	v_mul_f32_e32 v8, v6, v26
	v_fma_f32 v18, -v15, v8, v6
	v_fmac_f32_e32 v8, v18, v26
	v_fma_f32 v6, -v15, v8, v6
	v_div_fmas_f32 v6, v6, v26, v8
	v_mul_f32_e32 v8, 0xbfb8aa3b, v19
	v_exp_f32_e32 v23, v8
	v_div_fixup_f32 v20, v6, v20, v16
	v_mov_b32_e32 v8, v7
	v_pk_mul_f32 v[20:21], v[24:25], v[20:21]
	v_pk_add_f32 v[6:7], v[22:23], 1.0 op_sel_hi:[1,0]
	s_nop 0
	v_div_scale_f32 v15, s[8:9], v7, v7, v19
	v_rcp_f32_e32 v16, v15
	v_pk_mul_f32 v[8:9], v[8:9], v[14:15] op_sel_hi:[1,0]
	v_fma_f32 v18, -v15, v16, 1.0
	v_fmac_f32_e32 v16, v18, v16
	v_div_scale_f32 v18, vcc, v19, v7, v19
	v_mul_f32_e32 v22, v18, v16
	v_fma_f32 v23, -v15, v22, v18
	v_fmac_f32_e32 v22, v23, v16
	v_fma_f32 v15, -v15, v22, v18
	v_div_scale_f32 v18, s[8:9], v6, v6, v17
	v_rcp_f32_e32 v23, v18
	v_div_fmas_f32 v15, v15, v16, v22
	v_div_fixup_f32 v7, v15, v7, v19
	v_pk_mul_f32 v[8:9], v[8:9], v[108:109]
	v_fma_f32 v15, -v18, v23, 1.0
	v_fmac_f32_e32 v23, v15, v23
	v_div_scale_f32 v15, vcc, v17, v6, v17
	v_mul_f32_e32 v16, v15, v23
	v_fma_f32 v19, -v18, v16, v15
	v_fmac_f32_e32 v16, v19, v23
	v_fma_f32 v15, -v18, v16, v15
	v_div_fmas_f32 v15, v15, v23, v16
	v_div_fixup_f32 v6, v15, v6, v17
	v_pk_mul_f32 v[6:7], v[8:9], v[6:7]
	v_mul_f32_e32 v9, 0xbfb8aa3b, v35
	v_mul_f32_e32 v8, 0xbfb8aa3b, v34
	v_exp_f32_e32 v16, v9
	v_mul_f32_e32 v9, 0xbfb8aa3b, v36
	v_exp_f32_e32 v8, v8
	v_exp_f32_e32 v9, v9
	v_mov_b32_e32 v18, v2
	v_mov_b32_e32 v19, v4
	v_pk_mul_f32 v[18:19], v[18:19], v[14:15] op_sel_hi:[1,0]
	v_pk_add_f32 v[8:9], v[8:9], 1.0 op_sel_hi:[1,0]
	v_mov_b32_e32 v22, v38
	v_div_scale_f32 v2, s[8:9], v9, v9, v36
	v_rcp_f32_e32 v4, v2
	v_mov_b32_e32 v23, v40
	v_pk_mul_f32 v[18:19], v[18:19], v[22:23]
	v_mov_b32_e32 v40, v39
	v_fma_f32 v15, -v2, v4, 1.0
	v_fmac_f32_e32 v4, v15, v4
	v_div_scale_f32 v15, vcc, v36, v9, v36
	v_mul_f32_e32 v17, v15, v4
	v_fma_f32 v22, -v2, v17, v15
	v_fmac_f32_e32 v17, v22, v4
	v_fma_f32 v2, -v2, v17, v15
	v_div_scale_f32 v15, s[8:9], v8, v8, v34
	v_rcp_f32_e32 v22, v15
	v_div_fmas_f32 v2, v2, v4, v17
	v_div_fixup_f32 v9, v2, v9, v36
	v_fma_f32 v2, -v15, v22, 1.0
	v_fmac_f32_e32 v22, v2, v22
	v_div_scale_f32 v2, vcc, v34, v8, v34
	v_mul_f32_e32 v4, v2, v22
	v_fma_f32 v17, -v15, v4, v2
	v_fmac_f32_e32 v4, v17, v22
	v_fma_f32 v2, -v15, v4, v2
	v_div_fmas_f32 v2, v2, v22, v4
	v_mul_f32_e32 v4, 0xbfb8aa3b, v37
	v_exp_f32_e32 v17, v4
	v_div_fixup_f32 v8, v2, v8, v34
	v_mov_b32_e32 v4, v3
	v_pk_mul_f32 v[8:9], v[18:19], v[8:9]
	v_pk_add_f32 v[2:3], v[16:17], 1.0 op_sel_hi:[1,0]
	s_nop 0
	v_div_scale_f32 v15, s[8:9], v3, v3, v37
	v_rcp_f32_e32 v16, v15
	v_pk_mul_f32 v[4:5], v[4:5], v[14:15] op_sel_hi:[1,0]
	v_fma_f32 v14, -v15, v16, 1.0
	v_fmac_f32_e32 v16, v14, v16
	v_div_scale_f32 v14, vcc, v37, v3, v37
	v_mul_f32_e32 v17, v14, v16
	v_fma_f32 v18, -v15, v17, v14
	v_fmac_f32_e32 v17, v18, v16
	v_fma_f32 v14, -v15, v17, v14
	v_div_scale_f32 v15, s[8:9], v2, v2, v35
	v_rcp_f32_e32 v18, v15
	v_div_fmas_f32 v14, v14, v16, v17
	v_div_fixup_f32 v3, v14, v3, v37
	v_pk_mul_f32 v[4:5], v[4:5], v[40:41]
	v_fma_f32 v14, -v15, v18, 1.0
	v_fmac_f32_e32 v18, v14, v18
	v_div_scale_f32 v14, vcc, v35, v2, v35
	v_mul_f32_e32 v16, v14, v18
	v_fma_f32 v17, -v15, v16, v14
	v_fmac_f32_e32 v16, v17, v18
	v_fma_f32 v14, -v15, v16, v14
	v_div_fmas_f32 v14, v14, v18, v16
	v_div_fixup_f32 v2, v14, v2, v35
	v_pk_mul_f32 v[2:3], v[4:5], v[2:3]
	v_bfe_u32 v5, v2, 16, 1
	v_add3_u32 v2, v2, v5, s33
	v_bfe_u32 v14, v8, 16, 1
	v_add3_u32 v8, v8, v14, s33
	v_lshrrev_b32_e32 v4, 16, v8
	v_cvt_pk_bf16_f32 v5, v9, v3
	v_and_or_b32 v4, v2, s34, v4
	v_cvt_pk_bf16_f32 v3, v21, v7
	v_cvt_pk_bf16_f32 v2, v20, v6
	v_lshlrev_b64 v[6:7], 11, v[60:61]
	v_lshl_add_u64 v[6:7], s[68:69], 0, v[6:7]
	v_lshl_add_u64 v[6:7], v[6:7], 0, s[70:71]
	v_lshl_add_u64 v[6:7], v[6:7], 0, v[42:43]
	v_lshl_add_u64 v[8:9], v[6:7], 0, s[74:75]
	v_add_co_u32_e32 v6, vcc, 0xdc00000, v6
	s_nop 1
	v_addc_co_u32_e32 v7, vcc, 0, v7, vcc
	global_store_dwordx4 v[6:7], v[10:13], off offset:1024
	global_store_dwordx4 v[8:9], v[2:5], off offset:16
	s_branch .LBB0_5556

.LBB0_5691:
	s_or_b64 exec, exec, s[10:11]
	v_mov_b32_e32 v1, v0
	v_mov_b64_e32 v[2:3], s[0:1]
	s_barrier
	global_load_dwordx2 v[2:3], v[2:3], off offset:88
	s_waitcnt vmcnt(0)
	v_readfirstlane_b32 s5, v1
	s_ashr_i32 s5, s5, 4
	s_and_b32 s6, s5, -4
	s_cmp_gt_i32 s6, 63
	s_cbranch_scc1 .LBB0_5694
	v_and_b32_e32 v21, 63, v1
	v_mov_b32_e32 v91, 0
	v_lshlrev_b32_e32 v90, 4, v21
	s_waitcnt lgkmcnt(0)
	v_lshl_add_u64 v[2:3], v[2:3], 0, v[90:91]
	s_movk_i32 s5, 0x5000
	v_add_co_u32_e32 v18, vcc, s5, v2
	v_mbcnt_lo_u32_b32 v1, -1, 0
	s_nop 0
	v_addc_co_u32_e32 v19, vcc, 0, v3, vcc
	global_load_dwordx4 v[2:5], v[18:19], off
	global_load_dwordx4 v[6:9], v[18:19], off offset:1024
	global_load_dwordx4 v[10:13], v[18:19], off offset:2048
	global_load_dwordx4 v[14:17], v[18:19], off offset:3072
	v_mbcnt_hi_u32_b32 v18, -1, v1
	v_and_b32_e32 v1, 64, v18
	v_add_u32_e32 v19, 64, v1
	v_xor_b32_e32 v1, 1, v18
	v_cmp_lt_i32_e32 vcc, v1, v19
	v_xor_b32_e32 v20, 2, v18
	s_lshl_b32 s7, s28, 8
	v_cndmask_b32_e32 v1, v18, v1, vcc
	v_cmp_lt_i32_e32 vcc, v20, v19
	s_lshl_b32 s4, s4, 6
	s_add_i32 s8, s7, s4
	v_cndmask_b32_e32 v20, v18, v20, vcc
	v_lshlrev_b32_e32 v166, 2, v20
	v_xor_b32_e32 v20, 4, v18
	v_cmp_lt_i32_e32 vcc, v20, v19
	s_add_i32 s10, s6, s8
	s_add_u32 s4, s68, 0x5800000
	v_cndmask_b32_e32 v20, v18, v20, vcc
	v_lshlrev_b32_e32 v167, 2, v20
	v_xor_b32_e32 v20, 8, v18
	v_cmp_lt_i32_e32 vcc, v20, v19
	s_addc_u32 s5, s69, 0
	s_lshl_b32 s3, s3, 6
	v_cndmask_b32_e32 v20, v18, v20, vcc
	v_lshlrev_b32_e32 v168, 2, v20
	v_xor_b32_e32 v20, 16, v18
	v_cmp_lt_i32_e32 vcc, v20, v19
	s_add_i32 s3, s7, s3
	s_add_i32 s3, s3, s6
	v_cndmask_b32_e32 v20, v18, v20, vcc
	v_lshlrev_b32_e32 v169, 2, v20
	v_xor_b32_e32 v20, 32, v18
	v_cmp_lt_i32_e32 vcc, v20, v19
	s_lshl_b32 s2, s2, 6
	s_sub_i32 s2, s3, s2
	v_cndmask_b32_e32 v18, v18, v20, vcc
	s_ashr_i32 s11, s10, 31
	v_lshlrev_b32_e32 v170, 2, v18
	v_lshlrev_b32_e32 v18, 2, v21
	s_or_b32 s20, s8, 32
	s_sub_i32 s8, s2, 32
	s_lshl_b64 s[2:3], s[10:11], 11
	v_or_b32_e32 v20, 0x100, v18
	v_or_b32_e32 v22, 0x200, v18
	v_or_b32_e32 v24, 0x300, v18
	v_lshl_or_b32 v92, v21, 3, s2
	v_mov_b32_e32 v93, s3
	s_lshl_b64 s[2:3], s[10:11], 12
	v_lshlrev_b32_e32 v1, 2, v1
	v_or_b32_e32 v94, s2, v90
	v_mov_b32_e32 v95, s3
	v_mov_b32_e32 v171, 0x358637bd
	s_mov_b32 s2, 0xf800000
	v_mov_b32_e32 v172, 0x260
	v_lshlrev_b32_e32 v90, 2, v18
	s_movk_i32 s3, 0x7fff
	s_mov_b32 s21, 0xffff0000
	s_mov_b32 s22, 0xba00000
	v_lshlrev_b32_e32 v96, 2, v20
	v_lshlrev_b32_e32 v98, 2, v22
	v_mov_b32_e32 v99, v91
	v_lshlrev_b32_e32 v100, 2, v24
	v_mov_b32_e32 v101, v91
	s_mov_b32 s23, 0xba01000
	s_mov_b64 s[12:13], 0x10000
	s_mov_b64 s[14:15], 0x20000
	v_mov_b32_e32 v97, v91

.LBB0_5799:
	s_or_b64 exec, exec, s[6:7]
	v_mov_b32_e32 v1, v0
	v_mov_b64_e32 v[2:3], s[0:1]
	s_barrier
	global_load_dwordx2 v[2:3], v[2:3], off offset:200
	s_waitcnt vmcnt(0)
	v_readfirstlane_b32 s5, v1
	s_ashr_i32 s6, s5, 6
	s_cmp_gt_i32 s6, 7
	s_cbranch_scc1 .LBB0_5802
	v_and_b32_e32 v20, 63, v1
	v_mov_b32_e32 v83, 0
	v_lshlrev_b32_e32 v82, 4, v20
	s_waitcnt lgkmcnt(0)
	v_lshl_add_u64 v[18:19], v[2:3], 0, v[82:83]
	global_load_dwordx4 v[2:5], v[18:19], off
	global_load_dwordx4 v[6:9], v[18:19], off offset:1024
	global_load_dwordx4 v[10:13], v[18:19], off offset:2048
	global_load_dwordx4 v[14:17], v[18:19], off offset:3072
	v_mbcnt_lo_u32_b32 v1, -1, 0
	v_mbcnt_hi_u32_b32 v18, -1, v1
	v_and_b32_e32 v1, 64, v18
	v_add_u32_e32 v19, 64, v1
	v_xor_b32_e32 v1, 1, v18
	v_cmp_lt_i32_e32 vcc, v1, v19
	v_xor_b32_e32 v21, 2, v18
	s_lshl_b32 s7, s82, 5
	v_cndmask_b32_e32 v1, v18, v1, vcc
	v_cmp_lt_i32_e32 vcc, v21, v19
	s_lshl_b32 s6, s6, 2
	s_add_i32 s6, s7, s6
	v_cndmask_b32_e32 v21, v18, v21, vcc
	v_lshlrev_b32_e32 v94, 2, v21
	v_xor_b32_e32 v21, 4, v18
	v_cmp_lt_i32_e32 vcc, v21, v19
	s_add_i32 s5, s7, 0x20a0
	s_add_i32 s20, s6, 0x2080
	v_cndmask_b32_e32 v21, v18, v21, vcc
	v_lshlrev_b32_e32 v95, 2, v21
	v_xor_b32_e32 v21, 8, v18
	v_cmp_lt_i32_e32 vcc, v21, v19
	s_add_u32 s28, s68, 0x4000000
	s_addc_u32 s29, s69, 0
	v_cndmask_b32_e32 v21, v18, v21, vcc
	v_lshlrev_b32_e32 v96, 2, v21
	v_xor_b32_e32 v21, 16, v18
	v_cmp_lt_i32_e32 vcc, v21, v19
	s_ashr_i32 s21, s20, 31
	s_mov_b32 s23, 0
	v_cndmask_b32_e32 v21, v18, v21, vcc
	v_lshlrev_b32_e32 v97, 2, v21
	v_xor_b32_e32 v21, 32, v18
	v_cmp_lt_i32_e32 vcc, v21, v19
	v_lshlrev_b32_e32 v1, 2, v1
	s_lshl_b64 s[24:25], s[20:21], 12
	v_cndmask_b32_e32 v18, v18, v21, vcc
	v_lshlrev_b32_e32 v98, 2, v18
	v_lshlrev_b32_e32 v18, 2, v20
	v_lshl_add_u64 v[84:85], s[70:71], 0, v[82:83]
	v_mov_b32_e32 v99, 0x358637bd
	s_mov_b32 s21, 0xf800000
	v_mov_b32_e32 v100, 0x260
	v_lshlrev_b32_e32 v82, 2, v18
	s_mov_b64 s[26:27], 0x20000
	s_mov_b64 s[38:39], s[68:69]

.LBB0_5946:
	s_or_b64 exec, exec, s[6:7]
	v_mov_b64_e32 v[2:3], s[0:1]
	s_barrier
	global_load_dwordx2 v[2:3], v[2:3], off offset:200
	s_waitcnt vmcnt(0)
	v_readfirstlane_b32 s0, v0
	s_ashr_i32 s0, s0, 6
	s_cmp_gt_i32 s0, 15
	s_cbranch_scc1 .LBB0_5949
	v_and_b32_e32 v18, 63, v0
	v_mov_b32_e32 v81, 0
	v_lshlrev_b32_e32 v80, 4, v18
	s_waitcnt lgkmcnt(0)
	v_lshl_add_u64 v[16:17], v[2:3], 0, v[80:81]
	global_load_dwordx4 v[0:3], v[16:17], off
	global_load_dwordx4 v[4:7], v[16:17], off offset:1024
	global_load_dwordx4 v[8:11], v[16:17], off offset:2048
	global_load_dwordx4 v[12:15], v[16:17], off offset:3072
	v_mbcnt_lo_u32_b32 v16, -1, 0
	v_mbcnt_hi_u32_b32 v16, -1, v16
	v_and_b32_e32 v17, 64, v16
	v_add_u32_e32 v17, 64, v17
	v_xor_b32_e32 v19, 1, v16
	v_cmp_lt_i32_e32 vcc, v19, v17
	s_lshl_b32 s1, s31, 8
	s_lshl_b32 s2, s30, 6
	v_cndmask_b32_e32 v19, v16, v19, vcc
	v_lshlrev_b32_e32 v92, 2, v19
	v_xor_b32_e32 v19, 2, v16
	v_cmp_lt_i32_e32 vcc, v19, v17
	s_add_i32 s2, s1, s2
	s_lshl_b32 s3, s0, 2
	v_cndmask_b32_e32 v19, v16, v19, vcc
	v_lshlrev_b32_e32 v93, 2, v19
	v_xor_b32_e32 v19, 4, v16
	v_cmp_lt_i32_e32 vcc, v19, v17
	s_add_i32 s0, s3, s2
	s_or_b32 s14, s2, 32
	v_cndmask_b32_e32 v19, v16, v19, vcc
	v_lshlrev_b32_e32 v94, 2, v19
	v_xor_b32_e32 v19, 8, v16
	v_cmp_lt_i32_e32 vcc, v19, v17
	s_add_u32 s15, s68, 0x4000000
	s_addc_u32 s16, s69, 0
	v_cndmask_b32_e32 v19, v16, v19, vcc
	v_lshlrev_b32_e32 v95, 2, v19
	v_xor_b32_e32 v19, 16, v16
	v_cmp_lt_i32_e32 vcc, v19, v17
	s_lshl_b32 s2, s29, 6
	s_add_i32 s1, s1, s2
	v_cndmask_b32_e32 v19, v16, v19, vcc
	v_lshlrev_b32_e32 v96, 2, v19
	v_xor_b32_e32 v19, 32, v16
	v_cmp_lt_i32_e32 vcc, v19, v17
	s_add_i32 s1, s1, s3
	s_lshl_b32 s2, s28, 6
	v_cndmask_b32_e32 v16, v16, v19, vcc
	s_sub_i32 s1, s1, s2
	v_lshlrev_b32_e32 v97, 2, v16
	v_lshlrev_b32_e32 v16, 2, v18
	s_sub_i32 s17, s1, 32
	s_ashr_i32 s1, s0, 31
	s_mov_b32 s9, 0
	s_lshl_b64 s[10:11], s[0:1], 12
	v_lshl_add_u64 v[82:83], s[70:71], 0, v[80:81]
	v_mov_b32_e32 v98, 0x358637bd
	s_mov_b32 s18, 0xf800000
	v_mov_b32_e32 v99, 0x260
	v_lshlrev_b32_e32 v80, 2, v16
	s_mov_b64 s[12:13], 0x20000

	.amdhsa_kernel _Z10fwd_kernel4Args
		.amdhsa_group_segment_fixed_size 0
		.amdhsa_private_segment_fixed_size 0
		.amdhsa_kernarg_size 488
		.amdhsa_user_sgpr_count 2
		.amdhsa_user_sgpr_dispatch_ptr 0
		.amdhsa_user_sgpr_queue_ptr 0
		.amdhsa_user_sgpr_kernarg_segment_ptr 1
		.amdhsa_user_sgpr_dispatch_id 0
		.amdhsa_user_sgpr_kernarg_preload_length 0
		.amdhsa_user_sgpr_kernarg_preload_offset 0
		.amdhsa_user_sgpr_private_segment_size 0
		.amdhsa_uses_dynamic_stack 0
		.amdhsa_enable_private_segment 0
		.amdhsa_system_sgpr_workgroup_id_x 1
		.amdhsa_system_sgpr_workgroup_id_y 0
		.amdhsa_system_sgpr_workgroup_id_z 0
		.amdhsa_system_sgpr_workgroup_info 0
		.amdhsa_system_vgpr_workitem_id 0
		.amdhsa_next_free_vgpr 254
		.amdhsa_next_free_sgpr 102
		.amdhsa_accum_offset 256
		.amdhsa_reserve_vcc 1
		.amdhsa_float_round_mode_32 0
		.amdhsa_float_round_mode_16_64 0
		.amdhsa_float_denorm_mode_32 3
		.amdhsa_float_denorm_mode_16_64 3
		.amdhsa_dx10_clamp 1
		.amdhsa_ieee_mode 1
		.amdhsa_fp16_overflow 0
		.amdhsa_tg_split 0
		.amdhsa_exception_fp_ieee_invalid_op 0
		.amdhsa_exception_fp_denorm_src 0
		.amdhsa_exception_fp_ieee_div_zero 0
		.amdhsa_exception_fp_ieee_overflow 0
		.amdhsa_exception_fp_ieee_underflow 0
		.amdhsa_exception_fp_ieee_inexact 0
		.amdhsa_exception_int_div_zero 0
	.end_amdhsa_kernel

amdhsa.kernels:
  - .agpr_count:     0
    .args:
      - .offset:         0
        .size:           232
        .value_kind:     by_value
      - .offset:         232
        .size:           4
        .value_kind:     hidden_block_count_x
      - .offset:         236
        .size:           4
        .value_kind:     hidden_block_count_y
      - .offset:         240
        .size:           4
        .value_kind:     hidden_block_count_z
      - .offset:         244
        .size:           2
        .value_kind:     hidden_group_size_x
      - .offset:         246
        .size:           2
        .value_kind:     hidden_group_size_y
      - .offset:         248
        .size:           2
        .value_kind:     hidden_group_size_z
      - .offset:         250
        .size:           2
        .value_kind:     hidden_remainder_x
      - .offset:         252
        .size:           2
        .value_kind:     hidden_remainder_y
      - .offset:         254
        .size:           2
        .value_kind:     hidden_remainder_z
      - .offset:         272
        .size:           8
        .value_kind:     hidden_global_offset_x
      - .offset:         280
        .size:           8
        .value_kind:     hidden_global_offset_y
      - .offset:         288
        .size:           8
        .value_kind:     hidden_global_offset_z
      - .offset:         296
        .size:           2
        .value_kind:     hidden_grid_dims
      - .offset:         352
        .size:           4
        .value_kind:     hidden_dynamic_lds_size
    .group_segment_fixed_size: 0
    .kernarg_segment_align: 8
    .kernarg_segment_size: 488
    .language:       OpenCL C
    .language_version:
      - 2
      - 0
    .max_flat_workgroup_size: 512
    .name:           _Z10fwd_kernel4Args
    .private_segment_fixed_size: 0
    .sgpr_count:     108
    .sgpr_spill_count: 74
    .symbol:         _Z10fwd_kernel4Args.kd
    .uniform_work_group_size: 1
    .uses_dynamic_stack: false
    .vgpr_count:     254
    .vgpr_spill_count: 0
    .wavefront_size: 64
